# v-side gather: 1 KB dwordx4 loads with quad-contiguous lane map (lane pairs 4 apart exchange halves by DPP, permlane16 swap restores the output map)
# speedup vs baseline: 1.0632x; 1.0295x over previous
.LpgL0_unoflushu0:
	s_cmp_lt_u32 s0, 8
	s_cbranch_scc1 .LpgL0_uloopu0
	s_waitcnt vmcnt(0)
	s_nop 15
	v_cndmask_b32_e64 v176, v176, v177, s[4:5]
	v_cndmask_b32_e64 v180, v180, v181, s[4:5]
	v_cndmask_b32_e64 v184, v184, v185, s[4:5]
	v_cndmask_b32_e64 v188, v188, v189, s[4:5]
	v_cndmask_b32_e64 v176, v176, v178, s[6:7]
	v_cndmask_b32_e64 v180, v180, v182, s[6:7]
	v_cndmask_b32_e64 v184, v184, v186, s[6:7]
	v_cndmask_b32_e64 v188, v188, v190, s[6:7]
	v_cndmask_b32_e64 v176, v176, v179, s[8:9]
	v_cndmask_b32_e64 v180, v180, v183, s[8:9]
	v_cndmask_b32_e64 v184, v184, v187, s[8:9]
	v_cndmask_b32_e64 v188, v188, v191, s[8:9]
	v_add_f32_dpp v176, v176, v176 quad_perm:[1,0,3,2] row_mask:0xf bank_mask:0xf bound_ctrl:1
	v_add_f32_dpp v180, v180, v180 quad_perm:[1,0,3,2] row_mask:0xf bank_mask:0xf bound_ctrl:1
	v_add_f32_dpp v184, v184, v184 quad_perm:[1,0,3,2] row_mask:0xf bank_mask:0xf bound_ctrl:1
	v_add_f32_dpp v188, v188, v188 quad_perm:[1,0,3,2] row_mask:0xf bank_mask:0xf bound_ctrl:1
	v_add_f32_dpp v176, v176, v176 quad_perm:[2,3,0,1] row_mask:0xf bank_mask:0xf bound_ctrl:1
	v_add_f32_dpp v180, v180, v180 quad_perm:[2,3,0,1] row_mask:0xf bank_mask:0xf bound_ctrl:1
	v_add_f32_dpp v184, v184, v184 quad_perm:[2,3,0,1] row_mask:0xf bank_mask:0xf bound_ctrl:1
	v_add_f32_dpp v188, v188, v188 quad_perm:[2,3,0,1] row_mask:0xf bank_mask:0xf bound_ctrl:1
	v_cndmask_b32_e64 v176, v176, v180, s[4:5]
	v_cndmask_b32_e64 v176, v176, v184, s[6:7]
	v_cndmask_b32_e64 v176, v176, v188, s[8:9]
	v_add_f32_e32 v219, v219, v176
	ds_read_b32 v0, v243 offset:0
	ds_read_b32 v1, v243 offset:256
	ds_read_b32 v2, v243 offset:512
	ds_read_b32 v3, v243 offset:768
	ds_read_b32 v4, v243 offset:1024
	ds_read_b32 v5, v243 offset:1280
	ds_read_b32 v6, v243 offset:1536
	ds_read_b32 v7, v243 offset:1792
	ds_read_b32 v8, v243 offset:2048
	ds_read_b32 v9, v243 offset:2304
	ds_read_b32 v10, v243 offset:2560
	ds_read_b32 v11, v243 offset:2816
	ds_read_b32 v12, v243 offset:3072
	ds_read_b32 v13, v243 offset:3328
	ds_read_b32 v14, v243 offset:3584
	ds_read_b32 v15, v243 offset:3840
	global_load_dword v96, v246, s[40:41] offset:0
	global_load_dword v97, v246, s[40:41] offset:4
	global_load_dword v98, v246, s[40:41] offset:8
	global_load_dword v99, v246, s[40:41] offset:12
	global_load_dword v100, v246, s[40:41] offset:16
	global_load_dword v101, v246, s[40:41] offset:20
	global_load_dword v102, v246, s[40:41] offset:24
	global_load_dword v103, v246, s[40:41] offset:28
	global_load_dword v16, v244, s[26:27] offset:0
	global_load_dword v17, v244, s[26:27] offset:256
	global_load_dword v18, v244, s[26:27] offset:512
	global_load_dword v19, v244, s[26:27] offset:768
	global_load_dword v20, v244, s[26:27] offset:1024
	global_load_dword v21, v244, s[26:27] offset:1280
	global_load_dword v22, v244, s[26:27] offset:1536
	global_load_dword v23, v244, s[26:27] offset:1792
	global_load_dword v24, v244, s[26:27] offset:2048
	global_load_dword v25, v244, s[26:27] offset:2304
	global_load_dword v26, v244, s[26:27] offset:2560
	global_load_dword v27, v244, s[26:27] offset:2816
	global_load_dword v28, v244, s[26:27] offset:3072
	global_load_dword v29, v244, s[26:27] offset:3328
	global_load_dword v30, v244, s[26:27] offset:3584
	global_load_dword v31, v244, s[26:27] offset:3840
	s_waitcnt lgkmcnt(0)
	v_lshlrev_b32_e32 v0, 3, v0
	global_load_dwordx2 v[32:33], v0, s[30:31]
	global_load_dwordx2 v[64:65], v0, s[34:35]
	v_lshlrev_b32_e32 v1, 3, v1
	global_load_dwordx2 v[34:35], v1, s[30:31]
	global_load_dwordx2 v[66:67], v1, s[34:35]
	v_lshlrev_b32_e32 v2, 3, v2
	global_load_dwordx2 v[36:37], v2, s[30:31]
	global_load_dwordx2 v[68:69], v2, s[34:35]
	v_lshlrev_b32_e32 v3, 3, v3
	global_load_dwordx2 v[38:39], v3, s[30:31]
	global_load_dwordx2 v[70:71], v3, s[34:35]
	v_lshlrev_b32_e32 v4, 3, v4
	global_load_dwordx2 v[40:41], v4, s[30:31]
	global_load_dwordx2 v[72:73], v4, s[34:35]
	v_lshlrev_b32_e32 v5, 3, v5
	global_load_dwordx2 v[42:43], v5, s[30:31]
	global_load_dwordx2 v[74:75], v5, s[34:35]
	v_lshlrev_b32_e32 v6, 3, v6
	global_load_dwordx2 v[44:45], v6, s[30:31]
	global_load_dwordx2 v[76:77], v6, s[34:35]
	v_lshlrev_b32_e32 v7, 3, v7
	global_load_dwordx2 v[46:47], v7, s[30:31]
	global_load_dwordx2 v[78:79], v7, s[34:35]
	v_lshlrev_b32_e32 v8, 3, v8
	global_load_dwordx2 v[48:49], v8, s[30:31]
	global_load_dwordx2 v[80:81], v8, s[34:35]
	v_lshlrev_b32_e32 v9, 3, v9
	global_load_dwordx2 v[50:51], v9, s[30:31]
	global_load_dwordx2 v[82:83], v9, s[34:35]
	v_lshlrev_b32_e32 v10, 3, v10
	global_load_dwordx2 v[52:53], v10, s[30:31]
	global_load_dwordx2 v[84:85], v10, s[34:35]
	v_lshlrev_b32_e32 v11, 3, v11
	global_load_dwordx2 v[54:55], v11, s[30:31]
	global_load_dwordx2 v[86:87], v11, s[34:35]
	v_lshlrev_b32_e32 v12, 3, v12
	global_load_dwordx2 v[56:57], v12, s[30:31]
	global_load_dwordx2 v[88:89], v12, s[34:35]
	v_lshlrev_b32_e32 v13, 3, v13
	global_load_dwordx2 v[58:59], v13, s[30:31]
	global_load_dwordx2 v[90:91], v13, s[34:35]
	v_lshlrev_b32_e32 v14, 3, v14
	global_load_dwordx2 v[60:61], v14, s[30:31]
	global_load_dwordx2 v[92:93], v14, s[34:35]
	v_lshlrev_b32_e32 v15, 3, v15
	global_load_dwordx2 v[62:63], v15, s[30:31]
	global_load_dwordx2 v[94:95], v15, s[34:35]
	s_waitcnt vmcnt(0)
	v_mov_b32_e32 v120, 0x358637bd
	v_fmamk_f32 v96, v96, 0x3a000000, v120
	v_cmp_gt_f32_e32 vcc, s96, v96
	v_mul_f32_e32 v121, 0x4b800000, v96
	s_nop 0
	v_cndmask_b32_e32 v96, v96, v121, vcc
	v_rsq_f32_e32 v96, v96
	s_nop 0
	v_mul_f32_e32 v121, 0x45800000, v96
	v_cndmask_b32_e32 v96, v96, v121, vcc
	v_fmamk_f32 v97, v97, 0x3a000000, v120
	v_cmp_gt_f32_e32 vcc, s96, v97
	v_mul_f32_e32 v121, 0x4b800000, v97
	s_nop 0
	v_cndmask_b32_e32 v97, v97, v121, vcc
	v_rsq_f32_e32 v97, v97
	s_nop 0
	v_mul_f32_e32 v121, 0x45800000, v97
	v_cndmask_b32_e32 v97, v97, v121, vcc
	v_fmamk_f32 v98, v98, 0x3a000000, v120
	v_cmp_gt_f32_e32 vcc, s96, v98
	v_mul_f32_e32 v121, 0x4b800000, v98
	s_nop 0
	v_cndmask_b32_e32 v98, v98, v121, vcc
	v_rsq_f32_e32 v98, v98
	s_nop 0
	v_mul_f32_e32 v121, 0x45800000, v98
	v_cndmask_b32_e32 v98, v98, v121, vcc
	v_fmamk_f32 v99, v99, 0x3a000000, v120
	v_cmp_gt_f32_e32 vcc, s96, v99
	v_mul_f32_e32 v121, 0x4b800000, v99
	s_nop 0
	v_cndmask_b32_e32 v99, v99, v121, vcc
	v_rsq_f32_e32 v99, v99
	s_nop 0
	v_mul_f32_e32 v121, 0x45800000, v99
	v_cndmask_b32_e32 v99, v99, v121, vcc
	v_fmamk_f32 v100, v100, 0x3a000000, v120
	v_cmp_gt_f32_e32 vcc, s96, v100
	v_mul_f32_e32 v121, 0x4b800000, v100
	s_nop 0
	v_cndmask_b32_e32 v100, v100, v121, vcc
	v_rsq_f32_e32 v100, v100
	s_nop 0
	v_mul_f32_e32 v121, 0x45800000, v100
	v_cndmask_b32_e32 v100, v100, v121, vcc
	v_fmamk_f32 v101, v101, 0x3a000000, v120
	v_cmp_gt_f32_e32 vcc, s96, v101
	v_mul_f32_e32 v121, 0x4b800000, v101
	s_nop 0
	v_cndmask_b32_e32 v101, v101, v121, vcc
	v_rsq_f32_e32 v101, v101
	s_nop 0
	v_mul_f32_e32 v121, 0x45800000, v101
	v_cndmask_b32_e32 v101, v101, v121, vcc
	v_fmamk_f32 v102, v102, 0x3a000000, v120
	v_cmp_gt_f32_e32 vcc, s96, v102
	v_mul_f32_e32 v121, 0x4b800000, v102
	s_nop 0
	v_cndmask_b32_e32 v102, v102, v121, vcc
	v_rsq_f32_e32 v102, v102
	s_nop 0
	v_mul_f32_e32 v121, 0x45800000, v102
	v_cndmask_b32_e32 v102, v102, v121, vcc
	v_fmamk_f32 v103, v103, 0x3a000000, v120
	v_cmp_gt_f32_e32 vcc, s96, v103
	v_mul_f32_e32 v121, 0x4b800000, v103
	s_nop 0
	v_cndmask_b32_e32 v103, v103, v121, vcc
	v_rsq_f32_e32 v103, v103
	s_nop 0
	v_mul_f32_e32 v121, 0x45800000, v103
	v_cndmask_b32_e32 v103, v103, v121, vcc
	v_mul_f32_e32 v104, v220, v32
	v_fmac_f32_e32 v104, v204, v33
	v_mul_f32_e32 v104, v104, v96
	v_mul_f32_e32 v105, 0x3d372713, v104
	v_mul_f32_e32 v105, v104, v105
	v_fma_f32 v105, v104, v105, v104
	v_mul_f32_e32 v105, 0x3f4c422a, v105
	v_add_f32_e32 v105, v105, v105
	v_mul_f32_e32 v105, 0x3fb8aa3b, v105
	v_exp_f32_e32 v105, v105
	v_mul_f32_e32 v104, 0.5, v104
	v_add_f32_e32 v105, 1.0, v105
	v_div_scale_f32 v106, s[70:71], v105, v105, 2.0
	v_rcp_f32_e32 v107, v106
	s_nop 0
	v_fma_f32 v108, -v106, v107, 1.0
	v_fmac_f32_e32 v107, v108, v107
	v_div_scale_f32 v108, vcc, 2.0, v105, 2.0
	v_mul_f32_e32 v109, v108, v107
	v_fma_f32 v110, -v106, v109, v108
	v_fmac_f32_e32 v109, v110, v107
	v_fma_f32 v106, -v106, v109, v108
	v_div_fmas_f32 v106, v106, v107, v109
	v_div_fixup_f32 v105, v106, v105, 2.0
	v_sub_f32_e32 v105, 1.0, v105
	v_add_f32_e32 v105, 1.0, v105
	v_mul_f32_e32 v104, v104, v105
	v_mul_f32_e32 v104, v16, v104
	v_mul_f32_e32 v105, v64, v104
	v_mul_f32_e32 v105, 0x43800000, v105
	v_mov_b32_e32 v106, 0x43e00000
	v_med3_f32 v105, v105, s94, v106
	v_mov_b32_e32 v106, 0
	v_cvt_pk_fp8_f32 v106, v105, 0
	s_nop 0
	v_and_b32_e32 v106, 0xff, v106
	v_mul_lo_u32 v106, v106, s81
	ds_write_b32 v245, v106 offset:0
	v_mul_f32_e32 v105, v65, v104
	v_mul_f32_e32 v105, 0x43800000, v105
	v_mov_b32_e32 v106, 0x43e00000
	v_med3_f32 v105, v105, s94, v106
	v_mov_b32_e32 v106, 0
	v_cvt_pk_fp8_f32 v106, v105, 0
	s_nop 0
	v_and_b32_e32 v106, 0xff, v106
	v_mul_lo_u32 v106, v106, s81
	ds_write_b32 v245, v106 offset:4096
	v_mul_f32_e32 v104, v221, v34
	v_fmac_f32_e32 v104, v205, v35
	v_mul_f32_e32 v104, v104, v96
	v_mul_f32_e32 v105, 0x3d372713, v104
	v_mul_f32_e32 v105, v104, v105
	v_fma_f32 v105, v104, v105, v104
	v_mul_f32_e32 v105, 0x3f4c422a, v105
	v_add_f32_e32 v105, v105, v105
	v_mul_f32_e32 v105, 0x3fb8aa3b, v105
	v_exp_f32_e32 v105, v105
	v_mul_f32_e32 v104, 0.5, v104
	v_add_f32_e32 v105, 1.0, v105
	v_div_scale_f32 v106, s[70:71], v105, v105, 2.0
	v_rcp_f32_e32 v107, v106
	s_nop 0
	v_fma_f32 v108, -v106, v107, 1.0
	v_fmac_f32_e32 v107, v108, v107
	v_div_scale_f32 v108, vcc, 2.0, v105, 2.0
	v_mul_f32_e32 v109, v108, v107
	v_fma_f32 v110, -v106, v109, v108
	v_fmac_f32_e32 v109, v110, v107
	v_fma_f32 v106, -v106, v109, v108
	v_div_fmas_f32 v106, v106, v107, v109
	v_div_fixup_f32 v105, v106, v105, 2.0
	v_sub_f32_e32 v105, 1.0, v105
	v_add_f32_e32 v105, 1.0, v105
	v_mul_f32_e32 v104, v104, v105
	v_mul_f32_e32 v104, v17, v104
	v_mul_f32_e32 v105, v66, v104
	v_mul_f32_e32 v105, 0x43800000, v105
	v_mov_b32_e32 v106, 0x43e00000
	v_med3_f32 v105, v105, s94, v106
	v_mov_b32_e32 v106, 0
	v_cvt_pk_fp8_f32 v106, v105, 0
	s_nop 0
	v_and_b32_e32 v106, 0xff, v106
	v_mul_lo_u32 v106, v106, s81
	ds_write_b32 v245, v106 offset:256
	v_mul_f32_e32 v105, v67, v104
	v_mul_f32_e32 v105, 0x43800000, v105
	v_mov_b32_e32 v106, 0x43e00000
	v_med3_f32 v105, v105, s94, v106
	v_mov_b32_e32 v106, 0
	v_cvt_pk_fp8_f32 v106, v105, 0
	s_nop 0
	v_and_b32_e32 v106, 0xff, v106
	v_mul_lo_u32 v106, v106, s81
	ds_write_b32 v245, v106 offset:4352
	v_mul_f32_e32 v104, v222, v36
	v_fmac_f32_e32 v104, v206, v37
	v_mul_f32_e32 v104, v104, v97
	v_mul_f32_e32 v105, 0x3d372713, v104
	v_mul_f32_e32 v105, v104, v105
	v_fma_f32 v105, v104, v105, v104
	v_mul_f32_e32 v105, 0x3f4c422a, v105
	v_add_f32_e32 v105, v105, v105
	v_mul_f32_e32 v105, 0x3fb8aa3b, v105
	v_exp_f32_e32 v105, v105
	v_mul_f32_e32 v104, 0.5, v104
	v_add_f32_e32 v105, 1.0, v105
	v_div_scale_f32 v106, s[70:71], v105, v105, 2.0
	v_rcp_f32_e32 v107, v106
	s_nop 0
	v_fma_f32 v108, -v106, v107, 1.0
	v_fmac_f32_e32 v107, v108, v107
	v_div_scale_f32 v108, vcc, 2.0, v105, 2.0
	v_mul_f32_e32 v109, v108, v107
	v_fma_f32 v110, -v106, v109, v108
	v_fmac_f32_e32 v109, v110, v107
	v_fma_f32 v106, -v106, v109, v108
	v_div_fmas_f32 v106, v106, v107, v109
	v_div_fixup_f32 v105, v106, v105, 2.0
	v_sub_f32_e32 v105, 1.0, v105
	v_add_f32_e32 v105, 1.0, v105
	v_mul_f32_e32 v104, v104, v105
	v_mul_f32_e32 v104, v18, v104
	v_mul_f32_e32 v105, v68, v104
	v_mul_f32_e32 v105, 0x43800000, v105
	v_mov_b32_e32 v106, 0x43e00000
	v_med3_f32 v105, v105, s94, v106
	v_mov_b32_e32 v106, 0
	v_cvt_pk_fp8_f32 v106, v105, 0
	s_nop 0
	v_and_b32_e32 v106, 0xff, v106
	v_mul_lo_u32 v106, v106, s81
	ds_write_b32 v245, v106 offset:512
	v_mul_f32_e32 v105, v69, v104
	v_mul_f32_e32 v105, 0x43800000, v105
	v_mov_b32_e32 v106, 0x43e00000
	v_med3_f32 v105, v105, s94, v106
	v_mov_b32_e32 v106, 0
	v_cvt_pk_fp8_f32 v106, v105, 0
	s_nop 0
	v_and_b32_e32 v106, 0xff, v106
	v_mul_lo_u32 v106, v106, s81
	ds_write_b32 v245, v106 offset:4608
	v_mul_f32_e32 v104, v223, v38
	v_fmac_f32_e32 v104, v207, v39
	v_mul_f32_e32 v104, v104, v97
	v_mul_f32_e32 v105, 0x3d372713, v104
	v_mul_f32_e32 v105, v104, v105
	v_fma_f32 v105, v104, v105, v104
	v_mul_f32_e32 v105, 0x3f4c422a, v105
	v_add_f32_e32 v105, v105, v105
	v_mul_f32_e32 v105, 0x3fb8aa3b, v105
	v_exp_f32_e32 v105, v105
	v_mul_f32_e32 v104, 0.5, v104
	v_add_f32_e32 v105, 1.0, v105
	v_div_scale_f32 v106, s[70:71], v105, v105, 2.0
	v_rcp_f32_e32 v107, v106
	s_nop 0
	v_fma_f32 v108, -v106, v107, 1.0
	v_fmac_f32_e32 v107, v108, v107
	v_div_scale_f32 v108, vcc, 2.0, v105, 2.0
	v_mul_f32_e32 v109, v108, v107
	v_fma_f32 v110, -v106, v109, v108
	v_fmac_f32_e32 v109, v110, v107
	v_fma_f32 v106, -v106, v109, v108
	v_div_fmas_f32 v106, v106, v107, v109
	v_div_fixup_f32 v105, v106, v105, 2.0
	v_sub_f32_e32 v105, 1.0, v105
	v_add_f32_e32 v105, 1.0, v105
	v_mul_f32_e32 v104, v104, v105
	v_mul_f32_e32 v104, v19, v104
	v_mul_f32_e32 v105, v70, v104
	v_mul_f32_e32 v105, 0x43800000, v105
	v_mov_b32_e32 v106, 0x43e00000
	v_med3_f32 v105, v105, s94, v106
	v_mov_b32_e32 v106, 0
	v_cvt_pk_fp8_f32 v106, v105, 0
	s_nop 0
	v_and_b32_e32 v106, 0xff, v106
	v_mul_lo_u32 v106, v106, s81
	ds_write_b32 v245, v106 offset:768
	v_mul_f32_e32 v105, v71, v104
	v_mul_f32_e32 v105, 0x43800000, v105
	v_mov_b32_e32 v106, 0x43e00000
	v_med3_f32 v105, v105, s94, v106
	v_mov_b32_e32 v106, 0
	v_cvt_pk_fp8_f32 v106, v105, 0
	s_nop 0
	v_and_b32_e32 v106, 0xff, v106
	v_mul_lo_u32 v106, v106, s81
	ds_write_b32 v245, v106 offset:4864
	v_mul_f32_e32 v104, v224, v40
	v_fmac_f32_e32 v104, v208, v41
	v_mul_f32_e32 v104, v104, v98
	v_mul_f32_e32 v105, 0x3d372713, v104
	v_mul_f32_e32 v105, v104, v105
	v_fma_f32 v105, v104, v105, v104
	v_mul_f32_e32 v105, 0x3f4c422a, v105
	v_add_f32_e32 v105, v105, v105
	v_mul_f32_e32 v105, 0x3fb8aa3b, v105
	v_exp_f32_e32 v105, v105
	v_mul_f32_e32 v104, 0.5, v104
	v_add_f32_e32 v105, 1.0, v105
	v_div_scale_f32 v106, s[70:71], v105, v105, 2.0
	v_rcp_f32_e32 v107, v106
	s_nop 0
	v_fma_f32 v108, -v106, v107, 1.0
	v_fmac_f32_e32 v107, v108, v107
	v_div_scale_f32 v108, vcc, 2.0, v105, 2.0
	v_mul_f32_e32 v109, v108, v107
	v_fma_f32 v110, -v106, v109, v108
	v_fmac_f32_e32 v109, v110, v107
	v_fma_f32 v106, -v106, v109, v108
	v_div_fmas_f32 v106, v106, v107, v109
	v_div_fixup_f32 v105, v106, v105, 2.0
	v_sub_f32_e32 v105, 1.0, v105
	v_add_f32_e32 v105, 1.0, v105
	v_mul_f32_e32 v104, v104, v105
	v_mul_f32_e32 v104, v20, v104
	v_mul_f32_e32 v105, v72, v104
	v_mul_f32_e32 v105, 0x43800000, v105
	v_mov_b32_e32 v106, 0x43e00000
	v_med3_f32 v105, v105, s94, v106
	v_mov_b32_e32 v106, 0
	v_cvt_pk_fp8_f32 v106, v105, 0
	s_nop 0
	v_and_b32_e32 v106, 0xff, v106
	v_mul_lo_u32 v106, v106, s81
	ds_write_b32 v245, v106 offset:1024
	v_mul_f32_e32 v105, v73, v104
	v_mul_f32_e32 v105, 0x43800000, v105
	v_mov_b32_e32 v106, 0x43e00000
	v_med3_f32 v105, v105, s94, v106
	v_mov_b32_e32 v106, 0
	v_cvt_pk_fp8_f32 v106, v105, 0
	s_nop 0
	v_and_b32_e32 v106, 0xff, v106
	v_mul_lo_u32 v106, v106, s81
	ds_write_b32 v245, v106 offset:5120
	v_mul_f32_e32 v104, v225, v42
	v_fmac_f32_e32 v104, v209, v43
	v_mul_f32_e32 v104, v104, v98
	v_mul_f32_e32 v105, 0x3d372713, v104
	v_mul_f32_e32 v105, v104, v105
	v_fma_f32 v105, v104, v105, v104
	v_mul_f32_e32 v105, 0x3f4c422a, v105
	v_add_f32_e32 v105, v105, v105
	v_mul_f32_e32 v105, 0x3fb8aa3b, v105
	v_exp_f32_e32 v105, v105
	v_mul_f32_e32 v104, 0.5, v104
	v_add_f32_e32 v105, 1.0, v105
	v_div_scale_f32 v106, s[70:71], v105, v105, 2.0
	v_rcp_f32_e32 v107, v106
	s_nop 0
	v_fma_f32 v108, -v106, v107, 1.0
	v_fmac_f32_e32 v107, v108, v107
	v_div_scale_f32 v108, vcc, 2.0, v105, 2.0
	v_mul_f32_e32 v109, v108, v107
	v_fma_f32 v110, -v106, v109, v108
	v_fmac_f32_e32 v109, v110, v107
	v_fma_f32 v106, -v106, v109, v108
	v_div_fmas_f32 v106, v106, v107, v109
	v_div_fixup_f32 v105, v106, v105, 2.0
	v_sub_f32_e32 v105, 1.0, v105
	v_add_f32_e32 v105, 1.0, v105
	v_mul_f32_e32 v104, v104, v105
	v_mul_f32_e32 v104, v21, v104
	v_mul_f32_e32 v105, v74, v104
	v_mul_f32_e32 v105, 0x43800000, v105
	v_mov_b32_e32 v106, 0x43e00000
	v_med3_f32 v105, v105, s94, v106
	v_mov_b32_e32 v106, 0
	v_cvt_pk_fp8_f32 v106, v105, 0
	s_nop 0
	v_and_b32_e32 v106, 0xff, v106
	v_mul_lo_u32 v106, v106, s81
	ds_write_b32 v245, v106 offset:1280
	v_mul_f32_e32 v105, v75, v104
	v_mul_f32_e32 v105, 0x43800000, v105
	v_mov_b32_e32 v106, 0x43e00000
	v_med3_f32 v105, v105, s94, v106
	v_mov_b32_e32 v106, 0
	v_cvt_pk_fp8_f32 v106, v105, 0
	s_nop 0
	v_and_b32_e32 v106, 0xff, v106
	v_mul_lo_u32 v106, v106, s81
	ds_write_b32 v245, v106 offset:5376
	v_mul_f32_e32 v104, v226, v44
	v_fmac_f32_e32 v104, v210, v45
	v_mul_f32_e32 v104, v104, v99
	v_mul_f32_e32 v105, 0x3d372713, v104
	v_mul_f32_e32 v105, v104, v105
	v_fma_f32 v105, v104, v105, v104
	v_mul_f32_e32 v105, 0x3f4c422a, v105
	v_add_f32_e32 v105, v105, v105
	v_mul_f32_e32 v105, 0x3fb8aa3b, v105
	v_exp_f32_e32 v105, v105
	v_mul_f32_e32 v104, 0.5, v104
	v_add_f32_e32 v105, 1.0, v105
	v_div_scale_f32 v106, s[70:71], v105, v105, 2.0
	v_rcp_f32_e32 v107, v106
	s_nop 0
	v_fma_f32 v108, -v106, v107, 1.0
	v_fmac_f32_e32 v107, v108, v107
	v_div_scale_f32 v108, vcc, 2.0, v105, 2.0
	v_mul_f32_e32 v109, v108, v107
	v_fma_f32 v110, -v106, v109, v108
	v_fmac_f32_e32 v109, v110, v107
	v_fma_f32 v106, -v106, v109, v108
	v_div_fmas_f32 v106, v106, v107, v109
	v_div_fixup_f32 v105, v106, v105, 2.0
	v_sub_f32_e32 v105, 1.0, v105
	v_add_f32_e32 v105, 1.0, v105
	v_mul_f32_e32 v104, v104, v105
	v_mul_f32_e32 v104, v22, v104
	v_mul_f32_e32 v105, v76, v104
	v_mul_f32_e32 v105, 0x43800000, v105
	v_mov_b32_e32 v106, 0x43e00000
	v_med3_f32 v105, v105, s94, v106
	v_mov_b32_e32 v106, 0
	v_cvt_pk_fp8_f32 v106, v105, 0
	s_nop 0
	v_and_b32_e32 v106, 0xff, v106
	v_mul_lo_u32 v106, v106, s81
	ds_write_b32 v245, v106 offset:1536
	v_mul_f32_e32 v105, v77, v104
	v_mul_f32_e32 v105, 0x43800000, v105
	v_mov_b32_e32 v106, 0x43e00000
	v_med3_f32 v105, v105, s94, v106
	v_mov_b32_e32 v106, 0
	v_cvt_pk_fp8_f32 v106, v105, 0
	s_nop 0
	v_and_b32_e32 v106, 0xff, v106
	v_mul_lo_u32 v106, v106, s81
	ds_write_b32 v245, v106 offset:5632
	v_mul_f32_e32 v104, v227, v46
	v_fmac_f32_e32 v104, v211, v47
	v_mul_f32_e32 v104, v104, v99
	v_mul_f32_e32 v105, 0x3d372713, v104
	v_mul_f32_e32 v105, v104, v105
	v_fma_f32 v105, v104, v105, v104
	v_mul_f32_e32 v105, 0x3f4c422a, v105
	v_add_f32_e32 v105, v105, v105
	v_mul_f32_e32 v105, 0x3fb8aa3b, v105
	v_exp_f32_e32 v105, v105
	v_mul_f32_e32 v104, 0.5, v104
	v_add_f32_e32 v105, 1.0, v105
	v_div_scale_f32 v106, s[70:71], v105, v105, 2.0
	v_rcp_f32_e32 v107, v106
	s_nop 0
	v_fma_f32 v108, -v106, v107, 1.0
	v_fmac_f32_e32 v107, v108, v107
	v_div_scale_f32 v108, vcc, 2.0, v105, 2.0
	v_mul_f32_e32 v109, v108, v107
	v_fma_f32 v110, -v106, v109, v108
	v_fmac_f32_e32 v109, v110, v107
	v_fma_f32 v106, -v106, v109, v108
	v_div_fmas_f32 v106, v106, v107, v109
	v_div_fixup_f32 v105, v106, v105, 2.0
	v_sub_f32_e32 v105, 1.0, v105
	v_add_f32_e32 v105, 1.0, v105
	v_mul_f32_e32 v104, v104, v105
	v_mul_f32_e32 v104, v23, v104
	v_mul_f32_e32 v105, v78, v104
	v_mul_f32_e32 v105, 0x43800000, v105
	v_mov_b32_e32 v106, 0x43e00000
	v_med3_f32 v105, v105, s94, v106
	v_mov_b32_e32 v106, 0
	v_cvt_pk_fp8_f32 v106, v105, 0
	s_nop 0
	v_and_b32_e32 v106, 0xff, v106
	v_mul_lo_u32 v106, v106, s81
	ds_write_b32 v245, v106 offset:1792
	v_mul_f32_e32 v105, v79, v104
	v_mul_f32_e32 v105, 0x43800000, v105
	v_mov_b32_e32 v106, 0x43e00000
	v_med3_f32 v105, v105, s94, v106
	v_mov_b32_e32 v106, 0
	v_cvt_pk_fp8_f32 v106, v105, 0
	s_nop 0
	v_and_b32_e32 v106, 0xff, v106
	v_mul_lo_u32 v106, v106, s81
	ds_write_b32 v245, v106 offset:5888
	v_mul_f32_e32 v104, v228, v48
	v_fmac_f32_e32 v104, v212, v49
	v_mul_f32_e32 v104, v104, v100
	v_mul_f32_e32 v105, 0x3d372713, v104
	v_mul_f32_e32 v105, v104, v105
	v_fma_f32 v105, v104, v105, v104
	v_mul_f32_e32 v105, 0x3f4c422a, v105
	v_add_f32_e32 v105, v105, v105
	v_mul_f32_e32 v105, 0x3fb8aa3b, v105
	v_exp_f32_e32 v105, v105
	v_mul_f32_e32 v104, 0.5, v104
	v_add_f32_e32 v105, 1.0, v105
	v_div_scale_f32 v106, s[70:71], v105, v105, 2.0
	v_rcp_f32_e32 v107, v106
	s_nop 0
	v_fma_f32 v108, -v106, v107, 1.0
	v_fmac_f32_e32 v107, v108, v107
	v_div_scale_f32 v108, vcc, 2.0, v105, 2.0
	v_mul_f32_e32 v109, v108, v107
	v_fma_f32 v110, -v106, v109, v108
	v_fmac_f32_e32 v109, v110, v107
	v_fma_f32 v106, -v106, v109, v108
	v_div_fmas_f32 v106, v106, v107, v109
	v_div_fixup_f32 v105, v106, v105, 2.0
	v_sub_f32_e32 v105, 1.0, v105
	v_add_f32_e32 v105, 1.0, v105
	v_mul_f32_e32 v104, v104, v105
	v_mul_f32_e32 v104, v24, v104
	v_mul_f32_e32 v105, v80, v104
	v_mul_f32_e32 v105, 0x43800000, v105
	v_mov_b32_e32 v106, 0x43e00000
	v_med3_f32 v105, v105, s94, v106
	v_mov_b32_e32 v106, 0
	v_cvt_pk_fp8_f32 v106, v105, 0
	s_nop 0
	v_and_b32_e32 v106, 0xff, v106
	v_mul_lo_u32 v106, v106, s81
	ds_write_b32 v245, v106 offset:2048
	v_mul_f32_e32 v105, v81, v104
	v_mul_f32_e32 v105, 0x43800000, v105
	v_mov_b32_e32 v106, 0x43e00000
	v_med3_f32 v105, v105, s94, v106
	v_mov_b32_e32 v106, 0
	v_cvt_pk_fp8_f32 v106, v105, 0
	s_nop 0
	v_and_b32_e32 v106, 0xff, v106
	v_mul_lo_u32 v106, v106, s81
	ds_write_b32 v245, v106 offset:6144
	v_mul_f32_e32 v104, v229, v50
	v_fmac_f32_e32 v104, v213, v51
	v_mul_f32_e32 v104, v104, v100
	v_mul_f32_e32 v105, 0x3d372713, v104
	v_mul_f32_e32 v105, v104, v105
	v_fma_f32 v105, v104, v105, v104
	v_mul_f32_e32 v105, 0x3f4c422a, v105
	v_add_f32_e32 v105, v105, v105
	v_mul_f32_e32 v105, 0x3fb8aa3b, v105
	v_exp_f32_e32 v105, v105
	v_mul_f32_e32 v104, 0.5, v104
	v_add_f32_e32 v105, 1.0, v105
	v_div_scale_f32 v106, s[70:71], v105, v105, 2.0
	v_rcp_f32_e32 v107, v106
	s_nop 0
	v_fma_f32 v108, -v106, v107, 1.0
	v_fmac_f32_e32 v107, v108, v107
	v_div_scale_f32 v108, vcc, 2.0, v105, 2.0
	v_mul_f32_e32 v109, v108, v107
	v_fma_f32 v110, -v106, v109, v108
	v_fmac_f32_e32 v109, v110, v107
	v_fma_f32 v106, -v106, v109, v108
	v_div_fmas_f32 v106, v106, v107, v109
	v_div_fixup_f32 v105, v106, v105, 2.0
	v_sub_f32_e32 v105, 1.0, v105
	v_add_f32_e32 v105, 1.0, v105
	v_mul_f32_e32 v104, v104, v105
	v_mul_f32_e32 v104, v25, v104
	v_mul_f32_e32 v105, v82, v104
	v_mul_f32_e32 v105, 0x43800000, v105
	v_mov_b32_e32 v106, 0x43e00000
	v_med3_f32 v105, v105, s94, v106
	v_mov_b32_e32 v106, 0
	v_cvt_pk_fp8_f32 v106, v105, 0
	s_nop 0
	v_and_b32_e32 v106, 0xff, v106
	v_mul_lo_u32 v106, v106, s81
	ds_write_b32 v245, v106 offset:2304
	v_mul_f32_e32 v105, v83, v104
	v_mul_f32_e32 v105, 0x43800000, v105
	v_mov_b32_e32 v106, 0x43e00000
	v_med3_f32 v105, v105, s94, v106
	v_mov_b32_e32 v106, 0
	v_cvt_pk_fp8_f32 v106, v105, 0
	s_nop 0
	v_and_b32_e32 v106, 0xff, v106
	v_mul_lo_u32 v106, v106, s81
	ds_write_b32 v245, v106 offset:6400
	v_mul_f32_e32 v104, v230, v52
	v_fmac_f32_e32 v104, v214, v53
	v_mul_f32_e32 v104, v104, v101
	v_mul_f32_e32 v105, 0x3d372713, v104
	v_mul_f32_e32 v105, v104, v105
	v_fma_f32 v105, v104, v105, v104
	v_mul_f32_e32 v105, 0x3f4c422a, v105
	v_add_f32_e32 v105, v105, v105
	v_mul_f32_e32 v105, 0x3fb8aa3b, v105
	v_exp_f32_e32 v105, v105
	v_mul_f32_e32 v104, 0.5, v104
	v_add_f32_e32 v105, 1.0, v105
	v_div_scale_f32 v106, s[70:71], v105, v105, 2.0
	v_rcp_f32_e32 v107, v106
	s_nop 0
	v_fma_f32 v108, -v106, v107, 1.0
	v_fmac_f32_e32 v107, v108, v107
	v_div_scale_f32 v108, vcc, 2.0, v105, 2.0
	v_mul_f32_e32 v109, v108, v107
	v_fma_f32 v110, -v106, v109, v108
	v_fmac_f32_e32 v109, v110, v107
	v_fma_f32 v106, -v106, v109, v108
	v_div_fmas_f32 v106, v106, v107, v109
	v_div_fixup_f32 v105, v106, v105, 2.0
	v_sub_f32_e32 v105, 1.0, v105
	v_add_f32_e32 v105, 1.0, v105
	v_mul_f32_e32 v104, v104, v105
	v_mul_f32_e32 v104, v26, v104
	v_mul_f32_e32 v105, v84, v104
	v_mul_f32_e32 v105, 0x43800000, v105
	v_mov_b32_e32 v106, 0x43e00000
	v_med3_f32 v105, v105, s94, v106
	v_mov_b32_e32 v106, 0
	v_cvt_pk_fp8_f32 v106, v105, 0
	s_nop 0
	v_and_b32_e32 v106, 0xff, v106
	v_mul_lo_u32 v106, v106, s81
	ds_write_b32 v245, v106 offset:2560
	v_mul_f32_e32 v105, v85, v104
	v_mul_f32_e32 v105, 0x43800000, v105
	v_mov_b32_e32 v106, 0x43e00000
	v_med3_f32 v105, v105, s94, v106
	v_mov_b32_e32 v106, 0
	v_cvt_pk_fp8_f32 v106, v105, 0
	s_nop 0
	v_and_b32_e32 v106, 0xff, v106
	v_mul_lo_u32 v106, v106, s81
	ds_write_b32 v245, v106 offset:6656
	v_mul_f32_e32 v104, v231, v54
	v_fmac_f32_e32 v104, v215, v55
	v_mul_f32_e32 v104, v104, v101
	v_mul_f32_e32 v105, 0x3d372713, v104
	v_mul_f32_e32 v105, v104, v105
	v_fma_f32 v105, v104, v105, v104
	v_mul_f32_e32 v105, 0x3f4c422a, v105
	v_add_f32_e32 v105, v105, v105
	v_mul_f32_e32 v105, 0x3fb8aa3b, v105
	v_exp_f32_e32 v105, v105
	v_mul_f32_e32 v104, 0.5, v104
	v_add_f32_e32 v105, 1.0, v105
	v_div_scale_f32 v106, s[70:71], v105, v105, 2.0
	v_rcp_f32_e32 v107, v106
	s_nop 0
	v_fma_f32 v108, -v106, v107, 1.0
	v_fmac_f32_e32 v107, v108, v107
	v_div_scale_f32 v108, vcc, 2.0, v105, 2.0
	v_mul_f32_e32 v109, v108, v107
	v_fma_f32 v110, -v106, v109, v108
	v_fmac_f32_e32 v109, v110, v107
	v_fma_f32 v106, -v106, v109, v108
	v_div_fmas_f32 v106, v106, v107, v109
	v_div_fixup_f32 v105, v106, v105, 2.0
	v_sub_f32_e32 v105, 1.0, v105
	v_add_f32_e32 v105, 1.0, v105
	v_mul_f32_e32 v104, v104, v105
	v_mul_f32_e32 v104, v27, v104
	v_mul_f32_e32 v105, v86, v104
	v_mul_f32_e32 v105, 0x43800000, v105
	v_mov_b32_e32 v106, 0x43e00000
	v_med3_f32 v105, v105, s94, v106
	v_mov_b32_e32 v106, 0
	v_cvt_pk_fp8_f32 v106, v105, 0
	s_nop 0
	v_and_b32_e32 v106, 0xff, v106
	v_mul_lo_u32 v106, v106, s81
	ds_write_b32 v245, v106 offset:2816
	v_mul_f32_e32 v105, v87, v104
	v_mul_f32_e32 v105, 0x43800000, v105
	v_mov_b32_e32 v106, 0x43e00000
	v_med3_f32 v105, v105, s94, v106
	v_mov_b32_e32 v106, 0
	v_cvt_pk_fp8_f32 v106, v105, 0
	s_nop 0
	v_and_b32_e32 v106, 0xff, v106
	v_mul_lo_u32 v106, v106, s81
	ds_write_b32 v245, v106 offset:6912
	v_mul_f32_e32 v104, v232, v56
	v_fmac_f32_e32 v104, v216, v57
	v_mul_f32_e32 v104, v104, v102
	v_mul_f32_e32 v105, 0x3d372713, v104
	v_mul_f32_e32 v105, v104, v105
	v_fma_f32 v105, v104, v105, v104
	v_mul_f32_e32 v105, 0x3f4c422a, v105
	v_add_f32_e32 v105, v105, v105
	v_mul_f32_e32 v105, 0x3fb8aa3b, v105
	v_exp_f32_e32 v105, v105
	v_mul_f32_e32 v104, 0.5, v104
	v_add_f32_e32 v105, 1.0, v105
	v_div_scale_f32 v106, s[70:71], v105, v105, 2.0
	v_rcp_f32_e32 v107, v106
	s_nop 0
	v_fma_f32 v108, -v106, v107, 1.0
	v_fmac_f32_e32 v107, v108, v107
	v_div_scale_f32 v108, vcc, 2.0, v105, 2.0
	v_mul_f32_e32 v109, v108, v107
	v_fma_f32 v110, -v106, v109, v108
	v_fmac_f32_e32 v109, v110, v107
	v_fma_f32 v106, -v106, v109, v108
	v_div_fmas_f32 v106, v106, v107, v109
	v_div_fixup_f32 v105, v106, v105, 2.0
	v_sub_f32_e32 v105, 1.0, v105
	v_add_f32_e32 v105, 1.0, v105
	v_mul_f32_e32 v104, v104, v105
	v_mul_f32_e32 v104, v28, v104
	v_mul_f32_e32 v105, v88, v104
	v_mul_f32_e32 v105, 0x43800000, v105
	v_mov_b32_e32 v106, 0x43e00000
	v_med3_f32 v105, v105, s94, v106
	v_mov_b32_e32 v106, 0
	v_cvt_pk_fp8_f32 v106, v105, 0
	s_nop 0
	v_and_b32_e32 v106, 0xff, v106
	v_mul_lo_u32 v106, v106, s81
	ds_write_b32 v245, v106 offset:3072
	v_mul_f32_e32 v105, v89, v104
	v_mul_f32_e32 v105, 0x43800000, v105
	v_mov_b32_e32 v106, 0x43e00000
	v_med3_f32 v105, v105, s94, v106
	v_mov_b32_e32 v106, 0
	v_cvt_pk_fp8_f32 v106, v105, 0
	s_nop 0
	v_and_b32_e32 v106, 0xff, v106
	v_mul_lo_u32 v106, v106, s81
	ds_write_b32 v245, v106 offset:7168
	v_mul_f32_e32 v104, v233, v58
	v_fmac_f32_e32 v104, v217, v59
	v_mul_f32_e32 v104, v104, v102
	v_mul_f32_e32 v105, 0x3d372713, v104
	v_mul_f32_e32 v105, v104, v105
	v_fma_f32 v105, v104, v105, v104
	v_mul_f32_e32 v105, 0x3f4c422a, v105
	v_add_f32_e32 v105, v105, v105
	v_mul_f32_e32 v105, 0x3fb8aa3b, v105
	v_exp_f32_e32 v105, v105
	v_mul_f32_e32 v104, 0.5, v104
	v_add_f32_e32 v105, 1.0, v105
	v_div_scale_f32 v106, s[70:71], v105, v105, 2.0
	v_rcp_f32_e32 v107, v106
	s_nop 0
	v_fma_f32 v108, -v106, v107, 1.0
	v_fmac_f32_e32 v107, v108, v107
	v_div_scale_f32 v108, vcc, 2.0, v105, 2.0
	v_mul_f32_e32 v109, v108, v107
	v_fma_f32 v110, -v106, v109, v108
	v_fmac_f32_e32 v109, v110, v107
	v_fma_f32 v106, -v106, v109, v108
	v_div_fmas_f32 v106, v106, v107, v109
	v_div_fixup_f32 v105, v106, v105, 2.0
	v_sub_f32_e32 v105, 1.0, v105
	v_add_f32_e32 v105, 1.0, v105
	v_mul_f32_e32 v104, v104, v105
	v_mul_f32_e32 v104, v29, v104
	v_mul_f32_e32 v105, v90, v104
	v_mul_f32_e32 v105, 0x43800000, v105
	v_mov_b32_e32 v106, 0x43e00000
	v_med3_f32 v105, v105, s94, v106
	v_mov_b32_e32 v106, 0
	v_cvt_pk_fp8_f32 v106, v105, 0
	s_nop 0
	v_and_b32_e32 v106, 0xff, v106
	v_mul_lo_u32 v106, v106, s81
	ds_write_b32 v245, v106 offset:3328
	v_mul_f32_e32 v105, v91, v104
	v_mul_f32_e32 v105, 0x43800000, v105
	v_mov_b32_e32 v106, 0x43e00000
	v_med3_f32 v105, v105, s94, v106
	v_mov_b32_e32 v106, 0
	v_cvt_pk_fp8_f32 v106, v105, 0
	s_nop 0
	v_and_b32_e32 v106, 0xff, v106
	v_mul_lo_u32 v106, v106, s81
	ds_write_b32 v245, v106 offset:7424
	v_mul_f32_e32 v104, v234, v60
	v_fmac_f32_e32 v104, v218, v61
	v_mul_f32_e32 v104, v104, v103
	v_mul_f32_e32 v105, 0x3d372713, v104
	v_mul_f32_e32 v105, v104, v105
	v_fma_f32 v105, v104, v105, v104
	v_mul_f32_e32 v105, 0x3f4c422a, v105
	v_add_f32_e32 v105, v105, v105
	v_mul_f32_e32 v105, 0x3fb8aa3b, v105
	v_exp_f32_e32 v105, v105
	v_mul_f32_e32 v104, 0.5, v104
	v_add_f32_e32 v105, 1.0, v105
	v_div_scale_f32 v106, s[70:71], v105, v105, 2.0
	v_rcp_f32_e32 v107, v106
	s_nop 0
	v_fma_f32 v108, -v106, v107, 1.0
	v_fmac_f32_e32 v107, v108, v107
	v_div_scale_f32 v108, vcc, 2.0, v105, 2.0
	v_mul_f32_e32 v109, v108, v107
	v_fma_f32 v110, -v106, v109, v108
	v_fmac_f32_e32 v109, v110, v107
	v_fma_f32 v106, -v106, v109, v108
	v_div_fmas_f32 v106, v106, v107, v109
	v_div_fixup_f32 v105, v106, v105, 2.0
	v_sub_f32_e32 v105, 1.0, v105
	v_add_f32_e32 v105, 1.0, v105
	v_mul_f32_e32 v104, v104, v105
	v_mul_f32_e32 v104, v30, v104
	v_mul_f32_e32 v105, v92, v104
	v_mul_f32_e32 v105, 0x43800000, v105
	v_mov_b32_e32 v106, 0x43e00000
	v_med3_f32 v105, v105, s94, v106
	v_mov_b32_e32 v106, 0
	v_cvt_pk_fp8_f32 v106, v105, 0
	s_nop 0
	v_and_b32_e32 v106, 0xff, v106
	v_mul_lo_u32 v106, v106, s81
	ds_write_b32 v245, v106 offset:3584
	v_mul_f32_e32 v105, v93, v104
	v_mul_f32_e32 v105, 0x43800000, v105
	v_mov_b32_e32 v106, 0x43e00000
	v_med3_f32 v105, v105, s94, v106
	v_mov_b32_e32 v106, 0
	v_cvt_pk_fp8_f32 v106, v105, 0
	s_nop 0
	v_and_b32_e32 v106, 0xff, v106
	v_mul_lo_u32 v106, v106, s81
	ds_write_b32 v245, v106 offset:7680
	v_mul_f32_e32 v104, v235, v62
	v_fmac_f32_e32 v104, v219, v63
	v_mul_f32_e32 v104, v104, v103
	v_mul_f32_e32 v105, 0x3d372713, v104
	v_mul_f32_e32 v105, v104, v105
	v_fma_f32 v105, v104, v105, v104
	v_mul_f32_e32 v105, 0x3f4c422a, v105
	v_add_f32_e32 v105, v105, v105
	v_mul_f32_e32 v105, 0x3fb8aa3b, v105
	v_exp_f32_e32 v105, v105
	v_mul_f32_e32 v104, 0.5, v104
	v_add_f32_e32 v105, 1.0, v105
	v_div_scale_f32 v106, s[70:71], v105, v105, 2.0
	v_rcp_f32_e32 v107, v106
	s_nop 0
	v_fma_f32 v108, -v106, v107, 1.0
	v_fmac_f32_e32 v107, v108, v107
	v_div_scale_f32 v108, vcc, 2.0, v105, 2.0
	v_mul_f32_e32 v109, v108, v107
	v_fma_f32 v110, -v106, v109, v108
	v_fmac_f32_e32 v109, v110, v107
	v_fma_f32 v106, -v106, v109, v108
	v_div_fmas_f32 v106, v106, v107, v109
	v_div_fixup_f32 v105, v106, v105, 2.0
	v_sub_f32_e32 v105, 1.0, v105
	v_add_f32_e32 v105, 1.0, v105
	v_mul_f32_e32 v104, v104, v105
	v_mul_f32_e32 v104, v31, v104
	v_mul_f32_e32 v105, v94, v104
	v_mul_f32_e32 v105, 0x43800000, v105
	v_mov_b32_e32 v106, 0x43e00000
	v_med3_f32 v105, v105, s94, v106
	v_mov_b32_e32 v106, 0
	v_cvt_pk_fp8_f32 v106, v105, 0
	s_nop 0
	v_and_b32_e32 v106, 0xff, v106
	v_mul_lo_u32 v106, v106, s81
	ds_write_b32 v245, v106 offset:3840
	v_mul_f32_e32 v105, v95, v104
	v_mul_f32_e32 v105, 0x43800000, v105
	v_mov_b32_e32 v106, 0x43e00000
	v_med3_f32 v105, v105, s94, v106
	v_mov_b32_e32 v106, 0
	v_cvt_pk_fp8_f32 v106, v105, 0
	s_nop 0
	v_and_b32_e32 v106, 0xff, v106
	v_mul_lo_u32 v106, v106, s81
	ds_write_b32 v245, v106 offset:7936
	s_waitcnt lgkmcnt(0)
	v_mbcnt_lo_u32_b32 v249, -1, 0
	v_mbcnt_hi_u32_b32 v249, -1, v249
	v_and_b32_e32 v250, 15, v249
	v_lshrrev_b32_e32 v251, 4, v249
	v_and_b32_e32 v252, 3, v250
	v_lshl_add_u32 v233, v251, 3, s91
	v_lshrrev_b32_e32 v253, 3, v250
	v_lshl_add_u32 v253, v253, 2, v252
	v_lshlrev_b32_e32 v232, 4, v253
	v_bfe_u32 v253, v250, 2, 1
	v_lshl_add_u32 v254, v251, 1, v253
	v_lshl_add_u32 v243, v254, 2, s91
	v_cmp_eq_u32_e64 s[4:5], 1, v253
	v_cmp_eq_u32_e64 s[6:7], 0, v253
	v_lshlrev_b32_e32 v239, 3, v249
	v_mov_b32_e32 v241, 0x77777777
	v_lshlrev_b32_e32 v253, 3, v252
	v_mov_b32_e32 v254, 0xff
	v_lshlrev_b32_e32 v254, v253, v254
	v_lshrrev_b32_e32 v253, 2, v250
	v_cmp_eq_u32_e32 vcc, 0, v253
	s_nop 1
	v_cndmask_b32_e32 v235, 0, v254, vcc
	v_cmp_eq_u32_e32 vcc, 1, v253
	s_nop 1
	v_cndmask_b32_e32 v236, 0, v254, vcc
	v_cmp_eq_u32_e32 vcc, 2, v253
	s_nop 1
	v_cndmask_b32_e32 v237, 0, v254, vcc
	v_cmp_eq_u32_e32 vcc, 3, v253
	s_nop 1
	v_cndmask_b32_e32 v238, 0, v254, vcc
	v_add_u32_e32 v234, 0x1000, v233
	v_add_u32_e32 v247, 0x1000, v233
	v_mov_b32_e32 v220, 0
	v_mov_b32_e32 v221, 0
	v_mov_b32_e32 v222, 0
	v_mov_b32_e32 v223, 0
	v_mov_b32_e32 v224, 0
	v_mov_b32_e32 v225, 0
	v_mov_b32_e32 v226, 0
	v_mov_b32_e32 v227, 0
	s_mov_b32 s0, 0
	s_mov_b32 s1, 0
	s_mov_b32 s60, 0x200000
	ds_read_b32 v128, v243 offset:0
	ds_read_b32 v129, v243 offset:32
	ds_read_b32 v130, v243 offset:64
	ds_read_b32 v131, v243 offset:96
	ds_read_b32 v132, v243 offset:128
	ds_read_b32 v133, v243 offset:160
	ds_read_b32 v134, v243 offset:192
	ds_read_b32 v135, v243 offset:224
	s_waitcnt lgkmcnt(0)
	v_lshl_or_b32 v128, v128, 7, v232
	v_lshl_or_b32 v129, v129, 7, v232
	v_lshl_or_b32 v130, v130, 7, v232
	v_lshl_or_b32 v131, v131, 7, v232
	v_lshl_or_b32 v132, v132, 7, v232
	v_lshl_or_b32 v133, v133, 7, v232
	v_lshl_or_b32 v134, v134, 7, v232
	v_lshl_or_b32 v135, v135, 7, v232
	buffer_load_dwordx4 v[0:3], v128, s[20:23], s1 offen
	buffer_load_dwordx4 v[4:7], v129, s[20:23], s1 offen
	buffer_load_dwordx4 v[8:11], v130, s[20:23], s1 offen
	buffer_load_dwordx4 v[12:15], v131, s[20:23], s1 offen
	buffer_load_dwordx4 v[16:19], v132, s[20:23], s1 offen
	buffer_load_dwordx4 v[20:23], v133, s[20:23], s1 offen
	buffer_load_dwordx4 v[24:27], v134, s[20:23], s1 offen
	buffer_load_dwordx4 v[28:31], v135, s[20:23], s1 offen
	ds_read_b32 v128, v243 offset:256
	ds_read_b32 v129, v243 offset:288
	ds_read_b32 v130, v243 offset:320
	ds_read_b32 v131, v243 offset:352
	ds_read_b32 v132, v243 offset:384
	ds_read_b32 v133, v243 offset:416
	ds_read_b32 v134, v243 offset:448
	ds_read_b32 v135, v243 offset:480
	global_load_dword v242, v246, s[40:41]
	global_load_dword v242, v246, s[40:41]
	s_waitcnt lgkmcnt(0)
	v_lshl_or_b32 v128, v128, 7, v232
	v_lshl_or_b32 v129, v129, 7, v232
	v_lshl_or_b32 v130, v130, 7, v232
	v_lshl_or_b32 v131, v131, 7, v232
	v_lshl_or_b32 v132, v132, 7, v232
	v_lshl_or_b32 v133, v133, 7, v232
	v_lshl_or_b32 v134, v134, 7, v232
	v_lshl_or_b32 v135, v135, 7, v232
	buffer_load_dwordx4 v[32:35], v128, s[20:23], s1 offen
	buffer_load_dwordx4 v[36:39], v129, s[20:23], s1 offen
	buffer_load_dwordx4 v[40:43], v130, s[20:23], s1 offen
	buffer_load_dwordx4 v[44:47], v131, s[20:23], s1 offen
	buffer_load_dwordx4 v[48:51], v132, s[20:23], s1 offen
	buffer_load_dwordx4 v[52:55], v133, s[20:23], s1 offen
	buffer_load_dwordx4 v[56:59], v134, s[20:23], s1 offen
	buffer_load_dwordx4 v[60:63], v135, s[20:23], s1 offen
	ds_read_b32 v128, v243 offset:512
	ds_read_b32 v129, v243 offset:544
	ds_read_b32 v130, v243 offset:576
	ds_read_b32 v131, v243 offset:608
	ds_read_b32 v132, v243 offset:640
	ds_read_b32 v133, v243 offset:672
	ds_read_b32 v134, v243 offset:704
	ds_read_b32 v135, v243 offset:736
	s_waitcnt lgkmcnt(0)
	v_lshl_or_b32 v128, v128, 7, v232
	v_lshl_or_b32 v129, v129, 7, v232
	v_lshl_or_b32 v130, v130, 7, v232
	v_lshl_or_b32 v131, v131, 7, v232
	v_lshl_or_b32 v132, v132, 7, v232
	v_lshl_or_b32 v133, v133, 7, v232
	v_lshl_or_b32 v134, v134, 7, v232
	v_lshl_or_b32 v135, v135, 7, v232
	buffer_load_dwordx4 v[64:67], v128, s[20:23], s1 offen
	buffer_load_dwordx4 v[68:71], v129, s[20:23], s1 offen
	buffer_load_dwordx4 v[72:75], v130, s[20:23], s1 offen
	buffer_load_dwordx4 v[76:79], v131, s[20:23], s1 offen
	buffer_load_dwordx4 v[80:83], v132, s[20:23], s1 offen
	buffer_load_dwordx4 v[84:87], v133, s[20:23], s1 offen
	buffer_load_dwordx4 v[88:91], v134, s[20:23], s1 offen
	buffer_load_dwordx4 v[92:95], v135, s[20:23], s1 offen
	ds_read_b32 v128, v243 offset:768
	ds_read_b32 v129, v243 offset:800
	ds_read_b32 v130, v243 offset:832
	ds_read_b32 v131, v243 offset:864
	ds_read_b32 v132, v243 offset:896
	ds_read_b32 v133, v243 offset:928
	ds_read_b32 v134, v243 offset:960
	ds_read_b32 v135, v243 offset:992
	ds_read_b64 v[160:161], v234 offset:0
	ds_read_b64 v[162:163], v234 offset:32
	ds_read_b64 v[164:165], v234 offset:64
	ds_read_b64 v[166:167], v234 offset:96
	ds_read_b64 v[168:169], v234 offset:128
	ds_read_b64 v[170:171], v234 offset:160
	ds_read_b64 v[172:173], v234 offset:192
	ds_read_b64 v[174:175], v234 offset:224
	global_load_dword v242, v246, s[40:41]
.LpgL0_vloopv0:
	s_lshl_b32 s64, s0, 9
	s_add_u32 s64, s64, 0x0
	s_add_u32 s70, s28, s64
	s_addc_u32 s71, s29, 0
	global_load_dwordx2 v[228:229], v239, s[70:71]
	s_waitcnt lgkmcnt(0)
	v_lshl_or_b32 v128, v128, 7, v232
	v_lshl_or_b32 v129, v129, 7, v232
	v_lshl_or_b32 v130, v130, 7, v232
	v_lshl_or_b32 v131, v131, 7, v232
	v_lshl_or_b32 v132, v132, 7, v232
	v_lshl_or_b32 v133, v133, 7, v232
	v_lshl_or_b32 v134, v134, 7, v232
	v_lshl_or_b32 v135, v135, 7, v232
	buffer_load_dwordx4 v[96:99], v128, s[20:23], s1 offen
	buffer_load_dwordx4 v[100:103], v129, s[20:23], s1 offen
	buffer_load_dwordx4 v[104:107], v130, s[20:23], s1 offen
	buffer_load_dwordx4 v[108:111], v131, s[20:23], s1 offen
	buffer_load_dwordx4 v[112:115], v132, s[20:23], s1 offen
	buffer_load_dwordx4 v[116:119], v133, s[20:23], s1 offen
	buffer_load_dwordx4 v[120:123], v134, s[20:23], s1 offen
	buffer_load_dwordx4 v[124:127], v135, s[20:23], s1 offen
	ds_read_b32 v128, v243 offset:1024
	ds_read_b32 v129, v243 offset:1056
	ds_read_b32 v130, v243 offset:1088
	ds_read_b32 v131, v243 offset:1120
	ds_read_b32 v132, v243 offset:1152
	ds_read_b32 v133, v243 offset:1184
	ds_read_b32 v134, v243 offset:1216
	ds_read_b32 v135, v243 offset:1248
	ds_read_b64 v[176:177], v234 offset:256
	ds_read_b64 v[178:179], v234 offset:288
	ds_read_b64 v[180:181], v234 offset:320
	ds_read_b64 v[182:183], v234 offset:352
	ds_read_b64 v[184:185], v234 offset:384
	ds_read_b64 v[186:187], v234 offset:416
	ds_read_b64 v[188:189], v234 offset:448
	ds_read_b64 v[190:191], v234 offset:480
	s_waitcnt vmcnt(28)
	v_and_b32_e32 v144, v160, v235
	v_and_b32_e32 v145, v160, v236
	v_and_b32_e32 v146, v160, v237
	v_and_b32_e32 v147, v160, v238
	v_and_b32_e32 v148, v161, v235
	v_and_b32_e32 v149, v161, v236
	v_and_b32_e32 v150, v161, v237
	v_and_b32_e32 v151, v161, v238
	s_mov_b64 vcc, s[4:5]
	v_cndmask_b32_dpp v138, v0, v2, vcc row_shl:4 row_mask:0xf bank_mask:0xf bound_ctrl:1
	v_cndmask_b32_dpp v139, v1, v3, vcc row_shl:4 row_mask:0xf bank_mask:0xf bound_ctrl:1
	s_mov_b64 vcc, s[6:7]
	v_cndmask_b32_dpp v136, v2, v0, vcc row_shr:4 row_mask:0xf bank_mask:0xf bound_ctrl:1
	v_cndmask_b32_dpp v137, v3, v1, vcc row_shr:4 row_mask:0xf bank_mask:0xf bound_ctrl:1
	v_and_b32_e32 v204, v162, v235
	v_and_b32_e32 v205, v162, v236
	v_and_b32_e32 v206, v162, v237
	v_and_b32_e32 v207, v162, v238
	v_and_b32_e32 v208, v163, v235
	v_and_b32_e32 v209, v163, v236
	v_and_b32_e32 v210, v163, v237
	v_and_b32_e32 v211, v163, v238
	s_mov_b64 vcc, s[6:7]
	v_cndmask_b32_dpp v140, v6, v4, vcc row_shr:4 row_mask:0xf bank_mask:0xf bound_ctrl:1
	v_cndmask_b32_dpp v141, v7, v5, vcc row_shr:4 row_mask:0xf bank_mask:0xf bound_ctrl:1
	s_mov_b64 vcc, s[4:5]
	v_cndmask_b32_dpp v142, v4, v6, vcc row_shl:4 row_mask:0xf bank_mask:0xf bound_ctrl:1
	v_cndmask_b32_dpp v143, v5, v7, vcc row_shl:4 row_mask:0xf bank_mask:0xf bound_ctrl:1
	v_mfma_scale_f32_16x16x128_f8f6f4 v[212:215], v[136:139], v[144:151], 0, v240, v241 op_sel_hi:[0,0,0] cbsz:4
	v_and_b32_e32 v144, v164, v235
	v_and_b32_e32 v145, v164, v236
	v_and_b32_e32 v146, v164, v237
	v_and_b32_e32 v147, v164, v238
	v_and_b32_e32 v148, v165, v235
	v_and_b32_e32 v149, v165, v236
	v_and_b32_e32 v150, v165, v237
	v_and_b32_e32 v151, v165, v238
	s_mov_b64 vcc, s[4:5]
	v_cndmask_b32_dpp v138, v8, v10, vcc row_shl:4 row_mask:0xf bank_mask:0xf bound_ctrl:1
	v_cndmask_b32_dpp v139, v9, v11, vcc row_shl:4 row_mask:0xf bank_mask:0xf bound_ctrl:1
	s_mov_b64 vcc, s[6:7]
	v_cndmask_b32_dpp v136, v10, v8, vcc row_shr:4 row_mask:0xf bank_mask:0xf bound_ctrl:1
	v_cndmask_b32_dpp v137, v11, v9, vcc row_shr:4 row_mask:0xf bank_mask:0xf bound_ctrl:1
	v_mfma_scale_f32_16x16x128_f8f6f4 v[212:215], v[140:143], v[204:211], v[212:215], v240, v241 op_sel_hi:[0,0,0] cbsz:4
	v_and_b32_e32 v204, v166, v235
	v_and_b32_e32 v205, v166, v236
	v_and_b32_e32 v206, v166, v237
	v_and_b32_e32 v207, v166, v238
	v_and_b32_e32 v208, v167, v235
	v_and_b32_e32 v209, v167, v236
	v_and_b32_e32 v210, v167, v237
	v_and_b32_e32 v211, v167, v238
	s_mov_b64 vcc, s[6:7]
	v_cndmask_b32_dpp v140, v14, v12, vcc row_shr:4 row_mask:0xf bank_mask:0xf bound_ctrl:1
	v_cndmask_b32_dpp v141, v15, v13, vcc row_shr:4 row_mask:0xf bank_mask:0xf bound_ctrl:1
	s_mov_b64 vcc, s[4:5]
	v_cndmask_b32_dpp v142, v12, v14, vcc row_shl:4 row_mask:0xf bank_mask:0xf bound_ctrl:1
	v_cndmask_b32_dpp v143, v13, v15, vcc row_shl:4 row_mask:0xf bank_mask:0xf bound_ctrl:1
	v_mfma_scale_f32_16x16x128_f8f6f4 v[212:215], v[136:139], v[144:151], v[212:215], v240, v241 op_sel_hi:[0,0,0] cbsz:4
	v_and_b32_e32 v144, v168, v235
	v_and_b32_e32 v145, v168, v236
	v_and_b32_e32 v146, v168, v237
	v_and_b32_e32 v147, v168, v238
	v_and_b32_e32 v148, v169, v235
	v_and_b32_e32 v149, v169, v236
	v_and_b32_e32 v150, v169, v237
	v_and_b32_e32 v151, v169, v238
	s_mov_b64 vcc, s[4:5]
	v_cndmask_b32_dpp v138, v16, v18, vcc row_shl:4 row_mask:0xf bank_mask:0xf bound_ctrl:1
	v_cndmask_b32_dpp v139, v17, v19, vcc row_shl:4 row_mask:0xf bank_mask:0xf bound_ctrl:1
	s_mov_b64 vcc, s[6:7]
	v_cndmask_b32_dpp v136, v18, v16, vcc row_shr:4 row_mask:0xf bank_mask:0xf bound_ctrl:1
	v_cndmask_b32_dpp v137, v19, v17, vcc row_shr:4 row_mask:0xf bank_mask:0xf bound_ctrl:1
	v_mfma_scale_f32_16x16x128_f8f6f4 v[212:215], v[140:143], v[204:211], v[212:215], v240, v241 op_sel_hi:[0,0,0] cbsz:4
	v_and_b32_e32 v204, v170, v235
	v_and_b32_e32 v205, v170, v236
	v_and_b32_e32 v206, v170, v237
	v_and_b32_e32 v207, v170, v238
	v_and_b32_e32 v208, v171, v235
	v_and_b32_e32 v209, v171, v236
	v_and_b32_e32 v210, v171, v237
	v_and_b32_e32 v211, v171, v238
	s_mov_b64 vcc, s[6:7]
	v_cndmask_b32_dpp v140, v22, v20, vcc row_shr:4 row_mask:0xf bank_mask:0xf bound_ctrl:1
	v_cndmask_b32_dpp v141, v23, v21, vcc row_shr:4 row_mask:0xf bank_mask:0xf bound_ctrl:1
	s_mov_b64 vcc, s[4:5]
	v_cndmask_b32_dpp v142, v20, v22, vcc row_shl:4 row_mask:0xf bank_mask:0xf bound_ctrl:1
	v_cndmask_b32_dpp v143, v21, v23, vcc row_shl:4 row_mask:0xf bank_mask:0xf bound_ctrl:1
	v_mfma_scale_f32_16x16x128_f8f6f4 v[212:215], v[136:139], v[144:151], v[212:215], v240, v241 op_sel_hi:[0,0,0] cbsz:4
	v_and_b32_e32 v144, v172, v235
	v_and_b32_e32 v145, v172, v236
	v_and_b32_e32 v146, v172, v237
	v_and_b32_e32 v147, v172, v238
	v_and_b32_e32 v148, v173, v235
	v_and_b32_e32 v149, v173, v236
	v_and_b32_e32 v150, v173, v237
	v_and_b32_e32 v151, v173, v238
	s_mov_b64 vcc, s[4:5]
	v_cndmask_b32_dpp v138, v24, v26, vcc row_shl:4 row_mask:0xf bank_mask:0xf bound_ctrl:1
	v_cndmask_b32_dpp v139, v25, v27, vcc row_shl:4 row_mask:0xf bank_mask:0xf bound_ctrl:1
	s_mov_b64 vcc, s[6:7]
	v_cndmask_b32_dpp v136, v26, v24, vcc row_shr:4 row_mask:0xf bank_mask:0xf bound_ctrl:1
	v_cndmask_b32_dpp v137, v27, v25, vcc row_shr:4 row_mask:0xf bank_mask:0xf bound_ctrl:1
	v_mfma_scale_f32_16x16x128_f8f6f4 v[212:215], v[140:143], v[204:211], v[212:215], v240, v241 op_sel_hi:[0,0,0] cbsz:4
	v_and_b32_e32 v204, v174, v235
	v_and_b32_e32 v205, v174, v236
	v_and_b32_e32 v206, v174, v237
	v_and_b32_e32 v207, v174, v238
	v_and_b32_e32 v208, v175, v235
	v_and_b32_e32 v209, v175, v236
	v_and_b32_e32 v210, v175, v237
	v_and_b32_e32 v211, v175, v238
	s_mov_b64 vcc, s[6:7]
	v_cndmask_b32_dpp v140, v30, v28, vcc row_shr:4 row_mask:0xf bank_mask:0xf bound_ctrl:1
	v_cndmask_b32_dpp v141, v31, v29, vcc row_shr:4 row_mask:0xf bank_mask:0xf bound_ctrl:1
	s_mov_b64 vcc, s[4:5]
	v_cndmask_b32_dpp v142, v28, v30, vcc row_shl:4 row_mask:0xf bank_mask:0xf bound_ctrl:1
	v_cndmask_b32_dpp v143, v29, v31, vcc row_shl:4 row_mask:0xf bank_mask:0xf bound_ctrl:1
	v_mfma_scale_f32_16x16x128_f8f6f4 v[212:215], v[136:139], v[144:151], v[212:215], v240, v241 op_sel_hi:[0,0,0] cbsz:4
	s_nop 0
	v_mfma_scale_f32_16x16x128_f8f6f4 v[212:215], v[140:143], v[204:211], v[212:215], v240, v241 op_sel_hi:[0,0,0] cbsz:4
	s_waitcnt lgkmcnt(0)
	v_lshl_or_b32 v128, v128, 7, v232
	v_lshl_or_b32 v129, v129, 7, v232
	v_lshl_or_b32 v130, v130, 7, v232
	v_lshl_or_b32 v131, v131, 7, v232
	v_lshl_or_b32 v132, v132, 7, v232
	v_lshl_or_b32 v133, v133, 7, v232
	v_lshl_or_b32 v134, v134, 7, v232
	v_lshl_or_b32 v135, v135, 7, v232
	buffer_load_dwordx4 v[0:3], v128, s[20:23], s1 offen
	buffer_load_dwordx4 v[4:7], v129, s[20:23], s1 offen
	buffer_load_dwordx4 v[8:11], v130, s[20:23], s1 offen
	buffer_load_dwordx4 v[12:15], v131, s[20:23], s1 offen
	buffer_load_dwordx4 v[16:19], v132, s[20:23], s1 offen
	buffer_load_dwordx4 v[20:23], v133, s[20:23], s1 offen
	buffer_load_dwordx4 v[24:27], v134, s[20:23], s1 offen
	buffer_load_dwordx4 v[28:31], v135, s[20:23], s1 offen
	ds_read_b32 v128, v243 offset:1280
	ds_read_b32 v129, v243 offset:1312
	ds_read_b32 v130, v243 offset:1344
	ds_read_b32 v131, v243 offset:1376
	ds_read_b32 v132, v243 offset:1408
	ds_read_b32 v133, v243 offset:1440
	ds_read_b32 v134, v243 offset:1472
	ds_read_b32 v135, v243 offset:1504
	ds_read_b64 v[160:161], v234 offset:512
	ds_read_b64 v[162:163], v234 offset:544
	ds_read_b64 v[164:165], v234 offset:576
	ds_read_b64 v[166:167], v234 offset:608
	ds_read_b64 v[168:169], v234 offset:640
	ds_read_b64 v[170:171], v234 offset:672
	ds_read_b64 v[172:173], v234 offset:704
	ds_read_b64 v[174:175], v234 offset:736
	s_waitcnt vmcnt(26)
	s_cmp_eq_u32 s0, 0
	s_cbranch_scc1 .LpgL0_vdummyv0
	v_and_b32_e32 v144, v176, v235
	v_and_b32_e32 v145, v176, v236
	v_and_b32_e32 v146, v176, v237
	v_and_b32_e32 v147, v176, v238
	v_and_b32_e32 v148, v177, v235
	v_and_b32_e32 v149, v177, v236
	v_and_b32_e32 v150, v177, v237
	v_and_b32_e32 v151, v177, v238
	s_mov_b64 vcc, s[4:5]
	v_cndmask_b32_dpp v138, v32, v34, vcc row_shl:4 row_mask:0xf bank_mask:0xf bound_ctrl:1
	v_cndmask_b32_dpp v139, v33, v35, vcc row_shl:4 row_mask:0xf bank_mask:0xf bound_ctrl:1
	s_mov_b64 vcc, s[6:7]
	v_cndmask_b32_dpp v136, v34, v32, vcc row_shr:4 row_mask:0xf bank_mask:0xf bound_ctrl:1
	v_cndmask_b32_dpp v137, v35, v33, vcc row_shr:4 row_mask:0xf bank_mask:0xf bound_ctrl:1
	v_and_b32_e32 v204, v178, v235
	v_and_b32_e32 v205, v178, v236
	v_and_b32_e32 v206, v178, v237
	v_and_b32_e32 v207, v178, v238
	v_and_b32_e32 v208, v179, v235
	v_and_b32_e32 v209, v179, v236
	v_and_b32_e32 v210, v179, v237
	v_and_b32_e32 v211, v179, v238
	s_mov_b64 vcc, s[6:7]
	v_cndmask_b32_dpp v140, v38, v36, vcc row_shr:4 row_mask:0xf bank_mask:0xf bound_ctrl:1
	v_cndmask_b32_dpp v141, v39, v37, vcc row_shr:4 row_mask:0xf bank_mask:0xf bound_ctrl:1
	s_mov_b64 vcc, s[4:5]
	v_cndmask_b32_dpp v142, v36, v38, vcc row_shl:4 row_mask:0xf bank_mask:0xf bound_ctrl:1
	v_cndmask_b32_dpp v143, v37, v39, vcc row_shl:4 row_mask:0xf bank_mask:0xf bound_ctrl:1
	v_mfma_scale_f32_16x16x128_f8f6f4 v[212:215], v[136:139], v[144:151], v[212:215], v240, v241 op_sel_hi:[0,0,0] cbsz:4
	v_permlane16_swap_b32_e32 v216, v218
	v_permlane16_swap_b32_e32 v217, v219
	v_lshlrev_b32_e32 v252, 16, v230
	v_and_b32_e32 v144, v180, v235
	v_and_b32_e32 v145, v180, v236
	v_and_b32_e32 v146, v180, v237
	v_and_b32_e32 v147, v180, v238
	v_and_b32_e32 v148, v181, v235
	v_and_b32_e32 v149, v181, v236
	v_and_b32_e32 v150, v181, v237
	v_and_b32_e32 v151, v181, v238
	s_mov_b64 vcc, s[4:5]
	v_cndmask_b32_dpp v138, v40, v42, vcc row_shl:4 row_mask:0xf bank_mask:0xf bound_ctrl:1
	v_cndmask_b32_dpp v139, v41, v43, vcc row_shl:4 row_mask:0xf bank_mask:0xf bound_ctrl:1
	s_mov_b64 vcc, s[6:7]
	v_cndmask_b32_dpp v136, v42, v40, vcc row_shr:4 row_mask:0xf bank_mask:0xf bound_ctrl:1
	v_cndmask_b32_dpp v137, v43, v41, vcc row_shr:4 row_mask:0xf bank_mask:0xf bound_ctrl:1
	v_mfma_scale_f32_16x16x128_f8f6f4 v[212:215], v[140:143], v[204:211], v[212:215], v240, v241 op_sel_hi:[0,0,0] cbsz:4
	v_and_b32_e32 v253, 0xffff0000, v230
	v_lshlrev_b32_e32 v254, 16, v231
	v_and_b32_e32 v255, 0xffff0000, v231
	v_and_b32_e32 v204, v182, v235
	v_and_b32_e32 v205, v182, v236
	v_and_b32_e32 v206, v182, v237
	v_and_b32_e32 v207, v182, v238
	v_and_b32_e32 v208, v183, v235
	v_and_b32_e32 v209, v183, v236
	v_and_b32_e32 v210, v183, v237
	v_and_b32_e32 v211, v183, v238
	s_mov_b64 vcc, s[6:7]
	v_cndmask_b32_dpp v140, v46, v44, vcc row_shr:4 row_mask:0xf bank_mask:0xf bound_ctrl:1
	v_cndmask_b32_dpp v141, v47, v45, vcc row_shr:4 row_mask:0xf bank_mask:0xf bound_ctrl:1
	s_mov_b64 vcc, s[4:5]
	v_cndmask_b32_dpp v142, v44, v46, vcc row_shl:4 row_mask:0xf bank_mask:0xf bound_ctrl:1
	v_cndmask_b32_dpp v143, v45, v47, vcc row_shl:4 row_mask:0xf bank_mask:0xf bound_ctrl:1
	v_mfma_scale_f32_16x16x128_f8f6f4 v[212:215], v[136:139], v[144:151], v[212:215], v240, v241 op_sel_hi:[0,0,0] cbsz:4
	v_add_f32_e32 v252, v216, v252
	v_add_f32_e32 v253, v218, v253
	v_add_f32_e32 v254, v217, v254
	v_and_b32_e32 v144, v184, v235
	v_and_b32_e32 v145, v184, v236
	v_and_b32_e32 v146, v184, v237
	v_and_b32_e32 v147, v184, v238
	v_and_b32_e32 v148, v185, v235
	v_and_b32_e32 v149, v185, v236
	v_and_b32_e32 v150, v185, v237
	v_and_b32_e32 v151, v185, v238
	s_mov_b64 vcc, s[4:5]
	v_cndmask_b32_dpp v138, v48, v50, vcc row_shl:4 row_mask:0xf bank_mask:0xf bound_ctrl:1
	v_cndmask_b32_dpp v139, v49, v51, vcc row_shl:4 row_mask:0xf bank_mask:0xf bound_ctrl:1
	s_mov_b64 vcc, s[6:7]
	v_cndmask_b32_dpp v136, v50, v48, vcc row_shr:4 row_mask:0xf bank_mask:0xf bound_ctrl:1
	v_cndmask_b32_dpp v137, v51, v49, vcc row_shr:4 row_mask:0xf bank_mask:0xf bound_ctrl:1
	v_mfma_scale_f32_16x16x128_f8f6f4 v[212:215], v[140:143], v[204:211], v[212:215], v240, v241 op_sel_hi:[0,0,0] cbsz:4
	v_add_f32_e32 v255, v219, v255
	v_mul_f32_e32 v192, v252, v252
	v_mul_f32_e32 v193, v254, v254
	v_and_b32_e32 v204, v186, v235
	v_and_b32_e32 v205, v186, v236
	v_and_b32_e32 v206, v186, v237
	v_and_b32_e32 v207, v186, v238
	v_and_b32_e32 v208, v187, v235
	v_and_b32_e32 v209, v187, v236
	v_and_b32_e32 v210, v187, v237
	v_and_b32_e32 v211, v187, v238
	s_mov_b64 vcc, s[6:7]
	v_cndmask_b32_dpp v140, v54, v52, vcc row_shr:4 row_mask:0xf bank_mask:0xf bound_ctrl:1
	v_cndmask_b32_dpp v141, v55, v53, vcc row_shr:4 row_mask:0xf bank_mask:0xf bound_ctrl:1
	s_mov_b64 vcc, s[4:5]
	v_cndmask_b32_dpp v142, v52, v54, vcc row_shl:4 row_mask:0xf bank_mask:0xf bound_ctrl:1
	v_cndmask_b32_dpp v143, v53, v55, vcc row_shl:4 row_mask:0xf bank_mask:0xf bound_ctrl:1
	v_mfma_scale_f32_16x16x128_f8f6f4 v[212:215], v[136:139], v[144:151], v[212:215], v240, v241 op_sel_hi:[0,0,0] cbsz:4
	v_fmac_f32_e32 v192, v253, v253
	v_fmac_f32_e32 v193, v255, v255
	v_cvt_pk_bf16_f32 v250, v252, v253
	v_and_b32_e32 v144, v188, v235
	v_and_b32_e32 v145, v188, v236
	v_and_b32_e32 v146, v188, v237
	v_and_b32_e32 v147, v188, v238
	v_and_b32_e32 v148, v189, v235
	v_and_b32_e32 v149, v189, v236
	v_and_b32_e32 v150, v189, v237
	v_and_b32_e32 v151, v189, v238
	s_mov_b64 vcc, s[4:5]
	v_cndmask_b32_dpp v138, v56, v58, vcc row_shl:4 row_mask:0xf bank_mask:0xf bound_ctrl:1
	v_cndmask_b32_dpp v139, v57, v59, vcc row_shl:4 row_mask:0xf bank_mask:0xf bound_ctrl:1
	s_mov_b64 vcc, s[6:7]
	v_cndmask_b32_dpp v136, v58, v56, vcc row_shr:4 row_mask:0xf bank_mask:0xf bound_ctrl:1
	v_cndmask_b32_dpp v137, v59, v57, vcc row_shr:4 row_mask:0xf bank_mask:0xf bound_ctrl:1
	v_mfma_scale_f32_16x16x128_f8f6f4 v[212:215], v[140:143], v[204:211], v[212:215], v240, v241 op_sel_hi:[0,0,0] cbsz:4
	v_cvt_pk_bf16_f32 v251, v254, v255
	v_add_f32_e32 v192, v192, v193
	v_add_f32_e32 v227, v227, v192
	v_and_b32_e32 v204, v190, v235
	v_and_b32_e32 v205, v190, v236
	v_and_b32_e32 v206, v190, v237
	v_and_b32_e32 v207, v190, v238
	v_and_b32_e32 v208, v191, v235
	v_and_b32_e32 v209, v191, v236
	v_and_b32_e32 v210, v191, v237
	v_and_b32_e32 v211, v191, v238
	s_mov_b64 vcc, s[6:7]
	v_cndmask_b32_dpp v140, v62, v60, vcc row_shr:4 row_mask:0xf bank_mask:0xf bound_ctrl:1
	v_cndmask_b32_dpp v141, v63, v61, vcc row_shr:4 row_mask:0xf bank_mask:0xf bound_ctrl:1
	s_mov_b64 vcc, s[4:5]
	v_cndmask_b32_dpp v142, v60, v62, vcc row_shl:4 row_mask:0xf bank_mask:0xf bound_ctrl:1
	v_cndmask_b32_dpp v143, v61, v63, vcc row_shl:4 row_mask:0xf bank_mask:0xf bound_ctrl:1
	v_mfma_scale_f32_16x16x128_f8f6f4 v[212:215], v[136:139], v[144:151], v[212:215], v240, v241 op_sel_hi:[0,0,0] cbsz:4
	s_nop 0
	v_mfma_scale_f32_16x16x128_f8f6f4 v[212:215], v[140:143], v[204:211], v[212:215], v240, v241 op_sel_hi:[0,0,0] cbsz:4
	s_lshl_b32 s64, s0, 9
	s_add_u32 s64, s64, 0x6e00
	s_add_u32 s76, s28, s64
	s_addc_u32 s77, s29, 0
	global_store_dwordx2 v239, v[250:251], s[76:77]
	s_branch .LpgL0_vjoinv0
.LpgL0_vdummyv0:
	v_and_b32_e32 v144, v176, v235
	v_and_b32_e32 v145, v176, v236
	v_and_b32_e32 v146, v176, v237
	v_and_b32_e32 v147, v176, v238
	v_and_b32_e32 v148, v177, v235
	v_and_b32_e32 v149, v177, v236
	v_and_b32_e32 v150, v177, v237
	v_and_b32_e32 v151, v177, v238
	s_mov_b64 vcc, s[4:5]
	v_cndmask_b32_dpp v138, v32, v34, vcc row_shl:4 row_mask:0xf bank_mask:0xf bound_ctrl:1
	v_cndmask_b32_dpp v139, v33, v35, vcc row_shl:4 row_mask:0xf bank_mask:0xf bound_ctrl:1
	s_mov_b64 vcc, s[6:7]
	v_cndmask_b32_dpp v136, v34, v32, vcc row_shr:4 row_mask:0xf bank_mask:0xf bound_ctrl:1
	v_cndmask_b32_dpp v137, v35, v33, vcc row_shr:4 row_mask:0xf bank_mask:0xf bound_ctrl:1
	v_and_b32_e32 v204, v178, v235
	v_and_b32_e32 v205, v178, v236
	v_and_b32_e32 v206, v178, v237
	v_and_b32_e32 v207, v178, v238
	v_and_b32_e32 v208, v179, v235
	v_and_b32_e32 v209, v179, v236
	v_and_b32_e32 v210, v179, v237
	v_and_b32_e32 v211, v179, v238
	s_mov_b64 vcc, s[6:7]
	v_cndmask_b32_dpp v140, v38, v36, vcc row_shr:4 row_mask:0xf bank_mask:0xf bound_ctrl:1
	v_cndmask_b32_dpp v141, v39, v37, vcc row_shr:4 row_mask:0xf bank_mask:0xf bound_ctrl:1
	s_mov_b64 vcc, s[4:5]
	v_cndmask_b32_dpp v142, v36, v38, vcc row_shl:4 row_mask:0xf bank_mask:0xf bound_ctrl:1
	v_cndmask_b32_dpp v143, v37, v39, vcc row_shl:4 row_mask:0xf bank_mask:0xf bound_ctrl:1
	v_mfma_scale_f32_16x16x128_f8f6f4 v[212:215], v[136:139], v[144:151], v[212:215], v240, v241 op_sel_hi:[0,0,0] cbsz:4
	v_and_b32_e32 v144, v180, v235
	v_and_b32_e32 v145, v180, v236
	v_and_b32_e32 v146, v180, v237
	v_and_b32_e32 v147, v180, v238
	v_and_b32_e32 v148, v181, v235
	v_and_b32_e32 v149, v181, v236
	v_and_b32_e32 v150, v181, v237
	v_and_b32_e32 v151, v181, v238
	s_mov_b64 vcc, s[4:5]
	v_cndmask_b32_dpp v138, v40, v42, vcc row_shl:4 row_mask:0xf bank_mask:0xf bound_ctrl:1
	v_cndmask_b32_dpp v139, v41, v43, vcc row_shl:4 row_mask:0xf bank_mask:0xf bound_ctrl:1
	s_mov_b64 vcc, s[6:7]
	v_cndmask_b32_dpp v136, v42, v40, vcc row_shr:4 row_mask:0xf bank_mask:0xf bound_ctrl:1
	v_cndmask_b32_dpp v137, v43, v41, vcc row_shr:4 row_mask:0xf bank_mask:0xf bound_ctrl:1
	v_mfma_scale_f32_16x16x128_f8f6f4 v[212:215], v[140:143], v[204:211], v[212:215], v240, v241 op_sel_hi:[0,0,0] cbsz:4
	v_and_b32_e32 v204, v182, v235
	v_and_b32_e32 v205, v182, v236
	v_and_b32_e32 v206, v182, v237
	v_and_b32_e32 v207, v182, v238
	v_and_b32_e32 v208, v183, v235
	v_and_b32_e32 v209, v183, v236
	v_and_b32_e32 v210, v183, v237
	v_and_b32_e32 v211, v183, v238
	s_mov_b64 vcc, s[6:7]
	v_cndmask_b32_dpp v140, v46, v44, vcc row_shr:4 row_mask:0xf bank_mask:0xf bound_ctrl:1
	v_cndmask_b32_dpp v141, v47, v45, vcc row_shr:4 row_mask:0xf bank_mask:0xf bound_ctrl:1
	s_mov_b64 vcc, s[4:5]
	v_cndmask_b32_dpp v142, v44, v46, vcc row_shl:4 row_mask:0xf bank_mask:0xf bound_ctrl:1
	v_cndmask_b32_dpp v143, v45, v47, vcc row_shl:4 row_mask:0xf bank_mask:0xf bound_ctrl:1
	v_mfma_scale_f32_16x16x128_f8f6f4 v[212:215], v[136:139], v[144:151], v[212:215], v240, v241 op_sel_hi:[0,0,0] cbsz:4
	v_and_b32_e32 v144, v184, v235
	v_and_b32_e32 v145, v184, v236
	v_and_b32_e32 v146, v184, v237
	v_and_b32_e32 v147, v184, v238
	v_and_b32_e32 v148, v185, v235
	v_and_b32_e32 v149, v185, v236
	v_and_b32_e32 v150, v185, v237
	v_and_b32_e32 v151, v185, v238
	s_mov_b64 vcc, s[4:5]
	v_cndmask_b32_dpp v138, v48, v50, vcc row_shl:4 row_mask:0xf bank_mask:0xf bound_ctrl:1
	v_cndmask_b32_dpp v139, v49, v51, vcc row_shl:4 row_mask:0xf bank_mask:0xf bound_ctrl:1
	s_mov_b64 vcc, s[6:7]
	v_cndmask_b32_dpp v136, v50, v48, vcc row_shr:4 row_mask:0xf bank_mask:0xf bound_ctrl:1
	v_cndmask_b32_dpp v137, v51, v49, vcc row_shr:4 row_mask:0xf bank_mask:0xf bound_ctrl:1
	v_mfma_scale_f32_16x16x128_f8f6f4 v[212:215], v[140:143], v[204:211], v[212:215], v240, v241 op_sel_hi:[0,0,0] cbsz:4
	v_and_b32_e32 v204, v186, v235
	v_and_b32_e32 v205, v186, v236
	v_and_b32_e32 v206, v186, v237
	v_and_b32_e32 v207, v186, v238
	v_and_b32_e32 v208, v187, v235
	v_and_b32_e32 v209, v187, v236
	v_and_b32_e32 v210, v187, v237
	v_and_b32_e32 v211, v187, v238
	s_mov_b64 vcc, s[6:7]
	v_cndmask_b32_dpp v140, v54, v52, vcc row_shr:4 row_mask:0xf bank_mask:0xf bound_ctrl:1
	v_cndmask_b32_dpp v141, v55, v53, vcc row_shr:4 row_mask:0xf bank_mask:0xf bound_ctrl:1
	s_mov_b64 vcc, s[4:5]
	v_cndmask_b32_dpp v142, v52, v54, vcc row_shl:4 row_mask:0xf bank_mask:0xf bound_ctrl:1
	v_cndmask_b32_dpp v143, v53, v55, vcc row_shl:4 row_mask:0xf bank_mask:0xf bound_ctrl:1
	v_mfma_scale_f32_16x16x128_f8f6f4 v[212:215], v[136:139], v[144:151], v[212:215], v240, v241 op_sel_hi:[0,0,0] cbsz:4
	v_and_b32_e32 v144, v188, v235
	v_and_b32_e32 v145, v188, v236
	v_and_b32_e32 v146, v188, v237
	v_and_b32_e32 v147, v188, v238
	v_and_b32_e32 v148, v189, v235
	v_and_b32_e32 v149, v189, v236
	v_and_b32_e32 v150, v189, v237
	v_and_b32_e32 v151, v189, v238
	s_mov_b64 vcc, s[4:5]
	v_cndmask_b32_dpp v138, v56, v58, vcc row_shl:4 row_mask:0xf bank_mask:0xf bound_ctrl:1
	v_cndmask_b32_dpp v139, v57, v59, vcc row_shl:4 row_mask:0xf bank_mask:0xf bound_ctrl:1
	s_mov_b64 vcc, s[6:7]
	v_cndmask_b32_dpp v136, v58, v56, vcc row_shr:4 row_mask:0xf bank_mask:0xf bound_ctrl:1
	v_cndmask_b32_dpp v137, v59, v57, vcc row_shr:4 row_mask:0xf bank_mask:0xf bound_ctrl:1
	v_mfma_scale_f32_16x16x128_f8f6f4 v[212:215], v[140:143], v[204:211], v[212:215], v240, v241 op_sel_hi:[0,0,0] cbsz:4
	v_and_b32_e32 v204, v190, v235
	v_and_b32_e32 v205, v190, v236
	v_and_b32_e32 v206, v190, v237
	v_and_b32_e32 v207, v190, v238
	v_and_b32_e32 v208, v191, v235
	v_and_b32_e32 v209, v191, v236
	v_and_b32_e32 v210, v191, v237
	v_and_b32_e32 v211, v191, v238
	s_mov_b64 vcc, s[6:7]
	v_cndmask_b32_dpp v140, v62, v60, vcc row_shr:4 row_mask:0xf bank_mask:0xf bound_ctrl:1
	v_cndmask_b32_dpp v141, v63, v61, vcc row_shr:4 row_mask:0xf bank_mask:0xf bound_ctrl:1
	s_mov_b64 vcc, s[4:5]
	v_cndmask_b32_dpp v142, v60, v62, vcc row_shl:4 row_mask:0xf bank_mask:0xf bound_ctrl:1
	v_cndmask_b32_dpp v143, v61, v63, vcc row_shl:4 row_mask:0xf bank_mask:0xf bound_ctrl:1
	v_mfma_scale_f32_16x16x128_f8f6f4 v[212:215], v[136:139], v[144:151], v[212:215], v240, v241 op_sel_hi:[0,0,0] cbsz:4
	s_nop 0
	v_mfma_scale_f32_16x16x128_f8f6f4 v[212:215], v[140:143], v[204:211], v[212:215], v240, v241 op_sel_hi:[0,0,0] cbsz:4
	global_load_dword v242, v246, s[40:41]
.LpgL0_vjoinv0:
	s_lshl_b32 s64, s0, 9
	s_add_u32 s64, s64, 0x1000
	s_add_u32 s70, s28, s64
	s_addc_u32 s71, s29, 0
	global_load_dwordx2 v[230:231], v239, s[70:71]
	s_waitcnt lgkmcnt(0)
	v_lshl_or_b32 v128, v128, 7, v232
	v_lshl_or_b32 v129, v129, 7, v232
	v_lshl_or_b32 v130, v130, 7, v232
	v_lshl_or_b32 v131, v131, 7, v232
	v_lshl_or_b32 v132, v132, 7, v232
	v_lshl_or_b32 v133, v133, 7, v232
	v_lshl_or_b32 v134, v134, 7, v232
	v_lshl_or_b32 v135, v135, 7, v232
	buffer_load_dwordx4 v[32:35], v128, s[20:23], s1 offen
	buffer_load_dwordx4 v[36:39], v129, s[20:23], s1 offen
	buffer_load_dwordx4 v[40:43], v130, s[20:23], s1 offen
	buffer_load_dwordx4 v[44:47], v131, s[20:23], s1 offen
	buffer_load_dwordx4 v[48:51], v132, s[20:23], s1 offen
	buffer_load_dwordx4 v[52:55], v133, s[20:23], s1 offen
	buffer_load_dwordx4 v[56:59], v134, s[20:23], s1 offen
	buffer_load_dwordx4 v[60:63], v135, s[20:23], s1 offen
	ds_read_b32 v128, v243 offset:1536
	ds_read_b32 v129, v243 offset:1568
	ds_read_b32 v130, v243 offset:1600
	ds_read_b32 v131, v243 offset:1632
	ds_read_b32 v132, v243 offset:1664
	ds_read_b32 v133, v243 offset:1696
	ds_read_b32 v134, v243 offset:1728
	ds_read_b32 v135, v243 offset:1760
	ds_read_b64 v[176:177], v234 offset:768
	ds_read_b64 v[178:179], v234 offset:800
	ds_read_b64 v[180:181], v234 offset:832
	ds_read_b64 v[182:183], v234 offset:864
	ds_read_b64 v[184:185], v234 offset:896
	ds_read_b64 v[186:187], v234 offset:928
	ds_read_b64 v[188:189], v234 offset:960
	ds_read_b64 v[190:191], v234 offset:992
	s_waitcnt vmcnt(28)
	v_and_b32_e32 v144, v160, v235
	v_and_b32_e32 v145, v160, v236
	v_and_b32_e32 v146, v160, v237
	v_and_b32_e32 v147, v160, v238
	v_and_b32_e32 v148, v161, v235
	v_and_b32_e32 v149, v161, v236
	v_and_b32_e32 v150, v161, v237
	v_and_b32_e32 v151, v161, v238
	s_mov_b64 vcc, s[4:5]
	v_cndmask_b32_dpp v138, v64, v66, vcc row_shl:4 row_mask:0xf bank_mask:0xf bound_ctrl:1
	v_cndmask_b32_dpp v139, v65, v67, vcc row_shl:4 row_mask:0xf bank_mask:0xf bound_ctrl:1
	s_mov_b64 vcc, s[6:7]
	v_cndmask_b32_dpp v136, v66, v64, vcc row_shr:4 row_mask:0xf bank_mask:0xf bound_ctrl:1
	v_cndmask_b32_dpp v137, v67, v65, vcc row_shr:4 row_mask:0xf bank_mask:0xf bound_ctrl:1
	v_and_b32_e32 v204, v162, v235
	v_and_b32_e32 v205, v162, v236
	v_and_b32_e32 v206, v162, v237
	v_and_b32_e32 v207, v162, v238
	v_and_b32_e32 v208, v163, v235
	v_and_b32_e32 v209, v163, v236
	v_and_b32_e32 v210, v163, v237
	v_and_b32_e32 v211, v163, v238
	s_mov_b64 vcc, s[6:7]
	v_cndmask_b32_dpp v140, v70, v68, vcc row_shr:4 row_mask:0xf bank_mask:0xf bound_ctrl:1
	v_cndmask_b32_dpp v141, v71, v69, vcc row_shr:4 row_mask:0xf bank_mask:0xf bound_ctrl:1
	s_mov_b64 vcc, s[4:5]
	v_cndmask_b32_dpp v142, v68, v70, vcc row_shl:4 row_mask:0xf bank_mask:0xf bound_ctrl:1
	v_cndmask_b32_dpp v143, v69, v71, vcc row_shl:4 row_mask:0xf bank_mask:0xf bound_ctrl:1
	v_mfma_scale_f32_16x16x128_f8f6f4 v[216:219], v[136:139], v[144:151], 0, v240, v241 op_sel_hi:[0,0,0] cbsz:4
	v_and_b32_e32 v144, v164, v235
	v_and_b32_e32 v145, v164, v236
	v_and_b32_e32 v146, v164, v237
	v_and_b32_e32 v147, v164, v238
	v_and_b32_e32 v148, v165, v235
	v_and_b32_e32 v149, v165, v236
	v_and_b32_e32 v150, v165, v237
	v_and_b32_e32 v151, v165, v238
	s_mov_b64 vcc, s[4:5]
	v_cndmask_b32_dpp v138, v72, v74, vcc row_shl:4 row_mask:0xf bank_mask:0xf bound_ctrl:1
	v_cndmask_b32_dpp v139, v73, v75, vcc row_shl:4 row_mask:0xf bank_mask:0xf bound_ctrl:1
	s_mov_b64 vcc, s[6:7]
	v_cndmask_b32_dpp v136, v74, v72, vcc row_shr:4 row_mask:0xf bank_mask:0xf bound_ctrl:1
	v_cndmask_b32_dpp v137, v75, v73, vcc row_shr:4 row_mask:0xf bank_mask:0xf bound_ctrl:1
	v_mfma_scale_f32_16x16x128_f8f6f4 v[216:219], v[140:143], v[204:211], v[216:219], v240, v241 op_sel_hi:[0,0,0] cbsz:4
	v_and_b32_e32 v204, v166, v235
	v_and_b32_e32 v205, v166, v236
	v_and_b32_e32 v206, v166, v237
	v_and_b32_e32 v207, v166, v238
	v_and_b32_e32 v208, v167, v235
	v_and_b32_e32 v209, v167, v236
	v_and_b32_e32 v210, v167, v237
	v_and_b32_e32 v211, v167, v238
	s_mov_b64 vcc, s[6:7]
	v_cndmask_b32_dpp v140, v78, v76, vcc row_shr:4 row_mask:0xf bank_mask:0xf bound_ctrl:1
	v_cndmask_b32_dpp v141, v79, v77, vcc row_shr:4 row_mask:0xf bank_mask:0xf bound_ctrl:1
	s_mov_b64 vcc, s[4:5]
	v_cndmask_b32_dpp v142, v76, v78, vcc row_shl:4 row_mask:0xf bank_mask:0xf bound_ctrl:1
	v_cndmask_b32_dpp v143, v77, v79, vcc row_shl:4 row_mask:0xf bank_mask:0xf bound_ctrl:1
	v_mfma_scale_f32_16x16x128_f8f6f4 v[216:219], v[136:139], v[144:151], v[216:219], v240, v241 op_sel_hi:[0,0,0] cbsz:4
	v_and_b32_e32 v144, v168, v235
	v_and_b32_e32 v145, v168, v236
	v_and_b32_e32 v146, v168, v237
	v_and_b32_e32 v147, v168, v238
	v_and_b32_e32 v148, v169, v235
	v_and_b32_e32 v149, v169, v236
	v_and_b32_e32 v150, v169, v237
	v_and_b32_e32 v151, v169, v238
	s_mov_b64 vcc, s[4:5]
	v_cndmask_b32_dpp v138, v80, v82, vcc row_shl:4 row_mask:0xf bank_mask:0xf bound_ctrl:1
	v_cndmask_b32_dpp v139, v81, v83, vcc row_shl:4 row_mask:0xf bank_mask:0xf bound_ctrl:1
	s_mov_b64 vcc, s[6:7]
	v_cndmask_b32_dpp v136, v82, v80, vcc row_shr:4 row_mask:0xf bank_mask:0xf bound_ctrl:1
	v_cndmask_b32_dpp v137, v83, v81, vcc row_shr:4 row_mask:0xf bank_mask:0xf bound_ctrl:1
	v_mfma_scale_f32_16x16x128_f8f6f4 v[216:219], v[140:143], v[204:211], v[216:219], v240, v241 op_sel_hi:[0,0,0] cbsz:4
	v_and_b32_e32 v204, v170, v235
	v_and_b32_e32 v205, v170, v236
	v_and_b32_e32 v206, v170, v237
	v_and_b32_e32 v207, v170, v238
	v_and_b32_e32 v208, v171, v235
	v_and_b32_e32 v209, v171, v236
	v_and_b32_e32 v210, v171, v237
	v_and_b32_e32 v211, v171, v238
	s_mov_b64 vcc, s[6:7]
	v_cndmask_b32_dpp v140, v86, v84, vcc row_shr:4 row_mask:0xf bank_mask:0xf bound_ctrl:1
	v_cndmask_b32_dpp v141, v87, v85, vcc row_shr:4 row_mask:0xf bank_mask:0xf bound_ctrl:1
	s_mov_b64 vcc, s[4:5]
	v_cndmask_b32_dpp v142, v84, v86, vcc row_shl:4 row_mask:0xf bank_mask:0xf bound_ctrl:1
	v_cndmask_b32_dpp v143, v85, v87, vcc row_shl:4 row_mask:0xf bank_mask:0xf bound_ctrl:1
	v_mfma_scale_f32_16x16x128_f8f6f4 v[216:219], v[136:139], v[144:151], v[216:219], v240, v241 op_sel_hi:[0,0,0] cbsz:4
	v_and_b32_e32 v144, v172, v235
	v_and_b32_e32 v145, v172, v236
	v_and_b32_e32 v146, v172, v237
	v_and_b32_e32 v147, v172, v238
	v_and_b32_e32 v148, v173, v235
	v_and_b32_e32 v149, v173, v236
	v_and_b32_e32 v150, v173, v237
	v_and_b32_e32 v151, v173, v238
	s_mov_b64 vcc, s[4:5]
	v_cndmask_b32_dpp v138, v88, v90, vcc row_shl:4 row_mask:0xf bank_mask:0xf bound_ctrl:1
	v_cndmask_b32_dpp v139, v89, v91, vcc row_shl:4 row_mask:0xf bank_mask:0xf bound_ctrl:1
	s_mov_b64 vcc, s[6:7]
	v_cndmask_b32_dpp v136, v90, v88, vcc row_shr:4 row_mask:0xf bank_mask:0xf bound_ctrl:1
	v_cndmask_b32_dpp v137, v91, v89, vcc row_shr:4 row_mask:0xf bank_mask:0xf bound_ctrl:1
	v_mfma_scale_f32_16x16x128_f8f6f4 v[216:219], v[140:143], v[204:211], v[216:219], v240, v241 op_sel_hi:[0,0,0] cbsz:4
	v_and_b32_e32 v204, v174, v235
	v_and_b32_e32 v205, v174, v236
	v_and_b32_e32 v206, v174, v237
	v_and_b32_e32 v207, v174, v238
	v_and_b32_e32 v208, v175, v235
	v_and_b32_e32 v209, v175, v236
	v_and_b32_e32 v210, v175, v237
	v_and_b32_e32 v211, v175, v238
	s_mov_b64 vcc, s[6:7]
	v_cndmask_b32_dpp v140, v94, v92, vcc row_shr:4 row_mask:0xf bank_mask:0xf bound_ctrl:1
	v_cndmask_b32_dpp v141, v95, v93, vcc row_shr:4 row_mask:0xf bank_mask:0xf bound_ctrl:1
	s_mov_b64 vcc, s[4:5]
	v_cndmask_b32_dpp v142, v92, v94, vcc row_shl:4 row_mask:0xf bank_mask:0xf bound_ctrl:1
	v_cndmask_b32_dpp v143, v93, v95, vcc row_shl:4 row_mask:0xf bank_mask:0xf bound_ctrl:1
	v_mfma_scale_f32_16x16x128_f8f6f4 v[216:219], v[136:139], v[144:151], v[216:219], v240, v241 op_sel_hi:[0,0,0] cbsz:4
	s_nop 0
	v_mfma_scale_f32_16x16x128_f8f6f4 v[216:219], v[140:143], v[204:211], v[216:219], v240, v241 op_sel_hi:[0,0,0] cbsz:4
	s_waitcnt lgkmcnt(0)
	v_lshl_or_b32 v128, v128, 7, v232
	v_lshl_or_b32 v129, v129, 7, v232
	v_lshl_or_b32 v130, v130, 7, v232
	v_lshl_or_b32 v131, v131, 7, v232
	v_lshl_or_b32 v132, v132, 7, v232
	v_lshl_or_b32 v133, v133, 7, v232
	v_lshl_or_b32 v134, v134, 7, v232
	v_lshl_or_b32 v135, v135, 7, v232
	buffer_load_dwordx4 v[64:67], v128, s[20:23], s1 offen
	buffer_load_dwordx4 v[68:71], v129, s[20:23], s1 offen
	buffer_load_dwordx4 v[72:75], v130, s[20:23], s1 offen
	buffer_load_dwordx4 v[76:79], v131, s[20:23], s1 offen
	buffer_load_dwordx4 v[80:83], v132, s[20:23], s1 offen
	buffer_load_dwordx4 v[84:87], v133, s[20:23], s1 offen
	buffer_load_dwordx4 v[88:91], v134, s[20:23], s1 offen
	buffer_load_dwordx4 v[92:95], v135, s[20:23], s1 offen
	ds_read_b32 v128, v243 offset:1792
	ds_read_b32 v129, v243 offset:1824
	ds_read_b32 v130, v243 offset:1856
	ds_read_b32 v131, v243 offset:1888
	ds_read_b32 v132, v243 offset:1920
	ds_read_b32 v133, v243 offset:1952
	ds_read_b32 v134, v243 offset:1984
	ds_read_b32 v135, v243 offset:2016
	ds_read_b64 v[160:161], v234 offset:1024
	ds_read_b64 v[162:163], v234 offset:1056
	ds_read_b64 v[164:165], v234 offset:1088
	ds_read_b64 v[166:167], v234 offset:1120
	ds_read_b64 v[168:169], v234 offset:1152
	ds_read_b64 v[170:171], v234 offset:1184
	ds_read_b64 v[172:173], v234 offset:1216
	ds_read_b64 v[174:175], v234 offset:1248
	s_waitcnt vmcnt(26)
	v_and_b32_e32 v144, v176, v235
	v_and_b32_e32 v145, v176, v236
	v_and_b32_e32 v146, v176, v237
	v_and_b32_e32 v147, v176, v238
	v_and_b32_e32 v148, v177, v235
	v_and_b32_e32 v149, v177, v236
	v_and_b32_e32 v150, v177, v237
	v_and_b32_e32 v151, v177, v238
	s_mov_b64 vcc, s[4:5]
	v_cndmask_b32_dpp v138, v96, v98, vcc row_shl:4 row_mask:0xf bank_mask:0xf bound_ctrl:1
	v_cndmask_b32_dpp v139, v97, v99, vcc row_shl:4 row_mask:0xf bank_mask:0xf bound_ctrl:1
	s_mov_b64 vcc, s[6:7]
	v_cndmask_b32_dpp v136, v98, v96, vcc row_shr:4 row_mask:0xf bank_mask:0xf bound_ctrl:1
	v_cndmask_b32_dpp v137, v99, v97, vcc row_shr:4 row_mask:0xf bank_mask:0xf bound_ctrl:1
	v_and_b32_e32 v204, v178, v235
	v_and_b32_e32 v205, v178, v236
	v_and_b32_e32 v206, v178, v237
	v_and_b32_e32 v207, v178, v238
	v_and_b32_e32 v208, v179, v235
	v_and_b32_e32 v209, v179, v236
	v_and_b32_e32 v210, v179, v237
	v_and_b32_e32 v211, v179, v238
	s_mov_b64 vcc, s[6:7]
	v_cndmask_b32_dpp v140, v102, v100, vcc row_shr:4 row_mask:0xf bank_mask:0xf bound_ctrl:1
	v_cndmask_b32_dpp v141, v103, v101, vcc row_shr:4 row_mask:0xf bank_mask:0xf bound_ctrl:1
	s_mov_b64 vcc, s[4:5]
	v_cndmask_b32_dpp v142, v100, v102, vcc row_shl:4 row_mask:0xf bank_mask:0xf bound_ctrl:1
	v_cndmask_b32_dpp v143, v101, v103, vcc row_shl:4 row_mask:0xf bank_mask:0xf bound_ctrl:1
	v_mfma_scale_f32_16x16x128_f8f6f4 v[216:219], v[136:139], v[144:151], v[216:219], v240, v241 op_sel_hi:[0,0,0] cbsz:4
	v_permlane16_swap_b32_e32 v212, v214
	v_permlane16_swap_b32_e32 v213, v215
	v_lshlrev_b32_e32 v252, 16, v228
	v_and_b32_e32 v144, v180, v235
	v_and_b32_e32 v145, v180, v236
	v_and_b32_e32 v146, v180, v237
	v_and_b32_e32 v147, v180, v238
	v_and_b32_e32 v148, v181, v235
	v_and_b32_e32 v149, v181, v236
	v_and_b32_e32 v150, v181, v237
	v_and_b32_e32 v151, v181, v238
	s_mov_b64 vcc, s[4:5]
	v_cndmask_b32_dpp v138, v104, v106, vcc row_shl:4 row_mask:0xf bank_mask:0xf bound_ctrl:1
	v_cndmask_b32_dpp v139, v105, v107, vcc row_shl:4 row_mask:0xf bank_mask:0xf bound_ctrl:1
	s_mov_b64 vcc, s[6:7]
	v_cndmask_b32_dpp v136, v106, v104, vcc row_shr:4 row_mask:0xf bank_mask:0xf bound_ctrl:1
	v_cndmask_b32_dpp v137, v107, v105, vcc row_shr:4 row_mask:0xf bank_mask:0xf bound_ctrl:1
	v_mfma_scale_f32_16x16x128_f8f6f4 v[216:219], v[140:143], v[204:211], v[216:219], v240, v241 op_sel_hi:[0,0,0] cbsz:4
	v_and_b32_e32 v253, 0xffff0000, v228
	v_lshlrev_b32_e32 v254, 16, v229
	v_and_b32_e32 v255, 0xffff0000, v229
	v_and_b32_e32 v204, v182, v235
	v_and_b32_e32 v205, v182, v236
	v_and_b32_e32 v206, v182, v237
	v_and_b32_e32 v207, v182, v238
	v_and_b32_e32 v208, v183, v235
	v_and_b32_e32 v209, v183, v236
	v_and_b32_e32 v210, v183, v237
	v_and_b32_e32 v211, v183, v238
	s_mov_b64 vcc, s[6:7]
	v_cndmask_b32_dpp v140, v110, v108, vcc row_shr:4 row_mask:0xf bank_mask:0xf bound_ctrl:1
	v_cndmask_b32_dpp v141, v111, v109, vcc row_shr:4 row_mask:0xf bank_mask:0xf bound_ctrl:1
	s_mov_b64 vcc, s[4:5]
	v_cndmask_b32_dpp v142, v108, v110, vcc row_shl:4 row_mask:0xf bank_mask:0xf bound_ctrl:1
	v_cndmask_b32_dpp v143, v109, v111, vcc row_shl:4 row_mask:0xf bank_mask:0xf bound_ctrl:1
	v_mfma_scale_f32_16x16x128_f8f6f4 v[216:219], v[136:139], v[144:151], v[216:219], v240, v241 op_sel_hi:[0,0,0] cbsz:4
	v_add_f32_e32 v252, v212, v252
	v_add_f32_e32 v253, v214, v253
	v_add_f32_e32 v254, v213, v254
	v_and_b32_e32 v144, v184, v235
	v_and_b32_e32 v145, v184, v236
	v_and_b32_e32 v146, v184, v237
	v_and_b32_e32 v147, v184, v238
	v_and_b32_e32 v148, v185, v235
	v_and_b32_e32 v149, v185, v236
	v_and_b32_e32 v150, v185, v237
	v_and_b32_e32 v151, v185, v238
	s_mov_b64 vcc, s[4:5]
	v_cndmask_b32_dpp v138, v112, v114, vcc row_shl:4 row_mask:0xf bank_mask:0xf bound_ctrl:1
	v_cndmask_b32_dpp v139, v113, v115, vcc row_shl:4 row_mask:0xf bank_mask:0xf bound_ctrl:1
	s_mov_b64 vcc, s[6:7]
	v_cndmask_b32_dpp v136, v114, v112, vcc row_shr:4 row_mask:0xf bank_mask:0xf bound_ctrl:1
	v_cndmask_b32_dpp v137, v115, v113, vcc row_shr:4 row_mask:0xf bank_mask:0xf bound_ctrl:1
	v_mfma_scale_f32_16x16x128_f8f6f4 v[216:219], v[140:143], v[204:211], v[216:219], v240, v241 op_sel_hi:[0,0,0] cbsz:4
	v_add_f32_e32 v255, v215, v255
	v_mul_f32_e32 v192, v252, v252
	v_mul_f32_e32 v193, v254, v254
	v_and_b32_e32 v204, v186, v235
	v_and_b32_e32 v205, v186, v236
	v_and_b32_e32 v206, v186, v237
	v_and_b32_e32 v207, v186, v238
	v_and_b32_e32 v208, v187, v235
	v_and_b32_e32 v209, v187, v236
	v_and_b32_e32 v210, v187, v237
	v_and_b32_e32 v211, v187, v238
	s_mov_b64 vcc, s[6:7]
	v_cndmask_b32_dpp v140, v118, v116, vcc row_shr:4 row_mask:0xf bank_mask:0xf bound_ctrl:1
	v_cndmask_b32_dpp v141, v119, v117, vcc row_shr:4 row_mask:0xf bank_mask:0xf bound_ctrl:1
	s_mov_b64 vcc, s[4:5]
	v_cndmask_b32_dpp v142, v116, v118, vcc row_shl:4 row_mask:0xf bank_mask:0xf bound_ctrl:1
	v_cndmask_b32_dpp v143, v117, v119, vcc row_shl:4 row_mask:0xf bank_mask:0xf bound_ctrl:1
	v_mfma_scale_f32_16x16x128_f8f6f4 v[216:219], v[136:139], v[144:151], v[216:219], v240, v241 op_sel_hi:[0,0,0] cbsz:4
	v_fmac_f32_e32 v192, v253, v253
	v_fmac_f32_e32 v193, v255, v255
	v_cvt_pk_bf16_f32 v250, v252, v253
	v_and_b32_e32 v144, v188, v235
	v_and_b32_e32 v145, v188, v236
	v_and_b32_e32 v146, v188, v237
	v_and_b32_e32 v147, v188, v238
	v_and_b32_e32 v148, v189, v235
	v_and_b32_e32 v149, v189, v236
	v_and_b32_e32 v150, v189, v237
	v_and_b32_e32 v151, v189, v238
	s_mov_b64 vcc, s[4:5]
	v_cndmask_b32_dpp v138, v120, v122, vcc row_shl:4 row_mask:0xf bank_mask:0xf bound_ctrl:1
	v_cndmask_b32_dpp v139, v121, v123, vcc row_shl:4 row_mask:0xf bank_mask:0xf bound_ctrl:1
	s_mov_b64 vcc, s[6:7]
	v_cndmask_b32_dpp v136, v122, v120, vcc row_shr:4 row_mask:0xf bank_mask:0xf bound_ctrl:1
	v_cndmask_b32_dpp v137, v123, v121, vcc row_shr:4 row_mask:0xf bank_mask:0xf bound_ctrl:1
	v_mfma_scale_f32_16x16x128_f8f6f4 v[216:219], v[140:143], v[204:211], v[216:219], v240, v241 op_sel_hi:[0,0,0] cbsz:4
	v_cvt_pk_bf16_f32 v251, v254, v255
	v_add_f32_e32 v192, v192, v193
	v_add_f32_e32 v220, v220, v192
	v_and_b32_e32 v204, v190, v235
	v_and_b32_e32 v205, v190, v236
	v_and_b32_e32 v206, v190, v237
	v_and_b32_e32 v207, v190, v238
	v_and_b32_e32 v208, v191, v235
	v_and_b32_e32 v209, v191, v236
	v_and_b32_e32 v210, v191, v237
	v_and_b32_e32 v211, v191, v238
	s_mov_b64 vcc, s[6:7]
	v_cndmask_b32_dpp v140, v126, v124, vcc row_shr:4 row_mask:0xf bank_mask:0xf bound_ctrl:1
	v_cndmask_b32_dpp v141, v127, v125, vcc row_shr:4 row_mask:0xf bank_mask:0xf bound_ctrl:1
	s_mov_b64 vcc, s[4:5]
	v_cndmask_b32_dpp v142, v124, v126, vcc row_shl:4 row_mask:0xf bank_mask:0xf bound_ctrl:1
	v_cndmask_b32_dpp v143, v125, v127, vcc row_shl:4 row_mask:0xf bank_mask:0xf bound_ctrl:1
	v_mfma_scale_f32_16x16x128_f8f6f4 v[216:219], v[136:139], v[144:151], v[216:219], v240, v241 op_sel_hi:[0,0,0] cbsz:4
	s_nop 0
	v_mfma_scale_f32_16x16x128_f8f6f4 v[216:219], v[140:143], v[204:211], v[216:219], v240, v241 op_sel_hi:[0,0,0] cbsz:4
	s_lshl_b32 s64, s0, 9
	s_add_u32 s64, s64, 0x0
	s_add_u32 s76, s28, s64
	s_addc_u32 s77, s29, 0
	global_store_dwordx2 v239, v[250:251], s[76:77]
	s_lshl_b32 s64, s0, 9
	s_add_u32 s64, s64, 0x2000
	s_add_u32 s70, s28, s64
	s_addc_u32 s71, s29, 0
	global_load_dwordx2 v[228:229], v239, s[70:71]
	s_waitcnt lgkmcnt(0)
	v_lshl_or_b32 v128, v128, 7, v232
	v_lshl_or_b32 v129, v129, 7, v232
	v_lshl_or_b32 v130, v130, 7, v232
	v_lshl_or_b32 v131, v131, 7, v232
	v_lshl_or_b32 v132, v132, 7, v232
	v_lshl_or_b32 v133, v133, 7, v232
	v_lshl_or_b32 v134, v134, 7, v232
	v_lshl_or_b32 v135, v135, 7, v232
	buffer_load_dwordx4 v[96:99], v128, s[20:23], s1 offen
	buffer_load_dwordx4 v[100:103], v129, s[20:23], s1 offen
	buffer_load_dwordx4 v[104:107], v130, s[20:23], s1 offen
	buffer_load_dwordx4 v[108:111], v131, s[20:23], s1 offen
	buffer_load_dwordx4 v[112:115], v132, s[20:23], s1 offen
	buffer_load_dwordx4 v[116:119], v133, s[20:23], s1 offen
	buffer_load_dwordx4 v[120:123], v134, s[20:23], s1 offen
	buffer_load_dwordx4 v[124:127], v135, s[20:23], s1 offen
	ds_read_b32 v128, v243 offset:2048
	ds_read_b32 v129, v243 offset:2080
	ds_read_b32 v130, v243 offset:2112
	ds_read_b32 v131, v243 offset:2144
	ds_read_b32 v132, v243 offset:2176
	ds_read_b32 v133, v243 offset:2208
	ds_read_b32 v134, v243 offset:2240
	ds_read_b32 v135, v243 offset:2272
	ds_read_b64 v[176:177], v234 offset:1280
	ds_read_b64 v[178:179], v234 offset:1312
	ds_read_b64 v[180:181], v234 offset:1344
	ds_read_b64 v[182:183], v234 offset:1376
	ds_read_b64 v[184:185], v234 offset:1408
	ds_read_b64 v[186:187], v234 offset:1440
	ds_read_b64 v[188:189], v234 offset:1472
	ds_read_b64 v[190:191], v234 offset:1504
	s_waitcnt vmcnt(28)
	v_and_b32_e32 v144, v160, v235
	v_and_b32_e32 v145, v160, v236
	v_and_b32_e32 v146, v160, v237
	v_and_b32_e32 v147, v160, v238
	v_and_b32_e32 v148, v161, v235
	v_and_b32_e32 v149, v161, v236
	v_and_b32_e32 v150, v161, v237
	v_and_b32_e32 v151, v161, v238
	s_mov_b64 vcc, s[4:5]
	v_cndmask_b32_dpp v138, v0, v2, vcc row_shl:4 row_mask:0xf bank_mask:0xf bound_ctrl:1
	v_cndmask_b32_dpp v139, v1, v3, vcc row_shl:4 row_mask:0xf bank_mask:0xf bound_ctrl:1
	s_mov_b64 vcc, s[6:7]
	v_cndmask_b32_dpp v136, v2, v0, vcc row_shr:4 row_mask:0xf bank_mask:0xf bound_ctrl:1
	v_cndmask_b32_dpp v137, v3, v1, vcc row_shr:4 row_mask:0xf bank_mask:0xf bound_ctrl:1
	v_and_b32_e32 v204, v162, v235
	v_and_b32_e32 v205, v162, v236
	v_and_b32_e32 v206, v162, v237
	v_and_b32_e32 v207, v162, v238
	v_and_b32_e32 v208, v163, v235
	v_and_b32_e32 v209, v163, v236
	v_and_b32_e32 v210, v163, v237
	v_and_b32_e32 v211, v163, v238
	s_mov_b64 vcc, s[6:7]
	v_cndmask_b32_dpp v140, v6, v4, vcc row_shr:4 row_mask:0xf bank_mask:0xf bound_ctrl:1
	v_cndmask_b32_dpp v141, v7, v5, vcc row_shr:4 row_mask:0xf bank_mask:0xf bound_ctrl:1
	s_mov_b64 vcc, s[4:5]
	v_cndmask_b32_dpp v142, v4, v6, vcc row_shl:4 row_mask:0xf bank_mask:0xf bound_ctrl:1
	v_cndmask_b32_dpp v143, v5, v7, vcc row_shl:4 row_mask:0xf bank_mask:0xf bound_ctrl:1
	v_mfma_scale_f32_16x16x128_f8f6f4 v[212:215], v[136:139], v[144:151], 0, v240, v241 op_sel_hi:[0,0,0] cbsz:4
	v_and_b32_e32 v144, v164, v235
	v_and_b32_e32 v145, v164, v236
	v_and_b32_e32 v146, v164, v237
	v_and_b32_e32 v147, v164, v238
	v_and_b32_e32 v148, v165, v235
	v_and_b32_e32 v149, v165, v236
	v_and_b32_e32 v150, v165, v237
	v_and_b32_e32 v151, v165, v238
	s_mov_b64 vcc, s[4:5]
	v_cndmask_b32_dpp v138, v8, v10, vcc row_shl:4 row_mask:0xf bank_mask:0xf bound_ctrl:1
	v_cndmask_b32_dpp v139, v9, v11, vcc row_shl:4 row_mask:0xf bank_mask:0xf bound_ctrl:1
	s_mov_b64 vcc, s[6:7]
	v_cndmask_b32_dpp v136, v10, v8, vcc row_shr:4 row_mask:0xf bank_mask:0xf bound_ctrl:1
	v_cndmask_b32_dpp v137, v11, v9, vcc row_shr:4 row_mask:0xf bank_mask:0xf bound_ctrl:1
	v_mfma_scale_f32_16x16x128_f8f6f4 v[212:215], v[140:143], v[204:211], v[212:215], v240, v241 op_sel_hi:[0,0,0] cbsz:4
	v_and_b32_e32 v204, v166, v235
	v_and_b32_e32 v205, v166, v236
	v_and_b32_e32 v206, v166, v237
	v_and_b32_e32 v207, v166, v238
	v_and_b32_e32 v208, v167, v235
	v_and_b32_e32 v209, v167, v236
	v_and_b32_e32 v210, v167, v237
	v_and_b32_e32 v211, v167, v238
	s_mov_b64 vcc, s[6:7]
	v_cndmask_b32_dpp v140, v14, v12, vcc row_shr:4 row_mask:0xf bank_mask:0xf bound_ctrl:1
	v_cndmask_b32_dpp v141, v15, v13, vcc row_shr:4 row_mask:0xf bank_mask:0xf bound_ctrl:1
	s_mov_b64 vcc, s[4:5]
	v_cndmask_b32_dpp v142, v12, v14, vcc row_shl:4 row_mask:0xf bank_mask:0xf bound_ctrl:1
	v_cndmask_b32_dpp v143, v13, v15, vcc row_shl:4 row_mask:0xf bank_mask:0xf bound_ctrl:1
	v_mfma_scale_f32_16x16x128_f8f6f4 v[212:215], v[136:139], v[144:151], v[212:215], v240, v241 op_sel_hi:[0,0,0] cbsz:4
	v_and_b32_e32 v144, v168, v235
	v_and_b32_e32 v145, v168, v236
	v_and_b32_e32 v146, v168, v237
	v_and_b32_e32 v147, v168, v238
	v_and_b32_e32 v148, v169, v235
	v_and_b32_e32 v149, v169, v236
	v_and_b32_e32 v150, v169, v237
	v_and_b32_e32 v151, v169, v238
	s_mov_b64 vcc, s[4:5]
	v_cndmask_b32_dpp v138, v16, v18, vcc row_shl:4 row_mask:0xf bank_mask:0xf bound_ctrl:1
	v_cndmask_b32_dpp v139, v17, v19, vcc row_shl:4 row_mask:0xf bank_mask:0xf bound_ctrl:1
	s_mov_b64 vcc, s[6:7]
	v_cndmask_b32_dpp v136, v18, v16, vcc row_shr:4 row_mask:0xf bank_mask:0xf bound_ctrl:1
	v_cndmask_b32_dpp v137, v19, v17, vcc row_shr:4 row_mask:0xf bank_mask:0xf bound_ctrl:1
	v_mfma_scale_f32_16x16x128_f8f6f4 v[212:215], v[140:143], v[204:211], v[212:215], v240, v241 op_sel_hi:[0,0,0] cbsz:4
	v_and_b32_e32 v204, v170, v235
	v_and_b32_e32 v205, v170, v236
	v_and_b32_e32 v206, v170, v237
	v_and_b32_e32 v207, v170, v238
	v_and_b32_e32 v208, v171, v235
	v_and_b32_e32 v209, v171, v236
	v_and_b32_e32 v210, v171, v237
	v_and_b32_e32 v211, v171, v238
	s_mov_b64 vcc, s[6:7]
	v_cndmask_b32_dpp v140, v22, v20, vcc row_shr:4 row_mask:0xf bank_mask:0xf bound_ctrl:1
	v_cndmask_b32_dpp v141, v23, v21, vcc row_shr:4 row_mask:0xf bank_mask:0xf bound_ctrl:1
	s_mov_b64 vcc, s[4:5]
	v_cndmask_b32_dpp v142, v20, v22, vcc row_shl:4 row_mask:0xf bank_mask:0xf bound_ctrl:1
	v_cndmask_b32_dpp v143, v21, v23, vcc row_shl:4 row_mask:0xf bank_mask:0xf bound_ctrl:1
	v_mfma_scale_f32_16x16x128_f8f6f4 v[212:215], v[136:139], v[144:151], v[212:215], v240, v241 op_sel_hi:[0,0,0] cbsz:4
	v_and_b32_e32 v144, v172, v235
	v_and_b32_e32 v145, v172, v236
	v_and_b32_e32 v146, v172, v237
	v_and_b32_e32 v147, v172, v238
	v_and_b32_e32 v148, v173, v235
	v_and_b32_e32 v149, v173, v236
	v_and_b32_e32 v150, v173, v237
	v_and_b32_e32 v151, v173, v238
	s_mov_b64 vcc, s[4:5]
	v_cndmask_b32_dpp v138, v24, v26, vcc row_shl:4 row_mask:0xf bank_mask:0xf bound_ctrl:1
	v_cndmask_b32_dpp v139, v25, v27, vcc row_shl:4 row_mask:0xf bank_mask:0xf bound_ctrl:1
	s_mov_b64 vcc, s[6:7]
	v_cndmask_b32_dpp v136, v26, v24, vcc row_shr:4 row_mask:0xf bank_mask:0xf bound_ctrl:1
	v_cndmask_b32_dpp v137, v27, v25, vcc row_shr:4 row_mask:0xf bank_mask:0xf bound_ctrl:1
	v_mfma_scale_f32_16x16x128_f8f6f4 v[212:215], v[140:143], v[204:211], v[212:215], v240, v241 op_sel_hi:[0,0,0] cbsz:4
	v_and_b32_e32 v204, v174, v235
	v_and_b32_e32 v205, v174, v236
	v_and_b32_e32 v206, v174, v237
	v_and_b32_e32 v207, v174, v238
	v_and_b32_e32 v208, v175, v235
	v_and_b32_e32 v209, v175, v236
	v_and_b32_e32 v210, v175, v237
	v_and_b32_e32 v211, v175, v238
	s_mov_b64 vcc, s[6:7]
	v_cndmask_b32_dpp v140, v30, v28, vcc row_shr:4 row_mask:0xf bank_mask:0xf bound_ctrl:1
	v_cndmask_b32_dpp v141, v31, v29, vcc row_shr:4 row_mask:0xf bank_mask:0xf bound_ctrl:1
	s_mov_b64 vcc, s[4:5]
	v_cndmask_b32_dpp v142, v28, v30, vcc row_shl:4 row_mask:0xf bank_mask:0xf bound_ctrl:1
	v_cndmask_b32_dpp v143, v29, v31, vcc row_shl:4 row_mask:0xf bank_mask:0xf bound_ctrl:1
	v_mfma_scale_f32_16x16x128_f8f6f4 v[212:215], v[136:139], v[144:151], v[212:215], v240, v241 op_sel_hi:[0,0,0] cbsz:4
	s_nop 0
	v_mfma_scale_f32_16x16x128_f8f6f4 v[212:215], v[140:143], v[204:211], v[212:215], v240, v241 op_sel_hi:[0,0,0] cbsz:4
	s_waitcnt lgkmcnt(0)
	v_lshl_or_b32 v128, v128, 7, v232
	v_lshl_or_b32 v129, v129, 7, v232
	v_lshl_or_b32 v130, v130, 7, v232
	v_lshl_or_b32 v131, v131, 7, v232
	v_lshl_or_b32 v132, v132, 7, v232
	v_lshl_or_b32 v133, v133, 7, v232
	v_lshl_or_b32 v134, v134, 7, v232
	v_lshl_or_b32 v135, v135, 7, v232
	buffer_load_dwordx4 v[0:3], v128, s[20:23], s1 offen
	buffer_load_dwordx4 v[4:7], v129, s[20:23], s1 offen
	buffer_load_dwordx4 v[8:11], v130, s[20:23], s1 offen
	buffer_load_dwordx4 v[12:15], v131, s[20:23], s1 offen
	buffer_load_dwordx4 v[16:19], v132, s[20:23], s1 offen
	buffer_load_dwordx4 v[20:23], v133, s[20:23], s1 offen
	buffer_load_dwordx4 v[24:27], v134, s[20:23], s1 offen
	buffer_load_dwordx4 v[28:31], v135, s[20:23], s1 offen
	ds_read_b32 v128, v243 offset:2304
	ds_read_b32 v129, v243 offset:2336
	ds_read_b32 v130, v243 offset:2368
	ds_read_b32 v131, v243 offset:2400
	ds_read_b32 v132, v243 offset:2432
	ds_read_b32 v133, v243 offset:2464
	ds_read_b32 v134, v243 offset:2496
	ds_read_b32 v135, v243 offset:2528
	ds_read_b64 v[160:161], v234 offset:1536
	ds_read_b64 v[162:163], v234 offset:1568
	ds_read_b64 v[164:165], v234 offset:1600
	ds_read_b64 v[166:167], v234 offset:1632
	ds_read_b64 v[168:169], v234 offset:1664
	ds_read_b64 v[170:171], v234 offset:1696
	ds_read_b64 v[172:173], v234 offset:1728
	ds_read_b64 v[174:175], v234 offset:1760
	s_waitcnt vmcnt(26)
	v_and_b32_e32 v144, v176, v235
	v_and_b32_e32 v145, v176, v236
	v_and_b32_e32 v146, v176, v237
	v_and_b32_e32 v147, v176, v238
	v_and_b32_e32 v148, v177, v235
	v_and_b32_e32 v149, v177, v236
	v_and_b32_e32 v150, v177, v237
	v_and_b32_e32 v151, v177, v238
	s_mov_b64 vcc, s[4:5]
	v_cndmask_b32_dpp v138, v32, v34, vcc row_shl:4 row_mask:0xf bank_mask:0xf bound_ctrl:1
	v_cndmask_b32_dpp v139, v33, v35, vcc row_shl:4 row_mask:0xf bank_mask:0xf bound_ctrl:1
	s_mov_b64 vcc, s[6:7]
	v_cndmask_b32_dpp v136, v34, v32, vcc row_shr:4 row_mask:0xf bank_mask:0xf bound_ctrl:1
	v_cndmask_b32_dpp v137, v35, v33, vcc row_shr:4 row_mask:0xf bank_mask:0xf bound_ctrl:1
	v_and_b32_e32 v204, v178, v235
	v_and_b32_e32 v205, v178, v236
	v_and_b32_e32 v206, v178, v237
	v_and_b32_e32 v207, v178, v238
	v_and_b32_e32 v208, v179, v235
	v_and_b32_e32 v209, v179, v236
	v_and_b32_e32 v210, v179, v237
	v_and_b32_e32 v211, v179, v238
	s_mov_b64 vcc, s[6:7]
	v_cndmask_b32_dpp v140, v38, v36, vcc row_shr:4 row_mask:0xf bank_mask:0xf bound_ctrl:1
	v_cndmask_b32_dpp v141, v39, v37, vcc row_shr:4 row_mask:0xf bank_mask:0xf bound_ctrl:1
	s_mov_b64 vcc, s[4:5]
	v_cndmask_b32_dpp v142, v36, v38, vcc row_shl:4 row_mask:0xf bank_mask:0xf bound_ctrl:1
	v_cndmask_b32_dpp v143, v37, v39, vcc row_shl:4 row_mask:0xf bank_mask:0xf bound_ctrl:1
	v_mfma_scale_f32_16x16x128_f8f6f4 v[212:215], v[136:139], v[144:151], v[212:215], v240, v241 op_sel_hi:[0,0,0] cbsz:4
	v_permlane16_swap_b32_e32 v216, v218
	v_permlane16_swap_b32_e32 v217, v219
	v_lshlrev_b32_e32 v252, 16, v230
	v_and_b32_e32 v144, v180, v235
	v_and_b32_e32 v145, v180, v236
	v_and_b32_e32 v146, v180, v237
	v_and_b32_e32 v147, v180, v238
	v_and_b32_e32 v148, v181, v235
	v_and_b32_e32 v149, v181, v236
	v_and_b32_e32 v150, v181, v237
	v_and_b32_e32 v151, v181, v238
	s_mov_b64 vcc, s[4:5]
	v_cndmask_b32_dpp v138, v40, v42, vcc row_shl:4 row_mask:0xf bank_mask:0xf bound_ctrl:1
	v_cndmask_b32_dpp v139, v41, v43, vcc row_shl:4 row_mask:0xf bank_mask:0xf bound_ctrl:1
	s_mov_b64 vcc, s[6:7]
	v_cndmask_b32_dpp v136, v42, v40, vcc row_shr:4 row_mask:0xf bank_mask:0xf bound_ctrl:1
	v_cndmask_b32_dpp v137, v43, v41, vcc row_shr:4 row_mask:0xf bank_mask:0xf bound_ctrl:1
	v_mfma_scale_f32_16x16x128_f8f6f4 v[212:215], v[140:143], v[204:211], v[212:215], v240, v241 op_sel_hi:[0,0,0] cbsz:4
	v_and_b32_e32 v253, 0xffff0000, v230
	v_lshlrev_b32_e32 v254, 16, v231
	v_and_b32_e32 v255, 0xffff0000, v231
	v_and_b32_e32 v204, v182, v235
	v_and_b32_e32 v205, v182, v236
	v_and_b32_e32 v206, v182, v237
	v_and_b32_e32 v207, v182, v238
	v_and_b32_e32 v208, v183, v235
	v_and_b32_e32 v209, v183, v236
	v_and_b32_e32 v210, v183, v237
	v_and_b32_e32 v211, v183, v238
	s_mov_b64 vcc, s[6:7]
	v_cndmask_b32_dpp v140, v46, v44, vcc row_shr:4 row_mask:0xf bank_mask:0xf bound_ctrl:1
	v_cndmask_b32_dpp v141, v47, v45, vcc row_shr:4 row_mask:0xf bank_mask:0xf bound_ctrl:1
	s_mov_b64 vcc, s[4:5]
	v_cndmask_b32_dpp v142, v44, v46, vcc row_shl:4 row_mask:0xf bank_mask:0xf bound_ctrl:1
	v_cndmask_b32_dpp v143, v45, v47, vcc row_shl:4 row_mask:0xf bank_mask:0xf bound_ctrl:1
	v_mfma_scale_f32_16x16x128_f8f6f4 v[212:215], v[136:139], v[144:151], v[212:215], v240, v241 op_sel_hi:[0,0,0] cbsz:4
	v_add_f32_e32 v252, v216, v252
	v_add_f32_e32 v253, v218, v253
	v_add_f32_e32 v254, v217, v254
	v_and_b32_e32 v144, v184, v235
	v_and_b32_e32 v145, v184, v236
	v_and_b32_e32 v146, v184, v237
	v_and_b32_e32 v147, v184, v238
	v_and_b32_e32 v148, v185, v235
	v_and_b32_e32 v149, v185, v236
	v_and_b32_e32 v150, v185, v237
	v_and_b32_e32 v151, v185, v238
	s_mov_b64 vcc, s[4:5]
	v_cndmask_b32_dpp v138, v48, v50, vcc row_shl:4 row_mask:0xf bank_mask:0xf bound_ctrl:1
	v_cndmask_b32_dpp v139, v49, v51, vcc row_shl:4 row_mask:0xf bank_mask:0xf bound_ctrl:1
	s_mov_b64 vcc, s[6:7]
	v_cndmask_b32_dpp v136, v50, v48, vcc row_shr:4 row_mask:0xf bank_mask:0xf bound_ctrl:1
	v_cndmask_b32_dpp v137, v51, v49, vcc row_shr:4 row_mask:0xf bank_mask:0xf bound_ctrl:1
	v_mfma_scale_f32_16x16x128_f8f6f4 v[212:215], v[140:143], v[204:211], v[212:215], v240, v241 op_sel_hi:[0,0,0] cbsz:4
	v_add_f32_e32 v255, v219, v255
	v_mul_f32_e32 v192, v252, v252
	v_mul_f32_e32 v193, v254, v254
	v_and_b32_e32 v204, v186, v235
	v_and_b32_e32 v205, v186, v236
	v_and_b32_e32 v206, v186, v237
	v_and_b32_e32 v207, v186, v238
	v_and_b32_e32 v208, v187, v235
	v_and_b32_e32 v209, v187, v236
	v_and_b32_e32 v210, v187, v237
	v_and_b32_e32 v211, v187, v238
	s_mov_b64 vcc, s[6:7]
	v_cndmask_b32_dpp v140, v54, v52, vcc row_shr:4 row_mask:0xf bank_mask:0xf bound_ctrl:1
	v_cndmask_b32_dpp v141, v55, v53, vcc row_shr:4 row_mask:0xf bank_mask:0xf bound_ctrl:1
	s_mov_b64 vcc, s[4:5]
	v_cndmask_b32_dpp v142, v52, v54, vcc row_shl:4 row_mask:0xf bank_mask:0xf bound_ctrl:1
	v_cndmask_b32_dpp v143, v53, v55, vcc row_shl:4 row_mask:0xf bank_mask:0xf bound_ctrl:1
	v_mfma_scale_f32_16x16x128_f8f6f4 v[212:215], v[136:139], v[144:151], v[212:215], v240, v241 op_sel_hi:[0,0,0] cbsz:4
	v_fmac_f32_e32 v192, v253, v253
	v_fmac_f32_e32 v193, v255, v255
	v_cvt_pk_bf16_f32 v250, v252, v253
	v_and_b32_e32 v144, v188, v235
	v_and_b32_e32 v145, v188, v236
	v_and_b32_e32 v146, v188, v237
	v_and_b32_e32 v147, v188, v238
	v_and_b32_e32 v148, v189, v235
	v_and_b32_e32 v149, v189, v236
	v_and_b32_e32 v150, v189, v237
	v_and_b32_e32 v151, v189, v238
	s_mov_b64 vcc, s[4:5]
	v_cndmask_b32_dpp v138, v56, v58, vcc row_shl:4 row_mask:0xf bank_mask:0xf bound_ctrl:1
	v_cndmask_b32_dpp v139, v57, v59, vcc row_shl:4 row_mask:0xf bank_mask:0xf bound_ctrl:1
	s_mov_b64 vcc, s[6:7]
	v_cndmask_b32_dpp v136, v58, v56, vcc row_shr:4 row_mask:0xf bank_mask:0xf bound_ctrl:1
	v_cndmask_b32_dpp v137, v59, v57, vcc row_shr:4 row_mask:0xf bank_mask:0xf bound_ctrl:1
	v_mfma_scale_f32_16x16x128_f8f6f4 v[212:215], v[140:143], v[204:211], v[212:215], v240, v241 op_sel_hi:[0,0,0] cbsz:4
	v_cvt_pk_bf16_f32 v251, v254, v255
	v_add_f32_e32 v192, v192, v193
	v_add_f32_e32 v221, v221, v192
	v_and_b32_e32 v204, v190, v235
	v_and_b32_e32 v205, v190, v236
	v_and_b32_e32 v206, v190, v237
	v_and_b32_e32 v207, v190, v238
	v_and_b32_e32 v208, v191, v235
	v_and_b32_e32 v209, v191, v236
	v_and_b32_e32 v210, v191, v237
	v_and_b32_e32 v211, v191, v238
	s_mov_b64 vcc, s[6:7]
	v_cndmask_b32_dpp v140, v62, v60, vcc row_shr:4 row_mask:0xf bank_mask:0xf bound_ctrl:1
	v_cndmask_b32_dpp v141, v63, v61, vcc row_shr:4 row_mask:0xf bank_mask:0xf bound_ctrl:1
	s_mov_b64 vcc, s[4:5]
	v_cndmask_b32_dpp v142, v60, v62, vcc row_shl:4 row_mask:0xf bank_mask:0xf bound_ctrl:1
	v_cndmask_b32_dpp v143, v61, v63, vcc row_shl:4 row_mask:0xf bank_mask:0xf bound_ctrl:1
	v_mfma_scale_f32_16x16x128_f8f6f4 v[212:215], v[136:139], v[144:151], v[212:215], v240, v241 op_sel_hi:[0,0,0] cbsz:4
	s_nop 0
	v_mfma_scale_f32_16x16x128_f8f6f4 v[212:215], v[140:143], v[204:211], v[212:215], v240, v241 op_sel_hi:[0,0,0] cbsz:4
	s_lshl_b32 s64, s0, 9
	s_add_u32 s64, s64, 0x1000
	s_add_u32 s76, s28, s64
	s_addc_u32 s77, s29, 0
	global_store_dwordx2 v239, v[250:251], s[76:77]
	s_lshl_b32 s64, s0, 9
	s_add_u32 s64, s64, 0x3000
	s_add_u32 s70, s28, s64
	s_addc_u32 s71, s29, 0
	global_load_dwordx2 v[230:231], v239, s[70:71]
	s_waitcnt lgkmcnt(0)
	v_lshl_or_b32 v128, v128, 7, v232
	v_lshl_or_b32 v129, v129, 7, v232
	v_lshl_or_b32 v130, v130, 7, v232
	v_lshl_or_b32 v131, v131, 7, v232
	v_lshl_or_b32 v132, v132, 7, v232
	v_lshl_or_b32 v133, v133, 7, v232
	v_lshl_or_b32 v134, v134, 7, v232
	v_lshl_or_b32 v135, v135, 7, v232
	buffer_load_dwordx4 v[32:35], v128, s[20:23], s1 offen
	buffer_load_dwordx4 v[36:39], v129, s[20:23], s1 offen
	buffer_load_dwordx4 v[40:43], v130, s[20:23], s1 offen
	buffer_load_dwordx4 v[44:47], v131, s[20:23], s1 offen
	buffer_load_dwordx4 v[48:51], v132, s[20:23], s1 offen
	buffer_load_dwordx4 v[52:55], v133, s[20:23], s1 offen
	buffer_load_dwordx4 v[56:59], v134, s[20:23], s1 offen
	buffer_load_dwordx4 v[60:63], v135, s[20:23], s1 offen
	ds_read_b32 v128, v243 offset:2560
	ds_read_b32 v129, v243 offset:2592
	ds_read_b32 v130, v243 offset:2624
	ds_read_b32 v131, v243 offset:2656
	ds_read_b32 v132, v243 offset:2688
	ds_read_b32 v133, v243 offset:2720
	ds_read_b32 v134, v243 offset:2752
	ds_read_b32 v135, v243 offset:2784
	ds_read_b64 v[176:177], v234 offset:1792
	ds_read_b64 v[178:179], v234 offset:1824
	ds_read_b64 v[180:181], v234 offset:1856
	ds_read_b64 v[182:183], v234 offset:1888
	ds_read_b64 v[184:185], v234 offset:1920
	ds_read_b64 v[186:187], v234 offset:1952
	ds_read_b64 v[188:189], v234 offset:1984
	ds_read_b64 v[190:191], v234 offset:2016
	s_waitcnt vmcnt(28)
	v_and_b32_e32 v144, v160, v235
	v_and_b32_e32 v145, v160, v236
	v_and_b32_e32 v146, v160, v237
	v_and_b32_e32 v147, v160, v238
	v_and_b32_e32 v148, v161, v235
	v_and_b32_e32 v149, v161, v236
	v_and_b32_e32 v150, v161, v237
	v_and_b32_e32 v151, v161, v238
	s_mov_b64 vcc, s[4:5]
	v_cndmask_b32_dpp v138, v64, v66, vcc row_shl:4 row_mask:0xf bank_mask:0xf bound_ctrl:1
	v_cndmask_b32_dpp v139, v65, v67, vcc row_shl:4 row_mask:0xf bank_mask:0xf bound_ctrl:1
	s_mov_b64 vcc, s[6:7]
	v_cndmask_b32_dpp v136, v66, v64, vcc row_shr:4 row_mask:0xf bank_mask:0xf bound_ctrl:1
	v_cndmask_b32_dpp v137, v67, v65, vcc row_shr:4 row_mask:0xf bank_mask:0xf bound_ctrl:1
	v_and_b32_e32 v204, v162, v235
	v_and_b32_e32 v205, v162, v236
	v_and_b32_e32 v206, v162, v237
	v_and_b32_e32 v207, v162, v238
	v_and_b32_e32 v208, v163, v235
	v_and_b32_e32 v209, v163, v236
	v_and_b32_e32 v210, v163, v237
	v_and_b32_e32 v211, v163, v238
	s_mov_b64 vcc, s[6:7]
	v_cndmask_b32_dpp v140, v70, v68, vcc row_shr:4 row_mask:0xf bank_mask:0xf bound_ctrl:1
	v_cndmask_b32_dpp v141, v71, v69, vcc row_shr:4 row_mask:0xf bank_mask:0xf bound_ctrl:1
	s_mov_b64 vcc, s[4:5]
	v_cndmask_b32_dpp v142, v68, v70, vcc row_shl:4 row_mask:0xf bank_mask:0xf bound_ctrl:1
	v_cndmask_b32_dpp v143, v69, v71, vcc row_shl:4 row_mask:0xf bank_mask:0xf bound_ctrl:1
	v_mfma_scale_f32_16x16x128_f8f6f4 v[216:219], v[136:139], v[144:151], 0, v240, v241 op_sel_hi:[0,0,0] cbsz:4
	v_and_b32_e32 v144, v164, v235
	v_and_b32_e32 v145, v164, v236
	v_and_b32_e32 v146, v164, v237
	v_and_b32_e32 v147, v164, v238
	v_and_b32_e32 v148, v165, v235
	v_and_b32_e32 v149, v165, v236
	v_and_b32_e32 v150, v165, v237
	v_and_b32_e32 v151, v165, v238
	s_mov_b64 vcc, s[4:5]
	v_cndmask_b32_dpp v138, v72, v74, vcc row_shl:4 row_mask:0xf bank_mask:0xf bound_ctrl:1
	v_cndmask_b32_dpp v139, v73, v75, vcc row_shl:4 row_mask:0xf bank_mask:0xf bound_ctrl:1
	s_mov_b64 vcc, s[6:7]
	v_cndmask_b32_dpp v136, v74, v72, vcc row_shr:4 row_mask:0xf bank_mask:0xf bound_ctrl:1
	v_cndmask_b32_dpp v137, v75, v73, vcc row_shr:4 row_mask:0xf bank_mask:0xf bound_ctrl:1
	v_mfma_scale_f32_16x16x128_f8f6f4 v[216:219], v[140:143], v[204:211], v[216:219], v240, v241 op_sel_hi:[0,0,0] cbsz:4
	v_and_b32_e32 v204, v166, v235
	v_and_b32_e32 v205, v166, v236
	v_and_b32_e32 v206, v166, v237
	v_and_b32_e32 v207, v166, v238
	v_and_b32_e32 v208, v167, v235
	v_and_b32_e32 v209, v167, v236
	v_and_b32_e32 v210, v167, v237
	v_and_b32_e32 v211, v167, v238
	s_mov_b64 vcc, s[6:7]
	v_cndmask_b32_dpp v140, v78, v76, vcc row_shr:4 row_mask:0xf bank_mask:0xf bound_ctrl:1
	v_cndmask_b32_dpp v141, v79, v77, vcc row_shr:4 row_mask:0xf bank_mask:0xf bound_ctrl:1
	s_mov_b64 vcc, s[4:5]
	v_cndmask_b32_dpp v142, v76, v78, vcc row_shl:4 row_mask:0xf bank_mask:0xf bound_ctrl:1
	v_cndmask_b32_dpp v143, v77, v79, vcc row_shl:4 row_mask:0xf bank_mask:0xf bound_ctrl:1
	v_mfma_scale_f32_16x16x128_f8f6f4 v[216:219], v[136:139], v[144:151], v[216:219], v240, v241 op_sel_hi:[0,0,0] cbsz:4
	v_and_b32_e32 v144, v168, v235
	v_and_b32_e32 v145, v168, v236
	v_and_b32_e32 v146, v168, v237
	v_and_b32_e32 v147, v168, v238
	v_and_b32_e32 v148, v169, v235
	v_and_b32_e32 v149, v169, v236
	v_and_b32_e32 v150, v169, v237
	v_and_b32_e32 v151, v169, v238
	s_mov_b64 vcc, s[4:5]
	v_cndmask_b32_dpp v138, v80, v82, vcc row_shl:4 row_mask:0xf bank_mask:0xf bound_ctrl:1
	v_cndmask_b32_dpp v139, v81, v83, vcc row_shl:4 row_mask:0xf bank_mask:0xf bound_ctrl:1
	s_mov_b64 vcc, s[6:7]
	v_cndmask_b32_dpp v136, v82, v80, vcc row_shr:4 row_mask:0xf bank_mask:0xf bound_ctrl:1
	v_cndmask_b32_dpp v137, v83, v81, vcc row_shr:4 row_mask:0xf bank_mask:0xf bound_ctrl:1
	v_mfma_scale_f32_16x16x128_f8f6f4 v[216:219], v[140:143], v[204:211], v[216:219], v240, v241 op_sel_hi:[0,0,0] cbsz:4
	v_and_b32_e32 v204, v170, v235
	v_and_b32_e32 v205, v170, v236
	v_and_b32_e32 v206, v170, v237
	v_and_b32_e32 v207, v170, v238
	v_and_b32_e32 v208, v171, v235
	v_and_b32_e32 v209, v171, v236
	v_and_b32_e32 v210, v171, v237
	v_and_b32_e32 v211, v171, v238
	s_mov_b64 vcc, s[6:7]
	v_cndmask_b32_dpp v140, v86, v84, vcc row_shr:4 row_mask:0xf bank_mask:0xf bound_ctrl:1
	v_cndmask_b32_dpp v141, v87, v85, vcc row_shr:4 row_mask:0xf bank_mask:0xf bound_ctrl:1
	s_mov_b64 vcc, s[4:5]
	v_cndmask_b32_dpp v142, v84, v86, vcc row_shl:4 row_mask:0xf bank_mask:0xf bound_ctrl:1
	v_cndmask_b32_dpp v143, v85, v87, vcc row_shl:4 row_mask:0xf bank_mask:0xf bound_ctrl:1
	v_mfma_scale_f32_16x16x128_f8f6f4 v[216:219], v[136:139], v[144:151], v[216:219], v240, v241 op_sel_hi:[0,0,0] cbsz:4
	v_and_b32_e32 v144, v172, v235
	v_and_b32_e32 v145, v172, v236
	v_and_b32_e32 v146, v172, v237
	v_and_b32_e32 v147, v172, v238
	v_and_b32_e32 v148, v173, v235
	v_and_b32_e32 v149, v173, v236
	v_and_b32_e32 v150, v173, v237
	v_and_b32_e32 v151, v173, v238
	s_mov_b64 vcc, s[4:5]
	v_cndmask_b32_dpp v138, v88, v90, vcc row_shl:4 row_mask:0xf bank_mask:0xf bound_ctrl:1
	v_cndmask_b32_dpp v139, v89, v91, vcc row_shl:4 row_mask:0xf bank_mask:0xf bound_ctrl:1
	s_mov_b64 vcc, s[6:7]
	v_cndmask_b32_dpp v136, v90, v88, vcc row_shr:4 row_mask:0xf bank_mask:0xf bound_ctrl:1
	v_cndmask_b32_dpp v137, v91, v89, vcc row_shr:4 row_mask:0xf bank_mask:0xf bound_ctrl:1
	v_mfma_scale_f32_16x16x128_f8f6f4 v[216:219], v[140:143], v[204:211], v[216:219], v240, v241 op_sel_hi:[0,0,0] cbsz:4
	v_and_b32_e32 v204, v174, v235
	v_and_b32_e32 v205, v174, v236
	v_and_b32_e32 v206, v174, v237
	v_and_b32_e32 v207, v174, v238
	v_and_b32_e32 v208, v175, v235
	v_and_b32_e32 v209, v175, v236
	v_and_b32_e32 v210, v175, v237
	v_and_b32_e32 v211, v175, v238
	s_mov_b64 vcc, s[6:7]
	v_cndmask_b32_dpp v140, v94, v92, vcc row_shr:4 row_mask:0xf bank_mask:0xf bound_ctrl:1
	v_cndmask_b32_dpp v141, v95, v93, vcc row_shr:4 row_mask:0xf bank_mask:0xf bound_ctrl:1
	s_mov_b64 vcc, s[4:5]
	v_cndmask_b32_dpp v142, v92, v94, vcc row_shl:4 row_mask:0xf bank_mask:0xf bound_ctrl:1
	v_cndmask_b32_dpp v143, v93, v95, vcc row_shl:4 row_mask:0xf bank_mask:0xf bound_ctrl:1
	v_mfma_scale_f32_16x16x128_f8f6f4 v[216:219], v[136:139], v[144:151], v[216:219], v240, v241 op_sel_hi:[0,0,0] cbsz:4
	s_nop 0
	v_mfma_scale_f32_16x16x128_f8f6f4 v[216:219], v[140:143], v[204:211], v[216:219], v240, v241 op_sel_hi:[0,0,0] cbsz:4
	s_waitcnt lgkmcnt(0)
	v_lshl_or_b32 v128, v128, 7, v232
	v_lshl_or_b32 v129, v129, 7, v232
	v_lshl_or_b32 v130, v130, 7, v232
	v_lshl_or_b32 v131, v131, 7, v232
	v_lshl_or_b32 v132, v132, 7, v232
	v_lshl_or_b32 v133, v133, 7, v232
	v_lshl_or_b32 v134, v134, 7, v232
	v_lshl_or_b32 v135, v135, 7, v232
	buffer_load_dwordx4 v[64:67], v128, s[20:23], s1 offen
	buffer_load_dwordx4 v[68:71], v129, s[20:23], s1 offen
	buffer_load_dwordx4 v[72:75], v130, s[20:23], s1 offen
	buffer_load_dwordx4 v[76:79], v131, s[20:23], s1 offen
	buffer_load_dwordx4 v[80:83], v132, s[20:23], s1 offen
	buffer_load_dwordx4 v[84:87], v133, s[20:23], s1 offen
	buffer_load_dwordx4 v[88:91], v134, s[20:23], s1 offen
	buffer_load_dwordx4 v[92:95], v135, s[20:23], s1 offen
	ds_read_b32 v128, v243 offset:2816
	ds_read_b32 v129, v243 offset:2848
	ds_read_b32 v130, v243 offset:2880
	ds_read_b32 v131, v243 offset:2912
	ds_read_b32 v132, v243 offset:2944
	ds_read_b32 v133, v243 offset:2976
	ds_read_b32 v134, v243 offset:3008
	ds_read_b32 v135, v243 offset:3040
	ds_read_b64 v[160:161], v234 offset:2048
	ds_read_b64 v[162:163], v234 offset:2080
	ds_read_b64 v[164:165], v234 offset:2112
	ds_read_b64 v[166:167], v234 offset:2144
	ds_read_b64 v[168:169], v234 offset:2176
	ds_read_b64 v[170:171], v234 offset:2208
	ds_read_b64 v[172:173], v234 offset:2240
	ds_read_b64 v[174:175], v234 offset:2272
	s_waitcnt vmcnt(26)
	v_and_b32_e32 v144, v176, v235
	v_and_b32_e32 v145, v176, v236
	v_and_b32_e32 v146, v176, v237
	v_and_b32_e32 v147, v176, v238
	v_and_b32_e32 v148, v177, v235
	v_and_b32_e32 v149, v177, v236
	v_and_b32_e32 v150, v177, v237
	v_and_b32_e32 v151, v177, v238
	s_mov_b64 vcc, s[4:5]
	v_cndmask_b32_dpp v138, v96, v98, vcc row_shl:4 row_mask:0xf bank_mask:0xf bound_ctrl:1
	v_cndmask_b32_dpp v139, v97, v99, vcc row_shl:4 row_mask:0xf bank_mask:0xf bound_ctrl:1
	s_mov_b64 vcc, s[6:7]
	v_cndmask_b32_dpp v136, v98, v96, vcc row_shr:4 row_mask:0xf bank_mask:0xf bound_ctrl:1
	v_cndmask_b32_dpp v137, v99, v97, vcc row_shr:4 row_mask:0xf bank_mask:0xf bound_ctrl:1
	v_and_b32_e32 v204, v178, v235
	v_and_b32_e32 v205, v178, v236
	v_and_b32_e32 v206, v178, v237
	v_and_b32_e32 v207, v178, v238
	v_and_b32_e32 v208, v179, v235
	v_and_b32_e32 v209, v179, v236
	v_and_b32_e32 v210, v179, v237
	v_and_b32_e32 v211, v179, v238
	s_mov_b64 vcc, s[6:7]
	v_cndmask_b32_dpp v140, v102, v100, vcc row_shr:4 row_mask:0xf bank_mask:0xf bound_ctrl:1
	v_cndmask_b32_dpp v141, v103, v101, vcc row_shr:4 row_mask:0xf bank_mask:0xf bound_ctrl:1
	s_mov_b64 vcc, s[4:5]
	v_cndmask_b32_dpp v142, v100, v102, vcc row_shl:4 row_mask:0xf bank_mask:0xf bound_ctrl:1
	v_cndmask_b32_dpp v143, v101, v103, vcc row_shl:4 row_mask:0xf bank_mask:0xf bound_ctrl:1
	v_mfma_scale_f32_16x16x128_f8f6f4 v[216:219], v[136:139], v[144:151], v[216:219], v240, v241 op_sel_hi:[0,0,0] cbsz:4
	v_permlane16_swap_b32_e32 v212, v214
	v_permlane16_swap_b32_e32 v213, v215
	v_lshlrev_b32_e32 v252, 16, v228
	v_and_b32_e32 v144, v180, v235
	v_and_b32_e32 v145, v180, v236
	v_and_b32_e32 v146, v180, v237
	v_and_b32_e32 v147, v180, v238
	v_and_b32_e32 v148, v181, v235
	v_and_b32_e32 v149, v181, v236
	v_and_b32_e32 v150, v181, v237
	v_and_b32_e32 v151, v181, v238
	s_mov_b64 vcc, s[4:5]
	v_cndmask_b32_dpp v138, v104, v106, vcc row_shl:4 row_mask:0xf bank_mask:0xf bound_ctrl:1
	v_cndmask_b32_dpp v139, v105, v107, vcc row_shl:4 row_mask:0xf bank_mask:0xf bound_ctrl:1
	s_mov_b64 vcc, s[6:7]
	v_cndmask_b32_dpp v136, v106, v104, vcc row_shr:4 row_mask:0xf bank_mask:0xf bound_ctrl:1
	v_cndmask_b32_dpp v137, v107, v105, vcc row_shr:4 row_mask:0xf bank_mask:0xf bound_ctrl:1
	v_mfma_scale_f32_16x16x128_f8f6f4 v[216:219], v[140:143], v[204:211], v[216:219], v240, v241 op_sel_hi:[0,0,0] cbsz:4
	v_and_b32_e32 v253, 0xffff0000, v228
	v_lshlrev_b32_e32 v254, 16, v229
	v_and_b32_e32 v255, 0xffff0000, v229
	v_and_b32_e32 v204, v182, v235
	v_and_b32_e32 v205, v182, v236
	v_and_b32_e32 v206, v182, v237
	v_and_b32_e32 v207, v182, v238
	v_and_b32_e32 v208, v183, v235
	v_and_b32_e32 v209, v183, v236
	v_and_b32_e32 v210, v183, v237
	v_and_b32_e32 v211, v183, v238
	s_mov_b64 vcc, s[6:7]
	v_cndmask_b32_dpp v140, v110, v108, vcc row_shr:4 row_mask:0xf bank_mask:0xf bound_ctrl:1
	v_cndmask_b32_dpp v141, v111, v109, vcc row_shr:4 row_mask:0xf bank_mask:0xf bound_ctrl:1
	s_mov_b64 vcc, s[4:5]
	v_cndmask_b32_dpp v142, v108, v110, vcc row_shl:4 row_mask:0xf bank_mask:0xf bound_ctrl:1
	v_cndmask_b32_dpp v143, v109, v111, vcc row_shl:4 row_mask:0xf bank_mask:0xf bound_ctrl:1
	v_mfma_scale_f32_16x16x128_f8f6f4 v[216:219], v[136:139], v[144:151], v[216:219], v240, v241 op_sel_hi:[0,0,0] cbsz:4
	v_add_f32_e32 v252, v212, v252
	v_add_f32_e32 v253, v214, v253
	v_add_f32_e32 v254, v213, v254
	v_and_b32_e32 v144, v184, v235
	v_and_b32_e32 v145, v184, v236
	v_and_b32_e32 v146, v184, v237
	v_and_b32_e32 v147, v184, v238
	v_and_b32_e32 v148, v185, v235
	v_and_b32_e32 v149, v185, v236
	v_and_b32_e32 v150, v185, v237
	v_and_b32_e32 v151, v185, v238
	s_mov_b64 vcc, s[4:5]
	v_cndmask_b32_dpp v138, v112, v114, vcc row_shl:4 row_mask:0xf bank_mask:0xf bound_ctrl:1
	v_cndmask_b32_dpp v139, v113, v115, vcc row_shl:4 row_mask:0xf bank_mask:0xf bound_ctrl:1
	s_mov_b64 vcc, s[6:7]
	v_cndmask_b32_dpp v136, v114, v112, vcc row_shr:4 row_mask:0xf bank_mask:0xf bound_ctrl:1
	v_cndmask_b32_dpp v137, v115, v113, vcc row_shr:4 row_mask:0xf bank_mask:0xf bound_ctrl:1
	v_mfma_scale_f32_16x16x128_f8f6f4 v[216:219], v[140:143], v[204:211], v[216:219], v240, v241 op_sel_hi:[0,0,0] cbsz:4
	v_add_f32_e32 v255, v215, v255
	v_mul_f32_e32 v192, v252, v252
	v_mul_f32_e32 v193, v254, v254
	v_and_b32_e32 v204, v186, v235
	v_and_b32_e32 v205, v186, v236
	v_and_b32_e32 v206, v186, v237
	v_and_b32_e32 v207, v186, v238
	v_and_b32_e32 v208, v187, v235
	v_and_b32_e32 v209, v187, v236
	v_and_b32_e32 v210, v187, v237
	v_and_b32_e32 v211, v187, v238
	s_mov_b64 vcc, s[6:7]
	v_cndmask_b32_dpp v140, v118, v116, vcc row_shr:4 row_mask:0xf bank_mask:0xf bound_ctrl:1
	v_cndmask_b32_dpp v141, v119, v117, vcc row_shr:4 row_mask:0xf bank_mask:0xf bound_ctrl:1
	s_mov_b64 vcc, s[4:5]
	v_cndmask_b32_dpp v142, v116, v118, vcc row_shl:4 row_mask:0xf bank_mask:0xf bound_ctrl:1
	v_cndmask_b32_dpp v143, v117, v119, vcc row_shl:4 row_mask:0xf bank_mask:0xf bound_ctrl:1
	v_mfma_scale_f32_16x16x128_f8f6f4 v[216:219], v[136:139], v[144:151], v[216:219], v240, v241 op_sel_hi:[0,0,0] cbsz:4
	v_fmac_f32_e32 v192, v253, v253
	v_fmac_f32_e32 v193, v255, v255
	v_cvt_pk_bf16_f32 v250, v252, v253
	v_and_b32_e32 v144, v188, v235
	v_and_b32_e32 v145, v188, v236
	v_and_b32_e32 v146, v188, v237
	v_and_b32_e32 v147, v188, v238
	v_and_b32_e32 v148, v189, v235
	v_and_b32_e32 v149, v189, v236
	v_and_b32_e32 v150, v189, v237
	v_and_b32_e32 v151, v189, v238
	s_mov_b64 vcc, s[4:5]
	v_cndmask_b32_dpp v138, v120, v122, vcc row_shl:4 row_mask:0xf bank_mask:0xf bound_ctrl:1
	v_cndmask_b32_dpp v139, v121, v123, vcc row_shl:4 row_mask:0xf bank_mask:0xf bound_ctrl:1
	s_mov_b64 vcc, s[6:7]
	v_cndmask_b32_dpp v136, v122, v120, vcc row_shr:4 row_mask:0xf bank_mask:0xf bound_ctrl:1
	v_cndmask_b32_dpp v137, v123, v121, vcc row_shr:4 row_mask:0xf bank_mask:0xf bound_ctrl:1
	v_mfma_scale_f32_16x16x128_f8f6f4 v[216:219], v[140:143], v[204:211], v[216:219], v240, v241 op_sel_hi:[0,0,0] cbsz:4
	v_cvt_pk_bf16_f32 v251, v254, v255
	v_add_f32_e32 v192, v192, v193
	v_add_f32_e32 v222, v222, v192
	v_and_b32_e32 v204, v190, v235
	v_and_b32_e32 v205, v190, v236
	v_and_b32_e32 v206, v190, v237
	v_and_b32_e32 v207, v190, v238
	v_and_b32_e32 v208, v191, v235
	v_and_b32_e32 v209, v191, v236
	v_and_b32_e32 v210, v191, v237
	v_and_b32_e32 v211, v191, v238
	s_mov_b64 vcc, s[6:7]
	v_cndmask_b32_dpp v140, v126, v124, vcc row_shr:4 row_mask:0xf bank_mask:0xf bound_ctrl:1
	v_cndmask_b32_dpp v141, v127, v125, vcc row_shr:4 row_mask:0xf bank_mask:0xf bound_ctrl:1
	s_mov_b64 vcc, s[4:5]
	v_cndmask_b32_dpp v142, v124, v126, vcc row_shl:4 row_mask:0xf bank_mask:0xf bound_ctrl:1
	v_cndmask_b32_dpp v143, v125, v127, vcc row_shl:4 row_mask:0xf bank_mask:0xf bound_ctrl:1
	v_mfma_scale_f32_16x16x128_f8f6f4 v[216:219], v[136:139], v[144:151], v[216:219], v240, v241 op_sel_hi:[0,0,0] cbsz:4
	s_nop 0
	v_mfma_scale_f32_16x16x128_f8f6f4 v[216:219], v[140:143], v[204:211], v[216:219], v240, v241 op_sel_hi:[0,0,0] cbsz:4
	s_lshl_b32 s64, s0, 9
	s_add_u32 s64, s64, 0x2000
	s_add_u32 s76, s28, s64
	s_addc_u32 s77, s29, 0
	global_store_dwordx2 v239, v[250:251], s[76:77]
	s_lshl_b32 s64, s0, 9
	s_add_u32 s64, s64, 0x4000
	s_add_u32 s70, s28, s64
	s_addc_u32 s71, s29, 0
	global_load_dwordx2 v[228:229], v239, s[70:71]
	s_waitcnt lgkmcnt(0)
	v_lshl_or_b32 v128, v128, 7, v232
	v_lshl_or_b32 v129, v129, 7, v232
	v_lshl_or_b32 v130, v130, 7, v232
	v_lshl_or_b32 v131, v131, 7, v232
	v_lshl_or_b32 v132, v132, 7, v232
	v_lshl_or_b32 v133, v133, 7, v232
	v_lshl_or_b32 v134, v134, 7, v232
	v_lshl_or_b32 v135, v135, 7, v232
	buffer_load_dwordx4 v[96:99], v128, s[20:23], s1 offen
	buffer_load_dwordx4 v[100:103], v129, s[20:23], s1 offen
	buffer_load_dwordx4 v[104:107], v130, s[20:23], s1 offen
	buffer_load_dwordx4 v[108:111], v131, s[20:23], s1 offen
	buffer_load_dwordx4 v[112:115], v132, s[20:23], s1 offen
	buffer_load_dwordx4 v[116:119], v133, s[20:23], s1 offen
	buffer_load_dwordx4 v[120:123], v134, s[20:23], s1 offen
	buffer_load_dwordx4 v[124:127], v135, s[20:23], s1 offen
	ds_read_b32 v128, v243 offset:3072
	ds_read_b32 v129, v243 offset:3104
	ds_read_b32 v130, v243 offset:3136
	ds_read_b32 v131, v243 offset:3168
	ds_read_b32 v132, v243 offset:3200
	ds_read_b32 v133, v243 offset:3232
	ds_read_b32 v134, v243 offset:3264
	ds_read_b32 v135, v243 offset:3296
	ds_read_b64 v[176:177], v234 offset:2304
	ds_read_b64 v[178:179], v234 offset:2336
	ds_read_b64 v[180:181], v234 offset:2368
	ds_read_b64 v[182:183], v234 offset:2400
	ds_read_b64 v[184:185], v234 offset:2432
	ds_read_b64 v[186:187], v234 offset:2464
	ds_read_b64 v[188:189], v234 offset:2496
	ds_read_b64 v[190:191], v234 offset:2528
	s_waitcnt vmcnt(28)
	v_and_b32_e32 v144, v160, v235
	v_and_b32_e32 v145, v160, v236
	v_and_b32_e32 v146, v160, v237
	v_and_b32_e32 v147, v160, v238
	v_and_b32_e32 v148, v161, v235
	v_and_b32_e32 v149, v161, v236
	v_and_b32_e32 v150, v161, v237
	v_and_b32_e32 v151, v161, v238
	s_mov_b64 vcc, s[4:5]
	v_cndmask_b32_dpp v138, v0, v2, vcc row_shl:4 row_mask:0xf bank_mask:0xf bound_ctrl:1
	v_cndmask_b32_dpp v139, v1, v3, vcc row_shl:4 row_mask:0xf bank_mask:0xf bound_ctrl:1
	s_mov_b64 vcc, s[6:7]
	v_cndmask_b32_dpp v136, v2, v0, vcc row_shr:4 row_mask:0xf bank_mask:0xf bound_ctrl:1
	v_cndmask_b32_dpp v137, v3, v1, vcc row_shr:4 row_mask:0xf bank_mask:0xf bound_ctrl:1
	v_and_b32_e32 v204, v162, v235
	v_and_b32_e32 v205, v162, v236
	v_and_b32_e32 v206, v162, v237
	v_and_b32_e32 v207, v162, v238
	v_and_b32_e32 v208, v163, v235
	v_and_b32_e32 v209, v163, v236
	v_and_b32_e32 v210, v163, v237
	v_and_b32_e32 v211, v163, v238
	s_mov_b64 vcc, s[6:7]
	v_cndmask_b32_dpp v140, v6, v4, vcc row_shr:4 row_mask:0xf bank_mask:0xf bound_ctrl:1
	v_cndmask_b32_dpp v141, v7, v5, vcc row_shr:4 row_mask:0xf bank_mask:0xf bound_ctrl:1
	s_mov_b64 vcc, s[4:5]
	v_cndmask_b32_dpp v142, v4, v6, vcc row_shl:4 row_mask:0xf bank_mask:0xf bound_ctrl:1
	v_cndmask_b32_dpp v143, v5, v7, vcc row_shl:4 row_mask:0xf bank_mask:0xf bound_ctrl:1
	v_mfma_scale_f32_16x16x128_f8f6f4 v[212:215], v[136:139], v[144:151], 0, v240, v241 op_sel_hi:[0,0,0] cbsz:4
	v_and_b32_e32 v144, v164, v235
	v_and_b32_e32 v145, v164, v236
	v_and_b32_e32 v146, v164, v237
	v_and_b32_e32 v147, v164, v238
	v_and_b32_e32 v148, v165, v235
	v_and_b32_e32 v149, v165, v236
	v_and_b32_e32 v150, v165, v237
	v_and_b32_e32 v151, v165, v238
	s_mov_b64 vcc, s[4:5]
	v_cndmask_b32_dpp v138, v8, v10, vcc row_shl:4 row_mask:0xf bank_mask:0xf bound_ctrl:1
	v_cndmask_b32_dpp v139, v9, v11, vcc row_shl:4 row_mask:0xf bank_mask:0xf bound_ctrl:1
	s_mov_b64 vcc, s[6:7]
	v_cndmask_b32_dpp v136, v10, v8, vcc row_shr:4 row_mask:0xf bank_mask:0xf bound_ctrl:1
	v_cndmask_b32_dpp v137, v11, v9, vcc row_shr:4 row_mask:0xf bank_mask:0xf bound_ctrl:1
	v_mfma_scale_f32_16x16x128_f8f6f4 v[212:215], v[140:143], v[204:211], v[212:215], v240, v241 op_sel_hi:[0,0,0] cbsz:4
	v_and_b32_e32 v204, v166, v235
	v_and_b32_e32 v205, v166, v236
	v_and_b32_e32 v206, v166, v237
	v_and_b32_e32 v207, v166, v238
	v_and_b32_e32 v208, v167, v235
	v_and_b32_e32 v209, v167, v236
	v_and_b32_e32 v210, v167, v237
	v_and_b32_e32 v211, v167, v238
	s_mov_b64 vcc, s[6:7]
	v_cndmask_b32_dpp v140, v14, v12, vcc row_shr:4 row_mask:0xf bank_mask:0xf bound_ctrl:1
	v_cndmask_b32_dpp v141, v15, v13, vcc row_shr:4 row_mask:0xf bank_mask:0xf bound_ctrl:1
	s_mov_b64 vcc, s[4:5]
	v_cndmask_b32_dpp v142, v12, v14, vcc row_shl:4 row_mask:0xf bank_mask:0xf bound_ctrl:1
	v_cndmask_b32_dpp v143, v13, v15, vcc row_shl:4 row_mask:0xf bank_mask:0xf bound_ctrl:1
	v_mfma_scale_f32_16x16x128_f8f6f4 v[212:215], v[136:139], v[144:151], v[212:215], v240, v241 op_sel_hi:[0,0,0] cbsz:4
	v_and_b32_e32 v144, v168, v235
	v_and_b32_e32 v145, v168, v236
	v_and_b32_e32 v146, v168, v237
	v_and_b32_e32 v147, v168, v238
	v_and_b32_e32 v148, v169, v235
	v_and_b32_e32 v149, v169, v236
	v_and_b32_e32 v150, v169, v237
	v_and_b32_e32 v151, v169, v238
	s_mov_b64 vcc, s[4:5]
	v_cndmask_b32_dpp v138, v16, v18, vcc row_shl:4 row_mask:0xf bank_mask:0xf bound_ctrl:1
	v_cndmask_b32_dpp v139, v17, v19, vcc row_shl:4 row_mask:0xf bank_mask:0xf bound_ctrl:1
	s_mov_b64 vcc, s[6:7]
	v_cndmask_b32_dpp v136, v18, v16, vcc row_shr:4 row_mask:0xf bank_mask:0xf bound_ctrl:1
	v_cndmask_b32_dpp v137, v19, v17, vcc row_shr:4 row_mask:0xf bank_mask:0xf bound_ctrl:1
	v_mfma_scale_f32_16x16x128_f8f6f4 v[212:215], v[140:143], v[204:211], v[212:215], v240, v241 op_sel_hi:[0,0,0] cbsz:4
	v_and_b32_e32 v204, v170, v235
	v_and_b32_e32 v205, v170, v236
	v_and_b32_e32 v206, v170, v237
	v_and_b32_e32 v207, v170, v238
	v_and_b32_e32 v208, v171, v235
	v_and_b32_e32 v209, v171, v236
	v_and_b32_e32 v210, v171, v237
	v_and_b32_e32 v211, v171, v238
	s_mov_b64 vcc, s[6:7]
	v_cndmask_b32_dpp v140, v22, v20, vcc row_shr:4 row_mask:0xf bank_mask:0xf bound_ctrl:1
	v_cndmask_b32_dpp v141, v23, v21, vcc row_shr:4 row_mask:0xf bank_mask:0xf bound_ctrl:1
	s_mov_b64 vcc, s[4:5]
	v_cndmask_b32_dpp v142, v20, v22, vcc row_shl:4 row_mask:0xf bank_mask:0xf bound_ctrl:1
	v_cndmask_b32_dpp v143, v21, v23, vcc row_shl:4 row_mask:0xf bank_mask:0xf bound_ctrl:1
	v_mfma_scale_f32_16x16x128_f8f6f4 v[212:215], v[136:139], v[144:151], v[212:215], v240, v241 op_sel_hi:[0,0,0] cbsz:4
	v_and_b32_e32 v144, v172, v235
	v_and_b32_e32 v145, v172, v236
	v_and_b32_e32 v146, v172, v237
	v_and_b32_e32 v147, v172, v238
	v_and_b32_e32 v148, v173, v235
	v_and_b32_e32 v149, v173, v236
	v_and_b32_e32 v150, v173, v237
	v_and_b32_e32 v151, v173, v238
	s_mov_b64 vcc, s[4:5]
	v_cndmask_b32_dpp v138, v24, v26, vcc row_shl:4 row_mask:0xf bank_mask:0xf bound_ctrl:1
	v_cndmask_b32_dpp v139, v25, v27, vcc row_shl:4 row_mask:0xf bank_mask:0xf bound_ctrl:1
	s_mov_b64 vcc, s[6:7]
	v_cndmask_b32_dpp v136, v26, v24, vcc row_shr:4 row_mask:0xf bank_mask:0xf bound_ctrl:1
	v_cndmask_b32_dpp v137, v27, v25, vcc row_shr:4 row_mask:0xf bank_mask:0xf bound_ctrl:1
	v_mfma_scale_f32_16x16x128_f8f6f4 v[212:215], v[140:143], v[204:211], v[212:215], v240, v241 op_sel_hi:[0,0,0] cbsz:4
	v_and_b32_e32 v204, v174, v235
	v_and_b32_e32 v205, v174, v236
	v_and_b32_e32 v206, v174, v237
	v_and_b32_e32 v207, v174, v238
	v_and_b32_e32 v208, v175, v235
	v_and_b32_e32 v209, v175, v236
	v_and_b32_e32 v210, v175, v237
	v_and_b32_e32 v211, v175, v238
	s_mov_b64 vcc, s[6:7]
	v_cndmask_b32_dpp v140, v30, v28, vcc row_shr:4 row_mask:0xf bank_mask:0xf bound_ctrl:1
	v_cndmask_b32_dpp v141, v31, v29, vcc row_shr:4 row_mask:0xf bank_mask:0xf bound_ctrl:1
	s_mov_b64 vcc, s[4:5]
	v_cndmask_b32_dpp v142, v28, v30, vcc row_shl:4 row_mask:0xf bank_mask:0xf bound_ctrl:1
	v_cndmask_b32_dpp v143, v29, v31, vcc row_shl:4 row_mask:0xf bank_mask:0xf bound_ctrl:1
	v_mfma_scale_f32_16x16x128_f8f6f4 v[212:215], v[136:139], v[144:151], v[212:215], v240, v241 op_sel_hi:[0,0,0] cbsz:4
	s_nop 0
	v_mfma_scale_f32_16x16x128_f8f6f4 v[212:215], v[140:143], v[204:211], v[212:215], v240, v241 op_sel_hi:[0,0,0] cbsz:4
	s_waitcnt lgkmcnt(0)
	v_lshl_or_b32 v128, v128, 7, v232
	v_lshl_or_b32 v129, v129, 7, v232
	v_lshl_or_b32 v130, v130, 7, v232
	v_lshl_or_b32 v131, v131, 7, v232
	v_lshl_or_b32 v132, v132, 7, v232
	v_lshl_or_b32 v133, v133, 7, v232
	v_lshl_or_b32 v134, v134, 7, v232
	v_lshl_or_b32 v135, v135, 7, v232
	buffer_load_dwordx4 v[0:3], v128, s[20:23], s1 offen
	buffer_load_dwordx4 v[4:7], v129, s[20:23], s1 offen
	buffer_load_dwordx4 v[8:11], v130, s[20:23], s1 offen
	buffer_load_dwordx4 v[12:15], v131, s[20:23], s1 offen
	buffer_load_dwordx4 v[16:19], v132, s[20:23], s1 offen
	buffer_load_dwordx4 v[20:23], v133, s[20:23], s1 offen
	buffer_load_dwordx4 v[24:27], v134, s[20:23], s1 offen
	buffer_load_dwordx4 v[28:31], v135, s[20:23], s1 offen
	ds_read_b32 v128, v243 offset:3328
	ds_read_b32 v129, v243 offset:3360
	ds_read_b32 v130, v243 offset:3392
	ds_read_b32 v131, v243 offset:3424
	ds_read_b32 v132, v243 offset:3456
	ds_read_b32 v133, v243 offset:3488
	ds_read_b32 v134, v243 offset:3520
	ds_read_b32 v135, v243 offset:3552
	ds_read_b64 v[160:161], v234 offset:2560
	ds_read_b64 v[162:163], v234 offset:2592
	ds_read_b64 v[164:165], v234 offset:2624
	ds_read_b64 v[166:167], v234 offset:2656
	ds_read_b64 v[168:169], v234 offset:2688
	ds_read_b64 v[170:171], v234 offset:2720
	ds_read_b64 v[172:173], v234 offset:2752
	ds_read_b64 v[174:175], v234 offset:2784
	s_waitcnt vmcnt(26)
	v_and_b32_e32 v144, v176, v235
	v_and_b32_e32 v145, v176, v236
	v_and_b32_e32 v146, v176, v237
	v_and_b32_e32 v147, v176, v238
	v_and_b32_e32 v148, v177, v235
	v_and_b32_e32 v149, v177, v236
	v_and_b32_e32 v150, v177, v237
	v_and_b32_e32 v151, v177, v238
	s_mov_b64 vcc, s[4:5]
	v_cndmask_b32_dpp v138, v32, v34, vcc row_shl:4 row_mask:0xf bank_mask:0xf bound_ctrl:1
	v_cndmask_b32_dpp v139, v33, v35, vcc row_shl:4 row_mask:0xf bank_mask:0xf bound_ctrl:1
	s_mov_b64 vcc, s[6:7]
	v_cndmask_b32_dpp v136, v34, v32, vcc row_shr:4 row_mask:0xf bank_mask:0xf bound_ctrl:1
	v_cndmask_b32_dpp v137, v35, v33, vcc row_shr:4 row_mask:0xf bank_mask:0xf bound_ctrl:1
	v_and_b32_e32 v204, v178, v235
	v_and_b32_e32 v205, v178, v236
	v_and_b32_e32 v206, v178, v237
	v_and_b32_e32 v207, v178, v238
	v_and_b32_e32 v208, v179, v235
	v_and_b32_e32 v209, v179, v236
	v_and_b32_e32 v210, v179, v237
	v_and_b32_e32 v211, v179, v238
	s_mov_b64 vcc, s[6:7]
	v_cndmask_b32_dpp v140, v38, v36, vcc row_shr:4 row_mask:0xf bank_mask:0xf bound_ctrl:1
	v_cndmask_b32_dpp v141, v39, v37, vcc row_shr:4 row_mask:0xf bank_mask:0xf bound_ctrl:1
	s_mov_b64 vcc, s[4:5]
	v_cndmask_b32_dpp v142, v36, v38, vcc row_shl:4 row_mask:0xf bank_mask:0xf bound_ctrl:1
	v_cndmask_b32_dpp v143, v37, v39, vcc row_shl:4 row_mask:0xf bank_mask:0xf bound_ctrl:1
	v_mfma_scale_f32_16x16x128_f8f6f4 v[212:215], v[136:139], v[144:151], v[212:215], v240, v241 op_sel_hi:[0,0,0] cbsz:4
	v_permlane16_swap_b32_e32 v216, v218
	v_permlane16_swap_b32_e32 v217, v219
	v_lshlrev_b32_e32 v252, 16, v230
	v_and_b32_e32 v144, v180, v235
	v_and_b32_e32 v145, v180, v236
	v_and_b32_e32 v146, v180, v237
	v_and_b32_e32 v147, v180, v238
	v_and_b32_e32 v148, v181, v235
	v_and_b32_e32 v149, v181, v236
	v_and_b32_e32 v150, v181, v237
	v_and_b32_e32 v151, v181, v238
	s_mov_b64 vcc, s[4:5]
	v_cndmask_b32_dpp v138, v40, v42, vcc row_shl:4 row_mask:0xf bank_mask:0xf bound_ctrl:1
	v_cndmask_b32_dpp v139, v41, v43, vcc row_shl:4 row_mask:0xf bank_mask:0xf bound_ctrl:1
	s_mov_b64 vcc, s[6:7]
	v_cndmask_b32_dpp v136, v42, v40, vcc row_shr:4 row_mask:0xf bank_mask:0xf bound_ctrl:1
	v_cndmask_b32_dpp v137, v43, v41, vcc row_shr:4 row_mask:0xf bank_mask:0xf bound_ctrl:1
	v_mfma_scale_f32_16x16x128_f8f6f4 v[212:215], v[140:143], v[204:211], v[212:215], v240, v241 op_sel_hi:[0,0,0] cbsz:4
	v_and_b32_e32 v253, 0xffff0000, v230
	v_lshlrev_b32_e32 v254, 16, v231
	v_and_b32_e32 v255, 0xffff0000, v231
	v_and_b32_e32 v204, v182, v235
	v_and_b32_e32 v205, v182, v236
	v_and_b32_e32 v206, v182, v237
	v_and_b32_e32 v207, v182, v238
	v_and_b32_e32 v208, v183, v235
	v_and_b32_e32 v209, v183, v236
	v_and_b32_e32 v210, v183, v237
	v_and_b32_e32 v211, v183, v238
	s_mov_b64 vcc, s[6:7]
	v_cndmask_b32_dpp v140, v46, v44, vcc row_shr:4 row_mask:0xf bank_mask:0xf bound_ctrl:1
	v_cndmask_b32_dpp v141, v47, v45, vcc row_shr:4 row_mask:0xf bank_mask:0xf bound_ctrl:1
	s_mov_b64 vcc, s[4:5]
	v_cndmask_b32_dpp v142, v44, v46, vcc row_shl:4 row_mask:0xf bank_mask:0xf bound_ctrl:1
	v_cndmask_b32_dpp v143, v45, v47, vcc row_shl:4 row_mask:0xf bank_mask:0xf bound_ctrl:1
	v_mfma_scale_f32_16x16x128_f8f6f4 v[212:215], v[136:139], v[144:151], v[212:215], v240, v241 op_sel_hi:[0,0,0] cbsz:4
	v_add_f32_e32 v252, v216, v252
	v_add_f32_e32 v253, v218, v253
	v_add_f32_e32 v254, v217, v254
	v_and_b32_e32 v144, v184, v235
	v_and_b32_e32 v145, v184, v236
	v_and_b32_e32 v146, v184, v237
	v_and_b32_e32 v147, v184, v238
	v_and_b32_e32 v148, v185, v235
	v_and_b32_e32 v149, v185, v236
	v_and_b32_e32 v150, v185, v237
	v_and_b32_e32 v151, v185, v238
	s_mov_b64 vcc, s[4:5]
	v_cndmask_b32_dpp v138, v48, v50, vcc row_shl:4 row_mask:0xf bank_mask:0xf bound_ctrl:1
	v_cndmask_b32_dpp v139, v49, v51, vcc row_shl:4 row_mask:0xf bank_mask:0xf bound_ctrl:1
	s_mov_b64 vcc, s[6:7]
	v_cndmask_b32_dpp v136, v50, v48, vcc row_shr:4 row_mask:0xf bank_mask:0xf bound_ctrl:1
	v_cndmask_b32_dpp v137, v51, v49, vcc row_shr:4 row_mask:0xf bank_mask:0xf bound_ctrl:1
	v_mfma_scale_f32_16x16x128_f8f6f4 v[212:215], v[140:143], v[204:211], v[212:215], v240, v241 op_sel_hi:[0,0,0] cbsz:4
	v_add_f32_e32 v255, v219, v255
	v_mul_f32_e32 v192, v252, v252
	v_mul_f32_e32 v193, v254, v254
	v_and_b32_e32 v204, v186, v235
	v_and_b32_e32 v205, v186, v236
	v_and_b32_e32 v206, v186, v237
	v_and_b32_e32 v207, v186, v238
	v_and_b32_e32 v208, v187, v235
	v_and_b32_e32 v209, v187, v236
	v_and_b32_e32 v210, v187, v237
	v_and_b32_e32 v211, v187, v238
	s_mov_b64 vcc, s[6:7]
	v_cndmask_b32_dpp v140, v54, v52, vcc row_shr:4 row_mask:0xf bank_mask:0xf bound_ctrl:1
	v_cndmask_b32_dpp v141, v55, v53, vcc row_shr:4 row_mask:0xf bank_mask:0xf bound_ctrl:1
	s_mov_b64 vcc, s[4:5]
	v_cndmask_b32_dpp v142, v52, v54, vcc row_shl:4 row_mask:0xf bank_mask:0xf bound_ctrl:1
	v_cndmask_b32_dpp v143, v53, v55, vcc row_shl:4 row_mask:0xf bank_mask:0xf bound_ctrl:1
	v_mfma_scale_f32_16x16x128_f8f6f4 v[212:215], v[136:139], v[144:151], v[212:215], v240, v241 op_sel_hi:[0,0,0] cbsz:4
	v_fmac_f32_e32 v192, v253, v253
	v_fmac_f32_e32 v193, v255, v255
	v_cvt_pk_bf16_f32 v250, v252, v253
	v_and_b32_e32 v144, v188, v235
	v_and_b32_e32 v145, v188, v236
	v_and_b32_e32 v146, v188, v237
	v_and_b32_e32 v147, v188, v238
	v_and_b32_e32 v148, v189, v235
	v_and_b32_e32 v149, v189, v236
	v_and_b32_e32 v150, v189, v237
	v_and_b32_e32 v151, v189, v238
	s_mov_b64 vcc, s[4:5]
	v_cndmask_b32_dpp v138, v56, v58, vcc row_shl:4 row_mask:0xf bank_mask:0xf bound_ctrl:1
	v_cndmask_b32_dpp v139, v57, v59, vcc row_shl:4 row_mask:0xf bank_mask:0xf bound_ctrl:1
	s_mov_b64 vcc, s[6:7]
	v_cndmask_b32_dpp v136, v58, v56, vcc row_shr:4 row_mask:0xf bank_mask:0xf bound_ctrl:1
	v_cndmask_b32_dpp v137, v59, v57, vcc row_shr:4 row_mask:0xf bank_mask:0xf bound_ctrl:1
	v_mfma_scale_f32_16x16x128_f8f6f4 v[212:215], v[140:143], v[204:211], v[212:215], v240, v241 op_sel_hi:[0,0,0] cbsz:4
	v_cvt_pk_bf16_f32 v251, v254, v255
	v_add_f32_e32 v192, v192, v193
	v_add_f32_e32 v223, v223, v192
	v_and_b32_e32 v204, v190, v235
	v_and_b32_e32 v205, v190, v236
	v_and_b32_e32 v206, v190, v237
	v_and_b32_e32 v207, v190, v238
	v_and_b32_e32 v208, v191, v235
	v_and_b32_e32 v209, v191, v236
	v_and_b32_e32 v210, v191, v237
	v_and_b32_e32 v211, v191, v238
	s_mov_b64 vcc, s[6:7]
	v_cndmask_b32_dpp v140, v62, v60, vcc row_shr:4 row_mask:0xf bank_mask:0xf bound_ctrl:1
	v_cndmask_b32_dpp v141, v63, v61, vcc row_shr:4 row_mask:0xf bank_mask:0xf bound_ctrl:1
	s_mov_b64 vcc, s[4:5]
	v_cndmask_b32_dpp v142, v60, v62, vcc row_shl:4 row_mask:0xf bank_mask:0xf bound_ctrl:1
	v_cndmask_b32_dpp v143, v61, v63, vcc row_shl:4 row_mask:0xf bank_mask:0xf bound_ctrl:1
	v_mfma_scale_f32_16x16x128_f8f6f4 v[212:215], v[136:139], v[144:151], v[212:215], v240, v241 op_sel_hi:[0,0,0] cbsz:4
	s_nop 0
	v_mfma_scale_f32_16x16x128_f8f6f4 v[212:215], v[140:143], v[204:211], v[212:215], v240, v241 op_sel_hi:[0,0,0] cbsz:4
	s_lshl_b32 s64, s0, 9
	s_add_u32 s64, s64, 0x3000
	s_add_u32 s76, s28, s64
	s_addc_u32 s77, s29, 0
	global_store_dwordx2 v239, v[250:251], s[76:77]
	s_lshl_b32 s64, s0, 9
	s_add_u32 s64, s64, 0x5000
	s_add_u32 s70, s28, s64
	s_addc_u32 s71, s29, 0
	global_load_dwordx2 v[230:231], v239, s[70:71]
	s_waitcnt lgkmcnt(0)
	v_lshl_or_b32 v128, v128, 7, v232
	v_lshl_or_b32 v129, v129, 7, v232
	v_lshl_or_b32 v130, v130, 7, v232
	v_lshl_or_b32 v131, v131, 7, v232
	v_lshl_or_b32 v132, v132, 7, v232
	v_lshl_or_b32 v133, v133, 7, v232
	v_lshl_or_b32 v134, v134, 7, v232
	v_lshl_or_b32 v135, v135, 7, v232
	buffer_load_dwordx4 v[32:35], v128, s[20:23], s1 offen
	buffer_load_dwordx4 v[36:39], v129, s[20:23], s1 offen
	buffer_load_dwordx4 v[40:43], v130, s[20:23], s1 offen
	buffer_load_dwordx4 v[44:47], v131, s[20:23], s1 offen
	buffer_load_dwordx4 v[48:51], v132, s[20:23], s1 offen
	buffer_load_dwordx4 v[52:55], v133, s[20:23], s1 offen
	buffer_load_dwordx4 v[56:59], v134, s[20:23], s1 offen
	buffer_load_dwordx4 v[60:63], v135, s[20:23], s1 offen
	ds_read_b32 v128, v243 offset:3584
	ds_read_b32 v129, v243 offset:3616
	ds_read_b32 v130, v243 offset:3648
	ds_read_b32 v131, v243 offset:3680
	ds_read_b32 v132, v243 offset:3712
	ds_read_b32 v133, v243 offset:3744
	ds_read_b32 v134, v243 offset:3776
	ds_read_b32 v135, v243 offset:3808
	ds_read_b64 v[176:177], v234 offset:2816
	ds_read_b64 v[178:179], v234 offset:2848
	ds_read_b64 v[180:181], v234 offset:2880
	ds_read_b64 v[182:183], v234 offset:2912
	ds_read_b64 v[184:185], v234 offset:2944
	ds_read_b64 v[186:187], v234 offset:2976
	ds_read_b64 v[188:189], v234 offset:3008
	ds_read_b64 v[190:191], v234 offset:3040
	s_waitcnt vmcnt(28)
	v_and_b32_e32 v144, v160, v235
	v_and_b32_e32 v145, v160, v236
	v_and_b32_e32 v146, v160, v237
	v_and_b32_e32 v147, v160, v238
	v_and_b32_e32 v148, v161, v235
	v_and_b32_e32 v149, v161, v236
	v_and_b32_e32 v150, v161, v237
	v_and_b32_e32 v151, v161, v238
	s_mov_b64 vcc, s[4:5]
	v_cndmask_b32_dpp v138, v64, v66, vcc row_shl:4 row_mask:0xf bank_mask:0xf bound_ctrl:1
	v_cndmask_b32_dpp v139, v65, v67, vcc row_shl:4 row_mask:0xf bank_mask:0xf bound_ctrl:1
	s_mov_b64 vcc, s[6:7]
	v_cndmask_b32_dpp v136, v66, v64, vcc row_shr:4 row_mask:0xf bank_mask:0xf bound_ctrl:1
	v_cndmask_b32_dpp v137, v67, v65, vcc row_shr:4 row_mask:0xf bank_mask:0xf bound_ctrl:1
	v_and_b32_e32 v204, v162, v235
	v_and_b32_e32 v205, v162, v236
	v_and_b32_e32 v206, v162, v237
	v_and_b32_e32 v207, v162, v238
	v_and_b32_e32 v208, v163, v235
	v_and_b32_e32 v209, v163, v236
	v_and_b32_e32 v210, v163, v237
	v_and_b32_e32 v211, v163, v238
	s_mov_b64 vcc, s[6:7]
	v_cndmask_b32_dpp v140, v70, v68, vcc row_shr:4 row_mask:0xf bank_mask:0xf bound_ctrl:1
	v_cndmask_b32_dpp v141, v71, v69, vcc row_shr:4 row_mask:0xf bank_mask:0xf bound_ctrl:1
	s_mov_b64 vcc, s[4:5]
	v_cndmask_b32_dpp v142, v68, v70, vcc row_shl:4 row_mask:0xf bank_mask:0xf bound_ctrl:1
	v_cndmask_b32_dpp v143, v69, v71, vcc row_shl:4 row_mask:0xf bank_mask:0xf bound_ctrl:1
	v_mfma_scale_f32_16x16x128_f8f6f4 v[216:219], v[136:139], v[144:151], 0, v240, v241 op_sel_hi:[0,0,0] cbsz:4
	v_and_b32_e32 v144, v164, v235
	v_and_b32_e32 v145, v164, v236
	v_and_b32_e32 v146, v164, v237
	v_and_b32_e32 v147, v164, v238
	v_and_b32_e32 v148, v165, v235
	v_and_b32_e32 v149, v165, v236
	v_and_b32_e32 v150, v165, v237
	v_and_b32_e32 v151, v165, v238
	s_mov_b64 vcc, s[4:5]
	v_cndmask_b32_dpp v138, v72, v74, vcc row_shl:4 row_mask:0xf bank_mask:0xf bound_ctrl:1
	v_cndmask_b32_dpp v139, v73, v75, vcc row_shl:4 row_mask:0xf bank_mask:0xf bound_ctrl:1
	s_mov_b64 vcc, s[6:7]
	v_cndmask_b32_dpp v136, v74, v72, vcc row_shr:4 row_mask:0xf bank_mask:0xf bound_ctrl:1
	v_cndmask_b32_dpp v137, v75, v73, vcc row_shr:4 row_mask:0xf bank_mask:0xf bound_ctrl:1
	v_mfma_scale_f32_16x16x128_f8f6f4 v[216:219], v[140:143], v[204:211], v[216:219], v240, v241 op_sel_hi:[0,0,0] cbsz:4
	v_and_b32_e32 v204, v166, v235
	v_and_b32_e32 v205, v166, v236
	v_and_b32_e32 v206, v166, v237
	v_and_b32_e32 v207, v166, v238
	v_and_b32_e32 v208, v167, v235
	v_and_b32_e32 v209, v167, v236
	v_and_b32_e32 v210, v167, v237
	v_and_b32_e32 v211, v167, v238
	s_mov_b64 vcc, s[6:7]
	v_cndmask_b32_dpp v140, v78, v76, vcc row_shr:4 row_mask:0xf bank_mask:0xf bound_ctrl:1
	v_cndmask_b32_dpp v141, v79, v77, vcc row_shr:4 row_mask:0xf bank_mask:0xf bound_ctrl:1
	s_mov_b64 vcc, s[4:5]
	v_cndmask_b32_dpp v142, v76, v78, vcc row_shl:4 row_mask:0xf bank_mask:0xf bound_ctrl:1
	v_cndmask_b32_dpp v143, v77, v79, vcc row_shl:4 row_mask:0xf bank_mask:0xf bound_ctrl:1
	v_mfma_scale_f32_16x16x128_f8f6f4 v[216:219], v[136:139], v[144:151], v[216:219], v240, v241 op_sel_hi:[0,0,0] cbsz:4
	v_and_b32_e32 v144, v168, v235
	v_and_b32_e32 v145, v168, v236
	v_and_b32_e32 v146, v168, v237
	v_and_b32_e32 v147, v168, v238
	v_and_b32_e32 v148, v169, v235
	v_and_b32_e32 v149, v169, v236
	v_and_b32_e32 v150, v169, v237
	v_and_b32_e32 v151, v169, v238
	s_mov_b64 vcc, s[4:5]
	v_cndmask_b32_dpp v138, v80, v82, vcc row_shl:4 row_mask:0xf bank_mask:0xf bound_ctrl:1
	v_cndmask_b32_dpp v139, v81, v83, vcc row_shl:4 row_mask:0xf bank_mask:0xf bound_ctrl:1
	s_mov_b64 vcc, s[6:7]
	v_cndmask_b32_dpp v136, v82, v80, vcc row_shr:4 row_mask:0xf bank_mask:0xf bound_ctrl:1
	v_cndmask_b32_dpp v137, v83, v81, vcc row_shr:4 row_mask:0xf bank_mask:0xf bound_ctrl:1
	v_mfma_scale_f32_16x16x128_f8f6f4 v[216:219], v[140:143], v[204:211], v[216:219], v240, v241 op_sel_hi:[0,0,0] cbsz:4
	v_and_b32_e32 v204, v170, v235
	v_and_b32_e32 v205, v170, v236
	v_and_b32_e32 v206, v170, v237
	v_and_b32_e32 v207, v170, v238
	v_and_b32_e32 v208, v171, v235
	v_and_b32_e32 v209, v171, v236
	v_and_b32_e32 v210, v171, v237
	v_and_b32_e32 v211, v171, v238
	s_mov_b64 vcc, s[6:7]
	v_cndmask_b32_dpp v140, v86, v84, vcc row_shr:4 row_mask:0xf bank_mask:0xf bound_ctrl:1
	v_cndmask_b32_dpp v141, v87, v85, vcc row_shr:4 row_mask:0xf bank_mask:0xf bound_ctrl:1
	s_mov_b64 vcc, s[4:5]
	v_cndmask_b32_dpp v142, v84, v86, vcc row_shl:4 row_mask:0xf bank_mask:0xf bound_ctrl:1
	v_cndmask_b32_dpp v143, v85, v87, vcc row_shl:4 row_mask:0xf bank_mask:0xf bound_ctrl:1
	v_mfma_scale_f32_16x16x128_f8f6f4 v[216:219], v[136:139], v[144:151], v[216:219], v240, v241 op_sel_hi:[0,0,0] cbsz:4
	v_and_b32_e32 v144, v172, v235
	v_and_b32_e32 v145, v172, v236
	v_and_b32_e32 v146, v172, v237
	v_and_b32_e32 v147, v172, v238
	v_and_b32_e32 v148, v173, v235
	v_and_b32_e32 v149, v173, v236
	v_and_b32_e32 v150, v173, v237
	v_and_b32_e32 v151, v173, v238
	s_mov_b64 vcc, s[4:5]
	v_cndmask_b32_dpp v138, v88, v90, vcc row_shl:4 row_mask:0xf bank_mask:0xf bound_ctrl:1
	v_cndmask_b32_dpp v139, v89, v91, vcc row_shl:4 row_mask:0xf bank_mask:0xf bound_ctrl:1
	s_mov_b64 vcc, s[6:7]
	v_cndmask_b32_dpp v136, v90, v88, vcc row_shr:4 row_mask:0xf bank_mask:0xf bound_ctrl:1
	v_cndmask_b32_dpp v137, v91, v89, vcc row_shr:4 row_mask:0xf bank_mask:0xf bound_ctrl:1
	v_mfma_scale_f32_16x16x128_f8f6f4 v[216:219], v[140:143], v[204:211], v[216:219], v240, v241 op_sel_hi:[0,0,0] cbsz:4
	v_and_b32_e32 v204, v174, v235
	v_and_b32_e32 v205, v174, v236
	v_and_b32_e32 v206, v174, v237
	v_and_b32_e32 v207, v174, v238
	v_and_b32_e32 v208, v175, v235
	v_and_b32_e32 v209, v175, v236
	v_and_b32_e32 v210, v175, v237
	v_and_b32_e32 v211, v175, v238
	s_mov_b64 vcc, s[6:7]
	v_cndmask_b32_dpp v140, v94, v92, vcc row_shr:4 row_mask:0xf bank_mask:0xf bound_ctrl:1
	v_cndmask_b32_dpp v141, v95, v93, vcc row_shr:4 row_mask:0xf bank_mask:0xf bound_ctrl:1
	s_mov_b64 vcc, s[4:5]
	v_cndmask_b32_dpp v142, v92, v94, vcc row_shl:4 row_mask:0xf bank_mask:0xf bound_ctrl:1
	v_cndmask_b32_dpp v143, v93, v95, vcc row_shl:4 row_mask:0xf bank_mask:0xf bound_ctrl:1
	v_mfma_scale_f32_16x16x128_f8f6f4 v[216:219], v[136:139], v[144:151], v[216:219], v240, v241 op_sel_hi:[0,0,0] cbsz:4
	s_nop 0
	v_mfma_scale_f32_16x16x128_f8f6f4 v[216:219], v[140:143], v[204:211], v[216:219], v240, v241 op_sel_hi:[0,0,0] cbsz:4
	s_waitcnt lgkmcnt(0)
	v_lshl_or_b32 v128, v128, 7, v232
	v_lshl_or_b32 v129, v129, 7, v232
	v_lshl_or_b32 v130, v130, 7, v232
	v_lshl_or_b32 v131, v131, 7, v232
	v_lshl_or_b32 v132, v132, 7, v232
	v_lshl_or_b32 v133, v133, 7, v232
	v_lshl_or_b32 v134, v134, 7, v232
	v_lshl_or_b32 v135, v135, 7, v232
	buffer_load_dwordx4 v[64:67], v128, s[20:23], s1 offen
	buffer_load_dwordx4 v[68:71], v129, s[20:23], s1 offen
	buffer_load_dwordx4 v[72:75], v130, s[20:23], s1 offen
	buffer_load_dwordx4 v[76:79], v131, s[20:23], s1 offen
	buffer_load_dwordx4 v[80:83], v132, s[20:23], s1 offen
	buffer_load_dwordx4 v[84:87], v133, s[20:23], s1 offen
	buffer_load_dwordx4 v[88:91], v134, s[20:23], s1 offen
	buffer_load_dwordx4 v[92:95], v135, s[20:23], s1 offen
	ds_read_b32 v128, v243 offset:3840
	ds_read_b32 v129, v243 offset:3872
	ds_read_b32 v130, v243 offset:3904
	ds_read_b32 v131, v243 offset:3936
	ds_read_b32 v132, v243 offset:3968
	ds_read_b32 v133, v243 offset:4000
	ds_read_b32 v134, v243 offset:4032
	ds_read_b32 v135, v243 offset:4064
	ds_read_b64 v[160:161], v234 offset:3072
	ds_read_b64 v[162:163], v234 offset:3104
	ds_read_b64 v[164:165], v234 offset:3136
	ds_read_b64 v[166:167], v234 offset:3168
	ds_read_b64 v[168:169], v234 offset:3200
	ds_read_b64 v[170:171], v234 offset:3232
	ds_read_b64 v[172:173], v234 offset:3264
	ds_read_b64 v[174:175], v234 offset:3296
	s_waitcnt vmcnt(26)
	v_and_b32_e32 v144, v176, v235
	v_and_b32_e32 v145, v176, v236
	v_and_b32_e32 v146, v176, v237
	v_and_b32_e32 v147, v176, v238
	v_and_b32_e32 v148, v177, v235
	v_and_b32_e32 v149, v177, v236
	v_and_b32_e32 v150, v177, v237
	v_and_b32_e32 v151, v177, v238
	s_mov_b64 vcc, s[4:5]
	v_cndmask_b32_dpp v138, v96, v98, vcc row_shl:4 row_mask:0xf bank_mask:0xf bound_ctrl:1
	v_cndmask_b32_dpp v139, v97, v99, vcc row_shl:4 row_mask:0xf bank_mask:0xf bound_ctrl:1
	s_mov_b64 vcc, s[6:7]
	v_cndmask_b32_dpp v136, v98, v96, vcc row_shr:4 row_mask:0xf bank_mask:0xf bound_ctrl:1
	v_cndmask_b32_dpp v137, v99, v97, vcc row_shr:4 row_mask:0xf bank_mask:0xf bound_ctrl:1
	v_and_b32_e32 v204, v178, v235
	v_and_b32_e32 v205, v178, v236
	v_and_b32_e32 v206, v178, v237
	v_and_b32_e32 v207, v178, v238
	v_and_b32_e32 v208, v179, v235
	v_and_b32_e32 v209, v179, v236
	v_and_b32_e32 v210, v179, v237
	v_and_b32_e32 v211, v179, v238
	s_mov_b64 vcc, s[6:7]
	v_cndmask_b32_dpp v140, v102, v100, vcc row_shr:4 row_mask:0xf bank_mask:0xf bound_ctrl:1
	v_cndmask_b32_dpp v141, v103, v101, vcc row_shr:4 row_mask:0xf bank_mask:0xf bound_ctrl:1
	s_mov_b64 vcc, s[4:5]
	v_cndmask_b32_dpp v142, v100, v102, vcc row_shl:4 row_mask:0xf bank_mask:0xf bound_ctrl:1
	v_cndmask_b32_dpp v143, v101, v103, vcc row_shl:4 row_mask:0xf bank_mask:0xf bound_ctrl:1
	v_mfma_scale_f32_16x16x128_f8f6f4 v[216:219], v[136:139], v[144:151], v[216:219], v240, v241 op_sel_hi:[0,0,0] cbsz:4
	v_permlane16_swap_b32_e32 v212, v214
	v_permlane16_swap_b32_e32 v213, v215
	v_lshlrev_b32_e32 v252, 16, v228
	v_and_b32_e32 v144, v180, v235
	v_and_b32_e32 v145, v180, v236
	v_and_b32_e32 v146, v180, v237
	v_and_b32_e32 v147, v180, v238
	v_and_b32_e32 v148, v181, v235
	v_and_b32_e32 v149, v181, v236
	v_and_b32_e32 v150, v181, v237
	v_and_b32_e32 v151, v181, v238
	s_mov_b64 vcc, s[4:5]
	v_cndmask_b32_dpp v138, v104, v106, vcc row_shl:4 row_mask:0xf bank_mask:0xf bound_ctrl:1
	v_cndmask_b32_dpp v139, v105, v107, vcc row_shl:4 row_mask:0xf bank_mask:0xf bound_ctrl:1
	s_mov_b64 vcc, s[6:7]
	v_cndmask_b32_dpp v136, v106, v104, vcc row_shr:4 row_mask:0xf bank_mask:0xf bound_ctrl:1
	v_cndmask_b32_dpp v137, v107, v105, vcc row_shr:4 row_mask:0xf bank_mask:0xf bound_ctrl:1
	v_mfma_scale_f32_16x16x128_f8f6f4 v[216:219], v[140:143], v[204:211], v[216:219], v240, v241 op_sel_hi:[0,0,0] cbsz:4
	v_and_b32_e32 v253, 0xffff0000, v228
	v_lshlrev_b32_e32 v254, 16, v229
	v_and_b32_e32 v255, 0xffff0000, v229
	v_and_b32_e32 v204, v182, v235
	v_and_b32_e32 v205, v182, v236
	v_and_b32_e32 v206, v182, v237
	v_and_b32_e32 v207, v182, v238
	v_and_b32_e32 v208, v183, v235
	v_and_b32_e32 v209, v183, v236
	v_and_b32_e32 v210, v183, v237
	v_and_b32_e32 v211, v183, v238
	s_mov_b64 vcc, s[6:7]
	v_cndmask_b32_dpp v140, v110, v108, vcc row_shr:4 row_mask:0xf bank_mask:0xf bound_ctrl:1
	v_cndmask_b32_dpp v141, v111, v109, vcc row_shr:4 row_mask:0xf bank_mask:0xf bound_ctrl:1
	s_mov_b64 vcc, s[4:5]
	v_cndmask_b32_dpp v142, v108, v110, vcc row_shl:4 row_mask:0xf bank_mask:0xf bound_ctrl:1
	v_cndmask_b32_dpp v143, v109, v111, vcc row_shl:4 row_mask:0xf bank_mask:0xf bound_ctrl:1
	v_mfma_scale_f32_16x16x128_f8f6f4 v[216:219], v[136:139], v[144:151], v[216:219], v240, v241 op_sel_hi:[0,0,0] cbsz:4
	v_add_f32_e32 v252, v212, v252
	v_add_f32_e32 v253, v214, v253
	v_add_f32_e32 v254, v213, v254
	v_and_b32_e32 v144, v184, v235
	v_and_b32_e32 v145, v184, v236
	v_and_b32_e32 v146, v184, v237
	v_and_b32_e32 v147, v184, v238
	v_and_b32_e32 v148, v185, v235
	v_and_b32_e32 v149, v185, v236
	v_and_b32_e32 v150, v185, v237
	v_and_b32_e32 v151, v185, v238
	s_mov_b64 vcc, s[4:5]
	v_cndmask_b32_dpp v138, v112, v114, vcc row_shl:4 row_mask:0xf bank_mask:0xf bound_ctrl:1
	v_cndmask_b32_dpp v139, v113, v115, vcc row_shl:4 row_mask:0xf bank_mask:0xf bound_ctrl:1
	s_mov_b64 vcc, s[6:7]
	v_cndmask_b32_dpp v136, v114, v112, vcc row_shr:4 row_mask:0xf bank_mask:0xf bound_ctrl:1
	v_cndmask_b32_dpp v137, v115, v113, vcc row_shr:4 row_mask:0xf bank_mask:0xf bound_ctrl:1
	v_mfma_scale_f32_16x16x128_f8f6f4 v[216:219], v[140:143], v[204:211], v[216:219], v240, v241 op_sel_hi:[0,0,0] cbsz:4
	v_add_f32_e32 v255, v215, v255
	v_mul_f32_e32 v192, v252, v252
	v_mul_f32_e32 v193, v254, v254
	v_and_b32_e32 v204, v186, v235
	v_and_b32_e32 v205, v186, v236
	v_and_b32_e32 v206, v186, v237
	v_and_b32_e32 v207, v186, v238
	v_and_b32_e32 v208, v187, v235
	v_and_b32_e32 v209, v187, v236
	v_and_b32_e32 v210, v187, v237
	v_and_b32_e32 v211, v187, v238
	s_mov_b64 vcc, s[6:7]
	v_cndmask_b32_dpp v140, v118, v116, vcc row_shr:4 row_mask:0xf bank_mask:0xf bound_ctrl:1
	v_cndmask_b32_dpp v141, v119, v117, vcc row_shr:4 row_mask:0xf bank_mask:0xf bound_ctrl:1
	s_mov_b64 vcc, s[4:5]
	v_cndmask_b32_dpp v142, v116, v118, vcc row_shl:4 row_mask:0xf bank_mask:0xf bound_ctrl:1
	v_cndmask_b32_dpp v143, v117, v119, vcc row_shl:4 row_mask:0xf bank_mask:0xf bound_ctrl:1
	v_mfma_scale_f32_16x16x128_f8f6f4 v[216:219], v[136:139], v[144:151], v[216:219], v240, v241 op_sel_hi:[0,0,0] cbsz:4
	v_fmac_f32_e32 v192, v253, v253
	v_fmac_f32_e32 v193, v255, v255
	v_cvt_pk_bf16_f32 v250, v252, v253
	v_and_b32_e32 v144, v188, v235
	v_and_b32_e32 v145, v188, v236
	v_and_b32_e32 v146, v188, v237
	v_and_b32_e32 v147, v188, v238
	v_and_b32_e32 v148, v189, v235
	v_and_b32_e32 v149, v189, v236
	v_and_b32_e32 v150, v189, v237
	v_and_b32_e32 v151, v189, v238
	s_mov_b64 vcc, s[4:5]
	v_cndmask_b32_dpp v138, v120, v122, vcc row_shl:4 row_mask:0xf bank_mask:0xf bound_ctrl:1
	v_cndmask_b32_dpp v139, v121, v123, vcc row_shl:4 row_mask:0xf bank_mask:0xf bound_ctrl:1
	s_mov_b64 vcc, s[6:7]
	v_cndmask_b32_dpp v136, v122, v120, vcc row_shr:4 row_mask:0xf bank_mask:0xf bound_ctrl:1
	v_cndmask_b32_dpp v137, v123, v121, vcc row_shr:4 row_mask:0xf bank_mask:0xf bound_ctrl:1
	v_mfma_scale_f32_16x16x128_f8f6f4 v[216:219], v[140:143], v[204:211], v[216:219], v240, v241 op_sel_hi:[0,0,0] cbsz:4
	v_cvt_pk_bf16_f32 v251, v254, v255
	v_add_f32_e32 v192, v192, v193
	v_add_f32_e32 v224, v224, v192
	v_and_b32_e32 v204, v190, v235
	v_and_b32_e32 v205, v190, v236
	v_and_b32_e32 v206, v190, v237
	v_and_b32_e32 v207, v190, v238
	v_and_b32_e32 v208, v191, v235
	v_and_b32_e32 v209, v191, v236
	v_and_b32_e32 v210, v191, v237
	v_and_b32_e32 v211, v191, v238
	s_mov_b64 vcc, s[6:7]
	v_cndmask_b32_dpp v140, v126, v124, vcc row_shr:4 row_mask:0xf bank_mask:0xf bound_ctrl:1
	v_cndmask_b32_dpp v141, v127, v125, vcc row_shr:4 row_mask:0xf bank_mask:0xf bound_ctrl:1
	s_mov_b64 vcc, s[4:5]
	v_cndmask_b32_dpp v142, v124, v126, vcc row_shl:4 row_mask:0xf bank_mask:0xf bound_ctrl:1
	v_cndmask_b32_dpp v143, v125, v127, vcc row_shl:4 row_mask:0xf bank_mask:0xf bound_ctrl:1
	v_mfma_scale_f32_16x16x128_f8f6f4 v[216:219], v[136:139], v[144:151], v[216:219], v240, v241 op_sel_hi:[0,0,0] cbsz:4
	s_nop 0
	v_mfma_scale_f32_16x16x128_f8f6f4 v[216:219], v[140:143], v[204:211], v[216:219], v240, v241 op_sel_hi:[0,0,0] cbsz:4
	s_lshl_b32 s64, s0, 9
	s_add_u32 s64, s64, 0x4000
	s_add_u32 s76, s28, s64
	s_addc_u32 s77, s29, 0
	global_store_dwordx2 v239, v[250:251], s[76:77]
	s_lshl_b32 s64, s0, 9
	s_add_u32 s64, s64, 0x6000
	s_add_u32 s70, s28, s64
	s_addc_u32 s71, s29, 0
	global_load_dwordx2 v[228:229], v239, s[70:71]
	s_waitcnt lgkmcnt(0)
	v_lshl_or_b32 v128, v128, 7, v232
	v_lshl_or_b32 v129, v129, 7, v232
	v_lshl_or_b32 v130, v130, 7, v232
	v_lshl_or_b32 v131, v131, 7, v232
	v_lshl_or_b32 v132, v132, 7, v232
	v_lshl_or_b32 v133, v133, 7, v232
	v_lshl_or_b32 v134, v134, 7, v232
	v_lshl_or_b32 v135, v135, 7, v232
	buffer_load_dwordx4 v[96:99], v128, s[20:23], s1 offen
	buffer_load_dwordx4 v[100:103], v129, s[20:23], s1 offen
	buffer_load_dwordx4 v[104:107], v130, s[20:23], s1 offen
	buffer_load_dwordx4 v[108:111], v131, s[20:23], s1 offen
	buffer_load_dwordx4 v[112:115], v132, s[20:23], s1 offen
	buffer_load_dwordx4 v[116:119], v133, s[20:23], s1 offen
	buffer_load_dwordx4 v[120:123], v134, s[20:23], s1 offen
	buffer_load_dwordx4 v[124:127], v135, s[20:23], s1 offen
	ds_read_b32 v128, v243 offset:0
	ds_read_b32 v129, v243 offset:32
	ds_read_b32 v130, v243 offset:64
	ds_read_b32 v131, v243 offset:96
	ds_read_b32 v132, v243 offset:128
	ds_read_b32 v133, v243 offset:160
	ds_read_b32 v134, v243 offset:192
	ds_read_b32 v135, v243 offset:224
	ds_read_b64 v[176:177], v234 offset:3328
	ds_read_b64 v[178:179], v234 offset:3360
	ds_read_b64 v[180:181], v234 offset:3392
	ds_read_b64 v[182:183], v234 offset:3424
	ds_read_b64 v[184:185], v234 offset:3456
	ds_read_b64 v[186:187], v234 offset:3488
	ds_read_b64 v[188:189], v234 offset:3520
	ds_read_b64 v[190:191], v234 offset:3552
	s_waitcnt vmcnt(28)
	v_and_b32_e32 v144, v160, v235
	v_and_b32_e32 v145, v160, v236
	v_and_b32_e32 v146, v160, v237
	v_and_b32_e32 v147, v160, v238
	v_and_b32_e32 v148, v161, v235
	v_and_b32_e32 v149, v161, v236
	v_and_b32_e32 v150, v161, v237
	v_and_b32_e32 v151, v161, v238
	s_mov_b64 vcc, s[4:5]
	v_cndmask_b32_dpp v138, v0, v2, vcc row_shl:4 row_mask:0xf bank_mask:0xf bound_ctrl:1
	v_cndmask_b32_dpp v139, v1, v3, vcc row_shl:4 row_mask:0xf bank_mask:0xf bound_ctrl:1
	s_mov_b64 vcc, s[6:7]
	v_cndmask_b32_dpp v136, v2, v0, vcc row_shr:4 row_mask:0xf bank_mask:0xf bound_ctrl:1
	v_cndmask_b32_dpp v137, v3, v1, vcc row_shr:4 row_mask:0xf bank_mask:0xf bound_ctrl:1
	v_and_b32_e32 v204, v162, v235
	v_and_b32_e32 v205, v162, v236
	v_and_b32_e32 v206, v162, v237
	v_and_b32_e32 v207, v162, v238
	v_and_b32_e32 v208, v163, v235
	v_and_b32_e32 v209, v163, v236
	v_and_b32_e32 v210, v163, v237
	v_and_b32_e32 v211, v163, v238
	s_mov_b64 vcc, s[6:7]
	v_cndmask_b32_dpp v140, v6, v4, vcc row_shr:4 row_mask:0xf bank_mask:0xf bound_ctrl:1
	v_cndmask_b32_dpp v141, v7, v5, vcc row_shr:4 row_mask:0xf bank_mask:0xf bound_ctrl:1
	s_mov_b64 vcc, s[4:5]
	v_cndmask_b32_dpp v142, v4, v6, vcc row_shl:4 row_mask:0xf bank_mask:0xf bound_ctrl:1
	v_cndmask_b32_dpp v143, v5, v7, vcc row_shl:4 row_mask:0xf bank_mask:0xf bound_ctrl:1
	v_mfma_scale_f32_16x16x128_f8f6f4 v[212:215], v[136:139], v[144:151], 0, v240, v241 op_sel_hi:[0,0,0] cbsz:4
	v_and_b32_e32 v144, v164, v235
	v_and_b32_e32 v145, v164, v236
	v_and_b32_e32 v146, v164, v237
	v_and_b32_e32 v147, v164, v238
	v_and_b32_e32 v148, v165, v235
	v_and_b32_e32 v149, v165, v236
	v_and_b32_e32 v150, v165, v237
	v_and_b32_e32 v151, v165, v238
	s_mov_b64 vcc, s[4:5]
	v_cndmask_b32_dpp v138, v8, v10, vcc row_shl:4 row_mask:0xf bank_mask:0xf bound_ctrl:1
	v_cndmask_b32_dpp v139, v9, v11, vcc row_shl:4 row_mask:0xf bank_mask:0xf bound_ctrl:1
	s_mov_b64 vcc, s[6:7]
	v_cndmask_b32_dpp v136, v10, v8, vcc row_shr:4 row_mask:0xf bank_mask:0xf bound_ctrl:1
	v_cndmask_b32_dpp v137, v11, v9, vcc row_shr:4 row_mask:0xf bank_mask:0xf bound_ctrl:1
	v_mfma_scale_f32_16x16x128_f8f6f4 v[212:215], v[140:143], v[204:211], v[212:215], v240, v241 op_sel_hi:[0,0,0] cbsz:4
	v_and_b32_e32 v204, v166, v235
	v_and_b32_e32 v205, v166, v236
	v_and_b32_e32 v206, v166, v237
	v_and_b32_e32 v207, v166, v238
	v_and_b32_e32 v208, v167, v235
	v_and_b32_e32 v209, v167, v236
	v_and_b32_e32 v210, v167, v237
	v_and_b32_e32 v211, v167, v238
	s_mov_b64 vcc, s[6:7]
	v_cndmask_b32_dpp v140, v14, v12, vcc row_shr:4 row_mask:0xf bank_mask:0xf bound_ctrl:1
	v_cndmask_b32_dpp v141, v15, v13, vcc row_shr:4 row_mask:0xf bank_mask:0xf bound_ctrl:1
	s_mov_b64 vcc, s[4:5]
	v_cndmask_b32_dpp v142, v12, v14, vcc row_shl:4 row_mask:0xf bank_mask:0xf bound_ctrl:1
	v_cndmask_b32_dpp v143, v13, v15, vcc row_shl:4 row_mask:0xf bank_mask:0xf bound_ctrl:1
	v_mfma_scale_f32_16x16x128_f8f6f4 v[212:215], v[136:139], v[144:151], v[212:215], v240, v241 op_sel_hi:[0,0,0] cbsz:4
	v_and_b32_e32 v144, v168, v235
	v_and_b32_e32 v145, v168, v236
	v_and_b32_e32 v146, v168, v237
	v_and_b32_e32 v147, v168, v238
	v_and_b32_e32 v148, v169, v235
	v_and_b32_e32 v149, v169, v236
	v_and_b32_e32 v150, v169, v237
	v_and_b32_e32 v151, v169, v238
	s_mov_b64 vcc, s[4:5]
	v_cndmask_b32_dpp v138, v16, v18, vcc row_shl:4 row_mask:0xf bank_mask:0xf bound_ctrl:1
	v_cndmask_b32_dpp v139, v17, v19, vcc row_shl:4 row_mask:0xf bank_mask:0xf bound_ctrl:1
	s_mov_b64 vcc, s[6:7]
	v_cndmask_b32_dpp v136, v18, v16, vcc row_shr:4 row_mask:0xf bank_mask:0xf bound_ctrl:1
	v_cndmask_b32_dpp v137, v19, v17, vcc row_shr:4 row_mask:0xf bank_mask:0xf bound_ctrl:1
	v_mfma_scale_f32_16x16x128_f8f6f4 v[212:215], v[140:143], v[204:211], v[212:215], v240, v241 op_sel_hi:[0,0,0] cbsz:4
	v_and_b32_e32 v204, v170, v235
	v_and_b32_e32 v205, v170, v236
	v_and_b32_e32 v206, v170, v237
	v_and_b32_e32 v207, v170, v238
	v_and_b32_e32 v208, v171, v235
	v_and_b32_e32 v209, v171, v236
	v_and_b32_e32 v210, v171, v237
	v_and_b32_e32 v211, v171, v238
	s_mov_b64 vcc, s[6:7]
	v_cndmask_b32_dpp v140, v22, v20, vcc row_shr:4 row_mask:0xf bank_mask:0xf bound_ctrl:1
	v_cndmask_b32_dpp v141, v23, v21, vcc row_shr:4 row_mask:0xf bank_mask:0xf bound_ctrl:1
	s_mov_b64 vcc, s[4:5]
	v_cndmask_b32_dpp v142, v20, v22, vcc row_shl:4 row_mask:0xf bank_mask:0xf bound_ctrl:1
	v_cndmask_b32_dpp v143, v21, v23, vcc row_shl:4 row_mask:0xf bank_mask:0xf bound_ctrl:1
	v_mfma_scale_f32_16x16x128_f8f6f4 v[212:215], v[136:139], v[144:151], v[212:215], v240, v241 op_sel_hi:[0,0,0] cbsz:4
	v_and_b32_e32 v144, v172, v235
	v_and_b32_e32 v145, v172, v236
	v_and_b32_e32 v146, v172, v237
	v_and_b32_e32 v147, v172, v238
	v_and_b32_e32 v148, v173, v235
	v_and_b32_e32 v149, v173, v236
	v_and_b32_e32 v150, v173, v237
	v_and_b32_e32 v151, v173, v238
	s_mov_b64 vcc, s[4:5]
	v_cndmask_b32_dpp v138, v24, v26, vcc row_shl:4 row_mask:0xf bank_mask:0xf bound_ctrl:1
	v_cndmask_b32_dpp v139, v25, v27, vcc row_shl:4 row_mask:0xf bank_mask:0xf bound_ctrl:1
	s_mov_b64 vcc, s[6:7]
	v_cndmask_b32_dpp v136, v26, v24, vcc row_shr:4 row_mask:0xf bank_mask:0xf bound_ctrl:1
	v_cndmask_b32_dpp v137, v27, v25, vcc row_shr:4 row_mask:0xf bank_mask:0xf bound_ctrl:1
	v_mfma_scale_f32_16x16x128_f8f6f4 v[212:215], v[140:143], v[204:211], v[212:215], v240, v241 op_sel_hi:[0,0,0] cbsz:4
	v_and_b32_e32 v204, v174, v235
	v_and_b32_e32 v205, v174, v236
	v_and_b32_e32 v206, v174, v237
	v_and_b32_e32 v207, v174, v238
	v_and_b32_e32 v208, v175, v235
	v_and_b32_e32 v209, v175, v236
	v_and_b32_e32 v210, v175, v237
	v_and_b32_e32 v211, v175, v238
	s_mov_b64 vcc, s[6:7]
	v_cndmask_b32_dpp v140, v30, v28, vcc row_shr:4 row_mask:0xf bank_mask:0xf bound_ctrl:1
	v_cndmask_b32_dpp v141, v31, v29, vcc row_shr:4 row_mask:0xf bank_mask:0xf bound_ctrl:1
	s_mov_b64 vcc, s[4:5]
	v_cndmask_b32_dpp v142, v28, v30, vcc row_shl:4 row_mask:0xf bank_mask:0xf bound_ctrl:1
	v_cndmask_b32_dpp v143, v29, v31, vcc row_shl:4 row_mask:0xf bank_mask:0xf bound_ctrl:1
	v_mfma_scale_f32_16x16x128_f8f6f4 v[212:215], v[136:139], v[144:151], v[212:215], v240, v241 op_sel_hi:[0,0,0] cbsz:4
	s_nop 0
	v_mfma_scale_f32_16x16x128_f8f6f4 v[212:215], v[140:143], v[204:211], v[212:215], v240, v241 op_sel_hi:[0,0,0] cbsz:4
	s_waitcnt lgkmcnt(0)
	v_lshl_or_b32 v128, v128, 7, v232
	v_lshl_or_b32 v129, v129, 7, v232
	v_lshl_or_b32 v130, v130, 7, v232
	v_lshl_or_b32 v131, v131, 7, v232
	v_lshl_or_b32 v132, v132, 7, v232
	v_lshl_or_b32 v133, v133, 7, v232
	v_lshl_or_b32 v134, v134, 7, v232
	v_lshl_or_b32 v135, v135, 7, v232
	buffer_load_dwordx4 v[0:3], v128, s[20:23], s60 offen
	buffer_load_dwordx4 v[4:7], v129, s[20:23], s60 offen
	buffer_load_dwordx4 v[8:11], v130, s[20:23], s60 offen
	buffer_load_dwordx4 v[12:15], v131, s[20:23], s60 offen
	buffer_load_dwordx4 v[16:19], v132, s[20:23], s60 offen
	buffer_load_dwordx4 v[20:23], v133, s[20:23], s60 offen
	buffer_load_dwordx4 v[24:27], v134, s[20:23], s60 offen
	buffer_load_dwordx4 v[28:31], v135, s[20:23], s60 offen
	ds_read_b32 v128, v243 offset:256
	ds_read_b32 v129, v243 offset:288
	ds_read_b32 v130, v243 offset:320
	ds_read_b32 v131, v243 offset:352
	ds_read_b32 v132, v243 offset:384
	ds_read_b32 v133, v243 offset:416
	ds_read_b32 v134, v243 offset:448
	ds_read_b32 v135, v243 offset:480
	ds_read_b64 v[160:161], v234 offset:3584
	ds_read_b64 v[162:163], v234 offset:3616
	ds_read_b64 v[164:165], v234 offset:3648
	ds_read_b64 v[166:167], v234 offset:3680
	ds_read_b64 v[168:169], v234 offset:3712
	ds_read_b64 v[170:171], v234 offset:3744
	ds_read_b64 v[172:173], v234 offset:3776
	ds_read_b64 v[174:175], v234 offset:3808
	s_waitcnt vmcnt(26)
	v_and_b32_e32 v144, v176, v235
	v_and_b32_e32 v145, v176, v236
	v_and_b32_e32 v146, v176, v237
	v_and_b32_e32 v147, v176, v238
	v_and_b32_e32 v148, v177, v235
	v_and_b32_e32 v149, v177, v236
	v_and_b32_e32 v150, v177, v237
	v_and_b32_e32 v151, v177, v238
	s_mov_b64 vcc, s[4:5]
	v_cndmask_b32_dpp v138, v32, v34, vcc row_shl:4 row_mask:0xf bank_mask:0xf bound_ctrl:1
	v_cndmask_b32_dpp v139, v33, v35, vcc row_shl:4 row_mask:0xf bank_mask:0xf bound_ctrl:1
	s_mov_b64 vcc, s[6:7]
	v_cndmask_b32_dpp v136, v34, v32, vcc row_shr:4 row_mask:0xf bank_mask:0xf bound_ctrl:1
	v_cndmask_b32_dpp v137, v35, v33, vcc row_shr:4 row_mask:0xf bank_mask:0xf bound_ctrl:1
	v_and_b32_e32 v204, v178, v235
	v_and_b32_e32 v205, v178, v236
	v_and_b32_e32 v206, v178, v237
	v_and_b32_e32 v207, v178, v238
	v_and_b32_e32 v208, v179, v235
	v_and_b32_e32 v209, v179, v236
	v_and_b32_e32 v210, v179, v237
	v_and_b32_e32 v211, v179, v238
	s_mov_b64 vcc, s[6:7]
	v_cndmask_b32_dpp v140, v38, v36, vcc row_shr:4 row_mask:0xf bank_mask:0xf bound_ctrl:1
	v_cndmask_b32_dpp v141, v39, v37, vcc row_shr:4 row_mask:0xf bank_mask:0xf bound_ctrl:1
	s_mov_b64 vcc, s[4:5]
	v_cndmask_b32_dpp v142, v36, v38, vcc row_shl:4 row_mask:0xf bank_mask:0xf bound_ctrl:1
	v_cndmask_b32_dpp v143, v37, v39, vcc row_shl:4 row_mask:0xf bank_mask:0xf bound_ctrl:1
	v_mfma_scale_f32_16x16x128_f8f6f4 v[212:215], v[136:139], v[144:151], v[212:215], v240, v241 op_sel_hi:[0,0,0] cbsz:4
	v_permlane16_swap_b32_e32 v216, v218
	v_permlane16_swap_b32_e32 v217, v219
	v_lshlrev_b32_e32 v252, 16, v230
	v_and_b32_e32 v144, v180, v235
	v_and_b32_e32 v145, v180, v236
	v_and_b32_e32 v146, v180, v237
	v_and_b32_e32 v147, v180, v238
	v_and_b32_e32 v148, v181, v235
	v_and_b32_e32 v149, v181, v236
	v_and_b32_e32 v150, v181, v237
	v_and_b32_e32 v151, v181, v238
	s_mov_b64 vcc, s[4:5]
	v_cndmask_b32_dpp v138, v40, v42, vcc row_shl:4 row_mask:0xf bank_mask:0xf bound_ctrl:1
	v_cndmask_b32_dpp v139, v41, v43, vcc row_shl:4 row_mask:0xf bank_mask:0xf bound_ctrl:1
	s_mov_b64 vcc, s[6:7]
	v_cndmask_b32_dpp v136, v42, v40, vcc row_shr:4 row_mask:0xf bank_mask:0xf bound_ctrl:1
	v_cndmask_b32_dpp v137, v43, v41, vcc row_shr:4 row_mask:0xf bank_mask:0xf bound_ctrl:1
	v_mfma_scale_f32_16x16x128_f8f6f4 v[212:215], v[140:143], v[204:211], v[212:215], v240, v241 op_sel_hi:[0,0,0] cbsz:4
	v_and_b32_e32 v253, 0xffff0000, v230
	v_lshlrev_b32_e32 v254, 16, v231
	v_and_b32_e32 v255, 0xffff0000, v231
	v_and_b32_e32 v204, v182, v235
	v_and_b32_e32 v205, v182, v236
	v_and_b32_e32 v206, v182, v237
	v_and_b32_e32 v207, v182, v238
	v_and_b32_e32 v208, v183, v235
	v_and_b32_e32 v209, v183, v236
	v_and_b32_e32 v210, v183, v237
	v_and_b32_e32 v211, v183, v238
	s_mov_b64 vcc, s[6:7]
	v_cndmask_b32_dpp v140, v46, v44, vcc row_shr:4 row_mask:0xf bank_mask:0xf bound_ctrl:1
	v_cndmask_b32_dpp v141, v47, v45, vcc row_shr:4 row_mask:0xf bank_mask:0xf bound_ctrl:1
	s_mov_b64 vcc, s[4:5]
	v_cndmask_b32_dpp v142, v44, v46, vcc row_shl:4 row_mask:0xf bank_mask:0xf bound_ctrl:1
	v_cndmask_b32_dpp v143, v45, v47, vcc row_shl:4 row_mask:0xf bank_mask:0xf bound_ctrl:1
	v_mfma_scale_f32_16x16x128_f8f6f4 v[212:215], v[136:139], v[144:151], v[212:215], v240, v241 op_sel_hi:[0,0,0] cbsz:4
	v_add_f32_e32 v252, v216, v252
	v_add_f32_e32 v253, v218, v253
	v_add_f32_e32 v254, v217, v254
	v_and_b32_e32 v144, v184, v235
	v_and_b32_e32 v145, v184, v236
	v_and_b32_e32 v146, v184, v237
	v_and_b32_e32 v147, v184, v238
	v_and_b32_e32 v148, v185, v235
	v_and_b32_e32 v149, v185, v236
	v_and_b32_e32 v150, v185, v237
	v_and_b32_e32 v151, v185, v238
	s_mov_b64 vcc, s[4:5]
	v_cndmask_b32_dpp v138, v48, v50, vcc row_shl:4 row_mask:0xf bank_mask:0xf bound_ctrl:1
	v_cndmask_b32_dpp v139, v49, v51, vcc row_shl:4 row_mask:0xf bank_mask:0xf bound_ctrl:1
	s_mov_b64 vcc, s[6:7]
	v_cndmask_b32_dpp v136, v50, v48, vcc row_shr:4 row_mask:0xf bank_mask:0xf bound_ctrl:1
	v_cndmask_b32_dpp v137, v51, v49, vcc row_shr:4 row_mask:0xf bank_mask:0xf bound_ctrl:1
	v_mfma_scale_f32_16x16x128_f8f6f4 v[212:215], v[140:143], v[204:211], v[212:215], v240, v241 op_sel_hi:[0,0,0] cbsz:4
	v_add_f32_e32 v255, v219, v255
	v_mul_f32_e32 v192, v252, v252
	v_mul_f32_e32 v193, v254, v254
	v_and_b32_e32 v204, v186, v235
	v_and_b32_e32 v205, v186, v236
	v_and_b32_e32 v206, v186, v237
	v_and_b32_e32 v207, v186, v238
	v_and_b32_e32 v208, v187, v235
	v_and_b32_e32 v209, v187, v236
	v_and_b32_e32 v210, v187, v237
	v_and_b32_e32 v211, v187, v238
	s_mov_b64 vcc, s[6:7]
	v_cndmask_b32_dpp v140, v54, v52, vcc row_shr:4 row_mask:0xf bank_mask:0xf bound_ctrl:1
	v_cndmask_b32_dpp v141, v55, v53, vcc row_shr:4 row_mask:0xf bank_mask:0xf bound_ctrl:1
	s_mov_b64 vcc, s[4:5]
	v_cndmask_b32_dpp v142, v52, v54, vcc row_shl:4 row_mask:0xf bank_mask:0xf bound_ctrl:1
	v_cndmask_b32_dpp v143, v53, v55, vcc row_shl:4 row_mask:0xf bank_mask:0xf bound_ctrl:1
	v_mfma_scale_f32_16x16x128_f8f6f4 v[212:215], v[136:139], v[144:151], v[212:215], v240, v241 op_sel_hi:[0,0,0] cbsz:4
	v_fmac_f32_e32 v192, v253, v253
	v_fmac_f32_e32 v193, v255, v255
	v_cvt_pk_bf16_f32 v250, v252, v253
	v_and_b32_e32 v144, v188, v235
	v_and_b32_e32 v145, v188, v236
	v_and_b32_e32 v146, v188, v237
	v_and_b32_e32 v147, v188, v238
	v_and_b32_e32 v148, v189, v235
	v_and_b32_e32 v149, v189, v236
	v_and_b32_e32 v150, v189, v237
	v_and_b32_e32 v151, v189, v238
	s_mov_b64 vcc, s[4:5]
	v_cndmask_b32_dpp v138, v56, v58, vcc row_shl:4 row_mask:0xf bank_mask:0xf bound_ctrl:1
	v_cndmask_b32_dpp v139, v57, v59, vcc row_shl:4 row_mask:0xf bank_mask:0xf bound_ctrl:1
	s_mov_b64 vcc, s[6:7]
	v_cndmask_b32_dpp v136, v58, v56, vcc row_shr:4 row_mask:0xf bank_mask:0xf bound_ctrl:1
	v_cndmask_b32_dpp v137, v59, v57, vcc row_shr:4 row_mask:0xf bank_mask:0xf bound_ctrl:1
	v_mfma_scale_f32_16x16x128_f8f6f4 v[212:215], v[140:143], v[204:211], v[212:215], v240, v241 op_sel_hi:[0,0,0] cbsz:4
	v_cvt_pk_bf16_f32 v251, v254, v255
	v_add_f32_e32 v192, v192, v193
	v_add_f32_e32 v225, v225, v192
	v_and_b32_e32 v204, v190, v235
	v_and_b32_e32 v205, v190, v236
	v_and_b32_e32 v206, v190, v237
	v_and_b32_e32 v207, v190, v238
	v_and_b32_e32 v208, v191, v235
	v_and_b32_e32 v209, v191, v236
	v_and_b32_e32 v210, v191, v237
	v_and_b32_e32 v211, v191, v238
	s_mov_b64 vcc, s[6:7]
	v_cndmask_b32_dpp v140, v62, v60, vcc row_shr:4 row_mask:0xf bank_mask:0xf bound_ctrl:1
	v_cndmask_b32_dpp v141, v63, v61, vcc row_shr:4 row_mask:0xf bank_mask:0xf bound_ctrl:1
	s_mov_b64 vcc, s[4:5]
	v_cndmask_b32_dpp v142, v60, v62, vcc row_shl:4 row_mask:0xf bank_mask:0xf bound_ctrl:1
	v_cndmask_b32_dpp v143, v61, v63, vcc row_shl:4 row_mask:0xf bank_mask:0xf bound_ctrl:1
	v_mfma_scale_f32_16x16x128_f8f6f4 v[212:215], v[136:139], v[144:151], v[212:215], v240, v241 op_sel_hi:[0,0,0] cbsz:4
	s_nop 0
	v_mfma_scale_f32_16x16x128_f8f6f4 v[212:215], v[140:143], v[204:211], v[212:215], v240, v241 op_sel_hi:[0,0,0] cbsz:4
	s_lshl_b32 s64, s0, 9
	s_add_u32 s64, s64, 0x5000
	s_add_u32 s76, s28, s64
	s_addc_u32 s77, s29, 0
	global_store_dwordx2 v239, v[250:251], s[76:77]
	s_lshl_b32 s64, s0, 9
	s_add_u32 s64, s64, 0x7000
	s_add_u32 s70, s28, s64
	s_addc_u32 s71, s29, 0
	global_load_dwordx2 v[230:231], v239, s[70:71]
	s_waitcnt lgkmcnt(0)
	v_lshl_or_b32 v128, v128, 7, v232
	v_lshl_or_b32 v129, v129, 7, v232
	v_lshl_or_b32 v130, v130, 7, v232
	v_lshl_or_b32 v131, v131, 7, v232
	v_lshl_or_b32 v132, v132, 7, v232
	v_lshl_or_b32 v133, v133, 7, v232
	v_lshl_or_b32 v134, v134, 7, v232
	v_lshl_or_b32 v135, v135, 7, v232
	buffer_load_dwordx4 v[32:35], v128, s[20:23], s60 offen
	buffer_load_dwordx4 v[36:39], v129, s[20:23], s60 offen
	buffer_load_dwordx4 v[40:43], v130, s[20:23], s60 offen
	buffer_load_dwordx4 v[44:47], v131, s[20:23], s60 offen
	buffer_load_dwordx4 v[48:51], v132, s[20:23], s60 offen
	buffer_load_dwordx4 v[52:55], v133, s[20:23], s60 offen
	buffer_load_dwordx4 v[56:59], v134, s[20:23], s60 offen
	buffer_load_dwordx4 v[60:63], v135, s[20:23], s60 offen
	ds_read_b32 v128, v243 offset:512
	ds_read_b32 v129, v243 offset:544
	ds_read_b32 v130, v243 offset:576
	ds_read_b32 v131, v243 offset:608
	ds_read_b32 v132, v243 offset:640
	ds_read_b32 v133, v243 offset:672
	ds_read_b32 v134, v243 offset:704
	ds_read_b32 v135, v243 offset:736
	ds_read_b64 v[176:177], v234 offset:3840
	ds_read_b64 v[178:179], v234 offset:3872
	ds_read_b64 v[180:181], v234 offset:3904
	ds_read_b64 v[182:183], v234 offset:3936
	ds_read_b64 v[184:185], v234 offset:3968
	ds_read_b64 v[186:187], v234 offset:4000
	ds_read_b64 v[188:189], v234 offset:4032
	ds_read_b64 v[190:191], v234 offset:4064
	s_waitcnt vmcnt(28)
	v_and_b32_e32 v144, v160, v235
	v_and_b32_e32 v145, v160, v236
	v_and_b32_e32 v146, v160, v237
	v_and_b32_e32 v147, v160, v238
	v_and_b32_e32 v148, v161, v235
	v_and_b32_e32 v149, v161, v236
	v_and_b32_e32 v150, v161, v237
	v_and_b32_e32 v151, v161, v238
	s_mov_b64 vcc, s[4:5]
	v_cndmask_b32_dpp v138, v64, v66, vcc row_shl:4 row_mask:0xf bank_mask:0xf bound_ctrl:1
	v_cndmask_b32_dpp v139, v65, v67, vcc row_shl:4 row_mask:0xf bank_mask:0xf bound_ctrl:1
	s_mov_b64 vcc, s[6:7]
	v_cndmask_b32_dpp v136, v66, v64, vcc row_shr:4 row_mask:0xf bank_mask:0xf bound_ctrl:1
	v_cndmask_b32_dpp v137, v67, v65, vcc row_shr:4 row_mask:0xf bank_mask:0xf bound_ctrl:1
	v_and_b32_e32 v204, v162, v235
	v_and_b32_e32 v205, v162, v236
	v_and_b32_e32 v206, v162, v237
	v_and_b32_e32 v207, v162, v238
	v_and_b32_e32 v208, v163, v235
	v_and_b32_e32 v209, v163, v236
	v_and_b32_e32 v210, v163, v237
	v_and_b32_e32 v211, v163, v238
	s_mov_b64 vcc, s[6:7]
	v_cndmask_b32_dpp v140, v70, v68, vcc row_shr:4 row_mask:0xf bank_mask:0xf bound_ctrl:1
	v_cndmask_b32_dpp v141, v71, v69, vcc row_shr:4 row_mask:0xf bank_mask:0xf bound_ctrl:1
	s_mov_b64 vcc, s[4:5]
	v_cndmask_b32_dpp v142, v68, v70, vcc row_shl:4 row_mask:0xf bank_mask:0xf bound_ctrl:1
	v_cndmask_b32_dpp v143, v69, v71, vcc row_shl:4 row_mask:0xf bank_mask:0xf bound_ctrl:1
	v_mfma_scale_f32_16x16x128_f8f6f4 v[216:219], v[136:139], v[144:151], 0, v240, v241 op_sel_hi:[0,0,0] cbsz:4
	v_and_b32_e32 v144, v164, v235
	v_and_b32_e32 v145, v164, v236
	v_and_b32_e32 v146, v164, v237
	v_and_b32_e32 v147, v164, v238
	v_and_b32_e32 v148, v165, v235
	v_and_b32_e32 v149, v165, v236
	v_and_b32_e32 v150, v165, v237
	v_and_b32_e32 v151, v165, v238
	s_mov_b64 vcc, s[4:5]
	v_cndmask_b32_dpp v138, v72, v74, vcc row_shl:4 row_mask:0xf bank_mask:0xf bound_ctrl:1
	v_cndmask_b32_dpp v139, v73, v75, vcc row_shl:4 row_mask:0xf bank_mask:0xf bound_ctrl:1
	s_mov_b64 vcc, s[6:7]
	v_cndmask_b32_dpp v136, v74, v72, vcc row_shr:4 row_mask:0xf bank_mask:0xf bound_ctrl:1
	v_cndmask_b32_dpp v137, v75, v73, vcc row_shr:4 row_mask:0xf bank_mask:0xf bound_ctrl:1
	v_mfma_scale_f32_16x16x128_f8f6f4 v[216:219], v[140:143], v[204:211], v[216:219], v240, v241 op_sel_hi:[0,0,0] cbsz:4
	v_and_b32_e32 v204, v166, v235
	v_and_b32_e32 v205, v166, v236
	v_and_b32_e32 v206, v166, v237
	v_and_b32_e32 v207, v166, v238
	v_and_b32_e32 v208, v167, v235
	v_and_b32_e32 v209, v167, v236
	v_and_b32_e32 v210, v167, v237
	v_and_b32_e32 v211, v167, v238
	s_mov_b64 vcc, s[6:7]
	v_cndmask_b32_dpp v140, v78, v76, vcc row_shr:4 row_mask:0xf bank_mask:0xf bound_ctrl:1
	v_cndmask_b32_dpp v141, v79, v77, vcc row_shr:4 row_mask:0xf bank_mask:0xf bound_ctrl:1
	s_mov_b64 vcc, s[4:5]
	v_cndmask_b32_dpp v142, v76, v78, vcc row_shl:4 row_mask:0xf bank_mask:0xf bound_ctrl:1
	v_cndmask_b32_dpp v143, v77, v79, vcc row_shl:4 row_mask:0xf bank_mask:0xf bound_ctrl:1
	v_mfma_scale_f32_16x16x128_f8f6f4 v[216:219], v[136:139], v[144:151], v[216:219], v240, v241 op_sel_hi:[0,0,0] cbsz:4
	v_and_b32_e32 v144, v168, v235
	v_and_b32_e32 v145, v168, v236
	v_and_b32_e32 v146, v168, v237
	v_and_b32_e32 v147, v168, v238
	v_and_b32_e32 v148, v169, v235
	v_and_b32_e32 v149, v169, v236
	v_and_b32_e32 v150, v169, v237
	v_and_b32_e32 v151, v169, v238
	s_mov_b64 vcc, s[4:5]
	v_cndmask_b32_dpp v138, v80, v82, vcc row_shl:4 row_mask:0xf bank_mask:0xf bound_ctrl:1
	v_cndmask_b32_dpp v139, v81, v83, vcc row_shl:4 row_mask:0xf bank_mask:0xf bound_ctrl:1
	s_mov_b64 vcc, s[6:7]
	v_cndmask_b32_dpp v136, v82, v80, vcc row_shr:4 row_mask:0xf bank_mask:0xf bound_ctrl:1
	v_cndmask_b32_dpp v137, v83, v81, vcc row_shr:4 row_mask:0xf bank_mask:0xf bound_ctrl:1
	v_mfma_scale_f32_16x16x128_f8f6f4 v[216:219], v[140:143], v[204:211], v[216:219], v240, v241 op_sel_hi:[0,0,0] cbsz:4
	v_and_b32_e32 v204, v170, v235
	v_and_b32_e32 v205, v170, v236
	v_and_b32_e32 v206, v170, v237
	v_and_b32_e32 v207, v170, v238
	v_and_b32_e32 v208, v171, v235
	v_and_b32_e32 v209, v171, v236
	v_and_b32_e32 v210, v171, v237
	v_and_b32_e32 v211, v171, v238
	s_mov_b64 vcc, s[6:7]
	v_cndmask_b32_dpp v140, v86, v84, vcc row_shr:4 row_mask:0xf bank_mask:0xf bound_ctrl:1
	v_cndmask_b32_dpp v141, v87, v85, vcc row_shr:4 row_mask:0xf bank_mask:0xf bound_ctrl:1
	s_mov_b64 vcc, s[4:5]
	v_cndmask_b32_dpp v142, v84, v86, vcc row_shl:4 row_mask:0xf bank_mask:0xf bound_ctrl:1
	v_cndmask_b32_dpp v143, v85, v87, vcc row_shl:4 row_mask:0xf bank_mask:0xf bound_ctrl:1
	v_mfma_scale_f32_16x16x128_f8f6f4 v[216:219], v[136:139], v[144:151], v[216:219], v240, v241 op_sel_hi:[0,0,0] cbsz:4
	v_and_b32_e32 v144, v172, v235
	v_and_b32_e32 v145, v172, v236
	v_and_b32_e32 v146, v172, v237
	v_and_b32_e32 v147, v172, v238
	v_and_b32_e32 v148, v173, v235
	v_and_b32_e32 v149, v173, v236
	v_and_b32_e32 v150, v173, v237
	v_and_b32_e32 v151, v173, v238
	s_mov_b64 vcc, s[4:5]
	v_cndmask_b32_dpp v138, v88, v90, vcc row_shl:4 row_mask:0xf bank_mask:0xf bound_ctrl:1
	v_cndmask_b32_dpp v139, v89, v91, vcc row_shl:4 row_mask:0xf bank_mask:0xf bound_ctrl:1
	s_mov_b64 vcc, s[6:7]
	v_cndmask_b32_dpp v136, v90, v88, vcc row_shr:4 row_mask:0xf bank_mask:0xf bound_ctrl:1
	v_cndmask_b32_dpp v137, v91, v89, vcc row_shr:4 row_mask:0xf bank_mask:0xf bound_ctrl:1
	v_mfma_scale_f32_16x16x128_f8f6f4 v[216:219], v[140:143], v[204:211], v[216:219], v240, v241 op_sel_hi:[0,0,0] cbsz:4
	v_and_b32_e32 v204, v174, v235
	v_and_b32_e32 v205, v174, v236
	v_and_b32_e32 v206, v174, v237
	v_and_b32_e32 v207, v174, v238
	v_and_b32_e32 v208, v175, v235
	v_and_b32_e32 v209, v175, v236
	v_and_b32_e32 v210, v175, v237
	v_and_b32_e32 v211, v175, v238
	s_mov_b64 vcc, s[6:7]
	v_cndmask_b32_dpp v140, v94, v92, vcc row_shr:4 row_mask:0xf bank_mask:0xf bound_ctrl:1
	v_cndmask_b32_dpp v141, v95, v93, vcc row_shr:4 row_mask:0xf bank_mask:0xf bound_ctrl:1
	s_mov_b64 vcc, s[4:5]
	v_cndmask_b32_dpp v142, v92, v94, vcc row_shl:4 row_mask:0xf bank_mask:0xf bound_ctrl:1
	v_cndmask_b32_dpp v143, v93, v95, vcc row_shl:4 row_mask:0xf bank_mask:0xf bound_ctrl:1
	v_mfma_scale_f32_16x16x128_f8f6f4 v[216:219], v[136:139], v[144:151], v[216:219], v240, v241 op_sel_hi:[0,0,0] cbsz:4
	s_nop 0
	v_mfma_scale_f32_16x16x128_f8f6f4 v[216:219], v[140:143], v[204:211], v[216:219], v240, v241 op_sel_hi:[0,0,0] cbsz:4
	s_waitcnt lgkmcnt(0)
	v_lshl_or_b32 v128, v128, 7, v232
	v_lshl_or_b32 v129, v129, 7, v232
	v_lshl_or_b32 v130, v130, 7, v232
	v_lshl_or_b32 v131, v131, 7, v232
	v_lshl_or_b32 v132, v132, 7, v232
	v_lshl_or_b32 v133, v133, 7, v232
	v_lshl_or_b32 v134, v134, 7, v232
	v_lshl_or_b32 v135, v135, 7, v232
	buffer_load_dwordx4 v[64:67], v128, s[20:23], s60 offen
	buffer_load_dwordx4 v[68:71], v129, s[20:23], s60 offen
	buffer_load_dwordx4 v[72:75], v130, s[20:23], s60 offen
	buffer_load_dwordx4 v[76:79], v131, s[20:23], s60 offen
	buffer_load_dwordx4 v[80:83], v132, s[20:23], s60 offen
	buffer_load_dwordx4 v[84:87], v133, s[20:23], s60 offen
	buffer_load_dwordx4 v[88:91], v134, s[20:23], s60 offen
	buffer_load_dwordx4 v[92:95], v135, s[20:23], s60 offen
	ds_read_b32 v128, v243 offset:768
	ds_read_b32 v129, v243 offset:800
	ds_read_b32 v130, v243 offset:832
	ds_read_b32 v131, v243 offset:864
	ds_read_b32 v132, v243 offset:896
	ds_read_b32 v133, v243 offset:928
	ds_read_b32 v134, v243 offset:960
	ds_read_b32 v135, v243 offset:992
	ds_read_b64 v[160:161], v247 offset:0
	ds_read_b64 v[162:163], v247 offset:32
	ds_read_b64 v[164:165], v247 offset:64
	ds_read_b64 v[166:167], v247 offset:96
	ds_read_b64 v[168:169], v247 offset:128
	ds_read_b64 v[170:171], v247 offset:160
	ds_read_b64 v[172:173], v247 offset:192
	ds_read_b64 v[174:175], v247 offset:224
	s_waitcnt vmcnt(26)
	v_and_b32_e32 v144, v176, v235
	v_and_b32_e32 v145, v176, v236
	v_and_b32_e32 v146, v176, v237
	v_and_b32_e32 v147, v176, v238
	v_and_b32_e32 v148, v177, v235
	v_and_b32_e32 v149, v177, v236
	v_and_b32_e32 v150, v177, v237
	v_and_b32_e32 v151, v177, v238
	s_mov_b64 vcc, s[4:5]
	v_cndmask_b32_dpp v138, v96, v98, vcc row_shl:4 row_mask:0xf bank_mask:0xf bound_ctrl:1
	v_cndmask_b32_dpp v139, v97, v99, vcc row_shl:4 row_mask:0xf bank_mask:0xf bound_ctrl:1
	s_mov_b64 vcc, s[6:7]
	v_cndmask_b32_dpp v136, v98, v96, vcc row_shr:4 row_mask:0xf bank_mask:0xf bound_ctrl:1
	v_cndmask_b32_dpp v137, v99, v97, vcc row_shr:4 row_mask:0xf bank_mask:0xf bound_ctrl:1
	v_and_b32_e32 v204, v178, v235
	v_and_b32_e32 v205, v178, v236
	v_and_b32_e32 v206, v178, v237
	v_and_b32_e32 v207, v178, v238
	v_and_b32_e32 v208, v179, v235
	v_and_b32_e32 v209, v179, v236
	v_and_b32_e32 v210, v179, v237
	v_and_b32_e32 v211, v179, v238
	s_mov_b64 vcc, s[6:7]
	v_cndmask_b32_dpp v140, v102, v100, vcc row_shr:4 row_mask:0xf bank_mask:0xf bound_ctrl:1
	v_cndmask_b32_dpp v141, v103, v101, vcc row_shr:4 row_mask:0xf bank_mask:0xf bound_ctrl:1
	s_mov_b64 vcc, s[4:5]
	v_cndmask_b32_dpp v142, v100, v102, vcc row_shl:4 row_mask:0xf bank_mask:0xf bound_ctrl:1
	v_cndmask_b32_dpp v143, v101, v103, vcc row_shl:4 row_mask:0xf bank_mask:0xf bound_ctrl:1
	v_mfma_scale_f32_16x16x128_f8f6f4 v[216:219], v[136:139], v[144:151], v[216:219], v240, v241 op_sel_hi:[0,0,0] cbsz:4
	v_permlane16_swap_b32_e32 v212, v214
	v_permlane16_swap_b32_e32 v213, v215
	v_lshlrev_b32_e32 v252, 16, v228
	v_and_b32_e32 v144, v180, v235
	v_and_b32_e32 v145, v180, v236
	v_and_b32_e32 v146, v180, v237
	v_and_b32_e32 v147, v180, v238
	v_and_b32_e32 v148, v181, v235
	v_and_b32_e32 v149, v181, v236
	v_and_b32_e32 v150, v181, v237
	v_and_b32_e32 v151, v181, v238
	s_mov_b64 vcc, s[4:5]
	v_cndmask_b32_dpp v138, v104, v106, vcc row_shl:4 row_mask:0xf bank_mask:0xf bound_ctrl:1
	v_cndmask_b32_dpp v139, v105, v107, vcc row_shl:4 row_mask:0xf bank_mask:0xf bound_ctrl:1
	s_mov_b64 vcc, s[6:7]
	v_cndmask_b32_dpp v136, v106, v104, vcc row_shr:4 row_mask:0xf bank_mask:0xf bound_ctrl:1
	v_cndmask_b32_dpp v137, v107, v105, vcc row_shr:4 row_mask:0xf bank_mask:0xf bound_ctrl:1
	v_mfma_scale_f32_16x16x128_f8f6f4 v[216:219], v[140:143], v[204:211], v[216:219], v240, v241 op_sel_hi:[0,0,0] cbsz:4
	v_and_b32_e32 v253, 0xffff0000, v228
	v_lshlrev_b32_e32 v254, 16, v229
	v_and_b32_e32 v255, 0xffff0000, v229
	v_and_b32_e32 v204, v182, v235
	v_and_b32_e32 v205, v182, v236
	v_and_b32_e32 v206, v182, v237
	v_and_b32_e32 v207, v182, v238
	v_and_b32_e32 v208, v183, v235
	v_and_b32_e32 v209, v183, v236
	v_and_b32_e32 v210, v183, v237
	v_and_b32_e32 v211, v183, v238
	s_mov_b64 vcc, s[6:7]
	v_cndmask_b32_dpp v140, v110, v108, vcc row_shr:4 row_mask:0xf bank_mask:0xf bound_ctrl:1
	v_cndmask_b32_dpp v141, v111, v109, vcc row_shr:4 row_mask:0xf bank_mask:0xf bound_ctrl:1
	s_mov_b64 vcc, s[4:5]
	v_cndmask_b32_dpp v142, v108, v110, vcc row_shl:4 row_mask:0xf bank_mask:0xf bound_ctrl:1
	v_cndmask_b32_dpp v143, v109, v111, vcc row_shl:4 row_mask:0xf bank_mask:0xf bound_ctrl:1
	v_mfma_scale_f32_16x16x128_f8f6f4 v[216:219], v[136:139], v[144:151], v[216:219], v240, v241 op_sel_hi:[0,0,0] cbsz:4
	v_add_f32_e32 v252, v212, v252
	v_add_f32_e32 v253, v214, v253
	v_add_f32_e32 v254, v213, v254
	v_and_b32_e32 v144, v184, v235
	v_and_b32_e32 v145, v184, v236
	v_and_b32_e32 v146, v184, v237
	v_and_b32_e32 v147, v184, v238
	v_and_b32_e32 v148, v185, v235
	v_and_b32_e32 v149, v185, v236
	v_and_b32_e32 v150, v185, v237
	v_and_b32_e32 v151, v185, v238
	s_mov_b64 vcc, s[4:5]
	v_cndmask_b32_dpp v138, v112, v114, vcc row_shl:4 row_mask:0xf bank_mask:0xf bound_ctrl:1
	v_cndmask_b32_dpp v139, v113, v115, vcc row_shl:4 row_mask:0xf bank_mask:0xf bound_ctrl:1
	s_mov_b64 vcc, s[6:7]
	v_cndmask_b32_dpp v136, v114, v112, vcc row_shr:4 row_mask:0xf bank_mask:0xf bound_ctrl:1
	v_cndmask_b32_dpp v137, v115, v113, vcc row_shr:4 row_mask:0xf bank_mask:0xf bound_ctrl:1
	v_mfma_scale_f32_16x16x128_f8f6f4 v[216:219], v[140:143], v[204:211], v[216:219], v240, v241 op_sel_hi:[0,0,0] cbsz:4
	v_add_f32_e32 v255, v215, v255
	v_mul_f32_e32 v192, v252, v252
	v_mul_f32_e32 v193, v254, v254
	v_and_b32_e32 v204, v186, v235
	v_and_b32_e32 v205, v186, v236
	v_and_b32_e32 v206, v186, v237
	v_and_b32_e32 v207, v186, v238
	v_and_b32_e32 v208, v187, v235
	v_and_b32_e32 v209, v187, v236
	v_and_b32_e32 v210, v187, v237
	v_and_b32_e32 v211, v187, v238
	s_mov_b64 vcc, s[6:7]
	v_cndmask_b32_dpp v140, v118, v116, vcc row_shr:4 row_mask:0xf bank_mask:0xf bound_ctrl:1
	v_cndmask_b32_dpp v141, v119, v117, vcc row_shr:4 row_mask:0xf bank_mask:0xf bound_ctrl:1
	s_mov_b64 vcc, s[4:5]
	v_cndmask_b32_dpp v142, v116, v118, vcc row_shl:4 row_mask:0xf bank_mask:0xf bound_ctrl:1
	v_cndmask_b32_dpp v143, v117, v119, vcc row_shl:4 row_mask:0xf bank_mask:0xf bound_ctrl:1
	v_mfma_scale_f32_16x16x128_f8f6f4 v[216:219], v[136:139], v[144:151], v[216:219], v240, v241 op_sel_hi:[0,0,0] cbsz:4
	v_fmac_f32_e32 v192, v253, v253
	v_fmac_f32_e32 v193, v255, v255
	v_cvt_pk_bf16_f32 v250, v252, v253
	v_and_b32_e32 v144, v188, v235
	v_and_b32_e32 v145, v188, v236
	v_and_b32_e32 v146, v188, v237
	v_and_b32_e32 v147, v188, v238
	v_and_b32_e32 v148, v189, v235
	v_and_b32_e32 v149, v189, v236
	v_and_b32_e32 v150, v189, v237
	v_and_b32_e32 v151, v189, v238
	s_mov_b64 vcc, s[4:5]
	v_cndmask_b32_dpp v138, v120, v122, vcc row_shl:4 row_mask:0xf bank_mask:0xf bound_ctrl:1
	v_cndmask_b32_dpp v139, v121, v123, vcc row_shl:4 row_mask:0xf bank_mask:0xf bound_ctrl:1
	s_mov_b64 vcc, s[6:7]
	v_cndmask_b32_dpp v136, v122, v120, vcc row_shr:4 row_mask:0xf bank_mask:0xf bound_ctrl:1
	v_cndmask_b32_dpp v137, v123, v121, vcc row_shr:4 row_mask:0xf bank_mask:0xf bound_ctrl:1
	v_mfma_scale_f32_16x16x128_f8f6f4 v[216:219], v[140:143], v[204:211], v[216:219], v240, v241 op_sel_hi:[0,0,0] cbsz:4
	v_cvt_pk_bf16_f32 v251, v254, v255
	v_add_f32_e32 v192, v192, v193
	v_add_f32_e32 v226, v226, v192
	v_and_b32_e32 v204, v190, v235
	v_and_b32_e32 v205, v190, v236
	v_and_b32_e32 v206, v190, v237
	v_and_b32_e32 v207, v190, v238
	v_and_b32_e32 v208, v191, v235
	v_and_b32_e32 v209, v191, v236
	v_and_b32_e32 v210, v191, v237
	v_and_b32_e32 v211, v191, v238
	s_mov_b64 vcc, s[6:7]
	v_cndmask_b32_dpp v140, v126, v124, vcc row_shr:4 row_mask:0xf bank_mask:0xf bound_ctrl:1
	v_cndmask_b32_dpp v141, v127, v125, vcc row_shr:4 row_mask:0xf bank_mask:0xf bound_ctrl:1
	s_mov_b64 vcc, s[4:5]
	v_cndmask_b32_dpp v142, v124, v126, vcc row_shl:4 row_mask:0xf bank_mask:0xf bound_ctrl:1
	v_cndmask_b32_dpp v143, v125, v127, vcc row_shl:4 row_mask:0xf bank_mask:0xf bound_ctrl:1
	v_mfma_scale_f32_16x16x128_f8f6f4 v[216:219], v[136:139], v[144:151], v[216:219], v240, v241 op_sel_hi:[0,0,0] cbsz:4
	s_nop 0
	v_mfma_scale_f32_16x16x128_f8f6f4 v[216:219], v[140:143], v[204:211], v[216:219], v240, v241 op_sel_hi:[0,0,0] cbsz:4
	s_lshl_b32 s64, s0, 9
	s_add_u32 s64, s64, 0x6000
	s_add_u32 s76, s28, s64
	s_addc_u32 s77, s29, 0
	global_store_dwordx2 v239, v[250:251], s[76:77]
	s_add_u32 s0, s0, 1
	s_lshl_b32 s1, s0, 21
	s_add_u32 s60, s1, 0x200000
	s_cmp_ge_u32 s0, 3
	s_movk_i32 s65, 0x2000
	s_cselect_b32 s64, s65, 0x1000
	v_mov_b32_e32 v234, v247
	v_add_u32_e32 v247, s64, v233
	s_cmp_lt_u32 s0, 8
	s_cbranch_scc1 .LpgL0_vloopv0
	s_waitcnt vmcnt(0)
	s_nop 15
	v_permlane16_swap_b32_e32 v216, v218
	v_permlane16_swap_b32_e32 v217, v219
	v_lshlrev_b32_e32 v252, 16, v230
	v_and_b32_e32 v253, 0xffff0000, v230
	v_lshlrev_b32_e32 v254, 16, v231
	v_and_b32_e32 v255, 0xffff0000, v231
	v_add_f32_e32 v252, v216, v252
	v_add_f32_e32 v253, v218, v253
	v_add_f32_e32 v254, v217, v254
	v_add_f32_e32 v255, v219, v255
	v_mul_f32_e32 v192, v252, v252
	v_mul_f32_e32 v193, v254, v254
	v_fmac_f32_e32 v192, v253, v253
	v_fmac_f32_e32 v193, v255, v255
	v_cvt_pk_bf16_f32 v250, v252, v253
	v_cvt_pk_bf16_f32 v251, v254, v255
	v_add_f32_e32 v192, v192, v193
	v_add_f32_e32 v227, v227, v192
	s_lshl_b32 s64, s0, 9
	s_add_u32 s64, s64, 0x6e00
	s_add_u32 s76, s28, s64
	s_addc_u32 s77, s29, 0
	global_store_dwordx2 v239, v[250:251], s[76:77]
	s_nop 1
	v_add_f32_dpp v220, v220, v220 quad_perm:[1,0,3,2] row_mask:0xf bank_mask:0xf bound_ctrl:1
	s_nop 1
	v_add_f32_dpp v220, v220, v220 quad_perm:[2,3,0,1] row_mask:0xf bank_mask:0xf bound_ctrl:1
	s_nop 1
	v_add_f32_dpp v220, v220, v220 row_half_mirror row_mask:0xf bank_mask:0xf bound_ctrl:1
	s_nop 1
	v_add_f32_dpp v220, v220, v220 row_mirror row_mask:0xf bank_mask:0xf bound_ctrl:1
	v_mov_b32_e32 v249, v220
	s_nop 1
	v_permlane16_swap_b32_e32 v220, v249
	v_add_f32_e32 v220, v220, v249
	v_mov_b32_e32 v249, v220
	s_nop 1
	v_permlane32_swap_b32_e32 v220, v249
	v_add_f32_e32 v220, v220, v249
	s_nop 1
	v_add_f32_dpp v221, v221, v221 quad_perm:[1,0,3,2] row_mask:0xf bank_mask:0xf bound_ctrl:1
	s_nop 1
	v_add_f32_dpp v221, v221, v221 quad_perm:[2,3,0,1] row_mask:0xf bank_mask:0xf bound_ctrl:1
	s_nop 1
	v_add_f32_dpp v221, v221, v221 row_half_mirror row_mask:0xf bank_mask:0xf bound_ctrl:1
	s_nop 1
	v_add_f32_dpp v221, v221, v221 row_mirror row_mask:0xf bank_mask:0xf bound_ctrl:1
	v_mov_b32_e32 v249, v221
	s_nop 1
	v_permlane16_swap_b32_e32 v221, v249
	v_add_f32_e32 v221, v221, v249
	v_mov_b32_e32 v249, v221
	s_nop 1
	v_permlane32_swap_b32_e32 v221, v249
	v_add_f32_e32 v221, v221, v249
	s_nop 1
	v_add_f32_dpp v222, v222, v222 quad_perm:[1,0,3,2] row_mask:0xf bank_mask:0xf bound_ctrl:1
	s_nop 1
	v_add_f32_dpp v222, v222, v222 quad_perm:[2,3,0,1] row_mask:0xf bank_mask:0xf bound_ctrl:1
	s_nop 1
	v_add_f32_dpp v222, v222, v222 row_half_mirror row_mask:0xf bank_mask:0xf bound_ctrl:1
	s_nop 1
	v_add_f32_dpp v222, v222, v222 row_mirror row_mask:0xf bank_mask:0xf bound_ctrl:1
	v_mov_b32_e32 v249, v222
	s_nop 1
	v_permlane16_swap_b32_e32 v222, v249
	v_add_f32_e32 v222, v222, v249
	v_mov_b32_e32 v249, v222
	s_nop 1
	v_permlane32_swap_b32_e32 v222, v249
	v_add_f32_e32 v222, v222, v249
	s_nop 1
	v_add_f32_dpp v223, v223, v223 quad_perm:[1,0,3,2] row_mask:0xf bank_mask:0xf bound_ctrl:1
	s_nop 1
	v_add_f32_dpp v223, v223, v223 quad_perm:[2,3,0,1] row_mask:0xf bank_mask:0xf bound_ctrl:1
	s_nop 1
	v_add_f32_dpp v223, v223, v223 row_half_mirror row_mask:0xf bank_mask:0xf bound_ctrl:1
	s_nop 1
	v_add_f32_dpp v223, v223, v223 row_mirror row_mask:0xf bank_mask:0xf bound_ctrl:1
	v_mov_b32_e32 v249, v223
	s_nop 1
	v_permlane16_swap_b32_e32 v223, v249
	v_add_f32_e32 v223, v223, v249
	v_mov_b32_e32 v249, v223
	s_nop 1
	v_permlane32_swap_b32_e32 v223, v249
	v_add_f32_e32 v223, v223, v249
	s_nop 1
	v_add_f32_dpp v224, v224, v224 quad_perm:[1,0,3,2] row_mask:0xf bank_mask:0xf bound_ctrl:1
	s_nop 1
	v_add_f32_dpp v224, v224, v224 quad_perm:[2,3,0,1] row_mask:0xf bank_mask:0xf bound_ctrl:1
	s_nop 1
	v_add_f32_dpp v224, v224, v224 row_half_mirror row_mask:0xf bank_mask:0xf bound_ctrl:1
	s_nop 1
	v_add_f32_dpp v224, v224, v224 row_mirror row_mask:0xf bank_mask:0xf bound_ctrl:1
	v_mov_b32_e32 v249, v224
	s_nop 1
	v_permlane16_swap_b32_e32 v224, v249
	v_add_f32_e32 v224, v224, v249
	v_mov_b32_e32 v249, v224
	s_nop 1
	v_permlane32_swap_b32_e32 v224, v249
	v_add_f32_e32 v224, v224, v249
	s_nop 1
	v_add_f32_dpp v225, v225, v225 quad_perm:[1,0,3,2] row_mask:0xf bank_mask:0xf bound_ctrl:1
	s_nop 1
	v_add_f32_dpp v225, v225, v225 quad_perm:[2,3,0,1] row_mask:0xf bank_mask:0xf bound_ctrl:1
	s_nop 1
	v_add_f32_dpp v225, v225, v225 row_half_mirror row_mask:0xf bank_mask:0xf bound_ctrl:1
	s_nop 1
	v_add_f32_dpp v225, v225, v225 row_mirror row_mask:0xf bank_mask:0xf bound_ctrl:1
	v_mov_b32_e32 v249, v225
	s_nop 1
	v_permlane16_swap_b32_e32 v225, v249
	v_add_f32_e32 v225, v225, v249
	v_mov_b32_e32 v249, v225
	s_nop 1
	v_permlane32_swap_b32_e32 v225, v249
	v_add_f32_e32 v225, v225, v249
	s_nop 1
	v_add_f32_dpp v226, v226, v226 quad_perm:[1,0,3,2] row_mask:0xf bank_mask:0xf bound_ctrl:1
	s_nop 1
	v_add_f32_dpp v226, v226, v226 quad_perm:[2,3,0,1] row_mask:0xf bank_mask:0xf bound_ctrl:1
	s_nop 1
	v_add_f32_dpp v226, v226, v226 row_half_mirror row_mask:0xf bank_mask:0xf bound_ctrl:1
	s_nop 1
	v_add_f32_dpp v226, v226, v226 row_mirror row_mask:0xf bank_mask:0xf bound_ctrl:1
	v_mov_b32_e32 v249, v226
	s_nop 1
	v_permlane16_swap_b32_e32 v226, v249
	v_add_f32_e32 v226, v226, v249
	v_mov_b32_e32 v249, v226
	s_nop 1
	v_permlane32_swap_b32_e32 v226, v249
	v_add_f32_e32 v226, v226, v249
	s_nop 1
	v_add_f32_dpp v227, v227, v227 quad_perm:[1,0,3,2] row_mask:0xf bank_mask:0xf bound_ctrl:1
	s_nop 1
	v_add_f32_dpp v227, v227, v227 quad_perm:[2,3,0,1] row_mask:0xf bank_mask:0xf bound_ctrl:1
	s_nop 1
	v_add_f32_dpp v227, v227, v227 row_half_mirror row_mask:0xf bank_mask:0xf bound_ctrl:1
	s_nop 1
	v_add_f32_dpp v227, v227, v227 row_mirror row_mask:0xf bank_mask:0xf bound_ctrl:1
	v_mov_b32_e32 v249, v227
	s_nop 1
	v_permlane16_swap_b32_e32 v227, v249
	v_add_f32_e32 v227, v227, v249
	v_mov_b32_e32 v249, v227
	s_nop 1
	v_permlane32_swap_b32_e32 v227, v249
	v_add_f32_e32 v227, v227, v249
	s_mov_b64 s[78:79], exec
	s_mov_b64 exec, s[10:11]
	global_store_dword v246, v220, s[44:45] offset:0
	global_store_dword v246, v221, s[44:45] offset:4
	global_store_dword v246, v222, s[44:45] offset:8
	global_store_dword v246, v223, s[44:45] offset:12
	global_store_dword v246, v224, s[44:45] offset:16
	global_store_dword v246, v225, s[44:45] offset:20
	global_store_dword v246, v226, s[44:45] offset:24
	global_store_dword v246, v227, s[44:45] offset:28
	s_mov_b64 exec, s[78:79]
	s_add_u32 s63, s63, s90
	s_cmpk_lt_i32 s63, 0x800
	s_cbranch_scc1 .LpgL0_group

.LpgL1_vjoinv0:
	s_lshl_b32 s64, s0, 9
	s_add_u32 s64, s64, 0x1000
	s_add_u32 s70, s28, s64
	s_addc_u32 s71, s29, 0
	global_load_dwordx2 v[230:231], v239, s[70:71]
	s_waitcnt lgkmcnt(0)
	v_lshl_or_b32 v128, v128, 7, v232
	v_lshl_or_b32 v129, v129, 7, v232
	v_lshl_or_b32 v130, v130, 7, v232
	v_lshl_or_b32 v131, v131, 7, v232
	v_lshl_or_b32 v132, v132, 7, v232
	v_lshl_or_b32 v133, v133, 7, v232
	v_lshl_or_b32 v134, v134, 7, v232
	v_lshl_or_b32 v135, v135, 7, v232
	buffer_load_dwordx4 v[32:35], v128, s[20:23], s1 offen
	buffer_load_dwordx4 v[36:39], v129, s[20:23], s1 offen
	buffer_load_dwordx4 v[40:43], v130, s[20:23], s1 offen
	buffer_load_dwordx4 v[44:47], v131, s[20:23], s1 offen
	buffer_load_dwordx4 v[48:51], v132, s[20:23], s1 offen
	buffer_load_dwordx4 v[52:55], v133, s[20:23], s1 offen
	buffer_load_dwordx4 v[56:59], v134, s[20:23], s1 offen
	buffer_load_dwordx4 v[60:63], v135, s[20:23], s1 offen
	ds_read_b32 v128, v243 offset:1536
	ds_read_b32 v129, v243 offset:1568
	ds_read_b32 v130, v243 offset:1600
	ds_read_b32 v131, v243 offset:1632
	ds_read_b32 v132, v243 offset:1664
	ds_read_b32 v133, v243 offset:1696
	ds_read_b32 v134, v243 offset:1728
	ds_read_b32 v135, v243 offset:1760
	ds_read_b64 v[176:177], v234 offset:768
	ds_read_b64 v[178:179], v234 offset:800
	ds_read_b64 v[180:181], v234 offset:832
	ds_read_b64 v[182:183], v234 offset:864
	ds_read_b64 v[184:185], v234 offset:896
	ds_read_b64 v[186:187], v234 offset:928
	ds_read_b64 v[188:189], v234 offset:960
	ds_read_b64 v[190:191], v234 offset:992
	s_waitcnt vmcnt(28)
	v_and_b32_e32 v144, v160, v235
	v_and_b32_e32 v145, v160, v236
	v_and_b32_e32 v146, v160, v237
	v_and_b32_e32 v147, v160, v238
	v_and_b32_e32 v148, v161, v235
	v_and_b32_e32 v149, v161, v236
	v_and_b32_e32 v150, v161, v237
	v_and_b32_e32 v151, v161, v238
	s_mov_b64 vcc, s[4:5]
	v_cndmask_b32_dpp v138, v64, v66, vcc row_shl:4 row_mask:0xf bank_mask:0xf bound_ctrl:1
	v_cndmask_b32_dpp v139, v65, v67, vcc row_shl:4 row_mask:0xf bank_mask:0xf bound_ctrl:1
	s_mov_b64 vcc, s[6:7]
	v_cndmask_b32_dpp v136, v66, v64, vcc row_shr:4 row_mask:0xf bank_mask:0xf bound_ctrl:1
	v_cndmask_b32_dpp v137, v67, v65, vcc row_shr:4 row_mask:0xf bank_mask:0xf bound_ctrl:1
	v_and_b32_e32 v204, v162, v235
	v_and_b32_e32 v205, v162, v236
	v_and_b32_e32 v206, v162, v237
	v_and_b32_e32 v207, v162, v238
	v_and_b32_e32 v208, v163, v235
	v_and_b32_e32 v209, v163, v236
	v_and_b32_e32 v210, v163, v237
	v_and_b32_e32 v211, v163, v238
	s_mov_b64 vcc, s[6:7]
	v_cndmask_b32_dpp v140, v70, v68, vcc row_shr:4 row_mask:0xf bank_mask:0xf bound_ctrl:1
	v_cndmask_b32_dpp v141, v71, v69, vcc row_shr:4 row_mask:0xf bank_mask:0xf bound_ctrl:1
	s_mov_b64 vcc, s[4:5]
	v_cndmask_b32_dpp v142, v68, v70, vcc row_shl:4 row_mask:0xf bank_mask:0xf bound_ctrl:1
	v_cndmask_b32_dpp v143, v69, v71, vcc row_shl:4 row_mask:0xf bank_mask:0xf bound_ctrl:1
	v_mfma_scale_f32_16x16x128_f8f6f4 v[216:219], v[136:139], v[144:151], 0, v240, v241 op_sel_hi:[0,0,0] cbsz:4
	v_and_b32_e32 v144, v164, v235
	v_and_b32_e32 v145, v164, v236
	v_and_b32_e32 v146, v164, v237
	v_and_b32_e32 v147, v164, v238
	v_and_b32_e32 v148, v165, v235
	v_and_b32_e32 v149, v165, v236
	v_and_b32_e32 v150, v165, v237
	v_and_b32_e32 v151, v165, v238
	s_mov_b64 vcc, s[4:5]
	v_cndmask_b32_dpp v138, v72, v74, vcc row_shl:4 row_mask:0xf bank_mask:0xf bound_ctrl:1
	v_cndmask_b32_dpp v139, v73, v75, vcc row_shl:4 row_mask:0xf bank_mask:0xf bound_ctrl:1
	s_mov_b64 vcc, s[6:7]
	v_cndmask_b32_dpp v136, v74, v72, vcc row_shr:4 row_mask:0xf bank_mask:0xf bound_ctrl:1
	v_cndmask_b32_dpp v137, v75, v73, vcc row_shr:4 row_mask:0xf bank_mask:0xf bound_ctrl:1
	v_mfma_scale_f32_16x16x128_f8f6f4 v[216:219], v[140:143], v[204:211], v[216:219], v240, v241 op_sel_hi:[0,0,0] cbsz:4
	v_and_b32_e32 v204, v166, v235
	v_and_b32_e32 v205, v166, v236
	v_and_b32_e32 v206, v166, v237
	v_and_b32_e32 v207, v166, v238
	v_and_b32_e32 v208, v167, v235
	v_and_b32_e32 v209, v167, v236
	v_and_b32_e32 v210, v167, v237
	v_and_b32_e32 v211, v167, v238
	s_mov_b64 vcc, s[6:7]
	v_cndmask_b32_dpp v140, v78, v76, vcc row_shr:4 row_mask:0xf bank_mask:0xf bound_ctrl:1
	v_cndmask_b32_dpp v141, v79, v77, vcc row_shr:4 row_mask:0xf bank_mask:0xf bound_ctrl:1
	s_mov_b64 vcc, s[4:5]
	v_cndmask_b32_dpp v142, v76, v78, vcc row_shl:4 row_mask:0xf bank_mask:0xf bound_ctrl:1
	v_cndmask_b32_dpp v143, v77, v79, vcc row_shl:4 row_mask:0xf bank_mask:0xf bound_ctrl:1
	v_mfma_scale_f32_16x16x128_f8f6f4 v[216:219], v[136:139], v[144:151], v[216:219], v240, v241 op_sel_hi:[0,0,0] cbsz:4
	v_and_b32_e32 v144, v168, v235
	v_and_b32_e32 v145, v168, v236
	v_and_b32_e32 v146, v168, v237
	v_and_b32_e32 v147, v168, v238
	v_and_b32_e32 v148, v169, v235
	v_and_b32_e32 v149, v169, v236
	v_and_b32_e32 v150, v169, v237
	v_and_b32_e32 v151, v169, v238
	s_mov_b64 vcc, s[4:5]
	v_cndmask_b32_dpp v138, v80, v82, vcc row_shl:4 row_mask:0xf bank_mask:0xf bound_ctrl:1
	v_cndmask_b32_dpp v139, v81, v83, vcc row_shl:4 row_mask:0xf bank_mask:0xf bound_ctrl:1
	s_mov_b64 vcc, s[6:7]
	v_cndmask_b32_dpp v136, v82, v80, vcc row_shr:4 row_mask:0xf bank_mask:0xf bound_ctrl:1
	v_cndmask_b32_dpp v137, v83, v81, vcc row_shr:4 row_mask:0xf bank_mask:0xf bound_ctrl:1
	v_mfma_scale_f32_16x16x128_f8f6f4 v[216:219], v[140:143], v[204:211], v[216:219], v240, v241 op_sel_hi:[0,0,0] cbsz:4
	v_and_b32_e32 v204, v170, v235
	v_and_b32_e32 v205, v170, v236
	v_and_b32_e32 v206, v170, v237
	v_and_b32_e32 v207, v170, v238
	v_and_b32_e32 v208, v171, v235
	v_and_b32_e32 v209, v171, v236
	v_and_b32_e32 v210, v171, v237
	v_and_b32_e32 v211, v171, v238
	s_mov_b64 vcc, s[6:7]
	v_cndmask_b32_dpp v140, v86, v84, vcc row_shr:4 row_mask:0xf bank_mask:0xf bound_ctrl:1
	v_cndmask_b32_dpp v141, v87, v85, vcc row_shr:4 row_mask:0xf bank_mask:0xf bound_ctrl:1
	s_mov_b64 vcc, s[4:5]
	v_cndmask_b32_dpp v142, v84, v86, vcc row_shl:4 row_mask:0xf bank_mask:0xf bound_ctrl:1
	v_cndmask_b32_dpp v143, v85, v87, vcc row_shl:4 row_mask:0xf bank_mask:0xf bound_ctrl:1
	v_mfma_scale_f32_16x16x128_f8f6f4 v[216:219], v[136:139], v[144:151], v[216:219], v240, v241 op_sel_hi:[0,0,0] cbsz:4
	v_and_b32_e32 v144, v172, v235
	v_and_b32_e32 v145, v172, v236
	v_and_b32_e32 v146, v172, v237
	v_and_b32_e32 v147, v172, v238
	v_and_b32_e32 v148, v173, v235
	v_and_b32_e32 v149, v173, v236
	v_and_b32_e32 v150, v173, v237
	v_and_b32_e32 v151, v173, v238
	s_mov_b64 vcc, s[4:5]
	v_cndmask_b32_dpp v138, v88, v90, vcc row_shl:4 row_mask:0xf bank_mask:0xf bound_ctrl:1
	v_cndmask_b32_dpp v139, v89, v91, vcc row_shl:4 row_mask:0xf bank_mask:0xf bound_ctrl:1
	s_mov_b64 vcc, s[6:7]
	v_cndmask_b32_dpp v136, v90, v88, vcc row_shr:4 row_mask:0xf bank_mask:0xf bound_ctrl:1
	v_cndmask_b32_dpp v137, v91, v89, vcc row_shr:4 row_mask:0xf bank_mask:0xf bound_ctrl:1
	v_mfma_scale_f32_16x16x128_f8f6f4 v[216:219], v[140:143], v[204:211], v[216:219], v240, v241 op_sel_hi:[0,0,0] cbsz:4
	v_and_b32_e32 v204, v174, v235
	v_and_b32_e32 v205, v174, v236
	v_and_b32_e32 v206, v174, v237
	v_and_b32_e32 v207, v174, v238
	v_and_b32_e32 v208, v175, v235
	v_and_b32_e32 v209, v175, v236
	v_and_b32_e32 v210, v175, v237
	v_and_b32_e32 v211, v175, v238
	s_mov_b64 vcc, s[6:7]
	v_cndmask_b32_dpp v140, v94, v92, vcc row_shr:4 row_mask:0xf bank_mask:0xf bound_ctrl:1
	v_cndmask_b32_dpp v141, v95, v93, vcc row_shr:4 row_mask:0xf bank_mask:0xf bound_ctrl:1
	s_mov_b64 vcc, s[4:5]
	v_cndmask_b32_dpp v142, v92, v94, vcc row_shl:4 row_mask:0xf bank_mask:0xf bound_ctrl:1
	v_cndmask_b32_dpp v143, v93, v95, vcc row_shl:4 row_mask:0xf bank_mask:0xf bound_ctrl:1
	v_mfma_scale_f32_16x16x128_f8f6f4 v[216:219], v[136:139], v[144:151], v[216:219], v240, v241 op_sel_hi:[0,0,0] cbsz:4
	s_nop 0
	v_mfma_scale_f32_16x16x128_f8f6f4 v[216:219], v[140:143], v[204:211], v[216:219], v240, v241 op_sel_hi:[0,0,0] cbsz:4
	s_waitcnt lgkmcnt(0)
	v_lshl_or_b32 v128, v128, 7, v232
	v_lshl_or_b32 v129, v129, 7, v232
	v_lshl_or_b32 v130, v130, 7, v232
	v_lshl_or_b32 v131, v131, 7, v232
	v_lshl_or_b32 v132, v132, 7, v232
	v_lshl_or_b32 v133, v133, 7, v232
	v_lshl_or_b32 v134, v134, 7, v232
	v_lshl_or_b32 v135, v135, 7, v232
	buffer_load_dwordx4 v[64:67], v128, s[20:23], s1 offen
	buffer_load_dwordx4 v[68:71], v129, s[20:23], s1 offen
	buffer_load_dwordx4 v[72:75], v130, s[20:23], s1 offen
	buffer_load_dwordx4 v[76:79], v131, s[20:23], s1 offen
	buffer_load_dwordx4 v[80:83], v132, s[20:23], s1 offen
	buffer_load_dwordx4 v[84:87], v133, s[20:23], s1 offen
	buffer_load_dwordx4 v[88:91], v134, s[20:23], s1 offen
	buffer_load_dwordx4 v[92:95], v135, s[20:23], s1 offen
	ds_read_b32 v128, v243 offset:1792
	ds_read_b32 v129, v243 offset:1824
	ds_read_b32 v130, v243 offset:1856
	ds_read_b32 v131, v243 offset:1888
	ds_read_b32 v132, v243 offset:1920
	ds_read_b32 v133, v243 offset:1952
	ds_read_b32 v134, v243 offset:1984
	ds_read_b32 v135, v243 offset:2016
	ds_read_b64 v[160:161], v234 offset:1024
	ds_read_b64 v[162:163], v234 offset:1056
	ds_read_b64 v[164:165], v234 offset:1088
	ds_read_b64 v[166:167], v234 offset:1120
	ds_read_b64 v[168:169], v234 offset:1152
	ds_read_b64 v[170:171], v234 offset:1184
	ds_read_b64 v[172:173], v234 offset:1216
	ds_read_b64 v[174:175], v234 offset:1248
	s_waitcnt vmcnt(26)
	v_and_b32_e32 v144, v176, v235
	v_and_b32_e32 v145, v176, v236
	v_and_b32_e32 v146, v176, v237
	v_and_b32_e32 v147, v176, v238
	v_and_b32_e32 v148, v177, v235
	v_and_b32_e32 v149, v177, v236
	v_and_b32_e32 v150, v177, v237
	v_and_b32_e32 v151, v177, v238
	s_mov_b64 vcc, s[4:5]
	v_cndmask_b32_dpp v138, v96, v98, vcc row_shl:4 row_mask:0xf bank_mask:0xf bound_ctrl:1
	v_cndmask_b32_dpp v139, v97, v99, vcc row_shl:4 row_mask:0xf bank_mask:0xf bound_ctrl:1
	s_mov_b64 vcc, s[6:7]
	v_cndmask_b32_dpp v136, v98, v96, vcc row_shr:4 row_mask:0xf bank_mask:0xf bound_ctrl:1
	v_cndmask_b32_dpp v137, v99, v97, vcc row_shr:4 row_mask:0xf bank_mask:0xf bound_ctrl:1
	v_and_b32_e32 v204, v178, v235
	v_and_b32_e32 v205, v178, v236
	v_and_b32_e32 v206, v178, v237
	v_and_b32_e32 v207, v178, v238
	v_and_b32_e32 v208, v179, v235
	v_and_b32_e32 v209, v179, v236
	v_and_b32_e32 v210, v179, v237
	v_and_b32_e32 v211, v179, v238
	s_mov_b64 vcc, s[6:7]
	v_cndmask_b32_dpp v140, v102, v100, vcc row_shr:4 row_mask:0xf bank_mask:0xf bound_ctrl:1
	v_cndmask_b32_dpp v141, v103, v101, vcc row_shr:4 row_mask:0xf bank_mask:0xf bound_ctrl:1
	s_mov_b64 vcc, s[4:5]
	v_cndmask_b32_dpp v142, v100, v102, vcc row_shl:4 row_mask:0xf bank_mask:0xf bound_ctrl:1
	v_cndmask_b32_dpp v143, v101, v103, vcc row_shl:4 row_mask:0xf bank_mask:0xf bound_ctrl:1
	v_mfma_scale_f32_16x16x128_f8f6f4 v[216:219], v[136:139], v[144:151], v[216:219], v240, v241 op_sel_hi:[0,0,0] cbsz:4
	v_permlane16_swap_b32_e32 v212, v214
	v_permlane16_swap_b32_e32 v213, v215
	v_lshlrev_b32_e32 v252, 16, v228
	v_and_b32_e32 v144, v180, v235
	v_and_b32_e32 v145, v180, v236
	v_and_b32_e32 v146, v180, v237
	v_and_b32_e32 v147, v180, v238
	v_and_b32_e32 v148, v181, v235
	v_and_b32_e32 v149, v181, v236
	v_and_b32_e32 v150, v181, v237
	v_and_b32_e32 v151, v181, v238
	s_mov_b64 vcc, s[4:5]
	v_cndmask_b32_dpp v138, v104, v106, vcc row_shl:4 row_mask:0xf bank_mask:0xf bound_ctrl:1
	v_cndmask_b32_dpp v139, v105, v107, vcc row_shl:4 row_mask:0xf bank_mask:0xf bound_ctrl:1
	s_mov_b64 vcc, s[6:7]
	v_cndmask_b32_dpp v136, v106, v104, vcc row_shr:4 row_mask:0xf bank_mask:0xf bound_ctrl:1
	v_cndmask_b32_dpp v137, v107, v105, vcc row_shr:4 row_mask:0xf bank_mask:0xf bound_ctrl:1
	v_mfma_scale_f32_16x16x128_f8f6f4 v[216:219], v[140:143], v[204:211], v[216:219], v240, v241 op_sel_hi:[0,0,0] cbsz:4
	v_and_b32_e32 v253, 0xffff0000, v228
	v_lshlrev_b32_e32 v254, 16, v229
	v_and_b32_e32 v255, 0xffff0000, v229
	v_and_b32_e32 v204, v182, v235
	v_and_b32_e32 v205, v182, v236
	v_and_b32_e32 v206, v182, v237
	v_and_b32_e32 v207, v182, v238
	v_and_b32_e32 v208, v183, v235
	v_and_b32_e32 v209, v183, v236
	v_and_b32_e32 v210, v183, v237
	v_and_b32_e32 v211, v183, v238
	s_mov_b64 vcc, s[6:7]
	v_cndmask_b32_dpp v140, v110, v108, vcc row_shr:4 row_mask:0xf bank_mask:0xf bound_ctrl:1
	v_cndmask_b32_dpp v141, v111, v109, vcc row_shr:4 row_mask:0xf bank_mask:0xf bound_ctrl:1
	s_mov_b64 vcc, s[4:5]
	v_cndmask_b32_dpp v142, v108, v110, vcc row_shl:4 row_mask:0xf bank_mask:0xf bound_ctrl:1
	v_cndmask_b32_dpp v143, v109, v111, vcc row_shl:4 row_mask:0xf bank_mask:0xf bound_ctrl:1
	v_mfma_scale_f32_16x16x128_f8f6f4 v[216:219], v[136:139], v[144:151], v[216:219], v240, v241 op_sel_hi:[0,0,0] cbsz:4
	v_add_f32_e32 v252, v212, v252
	v_add_f32_e32 v253, v214, v253
	v_add_f32_e32 v254, v213, v254
	v_and_b32_e32 v144, v184, v235
	v_and_b32_e32 v145, v184, v236
	v_and_b32_e32 v146, v184, v237
	v_and_b32_e32 v147, v184, v238
	v_and_b32_e32 v148, v185, v235
	v_and_b32_e32 v149, v185, v236
	v_and_b32_e32 v150, v185, v237
	v_and_b32_e32 v151, v185, v238
	s_mov_b64 vcc, s[4:5]
	v_cndmask_b32_dpp v138, v112, v114, vcc row_shl:4 row_mask:0xf bank_mask:0xf bound_ctrl:1
	v_cndmask_b32_dpp v139, v113, v115, vcc row_shl:4 row_mask:0xf bank_mask:0xf bound_ctrl:1
	s_mov_b64 vcc, s[6:7]
	v_cndmask_b32_dpp v136, v114, v112, vcc row_shr:4 row_mask:0xf bank_mask:0xf bound_ctrl:1
	v_cndmask_b32_dpp v137, v115, v113, vcc row_shr:4 row_mask:0xf bank_mask:0xf bound_ctrl:1
	v_mfma_scale_f32_16x16x128_f8f6f4 v[216:219], v[140:143], v[204:211], v[216:219], v240, v241 op_sel_hi:[0,0,0] cbsz:4
	v_add_f32_e32 v255, v215, v255
	v_mul_f32_e32 v192, v252, v252
	v_mul_f32_e32 v193, v254, v254
	v_and_b32_e32 v204, v186, v235
	v_and_b32_e32 v205, v186, v236
	v_and_b32_e32 v206, v186, v237
	v_and_b32_e32 v207, v186, v238
	v_and_b32_e32 v208, v187, v235
	v_and_b32_e32 v209, v187, v236
	v_and_b32_e32 v210, v187, v237
	v_and_b32_e32 v211, v187, v238
	s_mov_b64 vcc, s[6:7]
	v_cndmask_b32_dpp v140, v118, v116, vcc row_shr:4 row_mask:0xf bank_mask:0xf bound_ctrl:1
	v_cndmask_b32_dpp v141, v119, v117, vcc row_shr:4 row_mask:0xf bank_mask:0xf bound_ctrl:1
	s_mov_b64 vcc, s[4:5]
	v_cndmask_b32_dpp v142, v116, v118, vcc row_shl:4 row_mask:0xf bank_mask:0xf bound_ctrl:1
	v_cndmask_b32_dpp v143, v117, v119, vcc row_shl:4 row_mask:0xf bank_mask:0xf bound_ctrl:1
	v_mfma_scale_f32_16x16x128_f8f6f4 v[216:219], v[136:139], v[144:151], v[216:219], v240, v241 op_sel_hi:[0,0,0] cbsz:4
	v_fmac_f32_e32 v192, v253, v253
	v_fmac_f32_e32 v193, v255, v255
	v_cvt_pk_bf16_f32 v250, v252, v253
	v_and_b32_e32 v144, v188, v235
	v_and_b32_e32 v145, v188, v236
	v_and_b32_e32 v146, v188, v237
	v_and_b32_e32 v147, v188, v238
	v_and_b32_e32 v148, v189, v235
	v_and_b32_e32 v149, v189, v236
	v_and_b32_e32 v150, v189, v237
	v_and_b32_e32 v151, v189, v238
	s_mov_b64 vcc, s[4:5]
	v_cndmask_b32_dpp v138, v120, v122, vcc row_shl:4 row_mask:0xf bank_mask:0xf bound_ctrl:1
	v_cndmask_b32_dpp v139, v121, v123, vcc row_shl:4 row_mask:0xf bank_mask:0xf bound_ctrl:1
	s_mov_b64 vcc, s[6:7]
	v_cndmask_b32_dpp v136, v122, v120, vcc row_shr:4 row_mask:0xf bank_mask:0xf bound_ctrl:1
	v_cndmask_b32_dpp v137, v123, v121, vcc row_shr:4 row_mask:0xf bank_mask:0xf bound_ctrl:1
	v_mfma_scale_f32_16x16x128_f8f6f4 v[216:219], v[140:143], v[204:211], v[216:219], v240, v241 op_sel_hi:[0,0,0] cbsz:4
	v_cvt_pk_bf16_f32 v251, v254, v255
	v_add_f32_e32 v192, v192, v193
	v_add_f32_e32 v220, v220, v192
	v_and_b32_e32 v204, v190, v235
	v_and_b32_e32 v205, v190, v236
	v_and_b32_e32 v206, v190, v237
	v_and_b32_e32 v207, v190, v238
	v_and_b32_e32 v208, v191, v235
	v_and_b32_e32 v209, v191, v236
	v_and_b32_e32 v210, v191, v237
	v_and_b32_e32 v211, v191, v238
	s_mov_b64 vcc, s[6:7]
	v_cndmask_b32_dpp v140, v126, v124, vcc row_shr:4 row_mask:0xf bank_mask:0xf bound_ctrl:1
	v_cndmask_b32_dpp v141, v127, v125, vcc row_shr:4 row_mask:0xf bank_mask:0xf bound_ctrl:1
	s_mov_b64 vcc, s[4:5]
	v_cndmask_b32_dpp v142, v124, v126, vcc row_shl:4 row_mask:0xf bank_mask:0xf bound_ctrl:1
	v_cndmask_b32_dpp v143, v125, v127, vcc row_shl:4 row_mask:0xf bank_mask:0xf bound_ctrl:1
	v_mfma_scale_f32_16x16x128_f8f6f4 v[216:219], v[136:139], v[144:151], v[216:219], v240, v241 op_sel_hi:[0,0,0] cbsz:4
	s_nop 0
	v_mfma_scale_f32_16x16x128_f8f6f4 v[216:219], v[140:143], v[204:211], v[216:219], v240, v241 op_sel_hi:[0,0,0] cbsz:4
	s_lshl_b32 s64, s0, 9
	s_add_u32 s64, s64, 0x0
	s_add_u32 s76, s28, s64
	s_addc_u32 s77, s29, 0
	global_store_dwordx2 v239, v[250:251], s[76:77]
	s_lshl_b32 s64, s0, 9
	s_add_u32 s64, s64, 0x2000
	s_add_u32 s70, s28, s64
	s_addc_u32 s71, s29, 0
	global_load_dwordx2 v[228:229], v239, s[70:71]
	s_waitcnt lgkmcnt(0)
	v_lshl_or_b32 v128, v128, 7, v232
	v_lshl_or_b32 v129, v129, 7, v232
	v_lshl_or_b32 v130, v130, 7, v232
	v_lshl_or_b32 v131, v131, 7, v232
	v_lshl_or_b32 v132, v132, 7, v232
	v_lshl_or_b32 v133, v133, 7, v232
	v_lshl_or_b32 v134, v134, 7, v232
	v_lshl_or_b32 v135, v135, 7, v232
	buffer_load_dwordx4 v[96:99], v128, s[20:23], s1 offen
	buffer_load_dwordx4 v[100:103], v129, s[20:23], s1 offen
	buffer_load_dwordx4 v[104:107], v130, s[20:23], s1 offen
	buffer_load_dwordx4 v[108:111], v131, s[20:23], s1 offen
	buffer_load_dwordx4 v[112:115], v132, s[20:23], s1 offen
	buffer_load_dwordx4 v[116:119], v133, s[20:23], s1 offen
	buffer_load_dwordx4 v[120:123], v134, s[20:23], s1 offen
	buffer_load_dwordx4 v[124:127], v135, s[20:23], s1 offen
	ds_read_b32 v128, v243 offset:2048
	ds_read_b32 v129, v243 offset:2080
	ds_read_b32 v130, v243 offset:2112
	ds_read_b32 v131, v243 offset:2144
	ds_read_b32 v132, v243 offset:2176
	ds_read_b32 v133, v243 offset:2208
	ds_read_b32 v134, v243 offset:2240
	ds_read_b32 v135, v243 offset:2272
	ds_read_b64 v[176:177], v234 offset:1280
	ds_read_b64 v[178:179], v234 offset:1312
	ds_read_b64 v[180:181], v234 offset:1344
	ds_read_b64 v[182:183], v234 offset:1376
	ds_read_b64 v[184:185], v234 offset:1408
	ds_read_b64 v[186:187], v234 offset:1440
	ds_read_b64 v[188:189], v234 offset:1472
	ds_read_b64 v[190:191], v234 offset:1504
	s_waitcnt vmcnt(28)
	v_and_b32_e32 v144, v160, v235
	v_and_b32_e32 v145, v160, v236
	v_and_b32_e32 v146, v160, v237
	v_and_b32_e32 v147, v160, v238
	v_and_b32_e32 v148, v161, v235
	v_and_b32_e32 v149, v161, v236
	v_and_b32_e32 v150, v161, v237
	v_and_b32_e32 v151, v161, v238
	s_mov_b64 vcc, s[4:5]
	v_cndmask_b32_dpp v138, v0, v2, vcc row_shl:4 row_mask:0xf bank_mask:0xf bound_ctrl:1
	v_cndmask_b32_dpp v139, v1, v3, vcc row_shl:4 row_mask:0xf bank_mask:0xf bound_ctrl:1
	s_mov_b64 vcc, s[6:7]
	v_cndmask_b32_dpp v136, v2, v0, vcc row_shr:4 row_mask:0xf bank_mask:0xf bound_ctrl:1
	v_cndmask_b32_dpp v137, v3, v1, vcc row_shr:4 row_mask:0xf bank_mask:0xf bound_ctrl:1
	v_and_b32_e32 v204, v162, v235
	v_and_b32_e32 v205, v162, v236
	v_and_b32_e32 v206, v162, v237
	v_and_b32_e32 v207, v162, v238
	v_and_b32_e32 v208, v163, v235
	v_and_b32_e32 v209, v163, v236
	v_and_b32_e32 v210, v163, v237
	v_and_b32_e32 v211, v163, v238
	s_mov_b64 vcc, s[6:7]
	v_cndmask_b32_dpp v140, v6, v4, vcc row_shr:4 row_mask:0xf bank_mask:0xf bound_ctrl:1
	v_cndmask_b32_dpp v141, v7, v5, vcc row_shr:4 row_mask:0xf bank_mask:0xf bound_ctrl:1
	s_mov_b64 vcc, s[4:5]
	v_cndmask_b32_dpp v142, v4, v6, vcc row_shl:4 row_mask:0xf bank_mask:0xf bound_ctrl:1
	v_cndmask_b32_dpp v143, v5, v7, vcc row_shl:4 row_mask:0xf bank_mask:0xf bound_ctrl:1
	v_mfma_scale_f32_16x16x128_f8f6f4 v[212:215], v[136:139], v[144:151], 0, v240, v241 op_sel_hi:[0,0,0] cbsz:4
	v_and_b32_e32 v144, v164, v235
	v_and_b32_e32 v145, v164, v236
	v_and_b32_e32 v146, v164, v237
	v_and_b32_e32 v147, v164, v238
	v_and_b32_e32 v148, v165, v235
	v_and_b32_e32 v149, v165, v236
	v_and_b32_e32 v150, v165, v237
	v_and_b32_e32 v151, v165, v238
	s_mov_b64 vcc, s[4:5]
	v_cndmask_b32_dpp v138, v8, v10, vcc row_shl:4 row_mask:0xf bank_mask:0xf bound_ctrl:1
	v_cndmask_b32_dpp v139, v9, v11, vcc row_shl:4 row_mask:0xf bank_mask:0xf bound_ctrl:1
	s_mov_b64 vcc, s[6:7]
	v_cndmask_b32_dpp v136, v10, v8, vcc row_shr:4 row_mask:0xf bank_mask:0xf bound_ctrl:1
	v_cndmask_b32_dpp v137, v11, v9, vcc row_shr:4 row_mask:0xf bank_mask:0xf bound_ctrl:1
	v_mfma_scale_f32_16x16x128_f8f6f4 v[212:215], v[140:143], v[204:211], v[212:215], v240, v241 op_sel_hi:[0,0,0] cbsz:4
	v_and_b32_e32 v204, v166, v235
	v_and_b32_e32 v205, v166, v236
	v_and_b32_e32 v206, v166, v237
	v_and_b32_e32 v207, v166, v238
	v_and_b32_e32 v208, v167, v235
	v_and_b32_e32 v209, v167, v236
	v_and_b32_e32 v210, v167, v237
	v_and_b32_e32 v211, v167, v238
	s_mov_b64 vcc, s[6:7]
	v_cndmask_b32_dpp v140, v14, v12, vcc row_shr:4 row_mask:0xf bank_mask:0xf bound_ctrl:1
	v_cndmask_b32_dpp v141, v15, v13, vcc row_shr:4 row_mask:0xf bank_mask:0xf bound_ctrl:1
	s_mov_b64 vcc, s[4:5]
	v_cndmask_b32_dpp v142, v12, v14, vcc row_shl:4 row_mask:0xf bank_mask:0xf bound_ctrl:1
	v_cndmask_b32_dpp v143, v13, v15, vcc row_shl:4 row_mask:0xf bank_mask:0xf bound_ctrl:1
	v_mfma_scale_f32_16x16x128_f8f6f4 v[212:215], v[136:139], v[144:151], v[212:215], v240, v241 op_sel_hi:[0,0,0] cbsz:4
	v_and_b32_e32 v144, v168, v235
	v_and_b32_e32 v145, v168, v236
	v_and_b32_e32 v146, v168, v237
	v_and_b32_e32 v147, v168, v238
	v_and_b32_e32 v148, v169, v235
	v_and_b32_e32 v149, v169, v236
	v_and_b32_e32 v150, v169, v237
	v_and_b32_e32 v151, v169, v238
	s_mov_b64 vcc, s[4:5]
	v_cndmask_b32_dpp v138, v16, v18, vcc row_shl:4 row_mask:0xf bank_mask:0xf bound_ctrl:1
	v_cndmask_b32_dpp v139, v17, v19, vcc row_shl:4 row_mask:0xf bank_mask:0xf bound_ctrl:1
	s_mov_b64 vcc, s[6:7]
	v_cndmask_b32_dpp v136, v18, v16, vcc row_shr:4 row_mask:0xf bank_mask:0xf bound_ctrl:1
	v_cndmask_b32_dpp v137, v19, v17, vcc row_shr:4 row_mask:0xf bank_mask:0xf bound_ctrl:1
	v_mfma_scale_f32_16x16x128_f8f6f4 v[212:215], v[140:143], v[204:211], v[212:215], v240, v241 op_sel_hi:[0,0,0] cbsz:4
	v_and_b32_e32 v204, v170, v235
	v_and_b32_e32 v205, v170, v236
	v_and_b32_e32 v206, v170, v237
	v_and_b32_e32 v207, v170, v238
	v_and_b32_e32 v208, v171, v235
	v_and_b32_e32 v209, v171, v236
	v_and_b32_e32 v210, v171, v237
	v_and_b32_e32 v211, v171, v238
	s_mov_b64 vcc, s[6:7]
	v_cndmask_b32_dpp v140, v22, v20, vcc row_shr:4 row_mask:0xf bank_mask:0xf bound_ctrl:1
	v_cndmask_b32_dpp v141, v23, v21, vcc row_shr:4 row_mask:0xf bank_mask:0xf bound_ctrl:1
	s_mov_b64 vcc, s[4:5]
	v_cndmask_b32_dpp v142, v20, v22, vcc row_shl:4 row_mask:0xf bank_mask:0xf bound_ctrl:1
	v_cndmask_b32_dpp v143, v21, v23, vcc row_shl:4 row_mask:0xf bank_mask:0xf bound_ctrl:1
	v_mfma_scale_f32_16x16x128_f8f6f4 v[212:215], v[136:139], v[144:151], v[212:215], v240, v241 op_sel_hi:[0,0,0] cbsz:4
	v_and_b32_e32 v144, v172, v235
	v_and_b32_e32 v145, v172, v236
	v_and_b32_e32 v146, v172, v237
	v_and_b32_e32 v147, v172, v238
	v_and_b32_e32 v148, v173, v235
	v_and_b32_e32 v149, v173, v236
	v_and_b32_e32 v150, v173, v237
	v_and_b32_e32 v151, v173, v238
	s_mov_b64 vcc, s[4:5]
	v_cndmask_b32_dpp v138, v24, v26, vcc row_shl:4 row_mask:0xf bank_mask:0xf bound_ctrl:1
	v_cndmask_b32_dpp v139, v25, v27, vcc row_shl:4 row_mask:0xf bank_mask:0xf bound_ctrl:1
	s_mov_b64 vcc, s[6:7]
	v_cndmask_b32_dpp v136, v26, v24, vcc row_shr:4 row_mask:0xf bank_mask:0xf bound_ctrl:1
	v_cndmask_b32_dpp v137, v27, v25, vcc row_shr:4 row_mask:0xf bank_mask:0xf bound_ctrl:1
	v_mfma_scale_f32_16x16x128_f8f6f4 v[212:215], v[140:143], v[204:211], v[212:215], v240, v241 op_sel_hi:[0,0,0] cbsz:4
	v_and_b32_e32 v204, v174, v235
	v_and_b32_e32 v205, v174, v236
	v_and_b32_e32 v206, v174, v237
	v_and_b32_e32 v207, v174, v238
	v_and_b32_e32 v208, v175, v235
	v_and_b32_e32 v209, v175, v236
	v_and_b32_e32 v210, v175, v237
	v_and_b32_e32 v211, v175, v238
	s_mov_b64 vcc, s[6:7]
	v_cndmask_b32_dpp v140, v30, v28, vcc row_shr:4 row_mask:0xf bank_mask:0xf bound_ctrl:1
	v_cndmask_b32_dpp v141, v31, v29, vcc row_shr:4 row_mask:0xf bank_mask:0xf bound_ctrl:1
	s_mov_b64 vcc, s[4:5]
	v_cndmask_b32_dpp v142, v28, v30, vcc row_shl:4 row_mask:0xf bank_mask:0xf bound_ctrl:1
	v_cndmask_b32_dpp v143, v29, v31, vcc row_shl:4 row_mask:0xf bank_mask:0xf bound_ctrl:1
	v_mfma_scale_f32_16x16x128_f8f6f4 v[212:215], v[136:139], v[144:151], v[212:215], v240, v241 op_sel_hi:[0,0,0] cbsz:4
	s_nop 0
	v_mfma_scale_f32_16x16x128_f8f6f4 v[212:215], v[140:143], v[204:211], v[212:215], v240, v241 op_sel_hi:[0,0,0] cbsz:4
	s_waitcnt lgkmcnt(0)
	v_lshl_or_b32 v128, v128, 7, v232
	v_lshl_or_b32 v129, v129, 7, v232
	v_lshl_or_b32 v130, v130, 7, v232
	v_lshl_or_b32 v131, v131, 7, v232
	v_lshl_or_b32 v132, v132, 7, v232
	v_lshl_or_b32 v133, v133, 7, v232
	v_lshl_or_b32 v134, v134, 7, v232
	v_lshl_or_b32 v135, v135, 7, v232
	buffer_load_dwordx4 v[0:3], v128, s[20:23], s1 offen
	buffer_load_dwordx4 v[4:7], v129, s[20:23], s1 offen
	buffer_load_dwordx4 v[8:11], v130, s[20:23], s1 offen
	buffer_load_dwordx4 v[12:15], v131, s[20:23], s1 offen
	buffer_load_dwordx4 v[16:19], v132, s[20:23], s1 offen
	buffer_load_dwordx4 v[20:23], v133, s[20:23], s1 offen
	buffer_load_dwordx4 v[24:27], v134, s[20:23], s1 offen
	buffer_load_dwordx4 v[28:31], v135, s[20:23], s1 offen
	ds_read_b32 v128, v243 offset:2304
	ds_read_b32 v129, v243 offset:2336
	ds_read_b32 v130, v243 offset:2368
	ds_read_b32 v131, v243 offset:2400
	ds_read_b32 v132, v243 offset:2432
	ds_read_b32 v133, v243 offset:2464
	ds_read_b32 v134, v243 offset:2496
	ds_read_b32 v135, v243 offset:2528
	ds_read_b64 v[160:161], v234 offset:1536
	ds_read_b64 v[162:163], v234 offset:1568
	ds_read_b64 v[164:165], v234 offset:1600
	ds_read_b64 v[166:167], v234 offset:1632
	ds_read_b64 v[168:169], v234 offset:1664
	ds_read_b64 v[170:171], v234 offset:1696
	ds_read_b64 v[172:173], v234 offset:1728
	ds_read_b64 v[174:175], v234 offset:1760
	s_waitcnt vmcnt(26)
	v_and_b32_e32 v144, v176, v235
	v_and_b32_e32 v145, v176, v236
	v_and_b32_e32 v146, v176, v237
	v_and_b32_e32 v147, v176, v238
	v_and_b32_e32 v148, v177, v235
	v_and_b32_e32 v149, v177, v236
	v_and_b32_e32 v150, v177, v237
	v_and_b32_e32 v151, v177, v238
	s_mov_b64 vcc, s[4:5]
	v_cndmask_b32_dpp v138, v32, v34, vcc row_shl:4 row_mask:0xf bank_mask:0xf bound_ctrl:1
	v_cndmask_b32_dpp v139, v33, v35, vcc row_shl:4 row_mask:0xf bank_mask:0xf bound_ctrl:1
	s_mov_b64 vcc, s[6:7]
	v_cndmask_b32_dpp v136, v34, v32, vcc row_shr:4 row_mask:0xf bank_mask:0xf bound_ctrl:1
	v_cndmask_b32_dpp v137, v35, v33, vcc row_shr:4 row_mask:0xf bank_mask:0xf bound_ctrl:1
	v_and_b32_e32 v204, v178, v235
	v_and_b32_e32 v205, v178, v236
	v_and_b32_e32 v206, v178, v237
	v_and_b32_e32 v207, v178, v238
	v_and_b32_e32 v208, v179, v235
	v_and_b32_e32 v209, v179, v236
	v_and_b32_e32 v210, v179, v237
	v_and_b32_e32 v211, v179, v238
	s_mov_b64 vcc, s[6:7]
	v_cndmask_b32_dpp v140, v38, v36, vcc row_shr:4 row_mask:0xf bank_mask:0xf bound_ctrl:1
	v_cndmask_b32_dpp v141, v39, v37, vcc row_shr:4 row_mask:0xf bank_mask:0xf bound_ctrl:1
	s_mov_b64 vcc, s[4:5]
	v_cndmask_b32_dpp v142, v36, v38, vcc row_shl:4 row_mask:0xf bank_mask:0xf bound_ctrl:1
	v_cndmask_b32_dpp v143, v37, v39, vcc row_shl:4 row_mask:0xf bank_mask:0xf bound_ctrl:1
	v_mfma_scale_f32_16x16x128_f8f6f4 v[212:215], v[136:139], v[144:151], v[212:215], v240, v241 op_sel_hi:[0,0,0] cbsz:4
	v_permlane16_swap_b32_e32 v216, v218
	v_permlane16_swap_b32_e32 v217, v219
	v_lshlrev_b32_e32 v252, 16, v230
	v_and_b32_e32 v144, v180, v235
	v_and_b32_e32 v145, v180, v236
	v_and_b32_e32 v146, v180, v237
	v_and_b32_e32 v147, v180, v238
	v_and_b32_e32 v148, v181, v235
	v_and_b32_e32 v149, v181, v236
	v_and_b32_e32 v150, v181, v237
	v_and_b32_e32 v151, v181, v238
	s_mov_b64 vcc, s[4:5]
	v_cndmask_b32_dpp v138, v40, v42, vcc row_shl:4 row_mask:0xf bank_mask:0xf bound_ctrl:1
	v_cndmask_b32_dpp v139, v41, v43, vcc row_shl:4 row_mask:0xf bank_mask:0xf bound_ctrl:1
	s_mov_b64 vcc, s[6:7]
	v_cndmask_b32_dpp v136, v42, v40, vcc row_shr:4 row_mask:0xf bank_mask:0xf bound_ctrl:1
	v_cndmask_b32_dpp v137, v43, v41, vcc row_shr:4 row_mask:0xf bank_mask:0xf bound_ctrl:1
	v_mfma_scale_f32_16x16x128_f8f6f4 v[212:215], v[140:143], v[204:211], v[212:215], v240, v241 op_sel_hi:[0,0,0] cbsz:4
	v_and_b32_e32 v253, 0xffff0000, v230
	v_lshlrev_b32_e32 v254, 16, v231
	v_and_b32_e32 v255, 0xffff0000, v231
	v_and_b32_e32 v204, v182, v235
	v_and_b32_e32 v205, v182, v236
	v_and_b32_e32 v206, v182, v237
	v_and_b32_e32 v207, v182, v238
	v_and_b32_e32 v208, v183, v235
	v_and_b32_e32 v209, v183, v236
	v_and_b32_e32 v210, v183, v237
	v_and_b32_e32 v211, v183, v238
	s_mov_b64 vcc, s[6:7]
	v_cndmask_b32_dpp v140, v46, v44, vcc row_shr:4 row_mask:0xf bank_mask:0xf bound_ctrl:1
	v_cndmask_b32_dpp v141, v47, v45, vcc row_shr:4 row_mask:0xf bank_mask:0xf bound_ctrl:1
	s_mov_b64 vcc, s[4:5]
	v_cndmask_b32_dpp v142, v44, v46, vcc row_shl:4 row_mask:0xf bank_mask:0xf bound_ctrl:1
	v_cndmask_b32_dpp v143, v45, v47, vcc row_shl:4 row_mask:0xf bank_mask:0xf bound_ctrl:1
	v_mfma_scale_f32_16x16x128_f8f6f4 v[212:215], v[136:139], v[144:151], v[212:215], v240, v241 op_sel_hi:[0,0,0] cbsz:4
	v_add_f32_e32 v252, v216, v252
	v_add_f32_e32 v253, v218, v253
	v_add_f32_e32 v254, v217, v254
	v_and_b32_e32 v144, v184, v235
	v_and_b32_e32 v145, v184, v236
	v_and_b32_e32 v146, v184, v237
	v_and_b32_e32 v147, v184, v238
	v_and_b32_e32 v148, v185, v235
	v_and_b32_e32 v149, v185, v236
	v_and_b32_e32 v150, v185, v237
	v_and_b32_e32 v151, v185, v238
	s_mov_b64 vcc, s[4:5]
	v_cndmask_b32_dpp v138, v48, v50, vcc row_shl:4 row_mask:0xf bank_mask:0xf bound_ctrl:1
	v_cndmask_b32_dpp v139, v49, v51, vcc row_shl:4 row_mask:0xf bank_mask:0xf bound_ctrl:1
	s_mov_b64 vcc, s[6:7]
	v_cndmask_b32_dpp v136, v50, v48, vcc row_shr:4 row_mask:0xf bank_mask:0xf bound_ctrl:1
	v_cndmask_b32_dpp v137, v51, v49, vcc row_shr:4 row_mask:0xf bank_mask:0xf bound_ctrl:1
	v_mfma_scale_f32_16x16x128_f8f6f4 v[212:215], v[140:143], v[204:211], v[212:215], v240, v241 op_sel_hi:[0,0,0] cbsz:4
	v_add_f32_e32 v255, v219, v255
	v_mul_f32_e32 v192, v252, v252
	v_mul_f32_e32 v193, v254, v254
	v_and_b32_e32 v204, v186, v235
	v_and_b32_e32 v205, v186, v236
	v_and_b32_e32 v206, v186, v237
	v_and_b32_e32 v207, v186, v238
	v_and_b32_e32 v208, v187, v235
	v_and_b32_e32 v209, v187, v236
	v_and_b32_e32 v210, v187, v237
	v_and_b32_e32 v211, v187, v238
	s_mov_b64 vcc, s[6:7]
	v_cndmask_b32_dpp v140, v54, v52, vcc row_shr:4 row_mask:0xf bank_mask:0xf bound_ctrl:1
	v_cndmask_b32_dpp v141, v55, v53, vcc row_shr:4 row_mask:0xf bank_mask:0xf bound_ctrl:1
	s_mov_b64 vcc, s[4:5]
	v_cndmask_b32_dpp v142, v52, v54, vcc row_shl:4 row_mask:0xf bank_mask:0xf bound_ctrl:1
	v_cndmask_b32_dpp v143, v53, v55, vcc row_shl:4 row_mask:0xf bank_mask:0xf bound_ctrl:1
	v_mfma_scale_f32_16x16x128_f8f6f4 v[212:215], v[136:139], v[144:151], v[212:215], v240, v241 op_sel_hi:[0,0,0] cbsz:4
	v_fmac_f32_e32 v192, v253, v253
	v_fmac_f32_e32 v193, v255, v255
	v_cvt_pk_bf16_f32 v250, v252, v253
	v_and_b32_e32 v144, v188, v235
	v_and_b32_e32 v145, v188, v236
	v_and_b32_e32 v146, v188, v237
	v_and_b32_e32 v147, v188, v238
	v_and_b32_e32 v148, v189, v235
	v_and_b32_e32 v149, v189, v236
	v_and_b32_e32 v150, v189, v237
	v_and_b32_e32 v151, v189, v238
	s_mov_b64 vcc, s[4:5]
	v_cndmask_b32_dpp v138, v56, v58, vcc row_shl:4 row_mask:0xf bank_mask:0xf bound_ctrl:1
	v_cndmask_b32_dpp v139, v57, v59, vcc row_shl:4 row_mask:0xf bank_mask:0xf bound_ctrl:1
	s_mov_b64 vcc, s[6:7]
	v_cndmask_b32_dpp v136, v58, v56, vcc row_shr:4 row_mask:0xf bank_mask:0xf bound_ctrl:1
	v_cndmask_b32_dpp v137, v59, v57, vcc row_shr:4 row_mask:0xf bank_mask:0xf bound_ctrl:1
	v_mfma_scale_f32_16x16x128_f8f6f4 v[212:215], v[140:143], v[204:211], v[212:215], v240, v241 op_sel_hi:[0,0,0] cbsz:4
	v_cvt_pk_bf16_f32 v251, v254, v255
	v_add_f32_e32 v192, v192, v193
	v_add_f32_e32 v221, v221, v192
	v_and_b32_e32 v204, v190, v235
	v_and_b32_e32 v205, v190, v236
	v_and_b32_e32 v206, v190, v237
	v_and_b32_e32 v207, v190, v238
	v_and_b32_e32 v208, v191, v235
	v_and_b32_e32 v209, v191, v236
	v_and_b32_e32 v210, v191, v237
	v_and_b32_e32 v211, v191, v238
	s_mov_b64 vcc, s[6:7]
	v_cndmask_b32_dpp v140, v62, v60, vcc row_shr:4 row_mask:0xf bank_mask:0xf bound_ctrl:1
	v_cndmask_b32_dpp v141, v63, v61, vcc row_shr:4 row_mask:0xf bank_mask:0xf bound_ctrl:1
	s_mov_b64 vcc, s[4:5]
	v_cndmask_b32_dpp v142, v60, v62, vcc row_shl:4 row_mask:0xf bank_mask:0xf bound_ctrl:1
	v_cndmask_b32_dpp v143, v61, v63, vcc row_shl:4 row_mask:0xf bank_mask:0xf bound_ctrl:1
	v_mfma_scale_f32_16x16x128_f8f6f4 v[212:215], v[136:139], v[144:151], v[212:215], v240, v241 op_sel_hi:[0,0,0] cbsz:4
	s_nop 0
	v_mfma_scale_f32_16x16x128_f8f6f4 v[212:215], v[140:143], v[204:211], v[212:215], v240, v241 op_sel_hi:[0,0,0] cbsz:4
	s_lshl_b32 s64, s0, 9
	s_add_u32 s64, s64, 0x1000
	s_add_u32 s76, s28, s64
	s_addc_u32 s77, s29, 0
	global_store_dwordx2 v239, v[250:251], s[76:77]
	s_lshl_b32 s64, s0, 9
	s_add_u32 s64, s64, 0x3000
	s_add_u32 s70, s28, s64
	s_addc_u32 s71, s29, 0
	global_load_dwordx2 v[230:231], v239, s[70:71]
	s_waitcnt lgkmcnt(0)
	v_lshl_or_b32 v128, v128, 7, v232
	v_lshl_or_b32 v129, v129, 7, v232
	v_lshl_or_b32 v130, v130, 7, v232
	v_lshl_or_b32 v131, v131, 7, v232
	v_lshl_or_b32 v132, v132, 7, v232
	v_lshl_or_b32 v133, v133, 7, v232
	v_lshl_or_b32 v134, v134, 7, v232
	v_lshl_or_b32 v135, v135, 7, v232
	buffer_load_dwordx4 v[32:35], v128, s[20:23], s1 offen
	buffer_load_dwordx4 v[36:39], v129, s[20:23], s1 offen
	buffer_load_dwordx4 v[40:43], v130, s[20:23], s1 offen
	buffer_load_dwordx4 v[44:47], v131, s[20:23], s1 offen
	buffer_load_dwordx4 v[48:51], v132, s[20:23], s1 offen
	buffer_load_dwordx4 v[52:55], v133, s[20:23], s1 offen
	buffer_load_dwordx4 v[56:59], v134, s[20:23], s1 offen
	buffer_load_dwordx4 v[60:63], v135, s[20:23], s1 offen
	ds_read_b32 v128, v243 offset:2560
	ds_read_b32 v129, v243 offset:2592
	ds_read_b32 v130, v243 offset:2624
	ds_read_b32 v131, v243 offset:2656
	ds_read_b32 v132, v243 offset:2688
	ds_read_b32 v133, v243 offset:2720
	ds_read_b32 v134, v243 offset:2752
	ds_read_b32 v135, v243 offset:2784
	ds_read_b64 v[176:177], v234 offset:1792
	ds_read_b64 v[178:179], v234 offset:1824
	ds_read_b64 v[180:181], v234 offset:1856
	ds_read_b64 v[182:183], v234 offset:1888
	ds_read_b64 v[184:185], v234 offset:1920
	ds_read_b64 v[186:187], v234 offset:1952
	ds_read_b64 v[188:189], v234 offset:1984
	ds_read_b64 v[190:191], v234 offset:2016
	s_waitcnt vmcnt(28)
	v_and_b32_e32 v144, v160, v235
	v_and_b32_e32 v145, v160, v236
	v_and_b32_e32 v146, v160, v237
	v_and_b32_e32 v147, v160, v238
	v_and_b32_e32 v148, v161, v235
	v_and_b32_e32 v149, v161, v236
	v_and_b32_e32 v150, v161, v237
	v_and_b32_e32 v151, v161, v238
	s_mov_b64 vcc, s[4:5]
	v_cndmask_b32_dpp v138, v64, v66, vcc row_shl:4 row_mask:0xf bank_mask:0xf bound_ctrl:1
	v_cndmask_b32_dpp v139, v65, v67, vcc row_shl:4 row_mask:0xf bank_mask:0xf bound_ctrl:1
	s_mov_b64 vcc, s[6:7]
	v_cndmask_b32_dpp v136, v66, v64, vcc row_shr:4 row_mask:0xf bank_mask:0xf bound_ctrl:1
	v_cndmask_b32_dpp v137, v67, v65, vcc row_shr:4 row_mask:0xf bank_mask:0xf bound_ctrl:1
	v_and_b32_e32 v204, v162, v235
	v_and_b32_e32 v205, v162, v236
	v_and_b32_e32 v206, v162, v237
	v_and_b32_e32 v207, v162, v238
	v_and_b32_e32 v208, v163, v235
	v_and_b32_e32 v209, v163, v236
	v_and_b32_e32 v210, v163, v237
	v_and_b32_e32 v211, v163, v238
	s_mov_b64 vcc, s[6:7]
	v_cndmask_b32_dpp v140, v70, v68, vcc row_shr:4 row_mask:0xf bank_mask:0xf bound_ctrl:1
	v_cndmask_b32_dpp v141, v71, v69, vcc row_shr:4 row_mask:0xf bank_mask:0xf bound_ctrl:1
	s_mov_b64 vcc, s[4:5]
	v_cndmask_b32_dpp v142, v68, v70, vcc row_shl:4 row_mask:0xf bank_mask:0xf bound_ctrl:1
	v_cndmask_b32_dpp v143, v69, v71, vcc row_shl:4 row_mask:0xf bank_mask:0xf bound_ctrl:1
	v_mfma_scale_f32_16x16x128_f8f6f4 v[216:219], v[136:139], v[144:151], 0, v240, v241 op_sel_hi:[0,0,0] cbsz:4
	v_and_b32_e32 v144, v164, v235
	v_and_b32_e32 v145, v164, v236
	v_and_b32_e32 v146, v164, v237
	v_and_b32_e32 v147, v164, v238
	v_and_b32_e32 v148, v165, v235
	v_and_b32_e32 v149, v165, v236
	v_and_b32_e32 v150, v165, v237
	v_and_b32_e32 v151, v165, v238
	s_mov_b64 vcc, s[4:5]
	v_cndmask_b32_dpp v138, v72, v74, vcc row_shl:4 row_mask:0xf bank_mask:0xf bound_ctrl:1
	v_cndmask_b32_dpp v139, v73, v75, vcc row_shl:4 row_mask:0xf bank_mask:0xf bound_ctrl:1
	s_mov_b64 vcc, s[6:7]
	v_cndmask_b32_dpp v136, v74, v72, vcc row_shr:4 row_mask:0xf bank_mask:0xf bound_ctrl:1
	v_cndmask_b32_dpp v137, v75, v73, vcc row_shr:4 row_mask:0xf bank_mask:0xf bound_ctrl:1
	v_mfma_scale_f32_16x16x128_f8f6f4 v[216:219], v[140:143], v[204:211], v[216:219], v240, v241 op_sel_hi:[0,0,0] cbsz:4
	v_and_b32_e32 v204, v166, v235
	v_and_b32_e32 v205, v166, v236
	v_and_b32_e32 v206, v166, v237
	v_and_b32_e32 v207, v166, v238
	v_and_b32_e32 v208, v167, v235
	v_and_b32_e32 v209, v167, v236
	v_and_b32_e32 v210, v167, v237
	v_and_b32_e32 v211, v167, v238
	s_mov_b64 vcc, s[6:7]
	v_cndmask_b32_dpp v140, v78, v76, vcc row_shr:4 row_mask:0xf bank_mask:0xf bound_ctrl:1
	v_cndmask_b32_dpp v141, v79, v77, vcc row_shr:4 row_mask:0xf bank_mask:0xf bound_ctrl:1
	s_mov_b64 vcc, s[4:5]
	v_cndmask_b32_dpp v142, v76, v78, vcc row_shl:4 row_mask:0xf bank_mask:0xf bound_ctrl:1
	v_cndmask_b32_dpp v143, v77, v79, vcc row_shl:4 row_mask:0xf bank_mask:0xf bound_ctrl:1
	v_mfma_scale_f32_16x16x128_f8f6f4 v[216:219], v[136:139], v[144:151], v[216:219], v240, v241 op_sel_hi:[0,0,0] cbsz:4
	v_and_b32_e32 v144, v168, v235
	v_and_b32_e32 v145, v168, v236
	v_and_b32_e32 v146, v168, v237
	v_and_b32_e32 v147, v168, v238
	v_and_b32_e32 v148, v169, v235
	v_and_b32_e32 v149, v169, v236
	v_and_b32_e32 v150, v169, v237
	v_and_b32_e32 v151, v169, v238
	s_mov_b64 vcc, s[4:5]
	v_cndmask_b32_dpp v138, v80, v82, vcc row_shl:4 row_mask:0xf bank_mask:0xf bound_ctrl:1
	v_cndmask_b32_dpp v139, v81, v83, vcc row_shl:4 row_mask:0xf bank_mask:0xf bound_ctrl:1
	s_mov_b64 vcc, s[6:7]
	v_cndmask_b32_dpp v136, v82, v80, vcc row_shr:4 row_mask:0xf bank_mask:0xf bound_ctrl:1
	v_cndmask_b32_dpp v137, v83, v81, vcc row_shr:4 row_mask:0xf bank_mask:0xf bound_ctrl:1
	v_mfma_scale_f32_16x16x128_f8f6f4 v[216:219], v[140:143], v[204:211], v[216:219], v240, v241 op_sel_hi:[0,0,0] cbsz:4
	v_and_b32_e32 v204, v170, v235
	v_and_b32_e32 v205, v170, v236
	v_and_b32_e32 v206, v170, v237
	v_and_b32_e32 v207, v170, v238
	v_and_b32_e32 v208, v171, v235
	v_and_b32_e32 v209, v171, v236
	v_and_b32_e32 v210, v171, v237
	v_and_b32_e32 v211, v171, v238
	s_mov_b64 vcc, s[6:7]
	v_cndmask_b32_dpp v140, v86, v84, vcc row_shr:4 row_mask:0xf bank_mask:0xf bound_ctrl:1
	v_cndmask_b32_dpp v141, v87, v85, vcc row_shr:4 row_mask:0xf bank_mask:0xf bound_ctrl:1
	s_mov_b64 vcc, s[4:5]
	v_cndmask_b32_dpp v142, v84, v86, vcc row_shl:4 row_mask:0xf bank_mask:0xf bound_ctrl:1
	v_cndmask_b32_dpp v143, v85, v87, vcc row_shl:4 row_mask:0xf bank_mask:0xf bound_ctrl:1
	v_mfma_scale_f32_16x16x128_f8f6f4 v[216:219], v[136:139], v[144:151], v[216:219], v240, v241 op_sel_hi:[0,0,0] cbsz:4
	v_and_b32_e32 v144, v172, v235
	v_and_b32_e32 v145, v172, v236
	v_and_b32_e32 v146, v172, v237
	v_and_b32_e32 v147, v172, v238
	v_and_b32_e32 v148, v173, v235
	v_and_b32_e32 v149, v173, v236
	v_and_b32_e32 v150, v173, v237
	v_and_b32_e32 v151, v173, v238
	s_mov_b64 vcc, s[4:5]
	v_cndmask_b32_dpp v138, v88, v90, vcc row_shl:4 row_mask:0xf bank_mask:0xf bound_ctrl:1
	v_cndmask_b32_dpp v139, v89, v91, vcc row_shl:4 row_mask:0xf bank_mask:0xf bound_ctrl:1
	s_mov_b64 vcc, s[6:7]
	v_cndmask_b32_dpp v136, v90, v88, vcc row_shr:4 row_mask:0xf bank_mask:0xf bound_ctrl:1
	v_cndmask_b32_dpp v137, v91, v89, vcc row_shr:4 row_mask:0xf bank_mask:0xf bound_ctrl:1
	v_mfma_scale_f32_16x16x128_f8f6f4 v[216:219], v[140:143], v[204:211], v[216:219], v240, v241 op_sel_hi:[0,0,0] cbsz:4
	v_and_b32_e32 v204, v174, v235
	v_and_b32_e32 v205, v174, v236
	v_and_b32_e32 v206, v174, v237
	v_and_b32_e32 v207, v174, v238
	v_and_b32_e32 v208, v175, v235
	v_and_b32_e32 v209, v175, v236
	v_and_b32_e32 v210, v175, v237
	v_and_b32_e32 v211, v175, v238
	s_mov_b64 vcc, s[6:7]
	v_cndmask_b32_dpp v140, v94, v92, vcc row_shr:4 row_mask:0xf bank_mask:0xf bound_ctrl:1
	v_cndmask_b32_dpp v141, v95, v93, vcc row_shr:4 row_mask:0xf bank_mask:0xf bound_ctrl:1
	s_mov_b64 vcc, s[4:5]
	v_cndmask_b32_dpp v142, v92, v94, vcc row_shl:4 row_mask:0xf bank_mask:0xf bound_ctrl:1
	v_cndmask_b32_dpp v143, v93, v95, vcc row_shl:4 row_mask:0xf bank_mask:0xf bound_ctrl:1
	v_mfma_scale_f32_16x16x128_f8f6f4 v[216:219], v[136:139], v[144:151], v[216:219], v240, v241 op_sel_hi:[0,0,0] cbsz:4
	s_nop 0
	v_mfma_scale_f32_16x16x128_f8f6f4 v[216:219], v[140:143], v[204:211], v[216:219], v240, v241 op_sel_hi:[0,0,0] cbsz:4
	s_waitcnt lgkmcnt(0)
	v_lshl_or_b32 v128, v128, 7, v232
	v_lshl_or_b32 v129, v129, 7, v232
	v_lshl_or_b32 v130, v130, 7, v232
	v_lshl_or_b32 v131, v131, 7, v232
	v_lshl_or_b32 v132, v132, 7, v232
	v_lshl_or_b32 v133, v133, 7, v232
	v_lshl_or_b32 v134, v134, 7, v232
	v_lshl_or_b32 v135, v135, 7, v232
	buffer_load_dwordx4 v[64:67], v128, s[20:23], s1 offen
	buffer_load_dwordx4 v[68:71], v129, s[20:23], s1 offen
	buffer_load_dwordx4 v[72:75], v130, s[20:23], s1 offen
	buffer_load_dwordx4 v[76:79], v131, s[20:23], s1 offen
	buffer_load_dwordx4 v[80:83], v132, s[20:23], s1 offen
	buffer_load_dwordx4 v[84:87], v133, s[20:23], s1 offen
	buffer_load_dwordx4 v[88:91], v134, s[20:23], s1 offen
	buffer_load_dwordx4 v[92:95], v135, s[20:23], s1 offen
	ds_read_b32 v128, v243 offset:2816
	ds_read_b32 v129, v243 offset:2848
	ds_read_b32 v130, v243 offset:2880
	ds_read_b32 v131, v243 offset:2912
	ds_read_b32 v132, v243 offset:2944
	ds_read_b32 v133, v243 offset:2976
	ds_read_b32 v134, v243 offset:3008
	ds_read_b32 v135, v243 offset:3040
	ds_read_b64 v[160:161], v234 offset:2048
	ds_read_b64 v[162:163], v234 offset:2080
	ds_read_b64 v[164:165], v234 offset:2112
	ds_read_b64 v[166:167], v234 offset:2144
	ds_read_b64 v[168:169], v234 offset:2176
	ds_read_b64 v[170:171], v234 offset:2208
	ds_read_b64 v[172:173], v234 offset:2240
	ds_read_b64 v[174:175], v234 offset:2272
	s_waitcnt vmcnt(26)
	v_and_b32_e32 v144, v176, v235
	v_and_b32_e32 v145, v176, v236
	v_and_b32_e32 v146, v176, v237
	v_and_b32_e32 v147, v176, v238
	v_and_b32_e32 v148, v177, v235
	v_and_b32_e32 v149, v177, v236
	v_and_b32_e32 v150, v177, v237
	v_and_b32_e32 v151, v177, v238
	s_mov_b64 vcc, s[4:5]
	v_cndmask_b32_dpp v138, v96, v98, vcc row_shl:4 row_mask:0xf bank_mask:0xf bound_ctrl:1
	v_cndmask_b32_dpp v139, v97, v99, vcc row_shl:4 row_mask:0xf bank_mask:0xf bound_ctrl:1
	s_mov_b64 vcc, s[6:7]
	v_cndmask_b32_dpp v136, v98, v96, vcc row_shr:4 row_mask:0xf bank_mask:0xf bound_ctrl:1
	v_cndmask_b32_dpp v137, v99, v97, vcc row_shr:4 row_mask:0xf bank_mask:0xf bound_ctrl:1
	v_and_b32_e32 v204, v178, v235
	v_and_b32_e32 v205, v178, v236
	v_and_b32_e32 v206, v178, v237
	v_and_b32_e32 v207, v178, v238
	v_and_b32_e32 v208, v179, v235
	v_and_b32_e32 v209, v179, v236
	v_and_b32_e32 v210, v179, v237
	v_and_b32_e32 v211, v179, v238
	s_mov_b64 vcc, s[6:7]
	v_cndmask_b32_dpp v140, v102, v100, vcc row_shr:4 row_mask:0xf bank_mask:0xf bound_ctrl:1
	v_cndmask_b32_dpp v141, v103, v101, vcc row_shr:4 row_mask:0xf bank_mask:0xf bound_ctrl:1
	s_mov_b64 vcc, s[4:5]
	v_cndmask_b32_dpp v142, v100, v102, vcc row_shl:4 row_mask:0xf bank_mask:0xf bound_ctrl:1
	v_cndmask_b32_dpp v143, v101, v103, vcc row_shl:4 row_mask:0xf bank_mask:0xf bound_ctrl:1
	v_mfma_scale_f32_16x16x128_f8f6f4 v[216:219], v[136:139], v[144:151], v[216:219], v240, v241 op_sel_hi:[0,0,0] cbsz:4
	v_permlane16_swap_b32_e32 v212, v214
	v_permlane16_swap_b32_e32 v213, v215
	v_lshlrev_b32_e32 v252, 16, v228
	v_and_b32_e32 v144, v180, v235
	v_and_b32_e32 v145, v180, v236
	v_and_b32_e32 v146, v180, v237
	v_and_b32_e32 v147, v180, v238
	v_and_b32_e32 v148, v181, v235
	v_and_b32_e32 v149, v181, v236
	v_and_b32_e32 v150, v181, v237
	v_and_b32_e32 v151, v181, v238
	s_mov_b64 vcc, s[4:5]
	v_cndmask_b32_dpp v138, v104, v106, vcc row_shl:4 row_mask:0xf bank_mask:0xf bound_ctrl:1
	v_cndmask_b32_dpp v139, v105, v107, vcc row_shl:4 row_mask:0xf bank_mask:0xf bound_ctrl:1
	s_mov_b64 vcc, s[6:7]
	v_cndmask_b32_dpp v136, v106, v104, vcc row_shr:4 row_mask:0xf bank_mask:0xf bound_ctrl:1
	v_cndmask_b32_dpp v137, v107, v105, vcc row_shr:4 row_mask:0xf bank_mask:0xf bound_ctrl:1
	v_mfma_scale_f32_16x16x128_f8f6f4 v[216:219], v[140:143], v[204:211], v[216:219], v240, v241 op_sel_hi:[0,0,0] cbsz:4
	v_and_b32_e32 v253, 0xffff0000, v228
	v_lshlrev_b32_e32 v254, 16, v229
	v_and_b32_e32 v255, 0xffff0000, v229
	v_and_b32_e32 v204, v182, v235
	v_and_b32_e32 v205, v182, v236
	v_and_b32_e32 v206, v182, v237
	v_and_b32_e32 v207, v182, v238
	v_and_b32_e32 v208, v183, v235
	v_and_b32_e32 v209, v183, v236
	v_and_b32_e32 v210, v183, v237
	v_and_b32_e32 v211, v183, v238
	s_mov_b64 vcc, s[6:7]
	v_cndmask_b32_dpp v140, v110, v108, vcc row_shr:4 row_mask:0xf bank_mask:0xf bound_ctrl:1
	v_cndmask_b32_dpp v141, v111, v109, vcc row_shr:4 row_mask:0xf bank_mask:0xf bound_ctrl:1
	s_mov_b64 vcc, s[4:5]
	v_cndmask_b32_dpp v142, v108, v110, vcc row_shl:4 row_mask:0xf bank_mask:0xf bound_ctrl:1
	v_cndmask_b32_dpp v143, v109, v111, vcc row_shl:4 row_mask:0xf bank_mask:0xf bound_ctrl:1
	v_mfma_scale_f32_16x16x128_f8f6f4 v[216:219], v[136:139], v[144:151], v[216:219], v240, v241 op_sel_hi:[0,0,0] cbsz:4
	v_add_f32_e32 v252, v212, v252
	v_add_f32_e32 v253, v214, v253
	v_add_f32_e32 v254, v213, v254
	v_and_b32_e32 v144, v184, v235
	v_and_b32_e32 v145, v184, v236
	v_and_b32_e32 v146, v184, v237
	v_and_b32_e32 v147, v184, v238
	v_and_b32_e32 v148, v185, v235
	v_and_b32_e32 v149, v185, v236
	v_and_b32_e32 v150, v185, v237
	v_and_b32_e32 v151, v185, v238
	s_mov_b64 vcc, s[4:5]
	v_cndmask_b32_dpp v138, v112, v114, vcc row_shl:4 row_mask:0xf bank_mask:0xf bound_ctrl:1
	v_cndmask_b32_dpp v139, v113, v115, vcc row_shl:4 row_mask:0xf bank_mask:0xf bound_ctrl:1
	s_mov_b64 vcc, s[6:7]
	v_cndmask_b32_dpp v136, v114, v112, vcc row_shr:4 row_mask:0xf bank_mask:0xf bound_ctrl:1
	v_cndmask_b32_dpp v137, v115, v113, vcc row_shr:4 row_mask:0xf bank_mask:0xf bound_ctrl:1
	v_mfma_scale_f32_16x16x128_f8f6f4 v[216:219], v[140:143], v[204:211], v[216:219], v240, v241 op_sel_hi:[0,0,0] cbsz:4
	v_add_f32_e32 v255, v215, v255
	v_mul_f32_e32 v192, v252, v252
	v_mul_f32_e32 v193, v254, v254
	v_and_b32_e32 v204, v186, v235
	v_and_b32_e32 v205, v186, v236
	v_and_b32_e32 v206, v186, v237
	v_and_b32_e32 v207, v186, v238
	v_and_b32_e32 v208, v187, v235
	v_and_b32_e32 v209, v187, v236
	v_and_b32_e32 v210, v187, v237
	v_and_b32_e32 v211, v187, v238
	s_mov_b64 vcc, s[6:7]
	v_cndmask_b32_dpp v140, v118, v116, vcc row_shr:4 row_mask:0xf bank_mask:0xf bound_ctrl:1
	v_cndmask_b32_dpp v141, v119, v117, vcc row_shr:4 row_mask:0xf bank_mask:0xf bound_ctrl:1
	s_mov_b64 vcc, s[4:5]
	v_cndmask_b32_dpp v142, v116, v118, vcc row_shl:4 row_mask:0xf bank_mask:0xf bound_ctrl:1
	v_cndmask_b32_dpp v143, v117, v119, vcc row_shl:4 row_mask:0xf bank_mask:0xf bound_ctrl:1
	v_mfma_scale_f32_16x16x128_f8f6f4 v[216:219], v[136:139], v[144:151], v[216:219], v240, v241 op_sel_hi:[0,0,0] cbsz:4
	v_fmac_f32_e32 v192, v253, v253
	v_fmac_f32_e32 v193, v255, v255
	v_cvt_pk_bf16_f32 v250, v252, v253
	v_and_b32_e32 v144, v188, v235
	v_and_b32_e32 v145, v188, v236
	v_and_b32_e32 v146, v188, v237
	v_and_b32_e32 v147, v188, v238
	v_and_b32_e32 v148, v189, v235
	v_and_b32_e32 v149, v189, v236
	v_and_b32_e32 v150, v189, v237
	v_and_b32_e32 v151, v189, v238
	s_mov_b64 vcc, s[4:5]
	v_cndmask_b32_dpp v138, v120, v122, vcc row_shl:4 row_mask:0xf bank_mask:0xf bound_ctrl:1
	v_cndmask_b32_dpp v139, v121, v123, vcc row_shl:4 row_mask:0xf bank_mask:0xf bound_ctrl:1
	s_mov_b64 vcc, s[6:7]
	v_cndmask_b32_dpp v136, v122, v120, vcc row_shr:4 row_mask:0xf bank_mask:0xf bound_ctrl:1
	v_cndmask_b32_dpp v137, v123, v121, vcc row_shr:4 row_mask:0xf bank_mask:0xf bound_ctrl:1
	v_mfma_scale_f32_16x16x128_f8f6f4 v[216:219], v[140:143], v[204:211], v[216:219], v240, v241 op_sel_hi:[0,0,0] cbsz:4
	v_cvt_pk_bf16_f32 v251, v254, v255
	v_add_f32_e32 v192, v192, v193
	v_add_f32_e32 v222, v222, v192
	v_and_b32_e32 v204, v190, v235
	v_and_b32_e32 v205, v190, v236
	v_and_b32_e32 v206, v190, v237
	v_and_b32_e32 v207, v190, v238
	v_and_b32_e32 v208, v191, v235
	v_and_b32_e32 v209, v191, v236
	v_and_b32_e32 v210, v191, v237
	v_and_b32_e32 v211, v191, v238
	s_mov_b64 vcc, s[6:7]
	v_cndmask_b32_dpp v140, v126, v124, vcc row_shr:4 row_mask:0xf bank_mask:0xf bound_ctrl:1
	v_cndmask_b32_dpp v141, v127, v125, vcc row_shr:4 row_mask:0xf bank_mask:0xf bound_ctrl:1
	s_mov_b64 vcc, s[4:5]
	v_cndmask_b32_dpp v142, v124, v126, vcc row_shl:4 row_mask:0xf bank_mask:0xf bound_ctrl:1
	v_cndmask_b32_dpp v143, v125, v127, vcc row_shl:4 row_mask:0xf bank_mask:0xf bound_ctrl:1
	v_mfma_scale_f32_16x16x128_f8f6f4 v[216:219], v[136:139], v[144:151], v[216:219], v240, v241 op_sel_hi:[0,0,0] cbsz:4
	s_nop 0
	v_mfma_scale_f32_16x16x128_f8f6f4 v[216:219], v[140:143], v[204:211], v[216:219], v240, v241 op_sel_hi:[0,0,0] cbsz:4
	s_lshl_b32 s64, s0, 9
	s_add_u32 s64, s64, 0x2000
	s_add_u32 s76, s28, s64
	s_addc_u32 s77, s29, 0
	global_store_dwordx2 v239, v[250:251], s[76:77]
	s_lshl_b32 s64, s0, 9
	s_add_u32 s64, s64, 0x4000
	s_add_u32 s70, s28, s64
	s_addc_u32 s71, s29, 0
	global_load_dwordx2 v[228:229], v239, s[70:71]
	s_waitcnt lgkmcnt(0)
	v_lshl_or_b32 v128, v128, 7, v232
	v_lshl_or_b32 v129, v129, 7, v232
	v_lshl_or_b32 v130, v130, 7, v232
	v_lshl_or_b32 v131, v131, 7, v232
	v_lshl_or_b32 v132, v132, 7, v232
	v_lshl_or_b32 v133, v133, 7, v232
	v_lshl_or_b32 v134, v134, 7, v232
	v_lshl_or_b32 v135, v135, 7, v232
	buffer_load_dwordx4 v[96:99], v128, s[20:23], s1 offen
	buffer_load_dwordx4 v[100:103], v129, s[20:23], s1 offen
	buffer_load_dwordx4 v[104:107], v130, s[20:23], s1 offen
	buffer_load_dwordx4 v[108:111], v131, s[20:23], s1 offen
	buffer_load_dwordx4 v[112:115], v132, s[20:23], s1 offen
	buffer_load_dwordx4 v[116:119], v133, s[20:23], s1 offen
	buffer_load_dwordx4 v[120:123], v134, s[20:23], s1 offen
	buffer_load_dwordx4 v[124:127], v135, s[20:23], s1 offen
	ds_read_b32 v128, v243 offset:3072
	ds_read_b32 v129, v243 offset:3104
	ds_read_b32 v130, v243 offset:3136
	ds_read_b32 v131, v243 offset:3168
	ds_read_b32 v132, v243 offset:3200
	ds_read_b32 v133, v243 offset:3232
	ds_read_b32 v134, v243 offset:3264
	ds_read_b32 v135, v243 offset:3296
	ds_read_b64 v[176:177], v234 offset:2304
	ds_read_b64 v[178:179], v234 offset:2336
	ds_read_b64 v[180:181], v234 offset:2368
	ds_read_b64 v[182:183], v234 offset:2400
	ds_read_b64 v[184:185], v234 offset:2432
	ds_read_b64 v[186:187], v234 offset:2464
	ds_read_b64 v[188:189], v234 offset:2496
	ds_read_b64 v[190:191], v234 offset:2528
	s_waitcnt vmcnt(28)
	v_and_b32_e32 v144, v160, v235
	v_and_b32_e32 v145, v160, v236
	v_and_b32_e32 v146, v160, v237
	v_and_b32_e32 v147, v160, v238
	v_and_b32_e32 v148, v161, v235
	v_and_b32_e32 v149, v161, v236
	v_and_b32_e32 v150, v161, v237
	v_and_b32_e32 v151, v161, v238
	s_mov_b64 vcc, s[4:5]
	v_cndmask_b32_dpp v138, v0, v2, vcc row_shl:4 row_mask:0xf bank_mask:0xf bound_ctrl:1
	v_cndmask_b32_dpp v139, v1, v3, vcc row_shl:4 row_mask:0xf bank_mask:0xf bound_ctrl:1
	s_mov_b64 vcc, s[6:7]
	v_cndmask_b32_dpp v136, v2, v0, vcc row_shr:4 row_mask:0xf bank_mask:0xf bound_ctrl:1
	v_cndmask_b32_dpp v137, v3, v1, vcc row_shr:4 row_mask:0xf bank_mask:0xf bound_ctrl:1
	v_and_b32_e32 v204, v162, v235
	v_and_b32_e32 v205, v162, v236
	v_and_b32_e32 v206, v162, v237
	v_and_b32_e32 v207, v162, v238
	v_and_b32_e32 v208, v163, v235
	v_and_b32_e32 v209, v163, v236
	v_and_b32_e32 v210, v163, v237
	v_and_b32_e32 v211, v163, v238
	s_mov_b64 vcc, s[6:7]
	v_cndmask_b32_dpp v140, v6, v4, vcc row_shr:4 row_mask:0xf bank_mask:0xf bound_ctrl:1
	v_cndmask_b32_dpp v141, v7, v5, vcc row_shr:4 row_mask:0xf bank_mask:0xf bound_ctrl:1
	s_mov_b64 vcc, s[4:5]
	v_cndmask_b32_dpp v142, v4, v6, vcc row_shl:4 row_mask:0xf bank_mask:0xf bound_ctrl:1
	v_cndmask_b32_dpp v143, v5, v7, vcc row_shl:4 row_mask:0xf bank_mask:0xf bound_ctrl:1
	v_mfma_scale_f32_16x16x128_f8f6f4 v[212:215], v[136:139], v[144:151], 0, v240, v241 op_sel_hi:[0,0,0] cbsz:4
	v_and_b32_e32 v144, v164, v235
	v_and_b32_e32 v145, v164, v236
	v_and_b32_e32 v146, v164, v237
	v_and_b32_e32 v147, v164, v238
	v_and_b32_e32 v148, v165, v235
	v_and_b32_e32 v149, v165, v236
	v_and_b32_e32 v150, v165, v237
	v_and_b32_e32 v151, v165, v238
	s_mov_b64 vcc, s[4:5]
	v_cndmask_b32_dpp v138, v8, v10, vcc row_shl:4 row_mask:0xf bank_mask:0xf bound_ctrl:1
	v_cndmask_b32_dpp v139, v9, v11, vcc row_shl:4 row_mask:0xf bank_mask:0xf bound_ctrl:1
	s_mov_b64 vcc, s[6:7]
	v_cndmask_b32_dpp v136, v10, v8, vcc row_shr:4 row_mask:0xf bank_mask:0xf bound_ctrl:1
	v_cndmask_b32_dpp v137, v11, v9, vcc row_shr:4 row_mask:0xf bank_mask:0xf bound_ctrl:1
	v_mfma_scale_f32_16x16x128_f8f6f4 v[212:215], v[140:143], v[204:211], v[212:215], v240, v241 op_sel_hi:[0,0,0] cbsz:4
	v_and_b32_e32 v204, v166, v235
	v_and_b32_e32 v205, v166, v236
	v_and_b32_e32 v206, v166, v237
	v_and_b32_e32 v207, v166, v238
	v_and_b32_e32 v208, v167, v235
	v_and_b32_e32 v209, v167, v236
	v_and_b32_e32 v210, v167, v237
	v_and_b32_e32 v211, v167, v238
	s_mov_b64 vcc, s[6:7]
	v_cndmask_b32_dpp v140, v14, v12, vcc row_shr:4 row_mask:0xf bank_mask:0xf bound_ctrl:1
	v_cndmask_b32_dpp v141, v15, v13, vcc row_shr:4 row_mask:0xf bank_mask:0xf bound_ctrl:1
	s_mov_b64 vcc, s[4:5]
	v_cndmask_b32_dpp v142, v12, v14, vcc row_shl:4 row_mask:0xf bank_mask:0xf bound_ctrl:1
	v_cndmask_b32_dpp v143, v13, v15, vcc row_shl:4 row_mask:0xf bank_mask:0xf bound_ctrl:1
	v_mfma_scale_f32_16x16x128_f8f6f4 v[212:215], v[136:139], v[144:151], v[212:215], v240, v241 op_sel_hi:[0,0,0] cbsz:4
	v_and_b32_e32 v144, v168, v235
	v_and_b32_e32 v145, v168, v236
	v_and_b32_e32 v146, v168, v237
	v_and_b32_e32 v147, v168, v238
	v_and_b32_e32 v148, v169, v235
	v_and_b32_e32 v149, v169, v236
	v_and_b32_e32 v150, v169, v237
	v_and_b32_e32 v151, v169, v238
	s_mov_b64 vcc, s[4:5]
	v_cndmask_b32_dpp v138, v16, v18, vcc row_shl:4 row_mask:0xf bank_mask:0xf bound_ctrl:1
	v_cndmask_b32_dpp v139, v17, v19, vcc row_shl:4 row_mask:0xf bank_mask:0xf bound_ctrl:1
	s_mov_b64 vcc, s[6:7]
	v_cndmask_b32_dpp v136, v18, v16, vcc row_shr:4 row_mask:0xf bank_mask:0xf bound_ctrl:1
	v_cndmask_b32_dpp v137, v19, v17, vcc row_shr:4 row_mask:0xf bank_mask:0xf bound_ctrl:1
	v_mfma_scale_f32_16x16x128_f8f6f4 v[212:215], v[140:143], v[204:211], v[212:215], v240, v241 op_sel_hi:[0,0,0] cbsz:4
	v_and_b32_e32 v204, v170, v235
	v_and_b32_e32 v205, v170, v236
	v_and_b32_e32 v206, v170, v237
	v_and_b32_e32 v207, v170, v238
	v_and_b32_e32 v208, v171, v235
	v_and_b32_e32 v209, v171, v236
	v_and_b32_e32 v210, v171, v237
	v_and_b32_e32 v211, v171, v238
	s_mov_b64 vcc, s[6:7]
	v_cndmask_b32_dpp v140, v22, v20, vcc row_shr:4 row_mask:0xf bank_mask:0xf bound_ctrl:1
	v_cndmask_b32_dpp v141, v23, v21, vcc row_shr:4 row_mask:0xf bank_mask:0xf bound_ctrl:1
	s_mov_b64 vcc, s[4:5]
	v_cndmask_b32_dpp v142, v20, v22, vcc row_shl:4 row_mask:0xf bank_mask:0xf bound_ctrl:1
	v_cndmask_b32_dpp v143, v21, v23, vcc row_shl:4 row_mask:0xf bank_mask:0xf bound_ctrl:1
	v_mfma_scale_f32_16x16x128_f8f6f4 v[212:215], v[136:139], v[144:151], v[212:215], v240, v241 op_sel_hi:[0,0,0] cbsz:4
	v_and_b32_e32 v144, v172, v235
	v_and_b32_e32 v145, v172, v236
	v_and_b32_e32 v146, v172, v237
	v_and_b32_e32 v147, v172, v238
	v_and_b32_e32 v148, v173, v235
	v_and_b32_e32 v149, v173, v236
	v_and_b32_e32 v150, v173, v237
	v_and_b32_e32 v151, v173, v238
	s_mov_b64 vcc, s[4:5]
	v_cndmask_b32_dpp v138, v24, v26, vcc row_shl:4 row_mask:0xf bank_mask:0xf bound_ctrl:1
	v_cndmask_b32_dpp v139, v25, v27, vcc row_shl:4 row_mask:0xf bank_mask:0xf bound_ctrl:1
	s_mov_b64 vcc, s[6:7]
	v_cndmask_b32_dpp v136, v26, v24, vcc row_shr:4 row_mask:0xf bank_mask:0xf bound_ctrl:1
	v_cndmask_b32_dpp v137, v27, v25, vcc row_shr:4 row_mask:0xf bank_mask:0xf bound_ctrl:1
	v_mfma_scale_f32_16x16x128_f8f6f4 v[212:215], v[140:143], v[204:211], v[212:215], v240, v241 op_sel_hi:[0,0,0] cbsz:4
	v_and_b32_e32 v204, v174, v235
	v_and_b32_e32 v205, v174, v236
	v_and_b32_e32 v206, v174, v237
	v_and_b32_e32 v207, v174, v238
	v_and_b32_e32 v208, v175, v235
	v_and_b32_e32 v209, v175, v236
	v_and_b32_e32 v210, v175, v237
	v_and_b32_e32 v211, v175, v238
	s_mov_b64 vcc, s[6:7]
	v_cndmask_b32_dpp v140, v30, v28, vcc row_shr:4 row_mask:0xf bank_mask:0xf bound_ctrl:1
	v_cndmask_b32_dpp v141, v31, v29, vcc row_shr:4 row_mask:0xf bank_mask:0xf bound_ctrl:1
	s_mov_b64 vcc, s[4:5]
	v_cndmask_b32_dpp v142, v28, v30, vcc row_shl:4 row_mask:0xf bank_mask:0xf bound_ctrl:1
	v_cndmask_b32_dpp v143, v29, v31, vcc row_shl:4 row_mask:0xf bank_mask:0xf bound_ctrl:1
	v_mfma_scale_f32_16x16x128_f8f6f4 v[212:215], v[136:139], v[144:151], v[212:215], v240, v241 op_sel_hi:[0,0,0] cbsz:4
	s_nop 0
	v_mfma_scale_f32_16x16x128_f8f6f4 v[212:215], v[140:143], v[204:211], v[212:215], v240, v241 op_sel_hi:[0,0,0] cbsz:4
	s_waitcnt lgkmcnt(0)
	v_lshl_or_b32 v128, v128, 7, v232
	v_lshl_or_b32 v129, v129, 7, v232
	v_lshl_or_b32 v130, v130, 7, v232
	v_lshl_or_b32 v131, v131, 7, v232
	v_lshl_or_b32 v132, v132, 7, v232
	v_lshl_or_b32 v133, v133, 7, v232
	v_lshl_or_b32 v134, v134, 7, v232
	v_lshl_or_b32 v135, v135, 7, v232
	buffer_load_dwordx4 v[0:3], v128, s[20:23], s1 offen
	buffer_load_dwordx4 v[4:7], v129, s[20:23], s1 offen
	buffer_load_dwordx4 v[8:11], v130, s[20:23], s1 offen
	buffer_load_dwordx4 v[12:15], v131, s[20:23], s1 offen
	buffer_load_dwordx4 v[16:19], v132, s[20:23], s1 offen
	buffer_load_dwordx4 v[20:23], v133, s[20:23], s1 offen
	buffer_load_dwordx4 v[24:27], v134, s[20:23], s1 offen
	buffer_load_dwordx4 v[28:31], v135, s[20:23], s1 offen
	ds_read_b32 v128, v243 offset:3328
	ds_read_b32 v129, v243 offset:3360
	ds_read_b32 v130, v243 offset:3392
	ds_read_b32 v131, v243 offset:3424
	ds_read_b32 v132, v243 offset:3456
	ds_read_b32 v133, v243 offset:3488
	ds_read_b32 v134, v243 offset:3520
	ds_read_b32 v135, v243 offset:3552
	ds_read_b64 v[160:161], v234 offset:2560
	ds_read_b64 v[162:163], v234 offset:2592
	ds_read_b64 v[164:165], v234 offset:2624
	ds_read_b64 v[166:167], v234 offset:2656
	ds_read_b64 v[168:169], v234 offset:2688
	ds_read_b64 v[170:171], v234 offset:2720
	ds_read_b64 v[172:173], v234 offset:2752
	ds_read_b64 v[174:175], v234 offset:2784
	s_waitcnt vmcnt(26)
	v_and_b32_e32 v144, v176, v235
	v_and_b32_e32 v145, v176, v236
	v_and_b32_e32 v146, v176, v237
	v_and_b32_e32 v147, v176, v238
	v_and_b32_e32 v148, v177, v235
	v_and_b32_e32 v149, v177, v236
	v_and_b32_e32 v150, v177, v237
	v_and_b32_e32 v151, v177, v238
	s_mov_b64 vcc, s[4:5]
	v_cndmask_b32_dpp v138, v32, v34, vcc row_shl:4 row_mask:0xf bank_mask:0xf bound_ctrl:1
	v_cndmask_b32_dpp v139, v33, v35, vcc row_shl:4 row_mask:0xf bank_mask:0xf bound_ctrl:1
	s_mov_b64 vcc, s[6:7]
	v_cndmask_b32_dpp v136, v34, v32, vcc row_shr:4 row_mask:0xf bank_mask:0xf bound_ctrl:1
	v_cndmask_b32_dpp v137, v35, v33, vcc row_shr:4 row_mask:0xf bank_mask:0xf bound_ctrl:1
	v_and_b32_e32 v204, v178, v235
	v_and_b32_e32 v205, v178, v236
	v_and_b32_e32 v206, v178, v237
	v_and_b32_e32 v207, v178, v238
	v_and_b32_e32 v208, v179, v235
	v_and_b32_e32 v209, v179, v236
	v_and_b32_e32 v210, v179, v237
	v_and_b32_e32 v211, v179, v238
	s_mov_b64 vcc, s[6:7]
	v_cndmask_b32_dpp v140, v38, v36, vcc row_shr:4 row_mask:0xf bank_mask:0xf bound_ctrl:1
	v_cndmask_b32_dpp v141, v39, v37, vcc row_shr:4 row_mask:0xf bank_mask:0xf bound_ctrl:1
	s_mov_b64 vcc, s[4:5]
	v_cndmask_b32_dpp v142, v36, v38, vcc row_shl:4 row_mask:0xf bank_mask:0xf bound_ctrl:1
	v_cndmask_b32_dpp v143, v37, v39, vcc row_shl:4 row_mask:0xf bank_mask:0xf bound_ctrl:1
	v_mfma_scale_f32_16x16x128_f8f6f4 v[212:215], v[136:139], v[144:151], v[212:215], v240, v241 op_sel_hi:[0,0,0] cbsz:4
	v_permlane16_swap_b32_e32 v216, v218
	v_permlane16_swap_b32_e32 v217, v219
	v_lshlrev_b32_e32 v252, 16, v230
	v_and_b32_e32 v144, v180, v235
	v_and_b32_e32 v145, v180, v236
	v_and_b32_e32 v146, v180, v237
	v_and_b32_e32 v147, v180, v238
	v_and_b32_e32 v148, v181, v235
	v_and_b32_e32 v149, v181, v236
	v_and_b32_e32 v150, v181, v237
	v_and_b32_e32 v151, v181, v238
	s_mov_b64 vcc, s[4:5]
	v_cndmask_b32_dpp v138, v40, v42, vcc row_shl:4 row_mask:0xf bank_mask:0xf bound_ctrl:1
	v_cndmask_b32_dpp v139, v41, v43, vcc row_shl:4 row_mask:0xf bank_mask:0xf bound_ctrl:1
	s_mov_b64 vcc, s[6:7]
	v_cndmask_b32_dpp v136, v42, v40, vcc row_shr:4 row_mask:0xf bank_mask:0xf bound_ctrl:1
	v_cndmask_b32_dpp v137, v43, v41, vcc row_shr:4 row_mask:0xf bank_mask:0xf bound_ctrl:1
	v_mfma_scale_f32_16x16x128_f8f6f4 v[212:215], v[140:143], v[204:211], v[212:215], v240, v241 op_sel_hi:[0,0,0] cbsz:4
	v_and_b32_e32 v253, 0xffff0000, v230
	v_lshlrev_b32_e32 v254, 16, v231
	v_and_b32_e32 v255, 0xffff0000, v231
	v_and_b32_e32 v204, v182, v235
	v_and_b32_e32 v205, v182, v236
	v_and_b32_e32 v206, v182, v237
	v_and_b32_e32 v207, v182, v238
	v_and_b32_e32 v208, v183, v235
	v_and_b32_e32 v209, v183, v236
	v_and_b32_e32 v210, v183, v237
	v_and_b32_e32 v211, v183, v238
	s_mov_b64 vcc, s[6:7]
	v_cndmask_b32_dpp v140, v46, v44, vcc row_shr:4 row_mask:0xf bank_mask:0xf bound_ctrl:1
	v_cndmask_b32_dpp v141, v47, v45, vcc row_shr:4 row_mask:0xf bank_mask:0xf bound_ctrl:1
	s_mov_b64 vcc, s[4:5]
	v_cndmask_b32_dpp v142, v44, v46, vcc row_shl:4 row_mask:0xf bank_mask:0xf bound_ctrl:1
	v_cndmask_b32_dpp v143, v45, v47, vcc row_shl:4 row_mask:0xf bank_mask:0xf bound_ctrl:1
	v_mfma_scale_f32_16x16x128_f8f6f4 v[212:215], v[136:139], v[144:151], v[212:215], v240, v241 op_sel_hi:[0,0,0] cbsz:4
	v_add_f32_e32 v252, v216, v252
	v_add_f32_e32 v253, v218, v253
	v_add_f32_e32 v254, v217, v254
	v_and_b32_e32 v144, v184, v235
	v_and_b32_e32 v145, v184, v236
	v_and_b32_e32 v146, v184, v237
	v_and_b32_e32 v147, v184, v238
	v_and_b32_e32 v148, v185, v235
	v_and_b32_e32 v149, v185, v236
	v_and_b32_e32 v150, v185, v237
	v_and_b32_e32 v151, v185, v238
	s_mov_b64 vcc, s[4:5]
	v_cndmask_b32_dpp v138, v48, v50, vcc row_shl:4 row_mask:0xf bank_mask:0xf bound_ctrl:1
	v_cndmask_b32_dpp v139, v49, v51, vcc row_shl:4 row_mask:0xf bank_mask:0xf bound_ctrl:1
	s_mov_b64 vcc, s[6:7]
	v_cndmask_b32_dpp v136, v50, v48, vcc row_shr:4 row_mask:0xf bank_mask:0xf bound_ctrl:1
	v_cndmask_b32_dpp v137, v51, v49, vcc row_shr:4 row_mask:0xf bank_mask:0xf bound_ctrl:1
	v_mfma_scale_f32_16x16x128_f8f6f4 v[212:215], v[140:143], v[204:211], v[212:215], v240, v241 op_sel_hi:[0,0,0] cbsz:4
	v_add_f32_e32 v255, v219, v255
	v_mul_f32_e32 v192, v252, v252
	v_mul_f32_e32 v193, v254, v254
	v_and_b32_e32 v204, v186, v235
	v_and_b32_e32 v205, v186, v236
	v_and_b32_e32 v206, v186, v237
	v_and_b32_e32 v207, v186, v238
	v_and_b32_e32 v208, v187, v235
	v_and_b32_e32 v209, v187, v236
	v_and_b32_e32 v210, v187, v237
	v_and_b32_e32 v211, v187, v238
	s_mov_b64 vcc, s[6:7]
	v_cndmask_b32_dpp v140, v54, v52, vcc row_shr:4 row_mask:0xf bank_mask:0xf bound_ctrl:1
	v_cndmask_b32_dpp v141, v55, v53, vcc row_shr:4 row_mask:0xf bank_mask:0xf bound_ctrl:1
	s_mov_b64 vcc, s[4:5]
	v_cndmask_b32_dpp v142, v52, v54, vcc row_shl:4 row_mask:0xf bank_mask:0xf bound_ctrl:1
	v_cndmask_b32_dpp v143, v53, v55, vcc row_shl:4 row_mask:0xf bank_mask:0xf bound_ctrl:1
	v_mfma_scale_f32_16x16x128_f8f6f4 v[212:215], v[136:139], v[144:151], v[212:215], v240, v241 op_sel_hi:[0,0,0] cbsz:4
	v_fmac_f32_e32 v192, v253, v253
	v_fmac_f32_e32 v193, v255, v255
	v_cvt_pk_bf16_f32 v250, v252, v253
	v_and_b32_e32 v144, v188, v235
	v_and_b32_e32 v145, v188, v236
	v_and_b32_e32 v146, v188, v237
	v_and_b32_e32 v147, v188, v238
	v_and_b32_e32 v148, v189, v235
	v_and_b32_e32 v149, v189, v236
	v_and_b32_e32 v150, v189, v237
	v_and_b32_e32 v151, v189, v238
	s_mov_b64 vcc, s[4:5]
	v_cndmask_b32_dpp v138, v56, v58, vcc row_shl:4 row_mask:0xf bank_mask:0xf bound_ctrl:1
	v_cndmask_b32_dpp v139, v57, v59, vcc row_shl:4 row_mask:0xf bank_mask:0xf bound_ctrl:1
	s_mov_b64 vcc, s[6:7]
	v_cndmask_b32_dpp v136, v58, v56, vcc row_shr:4 row_mask:0xf bank_mask:0xf bound_ctrl:1
	v_cndmask_b32_dpp v137, v59, v57, vcc row_shr:4 row_mask:0xf bank_mask:0xf bound_ctrl:1
	v_mfma_scale_f32_16x16x128_f8f6f4 v[212:215], v[140:143], v[204:211], v[212:215], v240, v241 op_sel_hi:[0,0,0] cbsz:4
	v_cvt_pk_bf16_f32 v251, v254, v255
	v_add_f32_e32 v192, v192, v193
	v_add_f32_e32 v223, v223, v192
	v_and_b32_e32 v204, v190, v235
	v_and_b32_e32 v205, v190, v236
	v_and_b32_e32 v206, v190, v237
	v_and_b32_e32 v207, v190, v238
	v_and_b32_e32 v208, v191, v235
	v_and_b32_e32 v209, v191, v236
	v_and_b32_e32 v210, v191, v237
	v_and_b32_e32 v211, v191, v238
	s_mov_b64 vcc, s[6:7]
	v_cndmask_b32_dpp v140, v62, v60, vcc row_shr:4 row_mask:0xf bank_mask:0xf bound_ctrl:1
	v_cndmask_b32_dpp v141, v63, v61, vcc row_shr:4 row_mask:0xf bank_mask:0xf bound_ctrl:1
	s_mov_b64 vcc, s[4:5]
	v_cndmask_b32_dpp v142, v60, v62, vcc row_shl:4 row_mask:0xf bank_mask:0xf bound_ctrl:1
	v_cndmask_b32_dpp v143, v61, v63, vcc row_shl:4 row_mask:0xf bank_mask:0xf bound_ctrl:1
	v_mfma_scale_f32_16x16x128_f8f6f4 v[212:215], v[136:139], v[144:151], v[212:215], v240, v241 op_sel_hi:[0,0,0] cbsz:4
	s_nop 0
	v_mfma_scale_f32_16x16x128_f8f6f4 v[212:215], v[140:143], v[204:211], v[212:215], v240, v241 op_sel_hi:[0,0,0] cbsz:4
	s_lshl_b32 s64, s0, 9
	s_add_u32 s64, s64, 0x3000
	s_add_u32 s76, s28, s64
	s_addc_u32 s77, s29, 0
	global_store_dwordx2 v239, v[250:251], s[76:77]
	s_lshl_b32 s64, s0, 9
	s_add_u32 s64, s64, 0x5000
	s_add_u32 s70, s28, s64
	s_addc_u32 s71, s29, 0
	global_load_dwordx2 v[230:231], v239, s[70:71]
	s_waitcnt lgkmcnt(0)
	v_lshl_or_b32 v128, v128, 7, v232
	v_lshl_or_b32 v129, v129, 7, v232
	v_lshl_or_b32 v130, v130, 7, v232
	v_lshl_or_b32 v131, v131, 7, v232
	v_lshl_or_b32 v132, v132, 7, v232
	v_lshl_or_b32 v133, v133, 7, v232
	v_lshl_or_b32 v134, v134, 7, v232
	v_lshl_or_b32 v135, v135, 7, v232
	buffer_load_dwordx4 v[32:35], v128, s[20:23], s1 offen
	buffer_load_dwordx4 v[36:39], v129, s[20:23], s1 offen
	buffer_load_dwordx4 v[40:43], v130, s[20:23], s1 offen
	buffer_load_dwordx4 v[44:47], v131, s[20:23], s1 offen
	buffer_load_dwordx4 v[48:51], v132, s[20:23], s1 offen
	buffer_load_dwordx4 v[52:55], v133, s[20:23], s1 offen
	buffer_load_dwordx4 v[56:59], v134, s[20:23], s1 offen
	buffer_load_dwordx4 v[60:63], v135, s[20:23], s1 offen
	ds_read_b32 v128, v243 offset:3584
	ds_read_b32 v129, v243 offset:3616
	ds_read_b32 v130, v243 offset:3648
	ds_read_b32 v131, v243 offset:3680
	ds_read_b32 v132, v243 offset:3712
	ds_read_b32 v133, v243 offset:3744
	ds_read_b32 v134, v243 offset:3776
	ds_read_b32 v135, v243 offset:3808
	ds_read_b64 v[176:177], v234 offset:2816
	ds_read_b64 v[178:179], v234 offset:2848
	ds_read_b64 v[180:181], v234 offset:2880
	ds_read_b64 v[182:183], v234 offset:2912
	ds_read_b64 v[184:185], v234 offset:2944
	ds_read_b64 v[186:187], v234 offset:2976
	ds_read_b64 v[188:189], v234 offset:3008
	ds_read_b64 v[190:191], v234 offset:3040
	s_waitcnt vmcnt(28)
	v_and_b32_e32 v144, v160, v235
	v_and_b32_e32 v145, v160, v236
	v_and_b32_e32 v146, v160, v237
	v_and_b32_e32 v147, v160, v238
	v_and_b32_e32 v148, v161, v235
	v_and_b32_e32 v149, v161, v236
	v_and_b32_e32 v150, v161, v237
	v_and_b32_e32 v151, v161, v238
	s_mov_b64 vcc, s[4:5]
	v_cndmask_b32_dpp v138, v64, v66, vcc row_shl:4 row_mask:0xf bank_mask:0xf bound_ctrl:1
	v_cndmask_b32_dpp v139, v65, v67, vcc row_shl:4 row_mask:0xf bank_mask:0xf bound_ctrl:1
	s_mov_b64 vcc, s[6:7]
	v_cndmask_b32_dpp v136, v66, v64, vcc row_shr:4 row_mask:0xf bank_mask:0xf bound_ctrl:1
	v_cndmask_b32_dpp v137, v67, v65, vcc row_shr:4 row_mask:0xf bank_mask:0xf bound_ctrl:1
	v_and_b32_e32 v204, v162, v235
	v_and_b32_e32 v205, v162, v236
	v_and_b32_e32 v206, v162, v237
	v_and_b32_e32 v207, v162, v238
	v_and_b32_e32 v208, v163, v235
	v_and_b32_e32 v209, v163, v236
	v_and_b32_e32 v210, v163, v237
	v_and_b32_e32 v211, v163, v238
	s_mov_b64 vcc, s[6:7]
	v_cndmask_b32_dpp v140, v70, v68, vcc row_shr:4 row_mask:0xf bank_mask:0xf bound_ctrl:1
	v_cndmask_b32_dpp v141, v71, v69, vcc row_shr:4 row_mask:0xf bank_mask:0xf bound_ctrl:1
	s_mov_b64 vcc, s[4:5]
	v_cndmask_b32_dpp v142, v68, v70, vcc row_shl:4 row_mask:0xf bank_mask:0xf bound_ctrl:1
	v_cndmask_b32_dpp v143, v69, v71, vcc row_shl:4 row_mask:0xf bank_mask:0xf bound_ctrl:1
	v_mfma_scale_f32_16x16x128_f8f6f4 v[216:219], v[136:139], v[144:151], 0, v240, v241 op_sel_hi:[0,0,0] cbsz:4
	v_and_b32_e32 v144, v164, v235
	v_and_b32_e32 v145, v164, v236
	v_and_b32_e32 v146, v164, v237
	v_and_b32_e32 v147, v164, v238
	v_and_b32_e32 v148, v165, v235
	v_and_b32_e32 v149, v165, v236
	v_and_b32_e32 v150, v165, v237
	v_and_b32_e32 v151, v165, v238
	s_mov_b64 vcc, s[4:5]
	v_cndmask_b32_dpp v138, v72, v74, vcc row_shl:4 row_mask:0xf bank_mask:0xf bound_ctrl:1
	v_cndmask_b32_dpp v139, v73, v75, vcc row_shl:4 row_mask:0xf bank_mask:0xf bound_ctrl:1
	s_mov_b64 vcc, s[6:7]
	v_cndmask_b32_dpp v136, v74, v72, vcc row_shr:4 row_mask:0xf bank_mask:0xf bound_ctrl:1
	v_cndmask_b32_dpp v137, v75, v73, vcc row_shr:4 row_mask:0xf bank_mask:0xf bound_ctrl:1
	v_mfma_scale_f32_16x16x128_f8f6f4 v[216:219], v[140:143], v[204:211], v[216:219], v240, v241 op_sel_hi:[0,0,0] cbsz:4
	v_and_b32_e32 v204, v166, v235
	v_and_b32_e32 v205, v166, v236
	v_and_b32_e32 v206, v166, v237
	v_and_b32_e32 v207, v166, v238
	v_and_b32_e32 v208, v167, v235
	v_and_b32_e32 v209, v167, v236
	v_and_b32_e32 v210, v167, v237
	v_and_b32_e32 v211, v167, v238
	s_mov_b64 vcc, s[6:7]
	v_cndmask_b32_dpp v140, v78, v76, vcc row_shr:4 row_mask:0xf bank_mask:0xf bound_ctrl:1
	v_cndmask_b32_dpp v141, v79, v77, vcc row_shr:4 row_mask:0xf bank_mask:0xf bound_ctrl:1
	s_mov_b64 vcc, s[4:5]
	v_cndmask_b32_dpp v142, v76, v78, vcc row_shl:4 row_mask:0xf bank_mask:0xf bound_ctrl:1
	v_cndmask_b32_dpp v143, v77, v79, vcc row_shl:4 row_mask:0xf bank_mask:0xf bound_ctrl:1
	v_mfma_scale_f32_16x16x128_f8f6f4 v[216:219], v[136:139], v[144:151], v[216:219], v240, v241 op_sel_hi:[0,0,0] cbsz:4
	v_and_b32_e32 v144, v168, v235
	v_and_b32_e32 v145, v168, v236
	v_and_b32_e32 v146, v168, v237
	v_and_b32_e32 v147, v168, v238
	v_and_b32_e32 v148, v169, v235
	v_and_b32_e32 v149, v169, v236
	v_and_b32_e32 v150, v169, v237
	v_and_b32_e32 v151, v169, v238
	s_mov_b64 vcc, s[4:5]
	v_cndmask_b32_dpp v138, v80, v82, vcc row_shl:4 row_mask:0xf bank_mask:0xf bound_ctrl:1
	v_cndmask_b32_dpp v139, v81, v83, vcc row_shl:4 row_mask:0xf bank_mask:0xf bound_ctrl:1
	s_mov_b64 vcc, s[6:7]
	v_cndmask_b32_dpp v136, v82, v80, vcc row_shr:4 row_mask:0xf bank_mask:0xf bound_ctrl:1
	v_cndmask_b32_dpp v137, v83, v81, vcc row_shr:4 row_mask:0xf bank_mask:0xf bound_ctrl:1
	v_mfma_scale_f32_16x16x128_f8f6f4 v[216:219], v[140:143], v[204:211], v[216:219], v240, v241 op_sel_hi:[0,0,0] cbsz:4
	v_and_b32_e32 v204, v170, v235
	v_and_b32_e32 v205, v170, v236
	v_and_b32_e32 v206, v170, v237
	v_and_b32_e32 v207, v170, v238
	v_and_b32_e32 v208, v171, v235
	v_and_b32_e32 v209, v171, v236
	v_and_b32_e32 v210, v171, v237
	v_and_b32_e32 v211, v171, v238
	s_mov_b64 vcc, s[6:7]
	v_cndmask_b32_dpp v140, v86, v84, vcc row_shr:4 row_mask:0xf bank_mask:0xf bound_ctrl:1
	v_cndmask_b32_dpp v141, v87, v85, vcc row_shr:4 row_mask:0xf bank_mask:0xf bound_ctrl:1
	s_mov_b64 vcc, s[4:5]
	v_cndmask_b32_dpp v142, v84, v86, vcc row_shl:4 row_mask:0xf bank_mask:0xf bound_ctrl:1
	v_cndmask_b32_dpp v143, v85, v87, vcc row_shl:4 row_mask:0xf bank_mask:0xf bound_ctrl:1
	v_mfma_scale_f32_16x16x128_f8f6f4 v[216:219], v[136:139], v[144:151], v[216:219], v240, v241 op_sel_hi:[0,0,0] cbsz:4
	v_and_b32_e32 v144, v172, v235
	v_and_b32_e32 v145, v172, v236
	v_and_b32_e32 v146, v172, v237
	v_and_b32_e32 v147, v172, v238
	v_and_b32_e32 v148, v173, v235
	v_and_b32_e32 v149, v173, v236
	v_and_b32_e32 v150, v173, v237
	v_and_b32_e32 v151, v173, v238
	s_mov_b64 vcc, s[4:5]
	v_cndmask_b32_dpp v138, v88, v90, vcc row_shl:4 row_mask:0xf bank_mask:0xf bound_ctrl:1
	v_cndmask_b32_dpp v139, v89, v91, vcc row_shl:4 row_mask:0xf bank_mask:0xf bound_ctrl:1
	s_mov_b64 vcc, s[6:7]
	v_cndmask_b32_dpp v136, v90, v88, vcc row_shr:4 row_mask:0xf bank_mask:0xf bound_ctrl:1
	v_cndmask_b32_dpp v137, v91, v89, vcc row_shr:4 row_mask:0xf bank_mask:0xf bound_ctrl:1
	v_mfma_scale_f32_16x16x128_f8f6f4 v[216:219], v[140:143], v[204:211], v[216:219], v240, v241 op_sel_hi:[0,0,0] cbsz:4
	v_and_b32_e32 v204, v174, v235
	v_and_b32_e32 v205, v174, v236
	v_and_b32_e32 v206, v174, v237
	v_and_b32_e32 v207, v174, v238
	v_and_b32_e32 v208, v175, v235
	v_and_b32_e32 v209, v175, v236
	v_and_b32_e32 v210, v175, v237
	v_and_b32_e32 v211, v175, v238
	s_mov_b64 vcc, s[6:7]
	v_cndmask_b32_dpp v140, v94, v92, vcc row_shr:4 row_mask:0xf bank_mask:0xf bound_ctrl:1
	v_cndmask_b32_dpp v141, v95, v93, vcc row_shr:4 row_mask:0xf bank_mask:0xf bound_ctrl:1
	s_mov_b64 vcc, s[4:5]
	v_cndmask_b32_dpp v142, v92, v94, vcc row_shl:4 row_mask:0xf bank_mask:0xf bound_ctrl:1
	v_cndmask_b32_dpp v143, v93, v95, vcc row_shl:4 row_mask:0xf bank_mask:0xf bound_ctrl:1
	v_mfma_scale_f32_16x16x128_f8f6f4 v[216:219], v[136:139], v[144:151], v[216:219], v240, v241 op_sel_hi:[0,0,0] cbsz:4
	s_nop 0
	v_mfma_scale_f32_16x16x128_f8f6f4 v[216:219], v[140:143], v[204:211], v[216:219], v240, v241 op_sel_hi:[0,0,0] cbsz:4
	s_waitcnt lgkmcnt(0)
	v_lshl_or_b32 v128, v128, 7, v232
	v_lshl_or_b32 v129, v129, 7, v232
	v_lshl_or_b32 v130, v130, 7, v232
	v_lshl_or_b32 v131, v131, 7, v232
	v_lshl_or_b32 v132, v132, 7, v232
	v_lshl_or_b32 v133, v133, 7, v232
	v_lshl_or_b32 v134, v134, 7, v232
	v_lshl_or_b32 v135, v135, 7, v232
	buffer_load_dwordx4 v[64:67], v128, s[20:23], s1 offen
	buffer_load_dwordx4 v[68:71], v129, s[20:23], s1 offen
	buffer_load_dwordx4 v[72:75], v130, s[20:23], s1 offen
	buffer_load_dwordx4 v[76:79], v131, s[20:23], s1 offen
	buffer_load_dwordx4 v[80:83], v132, s[20:23], s1 offen
	buffer_load_dwordx4 v[84:87], v133, s[20:23], s1 offen
	buffer_load_dwordx4 v[88:91], v134, s[20:23], s1 offen
	buffer_load_dwordx4 v[92:95], v135, s[20:23], s1 offen
	ds_read_b32 v128, v243 offset:3840
	ds_read_b32 v129, v243 offset:3872
	ds_read_b32 v130, v243 offset:3904
	ds_read_b32 v131, v243 offset:3936
	ds_read_b32 v132, v243 offset:3968
	ds_read_b32 v133, v243 offset:4000
	ds_read_b32 v134, v243 offset:4032
	ds_read_b32 v135, v243 offset:4064
	ds_read_b64 v[160:161], v234 offset:3072
	ds_read_b64 v[162:163], v234 offset:3104
	ds_read_b64 v[164:165], v234 offset:3136
	ds_read_b64 v[166:167], v234 offset:3168
	ds_read_b64 v[168:169], v234 offset:3200
	ds_read_b64 v[170:171], v234 offset:3232
	ds_read_b64 v[172:173], v234 offset:3264
	ds_read_b64 v[174:175], v234 offset:3296
	s_waitcnt vmcnt(26)
	v_and_b32_e32 v144, v176, v235
	v_and_b32_e32 v145, v176, v236
	v_and_b32_e32 v146, v176, v237
	v_and_b32_e32 v147, v176, v238
	v_and_b32_e32 v148, v177, v235
	v_and_b32_e32 v149, v177, v236
	v_and_b32_e32 v150, v177, v237
	v_and_b32_e32 v151, v177, v238
	s_mov_b64 vcc, s[4:5]
	v_cndmask_b32_dpp v138, v96, v98, vcc row_shl:4 row_mask:0xf bank_mask:0xf bound_ctrl:1
	v_cndmask_b32_dpp v139, v97, v99, vcc row_shl:4 row_mask:0xf bank_mask:0xf bound_ctrl:1
	s_mov_b64 vcc, s[6:7]
	v_cndmask_b32_dpp v136, v98, v96, vcc row_shr:4 row_mask:0xf bank_mask:0xf bound_ctrl:1
	v_cndmask_b32_dpp v137, v99, v97, vcc row_shr:4 row_mask:0xf bank_mask:0xf bound_ctrl:1
	v_and_b32_e32 v204, v178, v235
	v_and_b32_e32 v205, v178, v236
	v_and_b32_e32 v206, v178, v237
	v_and_b32_e32 v207, v178, v238
	v_and_b32_e32 v208, v179, v235
	v_and_b32_e32 v209, v179, v236
	v_and_b32_e32 v210, v179, v237
	v_and_b32_e32 v211, v179, v238
	s_mov_b64 vcc, s[6:7]
	v_cndmask_b32_dpp v140, v102, v100, vcc row_shr:4 row_mask:0xf bank_mask:0xf bound_ctrl:1
	v_cndmask_b32_dpp v141, v103, v101, vcc row_shr:4 row_mask:0xf bank_mask:0xf bound_ctrl:1
	s_mov_b64 vcc, s[4:5]
	v_cndmask_b32_dpp v142, v100, v102, vcc row_shl:4 row_mask:0xf bank_mask:0xf bound_ctrl:1
	v_cndmask_b32_dpp v143, v101, v103, vcc row_shl:4 row_mask:0xf bank_mask:0xf bound_ctrl:1
	v_mfma_scale_f32_16x16x128_f8f6f4 v[216:219], v[136:139], v[144:151], v[216:219], v240, v241 op_sel_hi:[0,0,0] cbsz:4
	v_permlane16_swap_b32_e32 v212, v214
	v_permlane16_swap_b32_e32 v213, v215
	v_lshlrev_b32_e32 v252, 16, v228
	v_and_b32_e32 v144, v180, v235
	v_and_b32_e32 v145, v180, v236
	v_and_b32_e32 v146, v180, v237
	v_and_b32_e32 v147, v180, v238
	v_and_b32_e32 v148, v181, v235
	v_and_b32_e32 v149, v181, v236
	v_and_b32_e32 v150, v181, v237
	v_and_b32_e32 v151, v181, v238
	s_mov_b64 vcc, s[4:5]
	v_cndmask_b32_dpp v138, v104, v106, vcc row_shl:4 row_mask:0xf bank_mask:0xf bound_ctrl:1
	v_cndmask_b32_dpp v139, v105, v107, vcc row_shl:4 row_mask:0xf bank_mask:0xf bound_ctrl:1
	s_mov_b64 vcc, s[6:7]
	v_cndmask_b32_dpp v136, v106, v104, vcc row_shr:4 row_mask:0xf bank_mask:0xf bound_ctrl:1
	v_cndmask_b32_dpp v137, v107, v105, vcc row_shr:4 row_mask:0xf bank_mask:0xf bound_ctrl:1
	v_mfma_scale_f32_16x16x128_f8f6f4 v[216:219], v[140:143], v[204:211], v[216:219], v240, v241 op_sel_hi:[0,0,0] cbsz:4
	v_and_b32_e32 v253, 0xffff0000, v228
	v_lshlrev_b32_e32 v254, 16, v229
	v_and_b32_e32 v255, 0xffff0000, v229
	v_and_b32_e32 v204, v182, v235
	v_and_b32_e32 v205, v182, v236
	v_and_b32_e32 v206, v182, v237
	v_and_b32_e32 v207, v182, v238
	v_and_b32_e32 v208, v183, v235
	v_and_b32_e32 v209, v183, v236
	v_and_b32_e32 v210, v183, v237
	v_and_b32_e32 v211, v183, v238
	s_mov_b64 vcc, s[6:7]
	v_cndmask_b32_dpp v140, v110, v108, vcc row_shr:4 row_mask:0xf bank_mask:0xf bound_ctrl:1
	v_cndmask_b32_dpp v141, v111, v109, vcc row_shr:4 row_mask:0xf bank_mask:0xf bound_ctrl:1
	s_mov_b64 vcc, s[4:5]
	v_cndmask_b32_dpp v142, v108, v110, vcc row_shl:4 row_mask:0xf bank_mask:0xf bound_ctrl:1
	v_cndmask_b32_dpp v143, v109, v111, vcc row_shl:4 row_mask:0xf bank_mask:0xf bound_ctrl:1
	v_mfma_scale_f32_16x16x128_f8f6f4 v[216:219], v[136:139], v[144:151], v[216:219], v240, v241 op_sel_hi:[0,0,0] cbsz:4
	v_add_f32_e32 v252, v212, v252
	v_add_f32_e32 v253, v214, v253
	v_add_f32_e32 v254, v213, v254
	v_and_b32_e32 v144, v184, v235
	v_and_b32_e32 v145, v184, v236
	v_and_b32_e32 v146, v184, v237
	v_and_b32_e32 v147, v184, v238
	v_and_b32_e32 v148, v185, v235
	v_and_b32_e32 v149, v185, v236
	v_and_b32_e32 v150, v185, v237
	v_and_b32_e32 v151, v185, v238
	s_mov_b64 vcc, s[4:5]
	v_cndmask_b32_dpp v138, v112, v114, vcc row_shl:4 row_mask:0xf bank_mask:0xf bound_ctrl:1
	v_cndmask_b32_dpp v139, v113, v115, vcc row_shl:4 row_mask:0xf bank_mask:0xf bound_ctrl:1
	s_mov_b64 vcc, s[6:7]
	v_cndmask_b32_dpp v136, v114, v112, vcc row_shr:4 row_mask:0xf bank_mask:0xf bound_ctrl:1
	v_cndmask_b32_dpp v137, v115, v113, vcc row_shr:4 row_mask:0xf bank_mask:0xf bound_ctrl:1
	v_mfma_scale_f32_16x16x128_f8f6f4 v[216:219], v[140:143], v[204:211], v[216:219], v240, v241 op_sel_hi:[0,0,0] cbsz:4
	v_add_f32_e32 v255, v215, v255
	v_mul_f32_e32 v192, v252, v252
	v_mul_f32_e32 v193, v254, v254
	v_and_b32_e32 v204, v186, v235
	v_and_b32_e32 v205, v186, v236
	v_and_b32_e32 v206, v186, v237
	v_and_b32_e32 v207, v186, v238
	v_and_b32_e32 v208, v187, v235
	v_and_b32_e32 v209, v187, v236
	v_and_b32_e32 v210, v187, v237
	v_and_b32_e32 v211, v187, v238
	s_mov_b64 vcc, s[6:7]
	v_cndmask_b32_dpp v140, v118, v116, vcc row_shr:4 row_mask:0xf bank_mask:0xf bound_ctrl:1
	v_cndmask_b32_dpp v141, v119, v117, vcc row_shr:4 row_mask:0xf bank_mask:0xf bound_ctrl:1
	s_mov_b64 vcc, s[4:5]
	v_cndmask_b32_dpp v142, v116, v118, vcc row_shl:4 row_mask:0xf bank_mask:0xf bound_ctrl:1
	v_cndmask_b32_dpp v143, v117, v119, vcc row_shl:4 row_mask:0xf bank_mask:0xf bound_ctrl:1
	v_mfma_scale_f32_16x16x128_f8f6f4 v[216:219], v[136:139], v[144:151], v[216:219], v240, v241 op_sel_hi:[0,0,0] cbsz:4
	v_fmac_f32_e32 v192, v253, v253
	v_fmac_f32_e32 v193, v255, v255
	v_cvt_pk_bf16_f32 v250, v252, v253
	v_and_b32_e32 v144, v188, v235
	v_and_b32_e32 v145, v188, v236
	v_and_b32_e32 v146, v188, v237
	v_and_b32_e32 v147, v188, v238
	v_and_b32_e32 v148, v189, v235
	v_and_b32_e32 v149, v189, v236
	v_and_b32_e32 v150, v189, v237
	v_and_b32_e32 v151, v189, v238
	s_mov_b64 vcc, s[4:5]
	v_cndmask_b32_dpp v138, v120, v122, vcc row_shl:4 row_mask:0xf bank_mask:0xf bound_ctrl:1
	v_cndmask_b32_dpp v139, v121, v123, vcc row_shl:4 row_mask:0xf bank_mask:0xf bound_ctrl:1
	s_mov_b64 vcc, s[6:7]
	v_cndmask_b32_dpp v136, v122, v120, vcc row_shr:4 row_mask:0xf bank_mask:0xf bound_ctrl:1
	v_cndmask_b32_dpp v137, v123, v121, vcc row_shr:4 row_mask:0xf bank_mask:0xf bound_ctrl:1
	v_mfma_scale_f32_16x16x128_f8f6f4 v[216:219], v[140:143], v[204:211], v[216:219], v240, v241 op_sel_hi:[0,0,0] cbsz:4
	v_cvt_pk_bf16_f32 v251, v254, v255
	v_add_f32_e32 v192, v192, v193
	v_add_f32_e32 v224, v224, v192
	v_and_b32_e32 v204, v190, v235
	v_and_b32_e32 v205, v190, v236
	v_and_b32_e32 v206, v190, v237
	v_and_b32_e32 v207, v190, v238
	v_and_b32_e32 v208, v191, v235
	v_and_b32_e32 v209, v191, v236
	v_and_b32_e32 v210, v191, v237
	v_and_b32_e32 v211, v191, v238
	s_mov_b64 vcc, s[6:7]
	v_cndmask_b32_dpp v140, v126, v124, vcc row_shr:4 row_mask:0xf bank_mask:0xf bound_ctrl:1
	v_cndmask_b32_dpp v141, v127, v125, vcc row_shr:4 row_mask:0xf bank_mask:0xf bound_ctrl:1
	s_mov_b64 vcc, s[4:5]
	v_cndmask_b32_dpp v142, v124, v126, vcc row_shl:4 row_mask:0xf bank_mask:0xf bound_ctrl:1
	v_cndmask_b32_dpp v143, v125, v127, vcc row_shl:4 row_mask:0xf bank_mask:0xf bound_ctrl:1
	v_mfma_scale_f32_16x16x128_f8f6f4 v[216:219], v[136:139], v[144:151], v[216:219], v240, v241 op_sel_hi:[0,0,0] cbsz:4
	s_nop 0
	v_mfma_scale_f32_16x16x128_f8f6f4 v[216:219], v[140:143], v[204:211], v[216:219], v240, v241 op_sel_hi:[0,0,0] cbsz:4
	s_lshl_b32 s64, s0, 9
	s_add_u32 s64, s64, 0x4000
	s_add_u32 s76, s28, s64
	s_addc_u32 s77, s29, 0
	global_store_dwordx2 v239, v[250:251], s[76:77]
	s_lshl_b32 s64, s0, 9
	s_add_u32 s64, s64, 0x6000
	s_add_u32 s70, s28, s64
	s_addc_u32 s71, s29, 0
	global_load_dwordx2 v[228:229], v239, s[70:71]
	s_waitcnt lgkmcnt(0)
	v_lshl_or_b32 v128, v128, 7, v232
	v_lshl_or_b32 v129, v129, 7, v232
	v_lshl_or_b32 v130, v130, 7, v232
	v_lshl_or_b32 v131, v131, 7, v232
	v_lshl_or_b32 v132, v132, 7, v232
	v_lshl_or_b32 v133, v133, 7, v232
	v_lshl_or_b32 v134, v134, 7, v232
	v_lshl_or_b32 v135, v135, 7, v232
	buffer_load_dwordx4 v[96:99], v128, s[20:23], s1 offen
	buffer_load_dwordx4 v[100:103], v129, s[20:23], s1 offen
	buffer_load_dwordx4 v[104:107], v130, s[20:23], s1 offen
	buffer_load_dwordx4 v[108:111], v131, s[20:23], s1 offen
	buffer_load_dwordx4 v[112:115], v132, s[20:23], s1 offen
	buffer_load_dwordx4 v[116:119], v133, s[20:23], s1 offen
	buffer_load_dwordx4 v[120:123], v134, s[20:23], s1 offen
	buffer_load_dwordx4 v[124:127], v135, s[20:23], s1 offen
	ds_read_b32 v128, v243 offset:0
	ds_read_b32 v129, v243 offset:32
	ds_read_b32 v130, v243 offset:64
	ds_read_b32 v131, v243 offset:96
	ds_read_b32 v132, v243 offset:128
	ds_read_b32 v133, v243 offset:160
	ds_read_b32 v134, v243 offset:192
	ds_read_b32 v135, v243 offset:224
	ds_read_b64 v[176:177], v234 offset:3328
	ds_read_b64 v[178:179], v234 offset:3360
	ds_read_b64 v[180:181], v234 offset:3392
	ds_read_b64 v[182:183], v234 offset:3424
	ds_read_b64 v[184:185], v234 offset:3456
	ds_read_b64 v[186:187], v234 offset:3488
	ds_read_b64 v[188:189], v234 offset:3520
	ds_read_b64 v[190:191], v234 offset:3552
	s_waitcnt vmcnt(28)
	v_and_b32_e32 v144, v160, v235
	v_and_b32_e32 v145, v160, v236
	v_and_b32_e32 v146, v160, v237
	v_and_b32_e32 v147, v160, v238
	v_and_b32_e32 v148, v161, v235
	v_and_b32_e32 v149, v161, v236
	v_and_b32_e32 v150, v161, v237
	v_and_b32_e32 v151, v161, v238
	s_mov_b64 vcc, s[4:5]
	v_cndmask_b32_dpp v138, v0, v2, vcc row_shl:4 row_mask:0xf bank_mask:0xf bound_ctrl:1
	v_cndmask_b32_dpp v139, v1, v3, vcc row_shl:4 row_mask:0xf bank_mask:0xf bound_ctrl:1
	s_mov_b64 vcc, s[6:7]
	v_cndmask_b32_dpp v136, v2, v0, vcc row_shr:4 row_mask:0xf bank_mask:0xf bound_ctrl:1
	v_cndmask_b32_dpp v137, v3, v1, vcc row_shr:4 row_mask:0xf bank_mask:0xf bound_ctrl:1
	v_and_b32_e32 v204, v162, v235
	v_and_b32_e32 v205, v162, v236
	v_and_b32_e32 v206, v162, v237
	v_and_b32_e32 v207, v162, v238
	v_and_b32_e32 v208, v163, v235
	v_and_b32_e32 v209, v163, v236
	v_and_b32_e32 v210, v163, v237
	v_and_b32_e32 v211, v163, v238
	s_mov_b64 vcc, s[6:7]
	v_cndmask_b32_dpp v140, v6, v4, vcc row_shr:4 row_mask:0xf bank_mask:0xf bound_ctrl:1
	v_cndmask_b32_dpp v141, v7, v5, vcc row_shr:4 row_mask:0xf bank_mask:0xf bound_ctrl:1
	s_mov_b64 vcc, s[4:5]
	v_cndmask_b32_dpp v142, v4, v6, vcc row_shl:4 row_mask:0xf bank_mask:0xf bound_ctrl:1
	v_cndmask_b32_dpp v143, v5, v7, vcc row_shl:4 row_mask:0xf bank_mask:0xf bound_ctrl:1
	v_mfma_scale_f32_16x16x128_f8f6f4 v[212:215], v[136:139], v[144:151], 0, v240, v241 op_sel_hi:[0,0,0] cbsz:4
	v_and_b32_e32 v144, v164, v235
	v_and_b32_e32 v145, v164, v236
	v_and_b32_e32 v146, v164, v237
	v_and_b32_e32 v147, v164, v238
	v_and_b32_e32 v148, v165, v235
	v_and_b32_e32 v149, v165, v236
	v_and_b32_e32 v150, v165, v237
	v_and_b32_e32 v151, v165, v238
	s_mov_b64 vcc, s[4:5]
	v_cndmask_b32_dpp v138, v8, v10, vcc row_shl:4 row_mask:0xf bank_mask:0xf bound_ctrl:1
	v_cndmask_b32_dpp v139, v9, v11, vcc row_shl:4 row_mask:0xf bank_mask:0xf bound_ctrl:1
	s_mov_b64 vcc, s[6:7]
	v_cndmask_b32_dpp v136, v10, v8, vcc row_shr:4 row_mask:0xf bank_mask:0xf bound_ctrl:1
	v_cndmask_b32_dpp v137, v11, v9, vcc row_shr:4 row_mask:0xf bank_mask:0xf bound_ctrl:1
	v_mfma_scale_f32_16x16x128_f8f6f4 v[212:215], v[140:143], v[204:211], v[212:215], v240, v241 op_sel_hi:[0,0,0] cbsz:4
	v_and_b32_e32 v204, v166, v235
	v_and_b32_e32 v205, v166, v236
	v_and_b32_e32 v206, v166, v237
	v_and_b32_e32 v207, v166, v238
	v_and_b32_e32 v208, v167, v235
	v_and_b32_e32 v209, v167, v236
	v_and_b32_e32 v210, v167, v237
	v_and_b32_e32 v211, v167, v238
	s_mov_b64 vcc, s[6:7]
	v_cndmask_b32_dpp v140, v14, v12, vcc row_shr:4 row_mask:0xf bank_mask:0xf bound_ctrl:1
	v_cndmask_b32_dpp v141, v15, v13, vcc row_shr:4 row_mask:0xf bank_mask:0xf bound_ctrl:1
	s_mov_b64 vcc, s[4:5]
	v_cndmask_b32_dpp v142, v12, v14, vcc row_shl:4 row_mask:0xf bank_mask:0xf bound_ctrl:1
	v_cndmask_b32_dpp v143, v13, v15, vcc row_shl:4 row_mask:0xf bank_mask:0xf bound_ctrl:1
	v_mfma_scale_f32_16x16x128_f8f6f4 v[212:215], v[136:139], v[144:151], v[212:215], v240, v241 op_sel_hi:[0,0,0] cbsz:4
	v_and_b32_e32 v144, v168, v235
	v_and_b32_e32 v145, v168, v236
	v_and_b32_e32 v146, v168, v237
	v_and_b32_e32 v147, v168, v238
	v_and_b32_e32 v148, v169, v235
	v_and_b32_e32 v149, v169, v236
	v_and_b32_e32 v150, v169, v237
	v_and_b32_e32 v151, v169, v238
	s_mov_b64 vcc, s[4:5]
	v_cndmask_b32_dpp v138, v16, v18, vcc row_shl:4 row_mask:0xf bank_mask:0xf bound_ctrl:1
	v_cndmask_b32_dpp v139, v17, v19, vcc row_shl:4 row_mask:0xf bank_mask:0xf bound_ctrl:1
	s_mov_b64 vcc, s[6:7]
	v_cndmask_b32_dpp v136, v18, v16, vcc row_shr:4 row_mask:0xf bank_mask:0xf bound_ctrl:1
	v_cndmask_b32_dpp v137, v19, v17, vcc row_shr:4 row_mask:0xf bank_mask:0xf bound_ctrl:1
	v_mfma_scale_f32_16x16x128_f8f6f4 v[212:215], v[140:143], v[204:211], v[212:215], v240, v241 op_sel_hi:[0,0,0] cbsz:4
	v_and_b32_e32 v204, v170, v235
	v_and_b32_e32 v205, v170, v236
	v_and_b32_e32 v206, v170, v237
	v_and_b32_e32 v207, v170, v238
	v_and_b32_e32 v208, v171, v235
	v_and_b32_e32 v209, v171, v236
	v_and_b32_e32 v210, v171, v237
	v_and_b32_e32 v211, v171, v238
	s_mov_b64 vcc, s[6:7]
	v_cndmask_b32_dpp v140, v22, v20, vcc row_shr:4 row_mask:0xf bank_mask:0xf bound_ctrl:1
	v_cndmask_b32_dpp v141, v23, v21, vcc row_shr:4 row_mask:0xf bank_mask:0xf bound_ctrl:1
	s_mov_b64 vcc, s[4:5]
	v_cndmask_b32_dpp v142, v20, v22, vcc row_shl:4 row_mask:0xf bank_mask:0xf bound_ctrl:1
	v_cndmask_b32_dpp v143, v21, v23, vcc row_shl:4 row_mask:0xf bank_mask:0xf bound_ctrl:1
	v_mfma_scale_f32_16x16x128_f8f6f4 v[212:215], v[136:139], v[144:151], v[212:215], v240, v241 op_sel_hi:[0,0,0] cbsz:4
	v_and_b32_e32 v144, v172, v235
	v_and_b32_e32 v145, v172, v236
	v_and_b32_e32 v146, v172, v237
	v_and_b32_e32 v147, v172, v238
	v_and_b32_e32 v148, v173, v235
	v_and_b32_e32 v149, v173, v236
	v_and_b32_e32 v150, v173, v237
	v_and_b32_e32 v151, v173, v238
	s_mov_b64 vcc, s[4:5]
	v_cndmask_b32_dpp v138, v24, v26, vcc row_shl:4 row_mask:0xf bank_mask:0xf bound_ctrl:1
	v_cndmask_b32_dpp v139, v25, v27, vcc row_shl:4 row_mask:0xf bank_mask:0xf bound_ctrl:1
	s_mov_b64 vcc, s[6:7]
	v_cndmask_b32_dpp v136, v26, v24, vcc row_shr:4 row_mask:0xf bank_mask:0xf bound_ctrl:1
	v_cndmask_b32_dpp v137, v27, v25, vcc row_shr:4 row_mask:0xf bank_mask:0xf bound_ctrl:1
	v_mfma_scale_f32_16x16x128_f8f6f4 v[212:215], v[140:143], v[204:211], v[212:215], v240, v241 op_sel_hi:[0,0,0] cbsz:4
	v_and_b32_e32 v204, v174, v235
	v_and_b32_e32 v205, v174, v236
	v_and_b32_e32 v206, v174, v237
	v_and_b32_e32 v207, v174, v238
	v_and_b32_e32 v208, v175, v235
	v_and_b32_e32 v209, v175, v236
	v_and_b32_e32 v210, v175, v237
	v_and_b32_e32 v211, v175, v238
	s_mov_b64 vcc, s[6:7]
	v_cndmask_b32_dpp v140, v30, v28, vcc row_shr:4 row_mask:0xf bank_mask:0xf bound_ctrl:1
	v_cndmask_b32_dpp v141, v31, v29, vcc row_shr:4 row_mask:0xf bank_mask:0xf bound_ctrl:1
	s_mov_b64 vcc, s[4:5]
	v_cndmask_b32_dpp v142, v28, v30, vcc row_shl:4 row_mask:0xf bank_mask:0xf bound_ctrl:1
	v_cndmask_b32_dpp v143, v29, v31, vcc row_shl:4 row_mask:0xf bank_mask:0xf bound_ctrl:1
	v_mfma_scale_f32_16x16x128_f8f6f4 v[212:215], v[136:139], v[144:151], v[212:215], v240, v241 op_sel_hi:[0,0,0] cbsz:4
	s_nop 0
	v_mfma_scale_f32_16x16x128_f8f6f4 v[212:215], v[140:143], v[204:211], v[212:215], v240, v241 op_sel_hi:[0,0,0] cbsz:4
	s_waitcnt lgkmcnt(0)
	v_lshl_or_b32 v128, v128, 7, v232
	v_lshl_or_b32 v129, v129, 7, v232
	v_lshl_or_b32 v130, v130, 7, v232
	v_lshl_or_b32 v131, v131, 7, v232
	v_lshl_or_b32 v132, v132, 7, v232
	v_lshl_or_b32 v133, v133, 7, v232
	v_lshl_or_b32 v134, v134, 7, v232
	v_lshl_or_b32 v135, v135, 7, v232
	buffer_load_dwordx4 v[0:3], v128, s[20:23], s60 offen
	buffer_load_dwordx4 v[4:7], v129, s[20:23], s60 offen
	buffer_load_dwordx4 v[8:11], v130, s[20:23], s60 offen
	buffer_load_dwordx4 v[12:15], v131, s[20:23], s60 offen
	buffer_load_dwordx4 v[16:19], v132, s[20:23], s60 offen
	buffer_load_dwordx4 v[20:23], v133, s[20:23], s60 offen
	buffer_load_dwordx4 v[24:27], v134, s[20:23], s60 offen
	buffer_load_dwordx4 v[28:31], v135, s[20:23], s60 offen
	ds_read_b32 v128, v243 offset:256
	ds_read_b32 v129, v243 offset:288
	ds_read_b32 v130, v243 offset:320
	ds_read_b32 v131, v243 offset:352
	ds_read_b32 v132, v243 offset:384
	ds_read_b32 v133, v243 offset:416
	ds_read_b32 v134, v243 offset:448
	ds_read_b32 v135, v243 offset:480
	ds_read_b64 v[160:161], v234 offset:3584
	ds_read_b64 v[162:163], v234 offset:3616
	ds_read_b64 v[164:165], v234 offset:3648
	ds_read_b64 v[166:167], v234 offset:3680
	ds_read_b64 v[168:169], v234 offset:3712
	ds_read_b64 v[170:171], v234 offset:3744
	ds_read_b64 v[172:173], v234 offset:3776
	ds_read_b64 v[174:175], v234 offset:3808
	s_waitcnt vmcnt(26)
	v_and_b32_e32 v144, v176, v235
	v_and_b32_e32 v145, v176, v236
	v_and_b32_e32 v146, v176, v237
	v_and_b32_e32 v147, v176, v238
	v_and_b32_e32 v148, v177, v235
	v_and_b32_e32 v149, v177, v236
	v_and_b32_e32 v150, v177, v237
	v_and_b32_e32 v151, v177, v238
	s_mov_b64 vcc, s[4:5]
	v_cndmask_b32_dpp v138, v32, v34, vcc row_shl:4 row_mask:0xf bank_mask:0xf bound_ctrl:1
	v_cndmask_b32_dpp v139, v33, v35, vcc row_shl:4 row_mask:0xf bank_mask:0xf bound_ctrl:1
	s_mov_b64 vcc, s[6:7]
	v_cndmask_b32_dpp v136, v34, v32, vcc row_shr:4 row_mask:0xf bank_mask:0xf bound_ctrl:1
	v_cndmask_b32_dpp v137, v35, v33, vcc row_shr:4 row_mask:0xf bank_mask:0xf bound_ctrl:1
	v_and_b32_e32 v204, v178, v235
	v_and_b32_e32 v205, v178, v236
	v_and_b32_e32 v206, v178, v237
	v_and_b32_e32 v207, v178, v238
	v_and_b32_e32 v208, v179, v235
	v_and_b32_e32 v209, v179, v236
	v_and_b32_e32 v210, v179, v237
	v_and_b32_e32 v211, v179, v238
	s_mov_b64 vcc, s[6:7]
	v_cndmask_b32_dpp v140, v38, v36, vcc row_shr:4 row_mask:0xf bank_mask:0xf bound_ctrl:1
	v_cndmask_b32_dpp v141, v39, v37, vcc row_shr:4 row_mask:0xf bank_mask:0xf bound_ctrl:1
	s_mov_b64 vcc, s[4:5]
	v_cndmask_b32_dpp v142, v36, v38, vcc row_shl:4 row_mask:0xf bank_mask:0xf bound_ctrl:1
	v_cndmask_b32_dpp v143, v37, v39, vcc row_shl:4 row_mask:0xf bank_mask:0xf bound_ctrl:1
	v_mfma_scale_f32_16x16x128_f8f6f4 v[212:215], v[136:139], v[144:151], v[212:215], v240, v241 op_sel_hi:[0,0,0] cbsz:4
	v_permlane16_swap_b32_e32 v216, v218
	v_permlane16_swap_b32_e32 v217, v219
	v_lshlrev_b32_e32 v252, 16, v230
	v_and_b32_e32 v144, v180, v235
	v_and_b32_e32 v145, v180, v236
	v_and_b32_e32 v146, v180, v237
	v_and_b32_e32 v147, v180, v238
	v_and_b32_e32 v148, v181, v235
	v_and_b32_e32 v149, v181, v236
	v_and_b32_e32 v150, v181, v237
	v_and_b32_e32 v151, v181, v238
	s_mov_b64 vcc, s[4:5]
	v_cndmask_b32_dpp v138, v40, v42, vcc row_shl:4 row_mask:0xf bank_mask:0xf bound_ctrl:1
	v_cndmask_b32_dpp v139, v41, v43, vcc row_shl:4 row_mask:0xf bank_mask:0xf bound_ctrl:1
	s_mov_b64 vcc, s[6:7]
	v_cndmask_b32_dpp v136, v42, v40, vcc row_shr:4 row_mask:0xf bank_mask:0xf bound_ctrl:1
	v_cndmask_b32_dpp v137, v43, v41, vcc row_shr:4 row_mask:0xf bank_mask:0xf bound_ctrl:1
	v_mfma_scale_f32_16x16x128_f8f6f4 v[212:215], v[140:143], v[204:211], v[212:215], v240, v241 op_sel_hi:[0,0,0] cbsz:4
	v_and_b32_e32 v253, 0xffff0000, v230
	v_lshlrev_b32_e32 v254, 16, v231
	v_and_b32_e32 v255, 0xffff0000, v231
	v_and_b32_e32 v204, v182, v235
	v_and_b32_e32 v205, v182, v236
	v_and_b32_e32 v206, v182, v237
	v_and_b32_e32 v207, v182, v238
	v_and_b32_e32 v208, v183, v235
	v_and_b32_e32 v209, v183, v236
	v_and_b32_e32 v210, v183, v237
	v_and_b32_e32 v211, v183, v238
	s_mov_b64 vcc, s[6:7]
	v_cndmask_b32_dpp v140, v46, v44, vcc row_shr:4 row_mask:0xf bank_mask:0xf bound_ctrl:1
	v_cndmask_b32_dpp v141, v47, v45, vcc row_shr:4 row_mask:0xf bank_mask:0xf bound_ctrl:1
	s_mov_b64 vcc, s[4:5]
	v_cndmask_b32_dpp v142, v44, v46, vcc row_shl:4 row_mask:0xf bank_mask:0xf bound_ctrl:1
	v_cndmask_b32_dpp v143, v45, v47, vcc row_shl:4 row_mask:0xf bank_mask:0xf bound_ctrl:1
	v_mfma_scale_f32_16x16x128_f8f6f4 v[212:215], v[136:139], v[144:151], v[212:215], v240, v241 op_sel_hi:[0,0,0] cbsz:4
	v_add_f32_e32 v252, v216, v252
	v_add_f32_e32 v253, v218, v253
	v_add_f32_e32 v254, v217, v254
	v_and_b32_e32 v144, v184, v235
	v_and_b32_e32 v145, v184, v236
	v_and_b32_e32 v146, v184, v237
	v_and_b32_e32 v147, v184, v238
	v_and_b32_e32 v148, v185, v235
	v_and_b32_e32 v149, v185, v236
	v_and_b32_e32 v150, v185, v237
	v_and_b32_e32 v151, v185, v238
	s_mov_b64 vcc, s[4:5]
	v_cndmask_b32_dpp v138, v48, v50, vcc row_shl:4 row_mask:0xf bank_mask:0xf bound_ctrl:1
	v_cndmask_b32_dpp v139, v49, v51, vcc row_shl:4 row_mask:0xf bank_mask:0xf bound_ctrl:1
	s_mov_b64 vcc, s[6:7]
	v_cndmask_b32_dpp v136, v50, v48, vcc row_shr:4 row_mask:0xf bank_mask:0xf bound_ctrl:1
	v_cndmask_b32_dpp v137, v51, v49, vcc row_shr:4 row_mask:0xf bank_mask:0xf bound_ctrl:1
	v_mfma_scale_f32_16x16x128_f8f6f4 v[212:215], v[140:143], v[204:211], v[212:215], v240, v241 op_sel_hi:[0,0,0] cbsz:4
	v_add_f32_e32 v255, v219, v255
	v_mul_f32_e32 v192, v252, v252
	v_mul_f32_e32 v193, v254, v254
	v_and_b32_e32 v204, v186, v235
	v_and_b32_e32 v205, v186, v236
	v_and_b32_e32 v206, v186, v237
	v_and_b32_e32 v207, v186, v238
	v_and_b32_e32 v208, v187, v235
	v_and_b32_e32 v209, v187, v236
	v_and_b32_e32 v210, v187, v237
	v_and_b32_e32 v211, v187, v238
	s_mov_b64 vcc, s[6:7]
	v_cndmask_b32_dpp v140, v54, v52, vcc row_shr:4 row_mask:0xf bank_mask:0xf bound_ctrl:1
	v_cndmask_b32_dpp v141, v55, v53, vcc row_shr:4 row_mask:0xf bank_mask:0xf bound_ctrl:1
	s_mov_b64 vcc, s[4:5]
	v_cndmask_b32_dpp v142, v52, v54, vcc row_shl:4 row_mask:0xf bank_mask:0xf bound_ctrl:1
	v_cndmask_b32_dpp v143, v53, v55, vcc row_shl:4 row_mask:0xf bank_mask:0xf bound_ctrl:1
	v_mfma_scale_f32_16x16x128_f8f6f4 v[212:215], v[136:139], v[144:151], v[212:215], v240, v241 op_sel_hi:[0,0,0] cbsz:4
	v_fmac_f32_e32 v192, v253, v253
	v_fmac_f32_e32 v193, v255, v255
	v_cvt_pk_bf16_f32 v250, v252, v253
	v_and_b32_e32 v144, v188, v235
	v_and_b32_e32 v145, v188, v236
	v_and_b32_e32 v146, v188, v237
	v_and_b32_e32 v147, v188, v238
	v_and_b32_e32 v148, v189, v235
	v_and_b32_e32 v149, v189, v236
	v_and_b32_e32 v150, v189, v237
	v_and_b32_e32 v151, v189, v238
	s_mov_b64 vcc, s[4:5]
	v_cndmask_b32_dpp v138, v56, v58, vcc row_shl:4 row_mask:0xf bank_mask:0xf bound_ctrl:1
	v_cndmask_b32_dpp v139, v57, v59, vcc row_shl:4 row_mask:0xf bank_mask:0xf bound_ctrl:1
	s_mov_b64 vcc, s[6:7]
	v_cndmask_b32_dpp v136, v58, v56, vcc row_shr:4 row_mask:0xf bank_mask:0xf bound_ctrl:1
	v_cndmask_b32_dpp v137, v59, v57, vcc row_shr:4 row_mask:0xf bank_mask:0xf bound_ctrl:1
	v_mfma_scale_f32_16x16x128_f8f6f4 v[212:215], v[140:143], v[204:211], v[212:215], v240, v241 op_sel_hi:[0,0,0] cbsz:4
	v_cvt_pk_bf16_f32 v251, v254, v255
	v_add_f32_e32 v192, v192, v193
	v_add_f32_e32 v225, v225, v192
	v_and_b32_e32 v204, v190, v235
	v_and_b32_e32 v205, v190, v236
	v_and_b32_e32 v206, v190, v237
	v_and_b32_e32 v207, v190, v238
	v_and_b32_e32 v208, v191, v235
	v_and_b32_e32 v209, v191, v236
	v_and_b32_e32 v210, v191, v237
	v_and_b32_e32 v211, v191, v238
	s_mov_b64 vcc, s[6:7]
	v_cndmask_b32_dpp v140, v62, v60, vcc row_shr:4 row_mask:0xf bank_mask:0xf bound_ctrl:1
	v_cndmask_b32_dpp v141, v63, v61, vcc row_shr:4 row_mask:0xf bank_mask:0xf bound_ctrl:1
	s_mov_b64 vcc, s[4:5]
	v_cndmask_b32_dpp v142, v60, v62, vcc row_shl:4 row_mask:0xf bank_mask:0xf bound_ctrl:1
	v_cndmask_b32_dpp v143, v61, v63, vcc row_shl:4 row_mask:0xf bank_mask:0xf bound_ctrl:1
	v_mfma_scale_f32_16x16x128_f8f6f4 v[212:215], v[136:139], v[144:151], v[212:215], v240, v241 op_sel_hi:[0,0,0] cbsz:4
	s_nop 0
	v_mfma_scale_f32_16x16x128_f8f6f4 v[212:215], v[140:143], v[204:211], v[212:215], v240, v241 op_sel_hi:[0,0,0] cbsz:4
	s_lshl_b32 s64, s0, 9
	s_add_u32 s64, s64, 0x5000
	s_add_u32 s76, s28, s64
	s_addc_u32 s77, s29, 0
	global_store_dwordx2 v239, v[250:251], s[76:77]
	s_lshl_b32 s64, s0, 9
	s_add_u32 s64, s64, 0x7000
	s_add_u32 s70, s28, s64
	s_addc_u32 s71, s29, 0
	global_load_dwordx2 v[230:231], v239, s[70:71]
	s_waitcnt lgkmcnt(0)
	v_lshl_or_b32 v128, v128, 7, v232
	v_lshl_or_b32 v129, v129, 7, v232
	v_lshl_or_b32 v130, v130, 7, v232
	v_lshl_or_b32 v131, v131, 7, v232
	v_lshl_or_b32 v132, v132, 7, v232
	v_lshl_or_b32 v133, v133, 7, v232
	v_lshl_or_b32 v134, v134, 7, v232
	v_lshl_or_b32 v135, v135, 7, v232
	buffer_load_dwordx4 v[32:35], v128, s[20:23], s60 offen
	buffer_load_dwordx4 v[36:39], v129, s[20:23], s60 offen
	buffer_load_dwordx4 v[40:43], v130, s[20:23], s60 offen
	buffer_load_dwordx4 v[44:47], v131, s[20:23], s60 offen
	buffer_load_dwordx4 v[48:51], v132, s[20:23], s60 offen
	buffer_load_dwordx4 v[52:55], v133, s[20:23], s60 offen
	buffer_load_dwordx4 v[56:59], v134, s[20:23], s60 offen
	buffer_load_dwordx4 v[60:63], v135, s[20:23], s60 offen
	ds_read_b32 v128, v243 offset:512
	ds_read_b32 v129, v243 offset:544
	ds_read_b32 v130, v243 offset:576
	ds_read_b32 v131, v243 offset:608
	ds_read_b32 v132, v243 offset:640
	ds_read_b32 v133, v243 offset:672
	ds_read_b32 v134, v243 offset:704
	ds_read_b32 v135, v243 offset:736
	ds_read_b64 v[176:177], v234 offset:3840
	ds_read_b64 v[178:179], v234 offset:3872
	ds_read_b64 v[180:181], v234 offset:3904
	ds_read_b64 v[182:183], v234 offset:3936
	ds_read_b64 v[184:185], v234 offset:3968
	ds_read_b64 v[186:187], v234 offset:4000
	ds_read_b64 v[188:189], v234 offset:4032
	ds_read_b64 v[190:191], v234 offset:4064
	s_waitcnt vmcnt(28)
	v_and_b32_e32 v144, v160, v235
	v_and_b32_e32 v145, v160, v236
	v_and_b32_e32 v146, v160, v237
	v_and_b32_e32 v147, v160, v238
	v_and_b32_e32 v148, v161, v235
	v_and_b32_e32 v149, v161, v236
	v_and_b32_e32 v150, v161, v237
	v_and_b32_e32 v151, v161, v238
	s_mov_b64 vcc, s[4:5]
	v_cndmask_b32_dpp v138, v64, v66, vcc row_shl:4 row_mask:0xf bank_mask:0xf bound_ctrl:1
	v_cndmask_b32_dpp v139, v65, v67, vcc row_shl:4 row_mask:0xf bank_mask:0xf bound_ctrl:1
	s_mov_b64 vcc, s[6:7]
	v_cndmask_b32_dpp v136, v66, v64, vcc row_shr:4 row_mask:0xf bank_mask:0xf bound_ctrl:1
	v_cndmask_b32_dpp v137, v67, v65, vcc row_shr:4 row_mask:0xf bank_mask:0xf bound_ctrl:1
	v_and_b32_e32 v204, v162, v235
	v_and_b32_e32 v205, v162, v236
	v_and_b32_e32 v206, v162, v237
	v_and_b32_e32 v207, v162, v238
	v_and_b32_e32 v208, v163, v235
	v_and_b32_e32 v209, v163, v236
	v_and_b32_e32 v210, v163, v237
	v_and_b32_e32 v211, v163, v238
	s_mov_b64 vcc, s[6:7]
	v_cndmask_b32_dpp v140, v70, v68, vcc row_shr:4 row_mask:0xf bank_mask:0xf bound_ctrl:1
	v_cndmask_b32_dpp v141, v71, v69, vcc row_shr:4 row_mask:0xf bank_mask:0xf bound_ctrl:1
	s_mov_b64 vcc, s[4:5]
	v_cndmask_b32_dpp v142, v68, v70, vcc row_shl:4 row_mask:0xf bank_mask:0xf bound_ctrl:1
	v_cndmask_b32_dpp v143, v69, v71, vcc row_shl:4 row_mask:0xf bank_mask:0xf bound_ctrl:1
	v_mfma_scale_f32_16x16x128_f8f6f4 v[216:219], v[136:139], v[144:151], 0, v240, v241 op_sel_hi:[0,0,0] cbsz:4
	v_and_b32_e32 v144, v164, v235
	v_and_b32_e32 v145, v164, v236
	v_and_b32_e32 v146, v164, v237
	v_and_b32_e32 v147, v164, v238
	v_and_b32_e32 v148, v165, v235
	v_and_b32_e32 v149, v165, v236
	v_and_b32_e32 v150, v165, v237
	v_and_b32_e32 v151, v165, v238
	s_mov_b64 vcc, s[4:5]
	v_cndmask_b32_dpp v138, v72, v74, vcc row_shl:4 row_mask:0xf bank_mask:0xf bound_ctrl:1
	v_cndmask_b32_dpp v139, v73, v75, vcc row_shl:4 row_mask:0xf bank_mask:0xf bound_ctrl:1
	s_mov_b64 vcc, s[6:7]
	v_cndmask_b32_dpp v136, v74, v72, vcc row_shr:4 row_mask:0xf bank_mask:0xf bound_ctrl:1
	v_cndmask_b32_dpp v137, v75, v73, vcc row_shr:4 row_mask:0xf bank_mask:0xf bound_ctrl:1
	v_mfma_scale_f32_16x16x128_f8f6f4 v[216:219], v[140:143], v[204:211], v[216:219], v240, v241 op_sel_hi:[0,0,0] cbsz:4
	v_and_b32_e32 v204, v166, v235
	v_and_b32_e32 v205, v166, v236
	v_and_b32_e32 v206, v166, v237
	v_and_b32_e32 v207, v166, v238
	v_and_b32_e32 v208, v167, v235
	v_and_b32_e32 v209, v167, v236
	v_and_b32_e32 v210, v167, v237
	v_and_b32_e32 v211, v167, v238
	s_mov_b64 vcc, s[6:7]
	v_cndmask_b32_dpp v140, v78, v76, vcc row_shr:4 row_mask:0xf bank_mask:0xf bound_ctrl:1
	v_cndmask_b32_dpp v141, v79, v77, vcc row_shr:4 row_mask:0xf bank_mask:0xf bound_ctrl:1
	s_mov_b64 vcc, s[4:5]
	v_cndmask_b32_dpp v142, v76, v78, vcc row_shl:4 row_mask:0xf bank_mask:0xf bound_ctrl:1
	v_cndmask_b32_dpp v143, v77, v79, vcc row_shl:4 row_mask:0xf bank_mask:0xf bound_ctrl:1
	v_mfma_scale_f32_16x16x128_f8f6f4 v[216:219], v[136:139], v[144:151], v[216:219], v240, v241 op_sel_hi:[0,0,0] cbsz:4
	v_and_b32_e32 v144, v168, v235
	v_and_b32_e32 v145, v168, v236
	v_and_b32_e32 v146, v168, v237
	v_and_b32_e32 v147, v168, v238
	v_and_b32_e32 v148, v169, v235
	v_and_b32_e32 v149, v169, v236
	v_and_b32_e32 v150, v169, v237
	v_and_b32_e32 v151, v169, v238
	s_mov_b64 vcc, s[4:5]
	v_cndmask_b32_dpp v138, v80, v82, vcc row_shl:4 row_mask:0xf bank_mask:0xf bound_ctrl:1
	v_cndmask_b32_dpp v139, v81, v83, vcc row_shl:4 row_mask:0xf bank_mask:0xf bound_ctrl:1
	s_mov_b64 vcc, s[6:7]
	v_cndmask_b32_dpp v136, v82, v80, vcc row_shr:4 row_mask:0xf bank_mask:0xf bound_ctrl:1
	v_cndmask_b32_dpp v137, v83, v81, vcc row_shr:4 row_mask:0xf bank_mask:0xf bound_ctrl:1
	v_mfma_scale_f32_16x16x128_f8f6f4 v[216:219], v[140:143], v[204:211], v[216:219], v240, v241 op_sel_hi:[0,0,0] cbsz:4
	v_and_b32_e32 v204, v170, v235
	v_and_b32_e32 v205, v170, v236
	v_and_b32_e32 v206, v170, v237
	v_and_b32_e32 v207, v170, v238
	v_and_b32_e32 v208, v171, v235
	v_and_b32_e32 v209, v171, v236
	v_and_b32_e32 v210, v171, v237
	v_and_b32_e32 v211, v171, v238
	s_mov_b64 vcc, s[6:7]
	v_cndmask_b32_dpp v140, v86, v84, vcc row_shr:4 row_mask:0xf bank_mask:0xf bound_ctrl:1
	v_cndmask_b32_dpp v141, v87, v85, vcc row_shr:4 row_mask:0xf bank_mask:0xf bound_ctrl:1
	s_mov_b64 vcc, s[4:5]
	v_cndmask_b32_dpp v142, v84, v86, vcc row_shl:4 row_mask:0xf bank_mask:0xf bound_ctrl:1
	v_cndmask_b32_dpp v143, v85, v87, vcc row_shl:4 row_mask:0xf bank_mask:0xf bound_ctrl:1
	v_mfma_scale_f32_16x16x128_f8f6f4 v[216:219], v[136:139], v[144:151], v[216:219], v240, v241 op_sel_hi:[0,0,0] cbsz:4
	v_and_b32_e32 v144, v172, v235
	v_and_b32_e32 v145, v172, v236
	v_and_b32_e32 v146, v172, v237
	v_and_b32_e32 v147, v172, v238
	v_and_b32_e32 v148, v173, v235
	v_and_b32_e32 v149, v173, v236
	v_and_b32_e32 v150, v173, v237
	v_and_b32_e32 v151, v173, v238
	s_mov_b64 vcc, s[4:5]
	v_cndmask_b32_dpp v138, v88, v90, vcc row_shl:4 row_mask:0xf bank_mask:0xf bound_ctrl:1
	v_cndmask_b32_dpp v139, v89, v91, vcc row_shl:4 row_mask:0xf bank_mask:0xf bound_ctrl:1
	s_mov_b64 vcc, s[6:7]
	v_cndmask_b32_dpp v136, v90, v88, vcc row_shr:4 row_mask:0xf bank_mask:0xf bound_ctrl:1
	v_cndmask_b32_dpp v137, v91, v89, vcc row_shr:4 row_mask:0xf bank_mask:0xf bound_ctrl:1
	v_mfma_scale_f32_16x16x128_f8f6f4 v[216:219], v[140:143], v[204:211], v[216:219], v240, v241 op_sel_hi:[0,0,0] cbsz:4
	v_and_b32_e32 v204, v174, v235
	v_and_b32_e32 v205, v174, v236
	v_and_b32_e32 v206, v174, v237
	v_and_b32_e32 v207, v174, v238
	v_and_b32_e32 v208, v175, v235
	v_and_b32_e32 v209, v175, v236
	v_and_b32_e32 v210, v175, v237
	v_and_b32_e32 v211, v175, v238
	s_mov_b64 vcc, s[6:7]
	v_cndmask_b32_dpp v140, v94, v92, vcc row_shr:4 row_mask:0xf bank_mask:0xf bound_ctrl:1
	v_cndmask_b32_dpp v141, v95, v93, vcc row_shr:4 row_mask:0xf bank_mask:0xf bound_ctrl:1
	s_mov_b64 vcc, s[4:5]
	v_cndmask_b32_dpp v142, v92, v94, vcc row_shl:4 row_mask:0xf bank_mask:0xf bound_ctrl:1
	v_cndmask_b32_dpp v143, v93, v95, vcc row_shl:4 row_mask:0xf bank_mask:0xf bound_ctrl:1
	v_mfma_scale_f32_16x16x128_f8f6f4 v[216:219], v[136:139], v[144:151], v[216:219], v240, v241 op_sel_hi:[0,0,0] cbsz:4
	s_nop 0
	v_mfma_scale_f32_16x16x128_f8f6f4 v[216:219], v[140:143], v[204:211], v[216:219], v240, v241 op_sel_hi:[0,0,0] cbsz:4
	s_waitcnt lgkmcnt(0)
	v_lshl_or_b32 v128, v128, 7, v232
	v_lshl_or_b32 v129, v129, 7, v232
	v_lshl_or_b32 v130, v130, 7, v232
	v_lshl_or_b32 v131, v131, 7, v232
	v_lshl_or_b32 v132, v132, 7, v232
	v_lshl_or_b32 v133, v133, 7, v232
	v_lshl_or_b32 v134, v134, 7, v232
	v_lshl_or_b32 v135, v135, 7, v232
	buffer_load_dwordx4 v[64:67], v128, s[20:23], s60 offen
	buffer_load_dwordx4 v[68:71], v129, s[20:23], s60 offen
	buffer_load_dwordx4 v[72:75], v130, s[20:23], s60 offen
	buffer_load_dwordx4 v[76:79], v131, s[20:23], s60 offen
	buffer_load_dwordx4 v[80:83], v132, s[20:23], s60 offen
	buffer_load_dwordx4 v[84:87], v133, s[20:23], s60 offen
	buffer_load_dwordx4 v[88:91], v134, s[20:23], s60 offen
	buffer_load_dwordx4 v[92:95], v135, s[20:23], s60 offen
	ds_read_b32 v128, v243 offset:768
	ds_read_b32 v129, v243 offset:800
	ds_read_b32 v130, v243 offset:832
	ds_read_b32 v131, v243 offset:864
	ds_read_b32 v132, v243 offset:896
	ds_read_b32 v133, v243 offset:928
	ds_read_b32 v134, v243 offset:960
	ds_read_b32 v135, v243 offset:992
	ds_read_b64 v[160:161], v247 offset:0
	ds_read_b64 v[162:163], v247 offset:32
	ds_read_b64 v[164:165], v247 offset:64
	ds_read_b64 v[166:167], v247 offset:96
	ds_read_b64 v[168:169], v247 offset:128
	ds_read_b64 v[170:171], v247 offset:160
	ds_read_b64 v[172:173], v247 offset:192
	ds_read_b64 v[174:175], v247 offset:224
	s_waitcnt vmcnt(26)
	v_and_b32_e32 v144, v176, v235
	v_and_b32_e32 v145, v176, v236
	v_and_b32_e32 v146, v176, v237
	v_and_b32_e32 v147, v176, v238
	v_and_b32_e32 v148, v177, v235
	v_and_b32_e32 v149, v177, v236
	v_and_b32_e32 v150, v177, v237
	v_and_b32_e32 v151, v177, v238
	s_mov_b64 vcc, s[4:5]
	v_cndmask_b32_dpp v138, v96, v98, vcc row_shl:4 row_mask:0xf bank_mask:0xf bound_ctrl:1
	v_cndmask_b32_dpp v139, v97, v99, vcc row_shl:4 row_mask:0xf bank_mask:0xf bound_ctrl:1
	s_mov_b64 vcc, s[6:7]
	v_cndmask_b32_dpp v136, v98, v96, vcc row_shr:4 row_mask:0xf bank_mask:0xf bound_ctrl:1
	v_cndmask_b32_dpp v137, v99, v97, vcc row_shr:4 row_mask:0xf bank_mask:0xf bound_ctrl:1
	v_and_b32_e32 v204, v178, v235
	v_and_b32_e32 v205, v178, v236
	v_and_b32_e32 v206, v178, v237
	v_and_b32_e32 v207, v178, v238
	v_and_b32_e32 v208, v179, v235
	v_and_b32_e32 v209, v179, v236
	v_and_b32_e32 v210, v179, v237
	v_and_b32_e32 v211, v179, v238
	s_mov_b64 vcc, s[6:7]
	v_cndmask_b32_dpp v140, v102, v100, vcc row_shr:4 row_mask:0xf bank_mask:0xf bound_ctrl:1
	v_cndmask_b32_dpp v141, v103, v101, vcc row_shr:4 row_mask:0xf bank_mask:0xf bound_ctrl:1
	s_mov_b64 vcc, s[4:5]
	v_cndmask_b32_dpp v142, v100, v102, vcc row_shl:4 row_mask:0xf bank_mask:0xf bound_ctrl:1
	v_cndmask_b32_dpp v143, v101, v103, vcc row_shl:4 row_mask:0xf bank_mask:0xf bound_ctrl:1
	v_mfma_scale_f32_16x16x128_f8f6f4 v[216:219], v[136:139], v[144:151], v[216:219], v240, v241 op_sel_hi:[0,0,0] cbsz:4
	v_permlane16_swap_b32_e32 v212, v214
	v_permlane16_swap_b32_e32 v213, v215
	v_lshlrev_b32_e32 v252, 16, v228
	v_and_b32_e32 v144, v180, v235
	v_and_b32_e32 v145, v180, v236
	v_and_b32_e32 v146, v180, v237
	v_and_b32_e32 v147, v180, v238
	v_and_b32_e32 v148, v181, v235
	v_and_b32_e32 v149, v181, v236
	v_and_b32_e32 v150, v181, v237
	v_and_b32_e32 v151, v181, v238
	s_mov_b64 vcc, s[4:5]
	v_cndmask_b32_dpp v138, v104, v106, vcc row_shl:4 row_mask:0xf bank_mask:0xf bound_ctrl:1
	v_cndmask_b32_dpp v139, v105, v107, vcc row_shl:4 row_mask:0xf bank_mask:0xf bound_ctrl:1
	s_mov_b64 vcc, s[6:7]
	v_cndmask_b32_dpp v136, v106, v104, vcc row_shr:4 row_mask:0xf bank_mask:0xf bound_ctrl:1
	v_cndmask_b32_dpp v137, v107, v105, vcc row_shr:4 row_mask:0xf bank_mask:0xf bound_ctrl:1
	v_mfma_scale_f32_16x16x128_f8f6f4 v[216:219], v[140:143], v[204:211], v[216:219], v240, v241 op_sel_hi:[0,0,0] cbsz:4
	v_and_b32_e32 v253, 0xffff0000, v228
	v_lshlrev_b32_e32 v254, 16, v229
	v_and_b32_e32 v255, 0xffff0000, v229
	v_and_b32_e32 v204, v182, v235
	v_and_b32_e32 v205, v182, v236
	v_and_b32_e32 v206, v182, v237
	v_and_b32_e32 v207, v182, v238
	v_and_b32_e32 v208, v183, v235
	v_and_b32_e32 v209, v183, v236
	v_and_b32_e32 v210, v183, v237
	v_and_b32_e32 v211, v183, v238
	s_mov_b64 vcc, s[6:7]
	v_cndmask_b32_dpp v140, v110, v108, vcc row_shr:4 row_mask:0xf bank_mask:0xf bound_ctrl:1
	v_cndmask_b32_dpp v141, v111, v109, vcc row_shr:4 row_mask:0xf bank_mask:0xf bound_ctrl:1
	s_mov_b64 vcc, s[4:5]
	v_cndmask_b32_dpp v142, v108, v110, vcc row_shl:4 row_mask:0xf bank_mask:0xf bound_ctrl:1
	v_cndmask_b32_dpp v143, v109, v111, vcc row_shl:4 row_mask:0xf bank_mask:0xf bound_ctrl:1
	v_mfma_scale_f32_16x16x128_f8f6f4 v[216:219], v[136:139], v[144:151], v[216:219], v240, v241 op_sel_hi:[0,0,0] cbsz:4
	v_add_f32_e32 v252, v212, v252
	v_add_f32_e32 v253, v214, v253
	v_add_f32_e32 v254, v213, v254
	v_and_b32_e32 v144, v184, v235
	v_and_b32_e32 v145, v184, v236
	v_and_b32_e32 v146, v184, v237
	v_and_b32_e32 v147, v184, v238
	v_and_b32_e32 v148, v185, v235
	v_and_b32_e32 v149, v185, v236
	v_and_b32_e32 v150, v185, v237
	v_and_b32_e32 v151, v185, v238
	s_mov_b64 vcc, s[4:5]
	v_cndmask_b32_dpp v138, v112, v114, vcc row_shl:4 row_mask:0xf bank_mask:0xf bound_ctrl:1
	v_cndmask_b32_dpp v139, v113, v115, vcc row_shl:4 row_mask:0xf bank_mask:0xf bound_ctrl:1
	s_mov_b64 vcc, s[6:7]
	v_cndmask_b32_dpp v136, v114, v112, vcc row_shr:4 row_mask:0xf bank_mask:0xf bound_ctrl:1
	v_cndmask_b32_dpp v137, v115, v113, vcc row_shr:4 row_mask:0xf bank_mask:0xf bound_ctrl:1
	v_mfma_scale_f32_16x16x128_f8f6f4 v[216:219], v[140:143], v[204:211], v[216:219], v240, v241 op_sel_hi:[0,0,0] cbsz:4
	v_add_f32_e32 v255, v215, v255
	v_mul_f32_e32 v192, v252, v252
	v_mul_f32_e32 v193, v254, v254
	v_and_b32_e32 v204, v186, v235
	v_and_b32_e32 v205, v186, v236
	v_and_b32_e32 v206, v186, v237
	v_and_b32_e32 v207, v186, v238
	v_and_b32_e32 v208, v187, v235
	v_and_b32_e32 v209, v187, v236
	v_and_b32_e32 v210, v187, v237
	v_and_b32_e32 v211, v187, v238
	s_mov_b64 vcc, s[6:7]
	v_cndmask_b32_dpp v140, v118, v116, vcc row_shr:4 row_mask:0xf bank_mask:0xf bound_ctrl:1
	v_cndmask_b32_dpp v141, v119, v117, vcc row_shr:4 row_mask:0xf bank_mask:0xf bound_ctrl:1
	s_mov_b64 vcc, s[4:5]
	v_cndmask_b32_dpp v142, v116, v118, vcc row_shl:4 row_mask:0xf bank_mask:0xf bound_ctrl:1
	v_cndmask_b32_dpp v143, v117, v119, vcc row_shl:4 row_mask:0xf bank_mask:0xf bound_ctrl:1
	v_mfma_scale_f32_16x16x128_f8f6f4 v[216:219], v[136:139], v[144:151], v[216:219], v240, v241 op_sel_hi:[0,0,0] cbsz:4
	v_fmac_f32_e32 v192, v253, v253
	v_fmac_f32_e32 v193, v255, v255
	v_cvt_pk_bf16_f32 v250, v252, v253
	v_and_b32_e32 v144, v188, v235
	v_and_b32_e32 v145, v188, v236
	v_and_b32_e32 v146, v188, v237
	v_and_b32_e32 v147, v188, v238
	v_and_b32_e32 v148, v189, v235
	v_and_b32_e32 v149, v189, v236
	v_and_b32_e32 v150, v189, v237
	v_and_b32_e32 v151, v189, v238
	s_mov_b64 vcc, s[4:5]
	v_cndmask_b32_dpp v138, v120, v122, vcc row_shl:4 row_mask:0xf bank_mask:0xf bound_ctrl:1
	v_cndmask_b32_dpp v139, v121, v123, vcc row_shl:4 row_mask:0xf bank_mask:0xf bound_ctrl:1
	s_mov_b64 vcc, s[6:7]
	v_cndmask_b32_dpp v136, v122, v120, vcc row_shr:4 row_mask:0xf bank_mask:0xf bound_ctrl:1
	v_cndmask_b32_dpp v137, v123, v121, vcc row_shr:4 row_mask:0xf bank_mask:0xf bound_ctrl:1
	v_mfma_scale_f32_16x16x128_f8f6f4 v[216:219], v[140:143], v[204:211], v[216:219], v240, v241 op_sel_hi:[0,0,0] cbsz:4
	v_cvt_pk_bf16_f32 v251, v254, v255
	v_add_f32_e32 v192, v192, v193
	v_add_f32_e32 v226, v226, v192
	v_and_b32_e32 v204, v190, v235
	v_and_b32_e32 v205, v190, v236
	v_and_b32_e32 v206, v190, v237
	v_and_b32_e32 v207, v190, v238
	v_and_b32_e32 v208, v191, v235
	v_and_b32_e32 v209, v191, v236
	v_and_b32_e32 v210, v191, v237
	v_and_b32_e32 v211, v191, v238
	s_mov_b64 vcc, s[6:7]
	v_cndmask_b32_dpp v140, v126, v124, vcc row_shr:4 row_mask:0xf bank_mask:0xf bound_ctrl:1
	v_cndmask_b32_dpp v141, v127, v125, vcc row_shr:4 row_mask:0xf bank_mask:0xf bound_ctrl:1
	s_mov_b64 vcc, s[4:5]
	v_cndmask_b32_dpp v142, v124, v126, vcc row_shl:4 row_mask:0xf bank_mask:0xf bound_ctrl:1
	v_cndmask_b32_dpp v143, v125, v127, vcc row_shl:4 row_mask:0xf bank_mask:0xf bound_ctrl:1
	v_mfma_scale_f32_16x16x128_f8f6f4 v[216:219], v[136:139], v[144:151], v[216:219], v240, v241 op_sel_hi:[0,0,0] cbsz:4
	s_nop 0
	v_mfma_scale_f32_16x16x128_f8f6f4 v[216:219], v[140:143], v[204:211], v[216:219], v240, v241 op_sel_hi:[0,0,0] cbsz:4
	s_lshl_b32 s64, s0, 9
	s_add_u32 s64, s64, 0x6000
	s_add_u32 s76, s28, s64
	s_addc_u32 s77, s29, 0
	global_store_dwordx2 v239, v[250:251], s[76:77]
	s_add_u32 s0, s0, 1
	s_lshl_b32 s1, s0, 21
	s_add_u32 s60, s1, 0x200000
	s_cmp_ge_u32 s0, 3
	s_movk_i32 s65, 0x2000
	s_cselect_b32 s64, s65, 0x1000
	v_mov_b32_e32 v234, v247
	v_add_u32_e32 v247, s64, v233
	s_cmp_lt_u32 s0, 8
	s_cbranch_scc1 .LpgL1_vloopv0
	s_waitcnt vmcnt(0)
	s_nop 15
	v_permlane16_swap_b32_e32 v216, v218
	v_permlane16_swap_b32_e32 v217, v219
	v_lshlrev_b32_e32 v252, 16, v230
	v_and_b32_e32 v253, 0xffff0000, v230
	v_lshlrev_b32_e32 v254, 16, v231
	v_and_b32_e32 v255, 0xffff0000, v231
	v_add_f32_e32 v252, v216, v252
	v_add_f32_e32 v253, v218, v253
	v_add_f32_e32 v254, v217, v254
	v_add_f32_e32 v255, v219, v255
	v_mul_f32_e32 v192, v252, v252
	v_mul_f32_e32 v193, v254, v254
	v_fmac_f32_e32 v192, v253, v253
	v_fmac_f32_e32 v193, v255, v255
	v_cvt_pk_bf16_f32 v250, v252, v253
	v_cvt_pk_bf16_f32 v251, v254, v255
	v_add_f32_e32 v192, v192, v193
	v_add_f32_e32 v227, v227, v192
	s_lshl_b32 s64, s0, 9
	s_add_u32 s64, s64, 0x6e00
	s_add_u32 s76, s28, s64
	s_addc_u32 s77, s29, 0
	global_store_dwordx2 v239, v[250:251], s[76:77]
	s_nop 1
	v_add_f32_dpp v220, v220, v220 quad_perm:[1,0,3,2] row_mask:0xf bank_mask:0xf bound_ctrl:1
	s_nop 1
	v_add_f32_dpp v220, v220, v220 quad_perm:[2,3,0,1] row_mask:0xf bank_mask:0xf bound_ctrl:1
	s_nop 1
	v_add_f32_dpp v220, v220, v220 row_half_mirror row_mask:0xf bank_mask:0xf bound_ctrl:1
	s_nop 1
	v_add_f32_dpp v220, v220, v220 row_mirror row_mask:0xf bank_mask:0xf bound_ctrl:1
	v_mov_b32_e32 v249, v220
	s_nop 1
	v_permlane16_swap_b32_e32 v220, v249
	v_add_f32_e32 v220, v220, v249
	v_mov_b32_e32 v249, v220
	s_nop 1
	v_permlane32_swap_b32_e32 v220, v249
	v_add_f32_e32 v220, v220, v249
	s_nop 1
	v_add_f32_dpp v221, v221, v221 quad_perm:[1,0,3,2] row_mask:0xf bank_mask:0xf bound_ctrl:1
	s_nop 1
	v_add_f32_dpp v221, v221, v221 quad_perm:[2,3,0,1] row_mask:0xf bank_mask:0xf bound_ctrl:1
	s_nop 1
	v_add_f32_dpp v221, v221, v221 row_half_mirror row_mask:0xf bank_mask:0xf bound_ctrl:1
	s_nop 1
	v_add_f32_dpp v221, v221, v221 row_mirror row_mask:0xf bank_mask:0xf bound_ctrl:1
	v_mov_b32_e32 v249, v221
	s_nop 1
	v_permlane16_swap_b32_e32 v221, v249
	v_add_f32_e32 v221, v221, v249
	v_mov_b32_e32 v249, v221
	s_nop 1
	v_permlane32_swap_b32_e32 v221, v249
	v_add_f32_e32 v221, v221, v249
	s_nop 1
	v_add_f32_dpp v222, v222, v222 quad_perm:[1,0,3,2] row_mask:0xf bank_mask:0xf bound_ctrl:1
	s_nop 1
	v_add_f32_dpp v222, v222, v222 quad_perm:[2,3,0,1] row_mask:0xf bank_mask:0xf bound_ctrl:1
	s_nop 1
	v_add_f32_dpp v222, v222, v222 row_half_mirror row_mask:0xf bank_mask:0xf bound_ctrl:1
	s_nop 1
	v_add_f32_dpp v222, v222, v222 row_mirror row_mask:0xf bank_mask:0xf bound_ctrl:1
	v_mov_b32_e32 v249, v222
	s_nop 1
	v_permlane16_swap_b32_e32 v222, v249
	v_add_f32_e32 v222, v222, v249
	v_mov_b32_e32 v249, v222
	s_nop 1
	v_permlane32_swap_b32_e32 v222, v249
	v_add_f32_e32 v222, v222, v249
	s_nop 1
	v_add_f32_dpp v223, v223, v223 quad_perm:[1,0,3,2] row_mask:0xf bank_mask:0xf bound_ctrl:1
	s_nop 1
	v_add_f32_dpp v223, v223, v223 quad_perm:[2,3,0,1] row_mask:0xf bank_mask:0xf bound_ctrl:1
	s_nop 1
	v_add_f32_dpp v223, v223, v223 row_half_mirror row_mask:0xf bank_mask:0xf bound_ctrl:1
	s_nop 1
	v_add_f32_dpp v223, v223, v223 row_mirror row_mask:0xf bank_mask:0xf bound_ctrl:1
	v_mov_b32_e32 v249, v223
	s_nop 1
	v_permlane16_swap_b32_e32 v223, v249
	v_add_f32_e32 v223, v223, v249
	v_mov_b32_e32 v249, v223
	s_nop 1
	v_permlane32_swap_b32_e32 v223, v249
	v_add_f32_e32 v223, v223, v249
	s_nop 1
	v_add_f32_dpp v224, v224, v224 quad_perm:[1,0,3,2] row_mask:0xf bank_mask:0xf bound_ctrl:1
	s_nop 1
	v_add_f32_dpp v224, v224, v224 quad_perm:[2,3,0,1] row_mask:0xf bank_mask:0xf bound_ctrl:1
	s_nop 1
	v_add_f32_dpp v224, v224, v224 row_half_mirror row_mask:0xf bank_mask:0xf bound_ctrl:1
	s_nop 1
	v_add_f32_dpp v224, v224, v224 row_mirror row_mask:0xf bank_mask:0xf bound_ctrl:1
	v_mov_b32_e32 v249, v224
	s_nop 1
	v_permlane16_swap_b32_e32 v224, v249
	v_add_f32_e32 v224, v224, v249
	v_mov_b32_e32 v249, v224
	s_nop 1
	v_permlane32_swap_b32_e32 v224, v249
	v_add_f32_e32 v224, v224, v249
	s_nop 1
	v_add_f32_dpp v225, v225, v225 quad_perm:[1,0,3,2] row_mask:0xf bank_mask:0xf bound_ctrl:1
	s_nop 1
	v_add_f32_dpp v225, v225, v225 quad_perm:[2,3,0,1] row_mask:0xf bank_mask:0xf bound_ctrl:1
	s_nop 1
	v_add_f32_dpp v225, v225, v225 row_half_mirror row_mask:0xf bank_mask:0xf bound_ctrl:1
	s_nop 1
	v_add_f32_dpp v225, v225, v225 row_mirror row_mask:0xf bank_mask:0xf bound_ctrl:1
	v_mov_b32_e32 v249, v225
	s_nop 1
	v_permlane16_swap_b32_e32 v225, v249
	v_add_f32_e32 v225, v225, v249
	v_mov_b32_e32 v249, v225
	s_nop 1
	v_permlane32_swap_b32_e32 v225, v249
	v_add_f32_e32 v225, v225, v249
	s_nop 1
	v_add_f32_dpp v226, v226, v226 quad_perm:[1,0,3,2] row_mask:0xf bank_mask:0xf bound_ctrl:1
	s_nop 1
	v_add_f32_dpp v226, v226, v226 quad_perm:[2,3,0,1] row_mask:0xf bank_mask:0xf bound_ctrl:1
	s_nop 1
	v_add_f32_dpp v226, v226, v226 row_half_mirror row_mask:0xf bank_mask:0xf bound_ctrl:1
	s_nop 1
	v_add_f32_dpp v226, v226, v226 row_mirror row_mask:0xf bank_mask:0xf bound_ctrl:1
	v_mov_b32_e32 v249, v226
	s_nop 1
	v_permlane16_swap_b32_e32 v226, v249
	v_add_f32_e32 v226, v226, v249
	v_mov_b32_e32 v249, v226
	s_nop 1
	v_permlane32_swap_b32_e32 v226, v249
	v_add_f32_e32 v226, v226, v249
	s_nop 1
	v_add_f32_dpp v227, v227, v227 quad_perm:[1,0,3,2] row_mask:0xf bank_mask:0xf bound_ctrl:1
	s_nop 1
	v_add_f32_dpp v227, v227, v227 quad_perm:[2,3,0,1] row_mask:0xf bank_mask:0xf bound_ctrl:1
	s_nop 1
	v_add_f32_dpp v227, v227, v227 row_half_mirror row_mask:0xf bank_mask:0xf bound_ctrl:1
	s_nop 1
	v_add_f32_dpp v227, v227, v227 row_mirror row_mask:0xf bank_mask:0xf bound_ctrl:1
	v_mov_b32_e32 v249, v227
	s_nop 1
	v_permlane16_swap_b32_e32 v227, v249
	v_add_f32_e32 v227, v227, v249
	v_mov_b32_e32 v249, v227
	s_nop 1
	v_permlane32_swap_b32_e32 v227, v249
	v_add_f32_e32 v227, v227, v249
	s_waitcnt vmcnt(0)
	v_lshlrev_b32_e32 v250, 1, v239
	v_add_u32_e32 v251, 0x1000, v250
	global_load_dwordx4 v[0:3], v250, s[66:67] offset:0
	global_load_dwordx4 v[4:7], v250, s[66:67] offset:1024
	global_load_dwordx4 v[8:11], v250, s[66:67] offset:2048
	global_load_dwordx4 v[12:15], v250, s[66:67] offset:3072
	global_load_dwordx4 v[16:19], v251, s[66:67] offset:0
	global_load_dwordx4 v[20:23], v251, s[66:67] offset:1024
	global_load_dwordx4 v[24:27], v251, s[66:67] offset:2048
	global_load_dwordx4 v[28:31], v251, s[66:67] offset:3072
	v_mov_b32_e32 v120, 0x358637bd
	v_fmamk_f32 v220, v220, 0x3a000000, v120
	v_cmp_gt_f32_e32 vcc, s96, v220
	v_mul_f32_e32 v121, 0x4b800000, v220
	s_nop 0
	v_cndmask_b32_e32 v220, v220, v121, vcc
	v_rsq_f32_e32 v220, v220
	s_nop 0
	v_mul_f32_e32 v121, 0x45800000, v220
	v_cndmask_b32_e32 v220, v220, v121, vcc
	v_fmamk_f32 v221, v221, 0x3a000000, v120
	v_cmp_gt_f32_e32 vcc, s96, v221
	v_mul_f32_e32 v121, 0x4b800000, v221
	s_nop 0
	v_cndmask_b32_e32 v221, v221, v121, vcc
	v_rsq_f32_e32 v221, v221
	s_nop 0
	v_mul_f32_e32 v121, 0x45800000, v221
	v_cndmask_b32_e32 v221, v221, v121, vcc
	v_fmamk_f32 v222, v222, 0x3a000000, v120
	v_cmp_gt_f32_e32 vcc, s96, v222
	v_mul_f32_e32 v121, 0x4b800000, v222
	s_nop 0
	v_cndmask_b32_e32 v222, v222, v121, vcc
	v_rsq_f32_e32 v222, v222
	s_nop 0
	v_mul_f32_e32 v121, 0x45800000, v222
	v_cndmask_b32_e32 v222, v222, v121, vcc
	v_fmamk_f32 v223, v223, 0x3a000000, v120
	v_cmp_gt_f32_e32 vcc, s96, v223
	v_mul_f32_e32 v121, 0x4b800000, v223
	s_nop 0
	v_cndmask_b32_e32 v223, v223, v121, vcc
	v_rsq_f32_e32 v223, v223
	s_nop 0
	v_mul_f32_e32 v121, 0x45800000, v223
	v_cndmask_b32_e32 v223, v223, v121, vcc
	v_fmamk_f32 v224, v224, 0x3a000000, v120
	v_cmp_gt_f32_e32 vcc, s96, v224
	v_mul_f32_e32 v121, 0x4b800000, v224
	s_nop 0
	v_cndmask_b32_e32 v224, v224, v121, vcc
	v_rsq_f32_e32 v224, v224
	s_nop 0
	v_mul_f32_e32 v121, 0x45800000, v224
	v_cndmask_b32_e32 v224, v224, v121, vcc
	v_fmamk_f32 v225, v225, 0x3a000000, v120
	v_cmp_gt_f32_e32 vcc, s96, v225
	v_mul_f32_e32 v121, 0x4b800000, v225
	s_nop 0
	v_cndmask_b32_e32 v225, v225, v121, vcc
	v_rsq_f32_e32 v225, v225
	s_nop 0
	v_mul_f32_e32 v121, 0x45800000, v225
	v_cndmask_b32_e32 v225, v225, v121, vcc
	v_fmamk_f32 v226, v226, 0x3a000000, v120
	v_cmp_gt_f32_e32 vcc, s96, v226
	v_mul_f32_e32 v121, 0x4b800000, v226
	s_nop 0
	v_cndmask_b32_e32 v226, v226, v121, vcc
	v_rsq_f32_e32 v226, v226
	s_nop 0
	v_mul_f32_e32 v121, 0x45800000, v226
	v_cndmask_b32_e32 v226, v226, v121, vcc
	v_fmamk_f32 v227, v227, 0x3a000000, v120
	v_cmp_gt_f32_e32 vcc, s96, v227
	v_mul_f32_e32 v121, 0x4b800000, v227
	s_nop 0
	v_cndmask_b32_e32 v227, v227, v121, vcc
	v_rsq_f32_e32 v227, v227
	s_nop 0
	v_mul_f32_e32 v121, 0x45800000, v227
	v_cndmask_b32_e32 v227, v227, v121, vcc
	s_add_u32 s70, s28, 0x0
	s_addc_u32 s71, s29, 0
	global_load_dwordx2 v[32:33], v239, s[70:71] offset:0
	global_load_dwordx2 v[34:35], v239, s[70:71] offset:512
	global_load_dwordx2 v[36:37], v239, s[70:71] offset:1024
	global_load_dwordx2 v[38:39], v239, s[70:71] offset:1536
	global_load_dwordx2 v[40:41], v239, s[70:71] offset:2048
	global_load_dwordx2 v[42:43], v239, s[70:71] offset:2560
	global_load_dwordx2 v[44:45], v239, s[70:71] offset:3072
	global_load_dwordx2 v[46:47], v239, s[70:71] offset:3584
	s_add_u32 s70, s28, 0x1000
	s_addc_u32 s71, s29, 0
	global_load_dwordx2 v[48:49], v239, s[70:71] offset:0
	global_load_dwordx2 v[50:51], v239, s[70:71] offset:512
	global_load_dwordx2 v[52:53], v239, s[70:71] offset:1024
	global_load_dwordx2 v[54:55], v239, s[70:71] offset:1536
	global_load_dwordx2 v[56:57], v239, s[70:71] offset:2048
	global_load_dwordx2 v[58:59], v239, s[70:71] offset:2560
	global_load_dwordx2 v[60:61], v239, s[70:71] offset:3072
	global_load_dwordx2 v[62:63], v239, s[70:71] offset:3584
	s_waitcnt vmcnt(8)
	s_add_u32 s76, s46, 0x0
	s_addc_u32 s77, s47, 0
	v_lshlrev_b32_e32 v64, 16, v32
	v_and_b32_e32 v65, 0xffff0000, v32
	v_lshlrev_b32_e32 v66, 16, v33
	v_and_b32_e32 v67, 0xffff0000, v33
	v_mul_f32_e32 v64, v64, v220
	v_mul_f32_e32 v65, v65, v220
	v_mul_f32_e32 v66, v66, v220
	v_mul_f32_e32 v67, v67, v220
	v_mul_f32_e32 v64, v64, v0
	v_mul_f32_e32 v65, v65, v1
	v_mul_f32_e32 v66, v66, v2
	v_mul_f32_e32 v67, v67, v3
	global_store_dwordx4 v250, v[64:67], s[76:77] offset:0 nt
	v_lshlrev_b32_e32 v68, 16, v34
	v_and_b32_e32 v69, 0xffff0000, v34
	v_lshlrev_b32_e32 v70, 16, v35
	v_and_b32_e32 v71, 0xffff0000, v35
	v_mul_f32_e32 v68, v68, v220
	v_mul_f32_e32 v69, v69, v220
	v_mul_f32_e32 v70, v70, v220
	v_mul_f32_e32 v71, v71, v220
	v_mul_f32_e32 v68, v68, v4
	v_mul_f32_e32 v69, v69, v5
	v_mul_f32_e32 v70, v70, v6
	v_mul_f32_e32 v71, v71, v7
	global_store_dwordx4 v250, v[68:71], s[76:77] offset:1024 nt
	v_lshlrev_b32_e32 v72, 16, v36
	v_and_b32_e32 v73, 0xffff0000, v36
	v_lshlrev_b32_e32 v74, 16, v37
	v_and_b32_e32 v75, 0xffff0000, v37
	v_mul_f32_e32 v72, v72, v220
	v_mul_f32_e32 v73, v73, v220
	v_mul_f32_e32 v74, v74, v220
	v_mul_f32_e32 v75, v75, v220
	v_mul_f32_e32 v72, v72, v8
	v_mul_f32_e32 v73, v73, v9
	v_mul_f32_e32 v74, v74, v10
	v_mul_f32_e32 v75, v75, v11
	global_store_dwordx4 v250, v[72:75], s[76:77] offset:2048 nt
	v_lshlrev_b32_e32 v76, 16, v38
	v_and_b32_e32 v77, 0xffff0000, v38
	v_lshlrev_b32_e32 v78, 16, v39
	v_and_b32_e32 v79, 0xffff0000, v39
	v_mul_f32_e32 v76, v76, v220
	v_mul_f32_e32 v77, v77, v220
	v_mul_f32_e32 v78, v78, v220
	v_mul_f32_e32 v79, v79, v220
	v_mul_f32_e32 v76, v76, v12
	v_mul_f32_e32 v77, v77, v13
	v_mul_f32_e32 v78, v78, v14
	v_mul_f32_e32 v79, v79, v15
	global_store_dwordx4 v250, v[76:79], s[76:77] offset:3072 nt
	v_lshlrev_b32_e32 v64, 16, v40
	v_and_b32_e32 v65, 0xffff0000, v40
	v_lshlrev_b32_e32 v66, 16, v41
	v_and_b32_e32 v67, 0xffff0000, v41
	v_mul_f32_e32 v64, v64, v220
	v_mul_f32_e32 v65, v65, v220
	v_mul_f32_e32 v66, v66, v220
	v_mul_f32_e32 v67, v67, v220
	v_mul_f32_e32 v64, v64, v16
	v_mul_f32_e32 v65, v65, v17
	v_mul_f32_e32 v66, v66, v18
	v_mul_f32_e32 v67, v67, v19
	global_store_dwordx4 v251, v[64:67], s[76:77] offset:0 nt
	v_lshlrev_b32_e32 v68, 16, v42
	v_and_b32_e32 v69, 0xffff0000, v42
	v_lshlrev_b32_e32 v70, 16, v43
	v_and_b32_e32 v71, 0xffff0000, v43
	v_mul_f32_e32 v68, v68, v220
	v_mul_f32_e32 v69, v69, v220
	v_mul_f32_e32 v70, v70, v220
	v_mul_f32_e32 v71, v71, v220
	v_mul_f32_e32 v68, v68, v20
	v_mul_f32_e32 v69, v69, v21
	v_mul_f32_e32 v70, v70, v22
	v_mul_f32_e32 v71, v71, v23
	global_store_dwordx4 v251, v[68:71], s[76:77] offset:1024 nt
	v_lshlrev_b32_e32 v72, 16, v44
	v_and_b32_e32 v73, 0xffff0000, v44
	v_lshlrev_b32_e32 v74, 16, v45
	v_and_b32_e32 v75, 0xffff0000, v45
	v_mul_f32_e32 v72, v72, v220
	v_mul_f32_e32 v73, v73, v220
	v_mul_f32_e32 v74, v74, v220
	v_mul_f32_e32 v75, v75, v220
	v_mul_f32_e32 v72, v72, v24
	v_mul_f32_e32 v73, v73, v25
	v_mul_f32_e32 v74, v74, v26
	v_mul_f32_e32 v75, v75, v27
	global_store_dwordx4 v251, v[72:75], s[76:77] offset:2048 nt
	v_lshlrev_b32_e32 v76, 16, v46
	v_and_b32_e32 v77, 0xffff0000, v46
	v_lshlrev_b32_e32 v78, 16, v47
	v_and_b32_e32 v79, 0xffff0000, v47
	v_mul_f32_e32 v76, v76, v220
	v_mul_f32_e32 v77, v77, v220
	v_mul_f32_e32 v78, v78, v220
	v_mul_f32_e32 v79, v79, v220
	v_mul_f32_e32 v76, v76, v28
	v_mul_f32_e32 v77, v77, v29
	v_mul_f32_e32 v78, v78, v30
	v_mul_f32_e32 v79, v79, v31
	global_store_dwordx4 v251, v[76:79], s[76:77] offset:3072 nt
	s_add_u32 s70, s28, 0x2000
	s_addc_u32 s71, s29, 0
	global_load_dwordx2 v[32:33], v239, s[70:71] offset:0
	global_load_dwordx2 v[34:35], v239, s[70:71] offset:512
	global_load_dwordx2 v[36:37], v239, s[70:71] offset:1024
	global_load_dwordx2 v[38:39], v239, s[70:71] offset:1536
	global_load_dwordx2 v[40:41], v239, s[70:71] offset:2048
	global_load_dwordx2 v[42:43], v239, s[70:71] offset:2560
	global_load_dwordx2 v[44:45], v239, s[70:71] offset:3072
	global_load_dwordx2 v[46:47], v239, s[70:71] offset:3584
	s_waitcnt vmcnt(16)
	s_add_u32 s76, s46, 0x2000
	s_addc_u32 s77, s47, 0
	v_lshlrev_b32_e32 v64, 16, v48
	v_and_b32_e32 v65, 0xffff0000, v48
	v_lshlrev_b32_e32 v66, 16, v49
	v_and_b32_e32 v67, 0xffff0000, v49
	v_mul_f32_e32 v64, v64, v221
	v_mul_f32_e32 v65, v65, v221
	v_mul_f32_e32 v66, v66, v221
	v_mul_f32_e32 v67, v67, v221
	v_mul_f32_e32 v64, v64, v0
	v_mul_f32_e32 v65, v65, v1
	v_mul_f32_e32 v66, v66, v2
	v_mul_f32_e32 v67, v67, v3
	global_store_dwordx4 v250, v[64:67], s[76:77] offset:0 nt
	v_lshlrev_b32_e32 v68, 16, v50
	v_and_b32_e32 v69, 0xffff0000, v50
	v_lshlrev_b32_e32 v70, 16, v51
	v_and_b32_e32 v71, 0xffff0000, v51
	v_mul_f32_e32 v68, v68, v221
	v_mul_f32_e32 v69, v69, v221
	v_mul_f32_e32 v70, v70, v221
	v_mul_f32_e32 v71, v71, v221
	v_mul_f32_e32 v68, v68, v4
	v_mul_f32_e32 v69, v69, v5
	v_mul_f32_e32 v70, v70, v6
	v_mul_f32_e32 v71, v71, v7
	global_store_dwordx4 v250, v[68:71], s[76:77] offset:1024 nt
	v_lshlrev_b32_e32 v72, 16, v52
	v_and_b32_e32 v73, 0xffff0000, v52
	v_lshlrev_b32_e32 v74, 16, v53
	v_and_b32_e32 v75, 0xffff0000, v53
	v_mul_f32_e32 v72, v72, v221
	v_mul_f32_e32 v73, v73, v221
	v_mul_f32_e32 v74, v74, v221
	v_mul_f32_e32 v75, v75, v221
	v_mul_f32_e32 v72, v72, v8
	v_mul_f32_e32 v73, v73, v9
	v_mul_f32_e32 v74, v74, v10
	v_mul_f32_e32 v75, v75, v11
	global_store_dwordx4 v250, v[72:75], s[76:77] offset:2048 nt
	v_lshlrev_b32_e32 v76, 16, v54
	v_and_b32_e32 v77, 0xffff0000, v54
	v_lshlrev_b32_e32 v78, 16, v55
	v_and_b32_e32 v79, 0xffff0000, v55
	v_mul_f32_e32 v76, v76, v221
	v_mul_f32_e32 v77, v77, v221
	v_mul_f32_e32 v78, v78, v221
	v_mul_f32_e32 v79, v79, v221
	v_mul_f32_e32 v76, v76, v12
	v_mul_f32_e32 v77, v77, v13
	v_mul_f32_e32 v78, v78, v14
	v_mul_f32_e32 v79, v79, v15
	global_store_dwordx4 v250, v[76:79], s[76:77] offset:3072 nt
	v_lshlrev_b32_e32 v64, 16, v56
	v_and_b32_e32 v65, 0xffff0000, v56
	v_lshlrev_b32_e32 v66, 16, v57
	v_and_b32_e32 v67, 0xffff0000, v57
	v_mul_f32_e32 v64, v64, v221
	v_mul_f32_e32 v65, v65, v221
	v_mul_f32_e32 v66, v66, v221
	v_mul_f32_e32 v67, v67, v221
	v_mul_f32_e32 v64, v64, v16
	v_mul_f32_e32 v65, v65, v17
	v_mul_f32_e32 v66, v66, v18
	v_mul_f32_e32 v67, v67, v19
	global_store_dwordx4 v251, v[64:67], s[76:77] offset:0 nt
	v_lshlrev_b32_e32 v68, 16, v58
	v_and_b32_e32 v69, 0xffff0000, v58
	v_lshlrev_b32_e32 v70, 16, v59
	v_and_b32_e32 v71, 0xffff0000, v59
	v_mul_f32_e32 v68, v68, v221
	v_mul_f32_e32 v69, v69, v221
	v_mul_f32_e32 v70, v70, v221
	v_mul_f32_e32 v71, v71, v221
	v_mul_f32_e32 v68, v68, v20
	v_mul_f32_e32 v69, v69, v21
	v_mul_f32_e32 v70, v70, v22
	v_mul_f32_e32 v71, v71, v23
	global_store_dwordx4 v251, v[68:71], s[76:77] offset:1024 nt
	v_lshlrev_b32_e32 v72, 16, v60
	v_and_b32_e32 v73, 0xffff0000, v60
	v_lshlrev_b32_e32 v74, 16, v61
	v_and_b32_e32 v75, 0xffff0000, v61
	v_mul_f32_e32 v72, v72, v221
	v_mul_f32_e32 v73, v73, v221
	v_mul_f32_e32 v74, v74, v221
	v_mul_f32_e32 v75, v75, v221
	v_mul_f32_e32 v72, v72, v24
	v_mul_f32_e32 v73, v73, v25
	v_mul_f32_e32 v74, v74, v26
	v_mul_f32_e32 v75, v75, v27
	global_store_dwordx4 v251, v[72:75], s[76:77] offset:2048 nt
	v_lshlrev_b32_e32 v76, 16, v62
	v_and_b32_e32 v77, 0xffff0000, v62
	v_lshlrev_b32_e32 v78, 16, v63
	v_and_b32_e32 v79, 0xffff0000, v63
	v_mul_f32_e32 v76, v76, v221
	v_mul_f32_e32 v77, v77, v221
	v_mul_f32_e32 v78, v78, v221
	v_mul_f32_e32 v79, v79, v221
	v_mul_f32_e32 v76, v76, v28
	v_mul_f32_e32 v77, v77, v29
	v_mul_f32_e32 v78, v78, v30
	v_mul_f32_e32 v79, v79, v31
	global_store_dwordx4 v251, v[76:79], s[76:77] offset:3072 nt
	s_add_u32 s70, s28, 0x3000
	s_addc_u32 s71, s29, 0
	global_load_dwordx2 v[48:49], v239, s[70:71] offset:0
	global_load_dwordx2 v[50:51], v239, s[70:71] offset:512
	global_load_dwordx2 v[52:53], v239, s[70:71] offset:1024
	global_load_dwordx2 v[54:55], v239, s[70:71] offset:1536
	global_load_dwordx2 v[56:57], v239, s[70:71] offset:2048
	global_load_dwordx2 v[58:59], v239, s[70:71] offset:2560
	global_load_dwordx2 v[60:61], v239, s[70:71] offset:3072
	global_load_dwordx2 v[62:63], v239, s[70:71] offset:3584
	s_waitcnt vmcnt(16)
	s_add_u32 s76, s46, 0x4000
	s_addc_u32 s77, s47, 0
	v_lshlrev_b32_e32 v64, 16, v32
	v_and_b32_e32 v65, 0xffff0000, v32
	v_lshlrev_b32_e32 v66, 16, v33
	v_and_b32_e32 v67, 0xffff0000, v33
	v_mul_f32_e32 v64, v64, v222
	v_mul_f32_e32 v65, v65, v222
	v_mul_f32_e32 v66, v66, v222
	v_mul_f32_e32 v67, v67, v222
	v_mul_f32_e32 v64, v64, v0
	v_mul_f32_e32 v65, v65, v1
	v_mul_f32_e32 v66, v66, v2
	v_mul_f32_e32 v67, v67, v3
	global_store_dwordx4 v250, v[64:67], s[76:77] offset:0 nt
	v_lshlrev_b32_e32 v68, 16, v34
	v_and_b32_e32 v69, 0xffff0000, v34
	v_lshlrev_b32_e32 v70, 16, v35
	v_and_b32_e32 v71, 0xffff0000, v35
	v_mul_f32_e32 v68, v68, v222
	v_mul_f32_e32 v69, v69, v222
	v_mul_f32_e32 v70, v70, v222
	v_mul_f32_e32 v71, v71, v222
	v_mul_f32_e32 v68, v68, v4
	v_mul_f32_e32 v69, v69, v5
	v_mul_f32_e32 v70, v70, v6
	v_mul_f32_e32 v71, v71, v7
	global_store_dwordx4 v250, v[68:71], s[76:77] offset:1024 nt
	v_lshlrev_b32_e32 v72, 16, v36
	v_and_b32_e32 v73, 0xffff0000, v36
	v_lshlrev_b32_e32 v74, 16, v37
	v_and_b32_e32 v75, 0xffff0000, v37
	v_mul_f32_e32 v72, v72, v222
	v_mul_f32_e32 v73, v73, v222
	v_mul_f32_e32 v74, v74, v222
	v_mul_f32_e32 v75, v75, v222
	v_mul_f32_e32 v72, v72, v8
	v_mul_f32_e32 v73, v73, v9
	v_mul_f32_e32 v74, v74, v10
	v_mul_f32_e32 v75, v75, v11
	global_store_dwordx4 v250, v[72:75], s[76:77] offset:2048 nt
	v_lshlrev_b32_e32 v76, 16, v38
	v_and_b32_e32 v77, 0xffff0000, v38
	v_lshlrev_b32_e32 v78, 16, v39
	v_and_b32_e32 v79, 0xffff0000, v39
	v_mul_f32_e32 v76, v76, v222
	v_mul_f32_e32 v77, v77, v222
	v_mul_f32_e32 v78, v78, v222
	v_mul_f32_e32 v79, v79, v222
	v_mul_f32_e32 v76, v76, v12
	v_mul_f32_e32 v77, v77, v13
	v_mul_f32_e32 v78, v78, v14
	v_mul_f32_e32 v79, v79, v15
	global_store_dwordx4 v250, v[76:79], s[76:77] offset:3072 nt
	v_lshlrev_b32_e32 v64, 16, v40
	v_and_b32_e32 v65, 0xffff0000, v40
	v_lshlrev_b32_e32 v66, 16, v41
	v_and_b32_e32 v67, 0xffff0000, v41
	v_mul_f32_e32 v64, v64, v222
	v_mul_f32_e32 v65, v65, v222
	v_mul_f32_e32 v66, v66, v222
	v_mul_f32_e32 v67, v67, v222
	v_mul_f32_e32 v64, v64, v16
	v_mul_f32_e32 v65, v65, v17
	v_mul_f32_e32 v66, v66, v18
	v_mul_f32_e32 v67, v67, v19
	global_store_dwordx4 v251, v[64:67], s[76:77] offset:0 nt
	v_lshlrev_b32_e32 v68, 16, v42
	v_and_b32_e32 v69, 0xffff0000, v42
	v_lshlrev_b32_e32 v70, 16, v43
	v_and_b32_e32 v71, 0xffff0000, v43
	v_mul_f32_e32 v68, v68, v222
	v_mul_f32_e32 v69, v69, v222
	v_mul_f32_e32 v70, v70, v222
	v_mul_f32_e32 v71, v71, v222
	v_mul_f32_e32 v68, v68, v20
	v_mul_f32_e32 v69, v69, v21
	v_mul_f32_e32 v70, v70, v22
	v_mul_f32_e32 v71, v71, v23
	global_store_dwordx4 v251, v[68:71], s[76:77] offset:1024 nt
	v_lshlrev_b32_e32 v72, 16, v44
	v_and_b32_e32 v73, 0xffff0000, v44
	v_lshlrev_b32_e32 v74, 16, v45
	v_and_b32_e32 v75, 0xffff0000, v45
	v_mul_f32_e32 v72, v72, v222
	v_mul_f32_e32 v73, v73, v222
	v_mul_f32_e32 v74, v74, v222
	v_mul_f32_e32 v75, v75, v222
	v_mul_f32_e32 v72, v72, v24
	v_mul_f32_e32 v73, v73, v25
	v_mul_f32_e32 v74, v74, v26
	v_mul_f32_e32 v75, v75, v27
	global_store_dwordx4 v251, v[72:75], s[76:77] offset:2048 nt
	v_lshlrev_b32_e32 v76, 16, v46
	v_and_b32_e32 v77, 0xffff0000, v46
	v_lshlrev_b32_e32 v78, 16, v47
	v_and_b32_e32 v79, 0xffff0000, v47
	v_mul_f32_e32 v76, v76, v222
	v_mul_f32_e32 v77, v77, v222
	v_mul_f32_e32 v78, v78, v222
	v_mul_f32_e32 v79, v79, v222
	v_mul_f32_e32 v76, v76, v28
	v_mul_f32_e32 v77, v77, v29
	v_mul_f32_e32 v78, v78, v30
	v_mul_f32_e32 v79, v79, v31
	global_store_dwordx4 v251, v[76:79], s[76:77] offset:3072 nt
	s_add_u32 s70, s28, 0x4000
	s_addc_u32 s71, s29, 0
	global_load_dwordx2 v[32:33], v239, s[70:71] offset:0
	global_load_dwordx2 v[34:35], v239, s[70:71] offset:512
	global_load_dwordx2 v[36:37], v239, s[70:71] offset:1024
	global_load_dwordx2 v[38:39], v239, s[70:71] offset:1536
	global_load_dwordx2 v[40:41], v239, s[70:71] offset:2048
	global_load_dwordx2 v[42:43], v239, s[70:71] offset:2560
	global_load_dwordx2 v[44:45], v239, s[70:71] offset:3072
	global_load_dwordx2 v[46:47], v239, s[70:71] offset:3584
	s_waitcnt vmcnt(16)
	s_add_u32 s76, s46, 0x6000
	s_addc_u32 s77, s47, 0
	v_lshlrev_b32_e32 v64, 16, v48
	v_and_b32_e32 v65, 0xffff0000, v48
	v_lshlrev_b32_e32 v66, 16, v49
	v_and_b32_e32 v67, 0xffff0000, v49
	v_mul_f32_e32 v64, v64, v223
	v_mul_f32_e32 v65, v65, v223
	v_mul_f32_e32 v66, v66, v223
	v_mul_f32_e32 v67, v67, v223
	v_mul_f32_e32 v64, v64, v0
	v_mul_f32_e32 v65, v65, v1
	v_mul_f32_e32 v66, v66, v2
	v_mul_f32_e32 v67, v67, v3
	global_store_dwordx4 v250, v[64:67], s[76:77] offset:0 nt
	v_lshlrev_b32_e32 v68, 16, v50
	v_and_b32_e32 v69, 0xffff0000, v50
	v_lshlrev_b32_e32 v70, 16, v51
	v_and_b32_e32 v71, 0xffff0000, v51
	v_mul_f32_e32 v68, v68, v223
	v_mul_f32_e32 v69, v69, v223
	v_mul_f32_e32 v70, v70, v223
	v_mul_f32_e32 v71, v71, v223
	v_mul_f32_e32 v68, v68, v4
	v_mul_f32_e32 v69, v69, v5
	v_mul_f32_e32 v70, v70, v6
	v_mul_f32_e32 v71, v71, v7
	global_store_dwordx4 v250, v[68:71], s[76:77] offset:1024 nt
	v_lshlrev_b32_e32 v72, 16, v52
	v_and_b32_e32 v73, 0xffff0000, v52
	v_lshlrev_b32_e32 v74, 16, v53
	v_and_b32_e32 v75, 0xffff0000, v53
	v_mul_f32_e32 v72, v72, v223
	v_mul_f32_e32 v73, v73, v223
	v_mul_f32_e32 v74, v74, v223
	v_mul_f32_e32 v75, v75, v223
	v_mul_f32_e32 v72, v72, v8
	v_mul_f32_e32 v73, v73, v9
	v_mul_f32_e32 v74, v74, v10
	v_mul_f32_e32 v75, v75, v11
	global_store_dwordx4 v250, v[72:75], s[76:77] offset:2048 nt
	v_lshlrev_b32_e32 v76, 16, v54
	v_and_b32_e32 v77, 0xffff0000, v54
	v_lshlrev_b32_e32 v78, 16, v55
	v_and_b32_e32 v79, 0xffff0000, v55
	v_mul_f32_e32 v76, v76, v223
	v_mul_f32_e32 v77, v77, v223
	v_mul_f32_e32 v78, v78, v223
	v_mul_f32_e32 v79, v79, v223
	v_mul_f32_e32 v76, v76, v12
	v_mul_f32_e32 v77, v77, v13
	v_mul_f32_e32 v78, v78, v14
	v_mul_f32_e32 v79, v79, v15
	global_store_dwordx4 v250, v[76:79], s[76:77] offset:3072 nt
	v_lshlrev_b32_e32 v64, 16, v56
	v_and_b32_e32 v65, 0xffff0000, v56
	v_lshlrev_b32_e32 v66, 16, v57
	v_and_b32_e32 v67, 0xffff0000, v57
	v_mul_f32_e32 v64, v64, v223
	v_mul_f32_e32 v65, v65, v223
	v_mul_f32_e32 v66, v66, v223
	v_mul_f32_e32 v67, v67, v223
	v_mul_f32_e32 v64, v64, v16
	v_mul_f32_e32 v65, v65, v17
	v_mul_f32_e32 v66, v66, v18
	v_mul_f32_e32 v67, v67, v19
	global_store_dwordx4 v251, v[64:67], s[76:77] offset:0 nt
	v_lshlrev_b32_e32 v68, 16, v58
	v_and_b32_e32 v69, 0xffff0000, v58
	v_lshlrev_b32_e32 v70, 16, v59
	v_and_b32_e32 v71, 0xffff0000, v59
	v_mul_f32_e32 v68, v68, v223
	v_mul_f32_e32 v69, v69, v223
	v_mul_f32_e32 v70, v70, v223
	v_mul_f32_e32 v71, v71, v223
	v_mul_f32_e32 v68, v68, v20
	v_mul_f32_e32 v69, v69, v21
	v_mul_f32_e32 v70, v70, v22
	v_mul_f32_e32 v71, v71, v23
	global_store_dwordx4 v251, v[68:71], s[76:77] offset:1024 nt
	v_lshlrev_b32_e32 v72, 16, v60
	v_and_b32_e32 v73, 0xffff0000, v60
	v_lshlrev_b32_e32 v74, 16, v61
	v_and_b32_e32 v75, 0xffff0000, v61
	v_mul_f32_e32 v72, v72, v223
	v_mul_f32_e32 v73, v73, v223
	v_mul_f32_e32 v74, v74, v223
	v_mul_f32_e32 v75, v75, v223
	v_mul_f32_e32 v72, v72, v24
	v_mul_f32_e32 v73, v73, v25
	v_mul_f32_e32 v74, v74, v26
	v_mul_f32_e32 v75, v75, v27
	global_store_dwordx4 v251, v[72:75], s[76:77] offset:2048 nt
	v_lshlrev_b32_e32 v76, 16, v62
	v_and_b32_e32 v77, 0xffff0000, v62
	v_lshlrev_b32_e32 v78, 16, v63
	v_and_b32_e32 v79, 0xffff0000, v63
	v_mul_f32_e32 v76, v76, v223
	v_mul_f32_e32 v77, v77, v223
	v_mul_f32_e32 v78, v78, v223
	v_mul_f32_e32 v79, v79, v223
	v_mul_f32_e32 v76, v76, v28
	v_mul_f32_e32 v77, v77, v29
	v_mul_f32_e32 v78, v78, v30
	v_mul_f32_e32 v79, v79, v31
	global_store_dwordx4 v251, v[76:79], s[76:77] offset:3072 nt
	s_add_u32 s70, s28, 0x5000
	s_addc_u32 s71, s29, 0
	global_load_dwordx2 v[48:49], v239, s[70:71] offset:0
	global_load_dwordx2 v[50:51], v239, s[70:71] offset:512
	global_load_dwordx2 v[52:53], v239, s[70:71] offset:1024
	global_load_dwordx2 v[54:55], v239, s[70:71] offset:1536
	global_load_dwordx2 v[56:57], v239, s[70:71] offset:2048
	global_load_dwordx2 v[58:59], v239, s[70:71] offset:2560
	global_load_dwordx2 v[60:61], v239, s[70:71] offset:3072
	global_load_dwordx2 v[62:63], v239, s[70:71] offset:3584
	s_waitcnt vmcnt(16)
	s_add_u32 s76, s46, 0x8000
	s_addc_u32 s77, s47, 0
	v_lshlrev_b32_e32 v64, 16, v32
	v_and_b32_e32 v65, 0xffff0000, v32
	v_lshlrev_b32_e32 v66, 16, v33
	v_and_b32_e32 v67, 0xffff0000, v33
	v_mul_f32_e32 v64, v64, v224
	v_mul_f32_e32 v65, v65, v224
	v_mul_f32_e32 v66, v66, v224
	v_mul_f32_e32 v67, v67, v224
	v_mul_f32_e32 v64, v64, v0
	v_mul_f32_e32 v65, v65, v1
	v_mul_f32_e32 v66, v66, v2
	v_mul_f32_e32 v67, v67, v3
	global_store_dwordx4 v250, v[64:67], s[76:77] offset:0 nt
	v_lshlrev_b32_e32 v68, 16, v34
	v_and_b32_e32 v69, 0xffff0000, v34
	v_lshlrev_b32_e32 v70, 16, v35
	v_and_b32_e32 v71, 0xffff0000, v35
	v_mul_f32_e32 v68, v68, v224
	v_mul_f32_e32 v69, v69, v224
	v_mul_f32_e32 v70, v70, v224
	v_mul_f32_e32 v71, v71, v224
	v_mul_f32_e32 v68, v68, v4
	v_mul_f32_e32 v69, v69, v5
	v_mul_f32_e32 v70, v70, v6
	v_mul_f32_e32 v71, v71, v7
	global_store_dwordx4 v250, v[68:71], s[76:77] offset:1024 nt
	v_lshlrev_b32_e32 v72, 16, v36
	v_and_b32_e32 v73, 0xffff0000, v36
	v_lshlrev_b32_e32 v74, 16, v37
	v_and_b32_e32 v75, 0xffff0000, v37
	v_mul_f32_e32 v72, v72, v224
	v_mul_f32_e32 v73, v73, v224
	v_mul_f32_e32 v74, v74, v224
	v_mul_f32_e32 v75, v75, v224
	v_mul_f32_e32 v72, v72, v8
	v_mul_f32_e32 v73, v73, v9
	v_mul_f32_e32 v74, v74, v10
	v_mul_f32_e32 v75, v75, v11
	global_store_dwordx4 v250, v[72:75], s[76:77] offset:2048 nt
	v_lshlrev_b32_e32 v76, 16, v38
	v_and_b32_e32 v77, 0xffff0000, v38
	v_lshlrev_b32_e32 v78, 16, v39
	v_and_b32_e32 v79, 0xffff0000, v39
	v_mul_f32_e32 v76, v76, v224
	v_mul_f32_e32 v77, v77, v224
	v_mul_f32_e32 v78, v78, v224
	v_mul_f32_e32 v79, v79, v224
	v_mul_f32_e32 v76, v76, v12
	v_mul_f32_e32 v77, v77, v13
	v_mul_f32_e32 v78, v78, v14
	v_mul_f32_e32 v79, v79, v15
	global_store_dwordx4 v250, v[76:79], s[76:77] offset:3072 nt
	v_lshlrev_b32_e32 v64, 16, v40
	v_and_b32_e32 v65, 0xffff0000, v40
	v_lshlrev_b32_e32 v66, 16, v41
	v_and_b32_e32 v67, 0xffff0000, v41
	v_mul_f32_e32 v64, v64, v224
	v_mul_f32_e32 v65, v65, v224
	v_mul_f32_e32 v66, v66, v224
	v_mul_f32_e32 v67, v67, v224
	v_mul_f32_e32 v64, v64, v16
	v_mul_f32_e32 v65, v65, v17
	v_mul_f32_e32 v66, v66, v18
	v_mul_f32_e32 v67, v67, v19
	global_store_dwordx4 v251, v[64:67], s[76:77] offset:0 nt
	v_lshlrev_b32_e32 v68, 16, v42
	v_and_b32_e32 v69, 0xffff0000, v42
	v_lshlrev_b32_e32 v70, 16, v43
	v_and_b32_e32 v71, 0xffff0000, v43
	v_mul_f32_e32 v68, v68, v224
	v_mul_f32_e32 v69, v69, v224
	v_mul_f32_e32 v70, v70, v224
	v_mul_f32_e32 v71, v71, v224
	v_mul_f32_e32 v68, v68, v20
	v_mul_f32_e32 v69, v69, v21
	v_mul_f32_e32 v70, v70, v22
	v_mul_f32_e32 v71, v71, v23
	global_store_dwordx4 v251, v[68:71], s[76:77] offset:1024 nt
	v_lshlrev_b32_e32 v72, 16, v44
	v_and_b32_e32 v73, 0xffff0000, v44
	v_lshlrev_b32_e32 v74, 16, v45
	v_and_b32_e32 v75, 0xffff0000, v45
	v_mul_f32_e32 v72, v72, v224
	v_mul_f32_e32 v73, v73, v224
	v_mul_f32_e32 v74, v74, v224
	v_mul_f32_e32 v75, v75, v224
	v_mul_f32_e32 v72, v72, v24
	v_mul_f32_e32 v73, v73, v25
	v_mul_f32_e32 v74, v74, v26
	v_mul_f32_e32 v75, v75, v27
	global_store_dwordx4 v251, v[72:75], s[76:77] offset:2048 nt
	v_lshlrev_b32_e32 v76, 16, v46
	v_and_b32_e32 v77, 0xffff0000, v46
	v_lshlrev_b32_e32 v78, 16, v47
	v_and_b32_e32 v79, 0xffff0000, v47
	v_mul_f32_e32 v76, v76, v224
	v_mul_f32_e32 v77, v77, v224
	v_mul_f32_e32 v78, v78, v224
	v_mul_f32_e32 v79, v79, v224
	v_mul_f32_e32 v76, v76, v28
	v_mul_f32_e32 v77, v77, v29
	v_mul_f32_e32 v78, v78, v30
	v_mul_f32_e32 v79, v79, v31
	global_store_dwordx4 v251, v[76:79], s[76:77] offset:3072 nt
	s_add_u32 s70, s28, 0x6000
	s_addc_u32 s71, s29, 0
	global_load_dwordx2 v[32:33], v239, s[70:71] offset:0
	global_load_dwordx2 v[34:35], v239, s[70:71] offset:512
	global_load_dwordx2 v[36:37], v239, s[70:71] offset:1024
	global_load_dwordx2 v[38:39], v239, s[70:71] offset:1536
	global_load_dwordx2 v[40:41], v239, s[70:71] offset:2048
	global_load_dwordx2 v[42:43], v239, s[70:71] offset:2560
	global_load_dwordx2 v[44:45], v239, s[70:71] offset:3072
	global_load_dwordx2 v[46:47], v239, s[70:71] offset:3584
	s_waitcnt vmcnt(16)
	s_add_u32 s76, s46, 0xa000
	s_addc_u32 s77, s47, 0
	v_lshlrev_b32_e32 v64, 16, v48
	v_and_b32_e32 v65, 0xffff0000, v48
	v_lshlrev_b32_e32 v66, 16, v49
	v_and_b32_e32 v67, 0xffff0000, v49
	v_mul_f32_e32 v64, v64, v225
	v_mul_f32_e32 v65, v65, v225
	v_mul_f32_e32 v66, v66, v225
	v_mul_f32_e32 v67, v67, v225
	v_mul_f32_e32 v64, v64, v0
	v_mul_f32_e32 v65, v65, v1
	v_mul_f32_e32 v66, v66, v2
	v_mul_f32_e32 v67, v67, v3
	global_store_dwordx4 v250, v[64:67], s[76:77] offset:0 nt
	v_lshlrev_b32_e32 v68, 16, v50
	v_and_b32_e32 v69, 0xffff0000, v50
	v_lshlrev_b32_e32 v70, 16, v51
	v_and_b32_e32 v71, 0xffff0000, v51
	v_mul_f32_e32 v68, v68, v225
	v_mul_f32_e32 v69, v69, v225
	v_mul_f32_e32 v70, v70, v225
	v_mul_f32_e32 v71, v71, v225
	v_mul_f32_e32 v68, v68, v4
	v_mul_f32_e32 v69, v69, v5
	v_mul_f32_e32 v70, v70, v6
	v_mul_f32_e32 v71, v71, v7
	global_store_dwordx4 v250, v[68:71], s[76:77] offset:1024 nt
	v_lshlrev_b32_e32 v72, 16, v52
	v_and_b32_e32 v73, 0xffff0000, v52
	v_lshlrev_b32_e32 v74, 16, v53
	v_and_b32_e32 v75, 0xffff0000, v53
	v_mul_f32_e32 v72, v72, v225
	v_mul_f32_e32 v73, v73, v225
	v_mul_f32_e32 v74, v74, v225
	v_mul_f32_e32 v75, v75, v225
	v_mul_f32_e32 v72, v72, v8
	v_mul_f32_e32 v73, v73, v9
	v_mul_f32_e32 v74, v74, v10
	v_mul_f32_e32 v75, v75, v11
	global_store_dwordx4 v250, v[72:75], s[76:77] offset:2048 nt
	v_lshlrev_b32_e32 v76, 16, v54
	v_and_b32_e32 v77, 0xffff0000, v54
	v_lshlrev_b32_e32 v78, 16, v55
	v_and_b32_e32 v79, 0xffff0000, v55
	v_mul_f32_e32 v76, v76, v225
	v_mul_f32_e32 v77, v77, v225
	v_mul_f32_e32 v78, v78, v225
	v_mul_f32_e32 v79, v79, v225
	v_mul_f32_e32 v76, v76, v12
	v_mul_f32_e32 v77, v77, v13
	v_mul_f32_e32 v78, v78, v14
	v_mul_f32_e32 v79, v79, v15
	global_store_dwordx4 v250, v[76:79], s[76:77] offset:3072 nt
	v_lshlrev_b32_e32 v64, 16, v56
	v_and_b32_e32 v65, 0xffff0000, v56
	v_lshlrev_b32_e32 v66, 16, v57
	v_and_b32_e32 v67, 0xffff0000, v57
	v_mul_f32_e32 v64, v64, v225
	v_mul_f32_e32 v65, v65, v225
	v_mul_f32_e32 v66, v66, v225
	v_mul_f32_e32 v67, v67, v225
	v_mul_f32_e32 v64, v64, v16
	v_mul_f32_e32 v65, v65, v17
	v_mul_f32_e32 v66, v66, v18
	v_mul_f32_e32 v67, v67, v19
	global_store_dwordx4 v251, v[64:67], s[76:77] offset:0 nt
	v_lshlrev_b32_e32 v68, 16, v58
	v_and_b32_e32 v69, 0xffff0000, v58
	v_lshlrev_b32_e32 v70, 16, v59
	v_and_b32_e32 v71, 0xffff0000, v59
	v_mul_f32_e32 v68, v68, v225
	v_mul_f32_e32 v69, v69, v225
	v_mul_f32_e32 v70, v70, v225
	v_mul_f32_e32 v71, v71, v225
	v_mul_f32_e32 v68, v68, v20
	v_mul_f32_e32 v69, v69, v21
	v_mul_f32_e32 v70, v70, v22
	v_mul_f32_e32 v71, v71, v23
	global_store_dwordx4 v251, v[68:71], s[76:77] offset:1024 nt
	v_lshlrev_b32_e32 v72, 16, v60
	v_and_b32_e32 v73, 0xffff0000, v60
	v_lshlrev_b32_e32 v74, 16, v61
	v_and_b32_e32 v75, 0xffff0000, v61
	v_mul_f32_e32 v72, v72, v225
	v_mul_f32_e32 v73, v73, v225
	v_mul_f32_e32 v74, v74, v225
	v_mul_f32_e32 v75, v75, v225
	v_mul_f32_e32 v72, v72, v24
	v_mul_f32_e32 v73, v73, v25
	v_mul_f32_e32 v74, v74, v26
	v_mul_f32_e32 v75, v75, v27
	global_store_dwordx4 v251, v[72:75], s[76:77] offset:2048 nt
	v_lshlrev_b32_e32 v76, 16, v62
	v_and_b32_e32 v77, 0xffff0000, v62
	v_lshlrev_b32_e32 v78, 16, v63
	v_and_b32_e32 v79, 0xffff0000, v63
	v_mul_f32_e32 v76, v76, v225
	v_mul_f32_e32 v77, v77, v225
	v_mul_f32_e32 v78, v78, v225
	v_mul_f32_e32 v79, v79, v225
	v_mul_f32_e32 v76, v76, v28
	v_mul_f32_e32 v77, v77, v29
	v_mul_f32_e32 v78, v78, v30
	v_mul_f32_e32 v79, v79, v31
	global_store_dwordx4 v251, v[76:79], s[76:77] offset:3072 nt
	s_add_u32 s70, s28, 0x7000
	s_addc_u32 s71, s29, 0
	global_load_dwordx2 v[48:49], v239, s[70:71] offset:0
	global_load_dwordx2 v[50:51], v239, s[70:71] offset:512
	global_load_dwordx2 v[52:53], v239, s[70:71] offset:1024
	global_load_dwordx2 v[54:55], v239, s[70:71] offset:1536
	global_load_dwordx2 v[56:57], v239, s[70:71] offset:2048
	global_load_dwordx2 v[58:59], v239, s[70:71] offset:2560
	global_load_dwordx2 v[60:61], v239, s[70:71] offset:3072
	global_load_dwordx2 v[62:63], v239, s[70:71] offset:3584
	s_waitcnt vmcnt(16)
	s_add_u32 s76, s46, 0xc000
	s_addc_u32 s77, s47, 0
	v_lshlrev_b32_e32 v64, 16, v32
	v_and_b32_e32 v65, 0xffff0000, v32
	v_lshlrev_b32_e32 v66, 16, v33
	v_and_b32_e32 v67, 0xffff0000, v33
	v_mul_f32_e32 v64, v64, v226
	v_mul_f32_e32 v65, v65, v226
	v_mul_f32_e32 v66, v66, v226
	v_mul_f32_e32 v67, v67, v226
	v_mul_f32_e32 v64, v64, v0
	v_mul_f32_e32 v65, v65, v1
	v_mul_f32_e32 v66, v66, v2
	v_mul_f32_e32 v67, v67, v3
	global_store_dwordx4 v250, v[64:67], s[76:77] offset:0 nt
	v_lshlrev_b32_e32 v68, 16, v34
	v_and_b32_e32 v69, 0xffff0000, v34
	v_lshlrev_b32_e32 v70, 16, v35
	v_and_b32_e32 v71, 0xffff0000, v35
	v_mul_f32_e32 v68, v68, v226
	v_mul_f32_e32 v69, v69, v226
	v_mul_f32_e32 v70, v70, v226
	v_mul_f32_e32 v71, v71, v226
	v_mul_f32_e32 v68, v68, v4
	v_mul_f32_e32 v69, v69, v5
	v_mul_f32_e32 v70, v70, v6
	v_mul_f32_e32 v71, v71, v7
	global_store_dwordx4 v250, v[68:71], s[76:77] offset:1024 nt
	v_lshlrev_b32_e32 v72, 16, v36
	v_and_b32_e32 v73, 0xffff0000, v36
	v_lshlrev_b32_e32 v74, 16, v37
	v_and_b32_e32 v75, 0xffff0000, v37
	v_mul_f32_e32 v72, v72, v226
	v_mul_f32_e32 v73, v73, v226
	v_mul_f32_e32 v74, v74, v226
	v_mul_f32_e32 v75, v75, v226
	v_mul_f32_e32 v72, v72, v8
	v_mul_f32_e32 v73, v73, v9
	v_mul_f32_e32 v74, v74, v10
	v_mul_f32_e32 v75, v75, v11
	global_store_dwordx4 v250, v[72:75], s[76:77] offset:2048 nt
	v_lshlrev_b32_e32 v76, 16, v38
	v_and_b32_e32 v77, 0xffff0000, v38
	v_lshlrev_b32_e32 v78, 16, v39
	v_and_b32_e32 v79, 0xffff0000, v39
	v_mul_f32_e32 v76, v76, v226
	v_mul_f32_e32 v77, v77, v226
	v_mul_f32_e32 v78, v78, v226
	v_mul_f32_e32 v79, v79, v226
	v_mul_f32_e32 v76, v76, v12
	v_mul_f32_e32 v77, v77, v13
	v_mul_f32_e32 v78, v78, v14
	v_mul_f32_e32 v79, v79, v15
	global_store_dwordx4 v250, v[76:79], s[76:77] offset:3072 nt
	v_lshlrev_b32_e32 v64, 16, v40
	v_and_b32_e32 v65, 0xffff0000, v40
	v_lshlrev_b32_e32 v66, 16, v41
	v_and_b32_e32 v67, 0xffff0000, v41
	v_mul_f32_e32 v64, v64, v226
	v_mul_f32_e32 v65, v65, v226
	v_mul_f32_e32 v66, v66, v226
	v_mul_f32_e32 v67, v67, v226
	v_mul_f32_e32 v64, v64, v16
	v_mul_f32_e32 v65, v65, v17
	v_mul_f32_e32 v66, v66, v18
	v_mul_f32_e32 v67, v67, v19
	global_store_dwordx4 v251, v[64:67], s[76:77] offset:0 nt
	v_lshlrev_b32_e32 v68, 16, v42
	v_and_b32_e32 v69, 0xffff0000, v42
	v_lshlrev_b32_e32 v70, 16, v43
	v_and_b32_e32 v71, 0xffff0000, v43
	v_mul_f32_e32 v68, v68, v226
	v_mul_f32_e32 v69, v69, v226
	v_mul_f32_e32 v70, v70, v226
	v_mul_f32_e32 v71, v71, v226
	v_mul_f32_e32 v68, v68, v20
	v_mul_f32_e32 v69, v69, v21
	v_mul_f32_e32 v70, v70, v22
	v_mul_f32_e32 v71, v71, v23
	global_store_dwordx4 v251, v[68:71], s[76:77] offset:1024 nt
	v_lshlrev_b32_e32 v72, 16, v44
	v_and_b32_e32 v73, 0xffff0000, v44
	v_lshlrev_b32_e32 v74, 16, v45
	v_and_b32_e32 v75, 0xffff0000, v45
	v_mul_f32_e32 v72, v72, v226
	v_mul_f32_e32 v73, v73, v226
	v_mul_f32_e32 v74, v74, v226
	v_mul_f32_e32 v75, v75, v226
	v_mul_f32_e32 v72, v72, v24
	v_mul_f32_e32 v73, v73, v25
	v_mul_f32_e32 v74, v74, v26
	v_mul_f32_e32 v75, v75, v27
	global_store_dwordx4 v251, v[72:75], s[76:77] offset:2048 nt
	v_lshlrev_b32_e32 v76, 16, v46
	v_and_b32_e32 v77, 0xffff0000, v46
	v_lshlrev_b32_e32 v78, 16, v47
	v_and_b32_e32 v79, 0xffff0000, v47
	v_mul_f32_e32 v76, v76, v226
	v_mul_f32_e32 v77, v77, v226
	v_mul_f32_e32 v78, v78, v226
	v_mul_f32_e32 v79, v79, v226
	v_mul_f32_e32 v76, v76, v28
	v_mul_f32_e32 v77, v77, v29
	v_mul_f32_e32 v78, v78, v30
	v_mul_f32_e32 v79, v79, v31
	global_store_dwordx4 v251, v[76:79], s[76:77] offset:3072 nt
	s_waitcnt vmcnt(8)
	s_add_u32 s76, s46, 0xe000
	s_addc_u32 s77, s47, 0
	v_lshlrev_b32_e32 v64, 16, v48
	v_and_b32_e32 v65, 0xffff0000, v48
	v_lshlrev_b32_e32 v66, 16, v49
	v_and_b32_e32 v67, 0xffff0000, v49
	v_mul_f32_e32 v64, v64, v227
	v_mul_f32_e32 v65, v65, v227
	v_mul_f32_e32 v66, v66, v227
	v_mul_f32_e32 v67, v67, v227
	v_mul_f32_e32 v64, v64, v0
	v_mul_f32_e32 v65, v65, v1
	v_mul_f32_e32 v66, v66, v2
	v_mul_f32_e32 v67, v67, v3
	global_store_dwordx4 v250, v[64:67], s[76:77] offset:0 nt
	v_lshlrev_b32_e32 v68, 16, v50
	v_and_b32_e32 v69, 0xffff0000, v50
	v_lshlrev_b32_e32 v70, 16, v51
	v_and_b32_e32 v71, 0xffff0000, v51
	v_mul_f32_e32 v68, v68, v227
	v_mul_f32_e32 v69, v69, v227
	v_mul_f32_e32 v70, v70, v227
	v_mul_f32_e32 v71, v71, v227
	v_mul_f32_e32 v68, v68, v4
	v_mul_f32_e32 v69, v69, v5
	v_mul_f32_e32 v70, v70, v6
	v_mul_f32_e32 v71, v71, v7
	global_store_dwordx4 v250, v[68:71], s[76:77] offset:1024 nt
	v_lshlrev_b32_e32 v72, 16, v52
	v_and_b32_e32 v73, 0xffff0000, v52
	v_lshlrev_b32_e32 v74, 16, v53
	v_and_b32_e32 v75, 0xffff0000, v53
	v_mul_f32_e32 v72, v72, v227
	v_mul_f32_e32 v73, v73, v227
	v_mul_f32_e32 v74, v74, v227
	v_mul_f32_e32 v75, v75, v227
	v_mul_f32_e32 v72, v72, v8
	v_mul_f32_e32 v73, v73, v9
	v_mul_f32_e32 v74, v74, v10
	v_mul_f32_e32 v75, v75, v11
	global_store_dwordx4 v250, v[72:75], s[76:77] offset:2048 nt
	v_lshlrev_b32_e32 v76, 16, v54
	v_and_b32_e32 v77, 0xffff0000, v54
	v_lshlrev_b32_e32 v78, 16, v55
	v_and_b32_e32 v79, 0xffff0000, v55
	v_mul_f32_e32 v76, v76, v227
	v_mul_f32_e32 v77, v77, v227
	v_mul_f32_e32 v78, v78, v227
	v_mul_f32_e32 v79, v79, v227
	v_mul_f32_e32 v76, v76, v12
	v_mul_f32_e32 v77, v77, v13
	v_mul_f32_e32 v78, v78, v14
	v_mul_f32_e32 v79, v79, v15
	global_store_dwordx4 v250, v[76:79], s[76:77] offset:3072 nt
	v_lshlrev_b32_e32 v64, 16, v56
	v_and_b32_e32 v65, 0xffff0000, v56
	v_lshlrev_b32_e32 v66, 16, v57
	v_and_b32_e32 v67, 0xffff0000, v57
	v_mul_f32_e32 v64, v64, v227
	v_mul_f32_e32 v65, v65, v227
	v_mul_f32_e32 v66, v66, v227
	v_mul_f32_e32 v67, v67, v227
	v_mul_f32_e32 v64, v64, v16
	v_mul_f32_e32 v65, v65, v17
	v_mul_f32_e32 v66, v66, v18
	v_mul_f32_e32 v67, v67, v19
	global_store_dwordx4 v251, v[64:67], s[76:77] offset:0 nt
	v_lshlrev_b32_e32 v68, 16, v58
	v_and_b32_e32 v69, 0xffff0000, v58
	v_lshlrev_b32_e32 v70, 16, v59
	v_and_b32_e32 v71, 0xffff0000, v59
	v_mul_f32_e32 v68, v68, v227
	v_mul_f32_e32 v69, v69, v227
	v_mul_f32_e32 v70, v70, v227
	v_mul_f32_e32 v71, v71, v227
	v_mul_f32_e32 v68, v68, v20
	v_mul_f32_e32 v69, v69, v21
	v_mul_f32_e32 v70, v70, v22
	v_mul_f32_e32 v71, v71, v23
	global_store_dwordx4 v251, v[68:71], s[76:77] offset:1024 nt
	v_lshlrev_b32_e32 v72, 16, v60
	v_and_b32_e32 v73, 0xffff0000, v60
	v_lshlrev_b32_e32 v74, 16, v61
	v_and_b32_e32 v75, 0xffff0000, v61
	v_mul_f32_e32 v72, v72, v227
	v_mul_f32_e32 v73, v73, v227
	v_mul_f32_e32 v74, v74, v227
	v_mul_f32_e32 v75, v75, v227
	v_mul_f32_e32 v72, v72, v24
	v_mul_f32_e32 v73, v73, v25
	v_mul_f32_e32 v74, v74, v26
	v_mul_f32_e32 v75, v75, v27
	global_store_dwordx4 v251, v[72:75], s[76:77] offset:2048 nt
	v_lshlrev_b32_e32 v76, 16, v62
	v_and_b32_e32 v77, 0xffff0000, v62
	v_lshlrev_b32_e32 v78, 16, v63
	v_and_b32_e32 v79, 0xffff0000, v63
	v_mul_f32_e32 v76, v76, v227
	v_mul_f32_e32 v77, v77, v227
	v_mul_f32_e32 v78, v78, v227
	v_mul_f32_e32 v79, v79, v227
	v_mul_f32_e32 v76, v76, v28
	v_mul_f32_e32 v77, v77, v29
	v_mul_f32_e32 v78, v78, v30
	v_mul_f32_e32 v79, v79, v31
	global_store_dwordx4 v251, v[76:79], s[76:77] offset:3072 nt
	s_add_u32 s63, s63, s90
	s_cmpk_lt_i32 s63, 0x800
	s_cbranch_scc1 .LpgL1_group
